# gla_prep pass-1 loop: all 16 gate-input loads of an 8-token iteration issued up front with counted vmcnt waits (was load->vmcnt(0) per token); on top of v52
# baseline (speedup 1.0000x reference)
.LBB0_569:
	s_add_u32 s4, s0, s10
	s_addc_u32 s5, s1, s11
	s_add_u32 s18, s4, 0x35802800
	s_addc_u32 s19, s5, 0
	global_load_dwordx4 v[180:183], v3, s[18:19] offset:16
	v_mov_b32_e32 v171, 0x35802000
	global_load_dwordx4 v[184:187], v171, s[4:5] offset:2048
	s_add_u32 s18, s4, 0x35805200
	s_addc_u32 s19, s5, 0
	global_load_dwordx4 v[188:191], v3, s[18:19] offset:16
	v_mov_b32_e32 v171, 0x35805000
	global_load_dwordx4 v[192:195], v171, s[4:5] offset:512
	s_add_u32 s18, s4, 0x35807c00
	s_addc_u32 s19, s5, 0
	global_load_dwordx4 v[196:199], v3, s[18:19] offset:16
	v_mov_b32_e32 v171, 0x35807000
	global_load_dwordx4 v[200:203], v171, s[4:5] offset:3072
	s_add_u32 s18, s4, 0x3580a600
	s_addc_u32 s19, s5, 0
	global_load_dwordx4 v[204:207], v3, s[18:19] offset:16
	v_mov_b32_e32 v171, 0x3580a000
	global_load_dwordx4 v[208:211], v171, s[4:5] offset:1536
	s_add_u32 s18, s4, 0x3580d000
	s_addc_u32 s19, s5, 0
	global_load_dwordx4 v[212:215], v3, s[18:19] offset:16
	v_mov_b32_e32 v171, 0x3580d000
	global_load_dwordx4 v[216:219], v171, s[4:5]
	s_add_u32 s18, s4, 0x3580fa00
	s_addc_u32 s19, s5, 0
	global_load_dwordx4 v[220:223], v3, s[18:19] offset:16
	v_mov_b32_e32 v171, 0x3580f000
	global_load_dwordx4 v[226:229], v171, s[4:5] offset:2560
	s_add_u32 s18, s4, 0x35812400
	s_addc_u32 s19, s5, 0
	global_load_dwordx4 v[236:239], v3, s[18:19] offset:16
	v_mov_b32_e32 v171, 0x35812000
	global_load_dwordx4 v[240:243], v171, s[4:5] offset:1024
	s_add_u32 s18, s4, 0x35814e00
	s_addc_u32 s19, s5, 0
	global_load_dwordx4 v[244:247], v3, s[18:19] offset:16
	v_mov_b32_e32 v171, 0x35814000
	global_load_dwordx4 v[248:251], v171, s[4:5] offset:3584
	s_add_u32 s18, s4, 0x35802800
	s_addc_u32 s19, s5, 0
	v_mov_b32_e32 v85, 0x35802000
	s_add_u32 s18, s4, 0x35805200
	s_addc_u32 s19, s5, 0
	s_waitcnt vmcnt(14)
	v_lshlrev_b32_e32 v132, 16, v184
	v_pk_fma_f32 v[134:135], v[70:71], v[132:133], v[66:67] op_sel_hi:[1,0,1]
	v_pk_fma_f32 v[132:133], v[68:69], v[132:133], v[64:65] op_sel_hi:[1,0,1]
	v_and_b32_e32 v128, 0xffff0000, v184
	v_pk_fma_f32 v[134:135], v[62:63], v[128:129], v[134:135] op_sel_hi:[1,0,1]
	v_pk_fma_f32 v[132:133], v[60:61], v[128:129], v[132:133] op_sel_hi:[1,0,1]
	v_lshlrev_b32_e32 v128, 16, v185
	v_pk_fma_f32 v[134:135], v[58:59], v[128:129], v[134:135] op_sel_hi:[1,0,1]
	v_pk_fma_f32 v[132:133], v[56:57], v[128:129], v[132:133] op_sel_hi:[1,0,1]
	v_and_b32_e32 v128, 0xffff0000, v185
	v_pk_fma_f32 v[134:135], v[54:55], v[128:129], v[134:135] op_sel_hi:[1,0,1]
	v_pk_fma_f32 v[128:129], v[52:53], v[128:129], v[132:133] op_sel_hi:[1,0,1]
	v_lshlrev_b32_e32 v132, 16, v186
	v_pk_fma_f32 v[134:135], v[50:51], v[132:133], v[134:135] op_sel_hi:[1,0,1]
	v_pk_fma_f32 v[128:129], v[48:49], v[132:133], v[128:129] op_sel_hi:[1,0,1]
	v_and_b32_e32 v130, 0xffff0000, v186
	v_pk_fma_f32 v[132:133], v[46:47], v[130:131], v[134:135] op_sel_hi:[1,0,1]
	v_pk_fma_f32 v[128:129], v[44:45], v[130:131], v[128:129] op_sel_hi:[1,0,1]
	v_lshlrev_b32_e32 v130, 16, v187
	v_pk_fma_f32 v[132:133], v[42:43], v[130:131], v[132:133] op_sel_hi:[1,0,1]
	v_pk_fma_f32 v[128:129], v[40:41], v[130:131], v[128:129] op_sel_hi:[1,0,1]
	v_and_b32_e32 v130, 0xffff0000, v187
	v_pk_fma_f32 v[132:133], v[38:39], v[130:131], v[132:133] op_sel_hi:[1,0,1]
	v_pk_fma_f32 v[128:129], v[36:37], v[130:131], v[128:129] op_sel_hi:[1,0,1]
	v_lshlrev_b32_e32 v130, 16, v180
	v_pk_fma_f32 v[132:133], v[34:35], v[130:131], v[132:133] op_sel_hi:[1,0,1]
	v_pk_fma_f32 v[128:129], v[32:33], v[130:131], v[128:129] op_sel_hi:[1,0,1]
	v_and_b32_e32 v76, 0xffff0000, v180
	v_pk_fma_f32 v[130:131], v[30:31], v[76:77], v[132:133] op_sel_hi:[1,0,1]
	v_pk_fma_f32 v[128:129], v[28:29], v[76:77], v[128:129] op_sel_hi:[1,0,1]
	v_lshlrev_b32_e32 v76, 16, v181
	v_pk_fma_f32 v[130:131], v[26:27], v[76:77], v[130:131] op_sel_hi:[1,0,1]
	v_pk_fma_f32 v[128:129], v[24:25], v[76:77], v[128:129] op_sel_hi:[1,0,1]
	v_and_b32_e32 v76, 0xffff0000, v181
	v_pk_fma_f32 v[130:131], v[22:23], v[76:77], v[130:131] op_sel_hi:[1,0,1]
	v_pk_fma_f32 v[76:77], v[20:21], v[76:77], v[128:129] op_sel_hi:[1,0,1]
	v_lshlrev_b32_e32 v128, 16, v182
	v_pk_fma_f32 v[130:131], v[18:19], v[128:129], v[130:131] op_sel_hi:[1,0,1]
	v_pk_fma_f32 v[76:77], v[16:17], v[128:129], v[76:77] op_sel_hi:[1,0,1]
	v_and_b32_e32 v78, 0xffff0000, v182
	v_pk_fma_f32 v[128:129], v[14:15], v[78:79], v[130:131] op_sel_hi:[1,0,1]
	v_pk_fma_f32 v[76:77], v[12:13], v[78:79], v[76:77] op_sel_hi:[1,0,1]
	v_lshlrev_b32_e32 v78, 16, v183
	v_pk_fma_f32 v[128:129], v[10:11], v[78:79], v[128:129] op_sel_hi:[1,0,1]
	v_pk_fma_f32 v[76:77], v[8:9], v[78:79], v[76:77] op_sel_hi:[1,0,1]
	v_and_b32_e32 v78, 0xffff0000, v183
	v_pk_fma_f32 v[76:77], v[4:5], v[78:79], v[76:77] op_sel_hi:[1,0,1]
	v_pk_fma_f32 v[128:129], v[6:7], v[78:79], v[128:129] op_sel_hi:[1,0,1]
	v_min_f32_e32 v78, 0, v76
	v_mul_f32_e64 v76, |v76|, s93
	v_exp_f32_e32 v76, v76
	v_min_f32_e32 v79, 0, v77
	v_add_f32_e32 v76, 1.0, v76
	v_log_f32_e32 v85, v76
	v_mul_f32_e64 v76, |v77|, s93
	v_mul_f32_e64 v77, |v128|, s93
	v_exp_f32_e32 v76, v76
	v_exp_f32_e32 v77, v77
	v_add_f32_e32 v76, 1.0, v76
	v_add_f32_e32 v77, 1.0, v77
	v_log_f32_e32 v91, v76
	v_min_f32_e32 v76, 0, v128
	v_log_f32_e32 v128, v77
	v_min_f32_e32 v77, 0, v129
	v_mul_f32_e64 v129, |v129|, s93
	v_exp_f32_e32 v129, v129
	v_xor_b32_e32 v128, 0x80000000, v128
	v_add_f32_e32 v129, 1.0, v129
	v_log_f32_e32 v129, v129
	s_nop 0
	v_xor_b32_e32 v129, 0x80000000, v129
	v_pk_fma_f32 v[76:77], v[128:129], s[88:89], v[76:77] op_sel_hi:[1,0,1]
	v_xor_b32_e32 v129, 0x80000000, v91
	v_xor_b32_e32 v128, 0x80000000, v85
	v_pk_fma_f32 v[78:79], v[128:129], s[88:89], v[78:79] op_sel_hi:[1,0,1]
	v_pk_add_f32 v[128:129], v[74:75], v[76:77]
	v_mov_b32_e32 v76, 0x35805000
	v_pk_add_f32 v[130:131], v[72:73], v[78:79]
	v_mov_b32_e32 v85, 0x35807000
	s_add_u32 s18, s4, 0x35807c00
	s_addc_u32 s19, s5, 0
	s_waitcnt vmcnt(12)
	v_lshlrev_b32_e32 v132, 16, v192
	v_pk_fma_f32 v[134:135], v[70:71], v[132:133], v[66:67] op_sel_hi:[1,0,1]
	v_pk_fma_f32 v[132:133], v[68:69], v[132:133], v[64:65] op_sel_hi:[1,0,1]
	v_and_b32_e32 v76, 0xffff0000, v192
	v_pk_fma_f32 v[134:135], v[62:63], v[76:77], v[134:135] op_sel_hi:[1,0,1]
	v_pk_fma_f32 v[132:133], v[60:61], v[76:77], v[132:133] op_sel_hi:[1,0,1]
	v_lshlrev_b32_e32 v76, 16, v193
	v_pk_fma_f32 v[134:135], v[58:59], v[76:77], v[134:135] op_sel_hi:[1,0,1]
	v_pk_fma_f32 v[132:133], v[56:57], v[76:77], v[132:133] op_sel_hi:[1,0,1]
	v_and_b32_e32 v76, 0xffff0000, v193
	v_pk_fma_f32 v[134:135], v[54:55], v[76:77], v[134:135] op_sel_hi:[1,0,1]
	v_pk_fma_f32 v[76:77], v[52:53], v[76:77], v[132:133] op_sel_hi:[1,0,1]
	v_lshlrev_b32_e32 v132, 16, v194
	v_pk_fma_f32 v[134:135], v[50:51], v[132:133], v[134:135] op_sel_hi:[1,0,1]
	v_pk_fma_f32 v[76:77], v[48:49], v[132:133], v[76:77] op_sel_hi:[1,0,1]
	v_and_b32_e32 v78, 0xffff0000, v194
	v_pk_fma_f32 v[132:133], v[46:47], v[78:79], v[134:135] op_sel_hi:[1,0,1]
	v_pk_fma_f32 v[76:77], v[44:45], v[78:79], v[76:77] op_sel_hi:[1,0,1]
	v_lshlrev_b32_e32 v78, 16, v195
	v_pk_fma_f32 v[132:133], v[42:43], v[78:79], v[132:133] op_sel_hi:[1,0,1]
	v_pk_fma_f32 v[76:77], v[40:41], v[78:79], v[76:77] op_sel_hi:[1,0,1]
	v_and_b32_e32 v78, 0xffff0000, v195
	v_pk_fma_f32 v[132:133], v[38:39], v[78:79], v[132:133] op_sel_hi:[1,0,1]
	v_pk_fma_f32 v[76:77], v[36:37], v[78:79], v[76:77] op_sel_hi:[1,0,1]
	v_lshlrev_b32_e32 v78, 16, v188
	v_pk_fma_f32 v[132:133], v[34:35], v[78:79], v[132:133] op_sel_hi:[1,0,1]
	v_pk_fma_f32 v[76:77], v[32:33], v[78:79], v[76:77] op_sel_hi:[1,0,1]
	v_and_b32_e32 v72, 0xffff0000, v188
	v_pk_fma_f32 v[78:79], v[30:31], v[72:73], v[132:133] op_sel_hi:[1,0,1]
	v_pk_fma_f32 v[76:77], v[28:29], v[72:73], v[76:77] op_sel_hi:[1,0,1]
	v_lshlrev_b32_e32 v72, 16, v189
	v_pk_fma_f32 v[78:79], v[26:27], v[72:73], v[78:79] op_sel_hi:[1,0,1]
	v_pk_fma_f32 v[76:77], v[24:25], v[72:73], v[76:77] op_sel_hi:[1,0,1]
	v_and_b32_e32 v72, 0xffff0000, v189
	v_pk_fma_f32 v[78:79], v[22:23], v[72:73], v[78:79] op_sel_hi:[1,0,1]
	v_pk_fma_f32 v[72:73], v[20:21], v[72:73], v[76:77] op_sel_hi:[1,0,1]
	v_lshlrev_b32_e32 v76, 16, v190
	v_pk_fma_f32 v[78:79], v[18:19], v[76:77], v[78:79] op_sel_hi:[1,0,1]
	v_pk_fma_f32 v[72:73], v[16:17], v[76:77], v[72:73] op_sel_hi:[1,0,1]
	v_and_b32_e32 v74, 0xffff0000, v190
	v_pk_fma_f32 v[76:77], v[14:15], v[74:75], v[78:79] op_sel_hi:[1,0,1]
	v_pk_fma_f32 v[72:73], v[12:13], v[74:75], v[72:73] op_sel_hi:[1,0,1]
	v_lshlrev_b32_e32 v74, 16, v191
	v_pk_fma_f32 v[76:77], v[10:11], v[74:75], v[76:77] op_sel_hi:[1,0,1]
	v_pk_fma_f32 v[72:73], v[8:9], v[74:75], v[72:73] op_sel_hi:[1,0,1]
	v_and_b32_e32 v74, 0xffff0000, v191
	v_pk_fma_f32 v[72:73], v[4:5], v[74:75], v[72:73] op_sel_hi:[1,0,1]
	v_pk_fma_f32 v[76:77], v[6:7], v[74:75], v[76:77] op_sel_hi:[1,0,1]
	v_min_f32_e32 v74, 0, v72
	v_mul_f32_e64 v72, |v72|, s93
	v_exp_f32_e32 v72, v72
	v_min_f32_e32 v75, 0, v73
	v_add_f32_e32 v72, 1.0, v72
	v_log_f32_e32 v78, v72
	v_mul_f32_e64 v72, |v73|, s93
	v_mul_f32_e64 v73, |v76|, s93
	v_exp_f32_e32 v72, v72
	v_exp_f32_e32 v73, v73
	v_add_f32_e32 v72, 1.0, v72
	v_add_f32_e32 v73, 1.0, v73
	v_log_f32_e32 v79, v72
	v_min_f32_e32 v72, 0, v76
	v_log_f32_e32 v76, v73
	v_min_f32_e32 v73, 0, v77
	v_mul_f32_e64 v77, |v77|, s93
	v_exp_f32_e32 v77, v77
	v_xor_b32_e32 v76, 0x80000000, v76
	v_add_f32_e32 v77, 1.0, v77
	v_log_f32_e32 v77, v77
	s_nop 0
	v_xor_b32_e32 v77, 0x80000000, v77
	v_pk_fma_f32 v[72:73], v[76:77], s[88:89], v[72:73] op_sel_hi:[1,0,1]
	v_xor_b32_e32 v77, 0x80000000, v79
	v_xor_b32_e32 v76, 0x80000000, v78
	v_pk_fma_f32 v[74:75], v[76:77], s[88:89], v[74:75] op_sel_hi:[1,0,1]
	v_pk_add_f32 v[76:77], v[128:129], v[72:73]
	v_pk_add_f32 v[78:79], v[130:131], v[74:75]
	s_add_u32 s18, s4, 0x3580a600
	s_addc_u32 s19, s5, 0
	s_waitcnt vmcnt(10)
	v_lshlrev_b32_e32 v132, 16, v200
	v_pk_fma_f32 v[134:135], v[70:71], v[132:133], v[66:67] op_sel_hi:[1,0,1]
	v_pk_fma_f32 v[132:133], v[68:69], v[132:133], v[64:65] op_sel_hi:[1,0,1]
	v_and_b32_e32 v128, 0xffff0000, v200
	v_pk_fma_f32 v[134:135], v[62:63], v[128:129], v[134:135] op_sel_hi:[1,0,1]
	v_pk_fma_f32 v[132:133], v[60:61], v[128:129], v[132:133] op_sel_hi:[1,0,1]
	v_lshlrev_b32_e32 v128, 16, v201
	v_pk_fma_f32 v[134:135], v[58:59], v[128:129], v[134:135] op_sel_hi:[1,0,1]
	v_pk_fma_f32 v[132:133], v[56:57], v[128:129], v[132:133] op_sel_hi:[1,0,1]
	v_and_b32_e32 v128, 0xffff0000, v201
	v_pk_fma_f32 v[134:135], v[54:55], v[128:129], v[134:135] op_sel_hi:[1,0,1]
	v_pk_fma_f32 v[128:129], v[52:53], v[128:129], v[132:133] op_sel_hi:[1,0,1]
	v_lshlrev_b32_e32 v132, 16, v202
	v_pk_fma_f32 v[134:135], v[50:51], v[132:133], v[134:135] op_sel_hi:[1,0,1]
	v_pk_fma_f32 v[128:129], v[48:49], v[132:133], v[128:129] op_sel_hi:[1,0,1]
	v_and_b32_e32 v130, 0xffff0000, v202
	v_pk_fma_f32 v[132:133], v[46:47], v[130:131], v[134:135] op_sel_hi:[1,0,1]
	v_pk_fma_f32 v[128:129], v[44:45], v[130:131], v[128:129] op_sel_hi:[1,0,1]
	v_lshlrev_b32_e32 v130, 16, v203
	v_pk_fma_f32 v[132:133], v[42:43], v[130:131], v[132:133] op_sel_hi:[1,0,1]
	v_pk_fma_f32 v[128:129], v[40:41], v[130:131], v[128:129] op_sel_hi:[1,0,1]
	v_and_b32_e32 v130, 0xffff0000, v203
	v_pk_fma_f32 v[132:133], v[38:39], v[130:131], v[132:133] op_sel_hi:[1,0,1]
	v_pk_fma_f32 v[128:129], v[36:37], v[130:131], v[128:129] op_sel_hi:[1,0,1]
	v_lshlrev_b32_e32 v130, 16, v196
	v_pk_fma_f32 v[132:133], v[34:35], v[130:131], v[132:133] op_sel_hi:[1,0,1]
	v_pk_fma_f32 v[128:129], v[32:33], v[130:131], v[128:129] op_sel_hi:[1,0,1]
	v_and_b32_e32 v72, 0xffff0000, v196
	v_pk_fma_f32 v[130:131], v[30:31], v[72:73], v[132:133] op_sel_hi:[1,0,1]
	v_pk_fma_f32 v[128:129], v[28:29], v[72:73], v[128:129] op_sel_hi:[1,0,1]
	v_lshlrev_b32_e32 v72, 16, v197
	v_pk_fma_f32 v[130:131], v[26:27], v[72:73], v[130:131] op_sel_hi:[1,0,1]
	v_pk_fma_f32 v[128:129], v[24:25], v[72:73], v[128:129] op_sel_hi:[1,0,1]
	v_and_b32_e32 v72, 0xffff0000, v197
	v_pk_fma_f32 v[130:131], v[22:23], v[72:73], v[130:131] op_sel_hi:[1,0,1]
	v_pk_fma_f32 v[72:73], v[20:21], v[72:73], v[128:129] op_sel_hi:[1,0,1]
	v_lshlrev_b32_e32 v128, 16, v198
	v_pk_fma_f32 v[130:131], v[18:19], v[128:129], v[130:131] op_sel_hi:[1,0,1]
	v_pk_fma_f32 v[72:73], v[16:17], v[128:129], v[72:73] op_sel_hi:[1,0,1]
	v_and_b32_e32 v74, 0xffff0000, v198
	v_pk_fma_f32 v[128:129], v[14:15], v[74:75], v[130:131] op_sel_hi:[1,0,1]
	v_pk_fma_f32 v[72:73], v[12:13], v[74:75], v[72:73] op_sel_hi:[1,0,1]
	v_lshlrev_b32_e32 v74, 16, v199
	v_pk_fma_f32 v[128:129], v[10:11], v[74:75], v[128:129] op_sel_hi:[1,0,1]
	v_pk_fma_f32 v[72:73], v[8:9], v[74:75], v[72:73] op_sel_hi:[1,0,1]
	v_and_b32_e32 v74, 0xffff0000, v199
	v_pk_fma_f32 v[72:73], v[4:5], v[74:75], v[72:73] op_sel_hi:[1,0,1]
	v_pk_fma_f32 v[128:129], v[6:7], v[74:75], v[128:129] op_sel_hi:[1,0,1]
	v_min_f32_e32 v74, 0, v72
	v_mul_f32_e64 v72, |v72|, s93
	v_exp_f32_e32 v72, v72
	v_min_f32_e32 v75, 0, v73
	v_add_f32_e32 v72, 1.0, v72
	v_log_f32_e32 v85, v72
	v_mul_f32_e64 v72, |v73|, s93
	v_mul_f32_e64 v73, |v128|, s93
	v_exp_f32_e32 v72, v72
	v_exp_f32_e32 v73, v73
	v_add_f32_e32 v72, 1.0, v72
	v_add_f32_e32 v73, 1.0, v73
	v_log_f32_e32 v91, v72
	v_min_f32_e32 v72, 0, v128
	v_log_f32_e32 v128, v73
	v_min_f32_e32 v73, 0, v129
	v_mul_f32_e64 v129, |v129|, s93
	v_exp_f32_e32 v129, v129
	v_xor_b32_e32 v128, 0x80000000, v128
	v_add_f32_e32 v129, 1.0, v129
	v_log_f32_e32 v129, v129
	s_nop 0
	v_xor_b32_e32 v129, 0x80000000, v129
	v_pk_fma_f32 v[72:73], v[128:129], s[88:89], v[72:73] op_sel_hi:[1,0,1]
	v_xor_b32_e32 v129, 0x80000000, v91
	v_xor_b32_e32 v128, 0x80000000, v85
	v_pk_fma_f32 v[74:75], v[128:129], s[88:89], v[74:75] op_sel_hi:[1,0,1]
	v_mov_b32_e32 v85, 0x3580a000
	v_pk_add_f32 v[76:77], v[76:77], v[72:73]
	v_pk_add_f32 v[78:79], v[78:79], v[74:75]
	s_add_u32 s18, s4, 0x3580d000
	s_addc_u32 s19, s5, 0
	s_waitcnt vmcnt(8)
	v_lshlrev_b32_e32 v132, 16, v208
	v_pk_fma_f32 v[134:135], v[70:71], v[132:133], v[66:67] op_sel_hi:[1,0,1]
	v_pk_fma_f32 v[132:133], v[68:69], v[132:133], v[64:65] op_sel_hi:[1,0,1]
	v_and_b32_e32 v128, 0xffff0000, v208
	v_pk_fma_f32 v[134:135], v[62:63], v[128:129], v[134:135] op_sel_hi:[1,0,1]
	v_pk_fma_f32 v[132:133], v[60:61], v[128:129], v[132:133] op_sel_hi:[1,0,1]
	v_lshlrev_b32_e32 v128, 16, v209
	v_pk_fma_f32 v[134:135], v[58:59], v[128:129], v[134:135] op_sel_hi:[1,0,1]
	v_pk_fma_f32 v[132:133], v[56:57], v[128:129], v[132:133] op_sel_hi:[1,0,1]
	v_and_b32_e32 v128, 0xffff0000, v209
	v_pk_fma_f32 v[134:135], v[54:55], v[128:129], v[134:135] op_sel_hi:[1,0,1]
	v_pk_fma_f32 v[128:129], v[52:53], v[128:129], v[132:133] op_sel_hi:[1,0,1]
	v_lshlrev_b32_e32 v132, 16, v210
	v_pk_fma_f32 v[134:135], v[50:51], v[132:133], v[134:135] op_sel_hi:[1,0,1]
	v_pk_fma_f32 v[128:129], v[48:49], v[132:133], v[128:129] op_sel_hi:[1,0,1]
	v_and_b32_e32 v130, 0xffff0000, v210
	v_pk_fma_f32 v[132:133], v[46:47], v[130:131], v[134:135] op_sel_hi:[1,0,1]
	v_pk_fma_f32 v[128:129], v[44:45], v[130:131], v[128:129] op_sel_hi:[1,0,1]
	v_lshlrev_b32_e32 v130, 16, v211
	v_pk_fma_f32 v[132:133], v[42:43], v[130:131], v[132:133] op_sel_hi:[1,0,1]
	v_pk_fma_f32 v[128:129], v[40:41], v[130:131], v[128:129] op_sel_hi:[1,0,1]
	v_and_b32_e32 v130, 0xffff0000, v211
	v_pk_fma_f32 v[132:133], v[38:39], v[130:131], v[132:133] op_sel_hi:[1,0,1]
	v_pk_fma_f32 v[128:129], v[36:37], v[130:131], v[128:129] op_sel_hi:[1,0,1]
	v_lshlrev_b32_e32 v130, 16, v204
	v_pk_fma_f32 v[132:133], v[34:35], v[130:131], v[132:133] op_sel_hi:[1,0,1]
	v_pk_fma_f32 v[128:129], v[32:33], v[130:131], v[128:129] op_sel_hi:[1,0,1]
	v_and_b32_e32 v72, 0xffff0000, v204
	v_pk_fma_f32 v[130:131], v[30:31], v[72:73], v[132:133] op_sel_hi:[1,0,1]
	v_pk_fma_f32 v[128:129], v[28:29], v[72:73], v[128:129] op_sel_hi:[1,0,1]
	v_lshlrev_b32_e32 v72, 16, v205
	v_pk_fma_f32 v[130:131], v[26:27], v[72:73], v[130:131] op_sel_hi:[1,0,1]
	v_pk_fma_f32 v[128:129], v[24:25], v[72:73], v[128:129] op_sel_hi:[1,0,1]
	v_and_b32_e32 v72, 0xffff0000, v205
	v_pk_fma_f32 v[130:131], v[22:23], v[72:73], v[130:131] op_sel_hi:[1,0,1]
	v_pk_fma_f32 v[72:73], v[20:21], v[72:73], v[128:129] op_sel_hi:[1,0,1]
	v_lshlrev_b32_e32 v128, 16, v206
	v_pk_fma_f32 v[130:131], v[18:19], v[128:129], v[130:131] op_sel_hi:[1,0,1]
	v_pk_fma_f32 v[72:73], v[16:17], v[128:129], v[72:73] op_sel_hi:[1,0,1]
	v_and_b32_e32 v74, 0xffff0000, v206
	v_pk_fma_f32 v[128:129], v[14:15], v[74:75], v[130:131] op_sel_hi:[1,0,1]
	v_pk_fma_f32 v[72:73], v[12:13], v[74:75], v[72:73] op_sel_hi:[1,0,1]
	v_lshlrev_b32_e32 v74, 16, v207
	v_pk_fma_f32 v[128:129], v[10:11], v[74:75], v[128:129] op_sel_hi:[1,0,1]
	v_pk_fma_f32 v[72:73], v[8:9], v[74:75], v[72:73] op_sel_hi:[1,0,1]
	v_and_b32_e32 v74, 0xffff0000, v207
	v_pk_fma_f32 v[72:73], v[4:5], v[74:75], v[72:73] op_sel_hi:[1,0,1]
	v_pk_fma_f32 v[128:129], v[6:7], v[74:75], v[128:129] op_sel_hi:[1,0,1]
	v_min_f32_e32 v74, 0, v72
	v_mul_f32_e64 v72, |v72|, s93
	v_exp_f32_e32 v72, v72
	v_min_f32_e32 v75, 0, v73
	v_add_f32_e32 v72, 1.0, v72
	v_log_f32_e32 v85, v72
	v_mul_f32_e64 v72, |v73|, s93
	v_mul_f32_e64 v73, |v128|, s93
	v_exp_f32_e32 v72, v72
	v_exp_f32_e32 v73, v73
	v_add_f32_e32 v72, 1.0, v72
	v_add_f32_e32 v73, 1.0, v73
	v_log_f32_e32 v91, v72
	v_min_f32_e32 v72, 0, v128
	v_log_f32_e32 v128, v73
	v_min_f32_e32 v73, 0, v129
	v_mul_f32_e64 v129, |v129|, s93
	v_exp_f32_e32 v129, v129
	v_xor_b32_e32 v128, 0x80000000, v128
	v_add_f32_e32 v129, 1.0, v129
	v_log_f32_e32 v129, v129
	s_nop 0
	v_xor_b32_e32 v129, 0x80000000, v129
	v_pk_fma_f32 v[72:73], v[128:129], s[88:89], v[72:73] op_sel_hi:[1,0,1]
	v_xor_b32_e32 v129, 0x80000000, v91
	v_xor_b32_e32 v128, 0x80000000, v85
	v_pk_fma_f32 v[74:75], v[128:129], s[88:89], v[74:75] op_sel_hi:[1,0,1]
	v_mov_b32_e32 v85, 0x3580d000
	v_pk_add_f32 v[76:77], v[76:77], v[72:73]
	v_pk_add_f32 v[78:79], v[78:79], v[74:75]
	s_add_u32 s18, s4, 0x3580fa00
	s_addc_u32 s19, s5, 0
	s_waitcnt vmcnt(6)
	v_lshlrev_b32_e32 v132, 16, v216
	v_pk_fma_f32 v[134:135], v[70:71], v[132:133], v[66:67] op_sel_hi:[1,0,1]
	v_pk_fma_f32 v[132:133], v[68:69], v[132:133], v[64:65] op_sel_hi:[1,0,1]
	v_and_b32_e32 v128, 0xffff0000, v216
	v_pk_fma_f32 v[134:135], v[62:63], v[128:129], v[134:135] op_sel_hi:[1,0,1]
	v_pk_fma_f32 v[132:133], v[60:61], v[128:129], v[132:133] op_sel_hi:[1,0,1]
	v_lshlrev_b32_e32 v128, 16, v217
	v_pk_fma_f32 v[134:135], v[58:59], v[128:129], v[134:135] op_sel_hi:[1,0,1]
	v_pk_fma_f32 v[132:133], v[56:57], v[128:129], v[132:133] op_sel_hi:[1,0,1]
	v_and_b32_e32 v128, 0xffff0000, v217
	v_pk_fma_f32 v[134:135], v[54:55], v[128:129], v[134:135] op_sel_hi:[1,0,1]
	v_pk_fma_f32 v[128:129], v[52:53], v[128:129], v[132:133] op_sel_hi:[1,0,1]
	v_lshlrev_b32_e32 v132, 16, v218
	v_pk_fma_f32 v[134:135], v[50:51], v[132:133], v[134:135] op_sel_hi:[1,0,1]
	v_pk_fma_f32 v[128:129], v[48:49], v[132:133], v[128:129] op_sel_hi:[1,0,1]
	v_and_b32_e32 v130, 0xffff0000, v218
	v_pk_fma_f32 v[132:133], v[46:47], v[130:131], v[134:135] op_sel_hi:[1,0,1]
	v_pk_fma_f32 v[128:129], v[44:45], v[130:131], v[128:129] op_sel_hi:[1,0,1]
	v_lshlrev_b32_e32 v130, 16, v219
	v_pk_fma_f32 v[132:133], v[42:43], v[130:131], v[132:133] op_sel_hi:[1,0,1]
	v_pk_fma_f32 v[128:129], v[40:41], v[130:131], v[128:129] op_sel_hi:[1,0,1]
	v_and_b32_e32 v130, 0xffff0000, v219
	v_pk_fma_f32 v[132:133], v[38:39], v[130:131], v[132:133] op_sel_hi:[1,0,1]
	v_pk_fma_f32 v[128:129], v[36:37], v[130:131], v[128:129] op_sel_hi:[1,0,1]
	v_lshlrev_b32_e32 v130, 16, v212
	v_pk_fma_f32 v[132:133], v[34:35], v[130:131], v[132:133] op_sel_hi:[1,0,1]
	v_pk_fma_f32 v[128:129], v[32:33], v[130:131], v[128:129] op_sel_hi:[1,0,1]
	v_and_b32_e32 v72, 0xffff0000, v212
	v_pk_fma_f32 v[130:131], v[30:31], v[72:73], v[132:133] op_sel_hi:[1,0,1]
	v_pk_fma_f32 v[128:129], v[28:29], v[72:73], v[128:129] op_sel_hi:[1,0,1]
	v_lshlrev_b32_e32 v72, 16, v213
	v_pk_fma_f32 v[130:131], v[26:27], v[72:73], v[130:131] op_sel_hi:[1,0,1]
	v_pk_fma_f32 v[128:129], v[24:25], v[72:73], v[128:129] op_sel_hi:[1,0,1]
	v_and_b32_e32 v72, 0xffff0000, v213
	v_pk_fma_f32 v[130:131], v[22:23], v[72:73], v[130:131] op_sel_hi:[1,0,1]
	v_pk_fma_f32 v[72:73], v[20:21], v[72:73], v[128:129] op_sel_hi:[1,0,1]
	v_lshlrev_b32_e32 v128, 16, v214
	v_pk_fma_f32 v[130:131], v[18:19], v[128:129], v[130:131] op_sel_hi:[1,0,1]
	v_pk_fma_f32 v[72:73], v[16:17], v[128:129], v[72:73] op_sel_hi:[1,0,1]
	v_and_b32_e32 v74, 0xffff0000, v214
	v_pk_fma_f32 v[128:129], v[14:15], v[74:75], v[130:131] op_sel_hi:[1,0,1]
	v_pk_fma_f32 v[72:73], v[12:13], v[74:75], v[72:73] op_sel_hi:[1,0,1]
	v_lshlrev_b32_e32 v74, 16, v215
	v_pk_fma_f32 v[128:129], v[10:11], v[74:75], v[128:129] op_sel_hi:[1,0,1]
	v_pk_fma_f32 v[72:73], v[8:9], v[74:75], v[72:73] op_sel_hi:[1,0,1]
	v_and_b32_e32 v74, 0xffff0000, v215
	v_pk_fma_f32 v[72:73], v[4:5], v[74:75], v[72:73] op_sel_hi:[1,0,1]
	v_pk_fma_f32 v[128:129], v[6:7], v[74:75], v[128:129] op_sel_hi:[1,0,1]
	v_min_f32_e32 v74, 0, v72
	v_mul_f32_e64 v72, |v72|, s93
	v_exp_f32_e32 v72, v72
	v_min_f32_e32 v75, 0, v73
	v_add_f32_e32 v72, 1.0, v72
	v_log_f32_e32 v85, v72
	v_mul_f32_e64 v72, |v73|, s93
	v_mul_f32_e64 v73, |v128|, s93
	v_exp_f32_e32 v72, v72
	v_exp_f32_e32 v73, v73
	v_add_f32_e32 v72, 1.0, v72
	v_add_f32_e32 v73, 1.0, v73
	v_log_f32_e32 v91, v72
	v_min_f32_e32 v72, 0, v128
	v_log_f32_e32 v128, v73
	v_min_f32_e32 v73, 0, v129
	v_mul_f32_e64 v129, |v129|, s93
	v_exp_f32_e32 v129, v129
	v_xor_b32_e32 v128, 0x80000000, v128
	v_add_f32_e32 v129, 1.0, v129
	v_log_f32_e32 v129, v129
	s_nop 0
	v_xor_b32_e32 v129, 0x80000000, v129
	v_pk_fma_f32 v[72:73], v[128:129], s[88:89], v[72:73] op_sel_hi:[1,0,1]
	v_xor_b32_e32 v129, 0x80000000, v91
	v_xor_b32_e32 v128, 0x80000000, v85
	v_pk_fma_f32 v[74:75], v[128:129], s[88:89], v[74:75] op_sel_hi:[1,0,1]
	v_mov_b32_e32 v85, 0x3580f000
	v_pk_add_f32 v[76:77], v[76:77], v[72:73]
	v_pk_add_f32 v[78:79], v[78:79], v[74:75]
	s_add_u32 s18, s4, 0x35812400
	s_addc_u32 s19, s5, 0
	s_waitcnt vmcnt(4)
	v_lshlrev_b32_e32 v132, 16, v226
	v_pk_fma_f32 v[134:135], v[70:71], v[132:133], v[66:67] op_sel_hi:[1,0,1]
	v_pk_fma_f32 v[132:133], v[68:69], v[132:133], v[64:65] op_sel_hi:[1,0,1]
	v_and_b32_e32 v128, 0xffff0000, v226
	v_pk_fma_f32 v[134:135], v[62:63], v[128:129], v[134:135] op_sel_hi:[1,0,1]
	v_pk_fma_f32 v[132:133], v[60:61], v[128:129], v[132:133] op_sel_hi:[1,0,1]
	v_lshlrev_b32_e32 v128, 16, v227
	v_pk_fma_f32 v[134:135], v[58:59], v[128:129], v[134:135] op_sel_hi:[1,0,1]
	v_pk_fma_f32 v[132:133], v[56:57], v[128:129], v[132:133] op_sel_hi:[1,0,1]
	v_and_b32_e32 v128, 0xffff0000, v227
	v_pk_fma_f32 v[134:135], v[54:55], v[128:129], v[134:135] op_sel_hi:[1,0,1]
	v_pk_fma_f32 v[128:129], v[52:53], v[128:129], v[132:133] op_sel_hi:[1,0,1]
	v_lshlrev_b32_e32 v132, 16, v228
	v_pk_fma_f32 v[134:135], v[50:51], v[132:133], v[134:135] op_sel_hi:[1,0,1]
	v_pk_fma_f32 v[128:129], v[48:49], v[132:133], v[128:129] op_sel_hi:[1,0,1]
	v_and_b32_e32 v130, 0xffff0000, v228
	v_pk_fma_f32 v[132:133], v[46:47], v[130:131], v[134:135] op_sel_hi:[1,0,1]
	v_pk_fma_f32 v[128:129], v[44:45], v[130:131], v[128:129] op_sel_hi:[1,0,1]
	v_lshlrev_b32_e32 v130, 16, v229
	v_pk_fma_f32 v[132:133], v[42:43], v[130:131], v[132:133] op_sel_hi:[1,0,1]
	v_pk_fma_f32 v[128:129], v[40:41], v[130:131], v[128:129] op_sel_hi:[1,0,1]
	v_and_b32_e32 v130, 0xffff0000, v229
	v_pk_fma_f32 v[132:133], v[38:39], v[130:131], v[132:133] op_sel_hi:[1,0,1]
	v_pk_fma_f32 v[128:129], v[36:37], v[130:131], v[128:129] op_sel_hi:[1,0,1]
	v_lshlrev_b32_e32 v130, 16, v220
	v_pk_fma_f32 v[132:133], v[34:35], v[130:131], v[132:133] op_sel_hi:[1,0,1]
	v_pk_fma_f32 v[128:129], v[32:33], v[130:131], v[128:129] op_sel_hi:[1,0,1]
	v_and_b32_e32 v72, 0xffff0000, v220
	v_pk_fma_f32 v[130:131], v[30:31], v[72:73], v[132:133] op_sel_hi:[1,0,1]
	v_pk_fma_f32 v[128:129], v[28:29], v[72:73], v[128:129] op_sel_hi:[1,0,1]
	v_lshlrev_b32_e32 v72, 16, v221
	v_pk_fma_f32 v[130:131], v[26:27], v[72:73], v[130:131] op_sel_hi:[1,0,1]
	v_pk_fma_f32 v[128:129], v[24:25], v[72:73], v[128:129] op_sel_hi:[1,0,1]
	v_and_b32_e32 v72, 0xffff0000, v221
	v_pk_fma_f32 v[130:131], v[22:23], v[72:73], v[130:131] op_sel_hi:[1,0,1]
	v_pk_fma_f32 v[72:73], v[20:21], v[72:73], v[128:129] op_sel_hi:[1,0,1]
	v_lshlrev_b32_e32 v128, 16, v222
	v_pk_fma_f32 v[130:131], v[18:19], v[128:129], v[130:131] op_sel_hi:[1,0,1]
	v_pk_fma_f32 v[72:73], v[16:17], v[128:129], v[72:73] op_sel_hi:[1,0,1]
	v_and_b32_e32 v74, 0xffff0000, v222
	v_pk_fma_f32 v[128:129], v[14:15], v[74:75], v[130:131] op_sel_hi:[1,0,1]
	v_pk_fma_f32 v[72:73], v[12:13], v[74:75], v[72:73] op_sel_hi:[1,0,1]
	v_lshlrev_b32_e32 v74, 16, v223
	v_pk_fma_f32 v[128:129], v[10:11], v[74:75], v[128:129] op_sel_hi:[1,0,1]
	v_pk_fma_f32 v[72:73], v[8:9], v[74:75], v[72:73] op_sel_hi:[1,0,1]
	v_and_b32_e32 v74, 0xffff0000, v223
	v_pk_fma_f32 v[72:73], v[4:5], v[74:75], v[72:73] op_sel_hi:[1,0,1]
	v_pk_fma_f32 v[128:129], v[6:7], v[74:75], v[128:129] op_sel_hi:[1,0,1]
	v_min_f32_e32 v74, 0, v72
	v_mul_f32_e64 v72, |v72|, s93
	v_exp_f32_e32 v72, v72
	v_min_f32_e32 v75, 0, v73
	v_add_f32_e32 v72, 1.0, v72
	v_log_f32_e32 v85, v72
	v_mul_f32_e64 v72, |v73|, s93
	v_mul_f32_e64 v73, |v128|, s93
	v_exp_f32_e32 v72, v72
	v_exp_f32_e32 v73, v73
	v_add_f32_e32 v72, 1.0, v72
	v_add_f32_e32 v73, 1.0, v73
	v_log_f32_e32 v91, v72
	v_min_f32_e32 v72, 0, v128
	v_log_f32_e32 v128, v73
	v_min_f32_e32 v73, 0, v129
	v_mul_f32_e64 v129, |v129|, s93
	v_exp_f32_e32 v129, v129
	v_xor_b32_e32 v128, 0x80000000, v128
	v_add_f32_e32 v129, 1.0, v129
	v_log_f32_e32 v129, v129
	s_nop 0
	v_xor_b32_e32 v129, 0x80000000, v129
	v_pk_fma_f32 v[72:73], v[128:129], s[88:89], v[72:73] op_sel_hi:[1,0,1]
	v_xor_b32_e32 v129, 0x80000000, v91
	v_xor_b32_e32 v128, 0x80000000, v85
	v_pk_fma_f32 v[74:75], v[128:129], s[88:89], v[74:75] op_sel_hi:[1,0,1]
	v_mov_b32_e32 v85, 0x35812000
	v_pk_add_f32 v[76:77], v[76:77], v[72:73]
	v_pk_add_f32 v[78:79], v[78:79], v[74:75]
	s_add_u32 s18, s4, 0x35814e00
	s_addc_u32 s19, s5, 0
	s_add_u32 s10, s10, 0x15000
	s_addc_u32 s11, s11, 0
	s_cmp_eq_u32 s10, 0xa8000
	s_waitcnt vmcnt(2)
	v_lshlrev_b32_e32 v132, 16, v240
	v_pk_fma_f32 v[134:135], v[70:71], v[132:133], v[66:67] op_sel_hi:[1,0,1]
	v_pk_fma_f32 v[132:133], v[68:69], v[132:133], v[64:65] op_sel_hi:[1,0,1]
	v_and_b32_e32 v128, 0xffff0000, v240
	v_pk_fma_f32 v[134:135], v[62:63], v[128:129], v[134:135] op_sel_hi:[1,0,1]
	v_pk_fma_f32 v[132:133], v[60:61], v[128:129], v[132:133] op_sel_hi:[1,0,1]
	v_lshlrev_b32_e32 v128, 16, v241
	v_pk_fma_f32 v[134:135], v[58:59], v[128:129], v[134:135] op_sel_hi:[1,0,1]
	v_pk_fma_f32 v[132:133], v[56:57], v[128:129], v[132:133] op_sel_hi:[1,0,1]
	v_and_b32_e32 v128, 0xffff0000, v241
	v_pk_fma_f32 v[134:135], v[54:55], v[128:129], v[134:135] op_sel_hi:[1,0,1]
	v_pk_fma_f32 v[128:129], v[52:53], v[128:129], v[132:133] op_sel_hi:[1,0,1]
	v_lshlrev_b32_e32 v132, 16, v242
	v_pk_fma_f32 v[134:135], v[50:51], v[132:133], v[134:135] op_sel_hi:[1,0,1]
	v_pk_fma_f32 v[128:129], v[48:49], v[132:133], v[128:129] op_sel_hi:[1,0,1]
	v_and_b32_e32 v130, 0xffff0000, v242
	v_pk_fma_f32 v[132:133], v[46:47], v[130:131], v[134:135] op_sel_hi:[1,0,1]
	v_pk_fma_f32 v[128:129], v[44:45], v[130:131], v[128:129] op_sel_hi:[1,0,1]
	v_lshlrev_b32_e32 v130, 16, v243
	v_pk_fma_f32 v[132:133], v[42:43], v[130:131], v[132:133] op_sel_hi:[1,0,1]
	v_pk_fma_f32 v[128:129], v[40:41], v[130:131], v[128:129] op_sel_hi:[1,0,1]
	v_and_b32_e32 v130, 0xffff0000, v243
	v_pk_fma_f32 v[132:133], v[38:39], v[130:131], v[132:133] op_sel_hi:[1,0,1]
	v_pk_fma_f32 v[128:129], v[36:37], v[130:131], v[128:129] op_sel_hi:[1,0,1]
	v_lshlrev_b32_e32 v130, 16, v236
	v_pk_fma_f32 v[132:133], v[34:35], v[130:131], v[132:133] op_sel_hi:[1,0,1]
	v_pk_fma_f32 v[128:129], v[32:33], v[130:131], v[128:129] op_sel_hi:[1,0,1]
	v_and_b32_e32 v72, 0xffff0000, v236
	v_pk_fma_f32 v[130:131], v[30:31], v[72:73], v[132:133] op_sel_hi:[1,0,1]
	v_pk_fma_f32 v[128:129], v[28:29], v[72:73], v[128:129] op_sel_hi:[1,0,1]
	v_lshlrev_b32_e32 v72, 16, v237
	v_pk_fma_f32 v[130:131], v[26:27], v[72:73], v[130:131] op_sel_hi:[1,0,1]
	v_pk_fma_f32 v[128:129], v[24:25], v[72:73], v[128:129] op_sel_hi:[1,0,1]
	v_and_b32_e32 v72, 0xffff0000, v237
	v_pk_fma_f32 v[130:131], v[22:23], v[72:73], v[130:131] op_sel_hi:[1,0,1]
	v_pk_fma_f32 v[72:73], v[20:21], v[72:73], v[128:129] op_sel_hi:[1,0,1]
	v_lshlrev_b32_e32 v128, 16, v238
	v_pk_fma_f32 v[130:131], v[18:19], v[128:129], v[130:131] op_sel_hi:[1,0,1]
	v_pk_fma_f32 v[72:73], v[16:17], v[128:129], v[72:73] op_sel_hi:[1,0,1]
	v_and_b32_e32 v74, 0xffff0000, v238
	v_pk_fma_f32 v[128:129], v[14:15], v[74:75], v[130:131] op_sel_hi:[1,0,1]
	v_pk_fma_f32 v[72:73], v[12:13], v[74:75], v[72:73] op_sel_hi:[1,0,1]
	v_lshlrev_b32_e32 v74, 16, v239
	v_pk_fma_f32 v[128:129], v[10:11], v[74:75], v[128:129] op_sel_hi:[1,0,1]
	v_pk_fma_f32 v[72:73], v[8:9], v[74:75], v[72:73] op_sel_hi:[1,0,1]
	v_and_b32_e32 v74, 0xffff0000, v239
	v_pk_fma_f32 v[72:73], v[4:5], v[74:75], v[72:73] op_sel_hi:[1,0,1]
	v_pk_fma_f32 v[128:129], v[6:7], v[74:75], v[128:129] op_sel_hi:[1,0,1]
	v_min_f32_e32 v74, 0, v72
	v_mul_f32_e64 v72, |v72|, s93
	v_exp_f32_e32 v72, v72
	v_min_f32_e32 v75, 0, v73
	v_add_f32_e32 v72, 1.0, v72
	v_log_f32_e32 v85, v72
	v_mul_f32_e64 v72, |v73|, s93
	v_mul_f32_e64 v73, |v128|, s93
	v_exp_f32_e32 v72, v72
	v_exp_f32_e32 v73, v73
	v_add_f32_e32 v72, 1.0, v72
	v_add_f32_e32 v73, 1.0, v73
	v_log_f32_e32 v91, v72
	v_min_f32_e32 v72, 0, v128
	v_log_f32_e32 v128, v73
	v_min_f32_e32 v73, 0, v129
	v_mul_f32_e64 v129, |v129|, s93
	v_exp_f32_e32 v129, v129
	v_xor_b32_e32 v128, 0x80000000, v128
	v_add_f32_e32 v129, 1.0, v129
	v_log_f32_e32 v129, v129
	s_nop 0
	v_xor_b32_e32 v129, 0x80000000, v129
	v_pk_fma_f32 v[72:73], v[128:129], s[88:89], v[72:73] op_sel_hi:[1,0,1]
	v_xor_b32_e32 v129, 0x80000000, v91
	v_xor_b32_e32 v128, 0x80000000, v85
	v_pk_fma_f32 v[74:75], v[128:129], s[88:89], v[74:75] op_sel_hi:[1,0,1]
	v_pk_add_f32 v[128:129], v[76:77], v[72:73]
	v_mov_b32_e32 v76, 0x35814000
	v_pk_add_f32 v[130:131], v[78:79], v[74:75]
	s_nop 0
	s_waitcnt vmcnt(0)
	v_lshlrev_b32_e32 v132, 16, v248
	v_pk_fma_f32 v[134:135], v[70:71], v[132:133], v[66:67] op_sel_hi:[1,0,1]
	v_pk_fma_f32 v[132:133], v[68:69], v[132:133], v[64:65] op_sel_hi:[1,0,1]
	v_and_b32_e32 v76, 0xffff0000, v248
	v_pk_fma_f32 v[134:135], v[62:63], v[76:77], v[134:135] op_sel_hi:[1,0,1]
	v_pk_fma_f32 v[132:133], v[60:61], v[76:77], v[132:133] op_sel_hi:[1,0,1]
	v_lshlrev_b32_e32 v76, 16, v249
	v_pk_fma_f32 v[134:135], v[58:59], v[76:77], v[134:135] op_sel_hi:[1,0,1]
	v_pk_fma_f32 v[132:133], v[56:57], v[76:77], v[132:133] op_sel_hi:[1,0,1]
	v_and_b32_e32 v76, 0xffff0000, v249
	v_pk_fma_f32 v[134:135], v[54:55], v[76:77], v[134:135] op_sel_hi:[1,0,1]
	v_pk_fma_f32 v[76:77], v[52:53], v[76:77], v[132:133] op_sel_hi:[1,0,1]
	v_lshlrev_b32_e32 v132, 16, v250
	v_pk_fma_f32 v[134:135], v[50:51], v[132:133], v[134:135] op_sel_hi:[1,0,1]
	v_pk_fma_f32 v[76:77], v[48:49], v[132:133], v[76:77] op_sel_hi:[1,0,1]
	v_and_b32_e32 v78, 0xffff0000, v250
	v_pk_fma_f32 v[132:133], v[46:47], v[78:79], v[134:135] op_sel_hi:[1,0,1]
	v_pk_fma_f32 v[76:77], v[44:45], v[78:79], v[76:77] op_sel_hi:[1,0,1]
	v_lshlrev_b32_e32 v78, 16, v251
	v_pk_fma_f32 v[132:133], v[42:43], v[78:79], v[132:133] op_sel_hi:[1,0,1]
	v_pk_fma_f32 v[76:77], v[40:41], v[78:79], v[76:77] op_sel_hi:[1,0,1]
	v_and_b32_e32 v78, 0xffff0000, v251
	v_pk_fma_f32 v[132:133], v[38:39], v[78:79], v[132:133] op_sel_hi:[1,0,1]
	v_pk_fma_f32 v[76:77], v[36:37], v[78:79], v[76:77] op_sel_hi:[1,0,1]
	v_lshlrev_b32_e32 v78, 16, v244
	v_pk_fma_f32 v[132:133], v[34:35], v[78:79], v[132:133] op_sel_hi:[1,0,1]
	v_pk_fma_f32 v[76:77], v[32:33], v[78:79], v[76:77] op_sel_hi:[1,0,1]
	v_and_b32_e32 v72, 0xffff0000, v244
	v_pk_fma_f32 v[78:79], v[30:31], v[72:73], v[132:133] op_sel_hi:[1,0,1]
	v_pk_fma_f32 v[76:77], v[28:29], v[72:73], v[76:77] op_sel_hi:[1,0,1]
	v_lshlrev_b32_e32 v72, 16, v245
	v_pk_fma_f32 v[78:79], v[26:27], v[72:73], v[78:79] op_sel_hi:[1,0,1]
	v_pk_fma_f32 v[76:77], v[24:25], v[72:73], v[76:77] op_sel_hi:[1,0,1]
	v_and_b32_e32 v72, 0xffff0000, v245
	v_pk_fma_f32 v[78:79], v[22:23], v[72:73], v[78:79] op_sel_hi:[1,0,1]
	v_pk_fma_f32 v[72:73], v[20:21], v[72:73], v[76:77] op_sel_hi:[1,0,1]
	v_lshlrev_b32_e32 v76, 16, v246
	v_pk_fma_f32 v[78:79], v[18:19], v[76:77], v[78:79] op_sel_hi:[1,0,1]
	v_pk_fma_f32 v[72:73], v[16:17], v[76:77], v[72:73] op_sel_hi:[1,0,1]
	v_and_b32_e32 v74, 0xffff0000, v246
	v_pk_fma_f32 v[76:77], v[14:15], v[74:75], v[78:79] op_sel_hi:[1,0,1]
	v_pk_fma_f32 v[72:73], v[12:13], v[74:75], v[72:73] op_sel_hi:[1,0,1]
	v_lshlrev_b32_e32 v74, 16, v247
	v_pk_fma_f32 v[76:77], v[10:11], v[74:75], v[76:77] op_sel_hi:[1,0,1]
	v_pk_fma_f32 v[72:73], v[8:9], v[74:75], v[72:73] op_sel_hi:[1,0,1]
	v_and_b32_e32 v74, 0xffff0000, v247
	v_pk_fma_f32 v[72:73], v[4:5], v[74:75], v[72:73] op_sel_hi:[1,0,1]
	v_pk_fma_f32 v[76:77], v[6:7], v[74:75], v[76:77] op_sel_hi:[1,0,1]
	v_min_f32_e32 v74, 0, v72
	v_mul_f32_e64 v72, |v72|, s93
	v_exp_f32_e32 v72, v72
	v_min_f32_e32 v75, 0, v73
	v_add_f32_e32 v72, 1.0, v72
	v_log_f32_e32 v78, v72
	v_mul_f32_e64 v72, |v73|, s93
	v_mul_f32_e64 v73, |v76|, s93
	v_exp_f32_e32 v72, v72
	v_exp_f32_e32 v73, v73
	v_add_f32_e32 v72, 1.0, v72
	v_add_f32_e32 v73, 1.0, v73
	v_log_f32_e32 v79, v72
	v_min_f32_e32 v72, 0, v76
	v_log_f32_e32 v76, v73
	v_min_f32_e32 v73, 0, v77
	v_mul_f32_e64 v77, |v77|, s93
	v_exp_f32_e32 v77, v77
	v_xor_b32_e32 v76, 0x80000000, v76
	v_add_f32_e32 v77, 1.0, v77
	v_log_f32_e32 v77, v77
	s_nop 0
	v_xor_b32_e32 v77, 0x80000000, v77
	v_pk_fma_f32 v[72:73], v[76:77], s[88:89], v[72:73] op_sel_hi:[1,0,1]
	v_xor_b32_e32 v77, 0x80000000, v79
	v_xor_b32_e32 v76, 0x80000000, v78
	v_pk_fma_f32 v[76:77], v[76:77], s[88:89], v[74:75] op_sel_hi:[1,0,1]
	v_pk_add_f32 v[74:75], v[128:129], v[72:73]
	v_pk_add_f32 v[72:73], v[130:131], v[76:77]
	s_cbranch_scc0 .LBB0_569
	s_add_u32 s0, s6, 0x2800
	s_mov_b32 s2, 0x3d800000
	s_addc_u32 s1, s7, 0
	v_pk_mul_f32 v[128:129], v[74:75], s[2:3] op_sel_hi:[1,0]
	v_pk_mul_f32 v[130:131], v[72:73], s[2:3] op_sel_hi:[1,0]
	s_add_u32 s4, s6, s58
	v_mul_f32_e32 v72, 0x3fb8aa3b, v130
	v_mul_f32_e32 v73, 0x3fb8aa3b, v131
	v_mul_f32_e32 v74, 0x3fb8aa3b, v128
	v_mul_f32_e32 v75, 0x3fb8aa3b, v129
	s_addc_u32 s5, s7, 0
	v_exp_f32_e32 v72, v72
	v_exp_f32_e32 v73, v73
	v_exp_f32_e32 v74, v74
	v_exp_f32_e32 v75, v75
	v_lshl_add_u64 v[76:77], v[80:81], 1, s[4:5]
	s_mul_i32 s4, s17, 0xc0
	s_ashr_i32 s5, s4, 31
	v_lshl_add_u64 v[78:79], s[4:5], 2, v[82:83]
	global_store_dwordx4 v[78:79], v[72:75], off
	v_mov_b32_e32 v78, 0x2000
	s_mov_b32 s11, 0xd000
	v_mad_u64_u32 v[72:73], s[4:5], s17, 6, v[84:85]
	v_ashrrev_i32_e32 v73, 31, v72
	v_lshlrev_b64 v[72:73], 12, v[72:73]
	v_lshl_add_u64 v[132:133], v[86:87], 0, v[72:73]
	global_load_dwordx2 v[134:135], v[76:77], off offset:1536
	global_load_dwordx4 v[72:75], v3, s[0:1] offset:16
	global_load_dwordx4 v[136:139], v78, s[6:7] offset:2048
	s_add_u32 s0, s6, 0x5200
	s_addc_u32 s1, s7, 0
	s_mov_b32 s5, 0x8000
	s_mov_b32 s18, 0x15000
	s_mov_b32 s4, 0x18000
	s_mov_b32 s19, 0x1d000
	s_mov_b32 s20, 0x22000
	s_mov_b32 s21, 0x25000
	s_mov_b32 s22, 0x2a000
	s_mov_b32 s23, 0x2d000
	s_mov_b32 s24, 0x32000
	s_mov_b32 s25, 0x37000
	s_mov_b32 s26, 0x3a000
	s_mov_b32 s27, 0x3f000
	s_mov_b32 s28, 0x42000
	s_mov_b32 s29, 0x47000
	s_mov_b32 s30, 0x4c000
	s_mov_b32 s31, 0x4f000
	s_mov_b32 s34, 0x54000
	s_mov_b32 s35, 0x57000
	s_mov_b32 s46, 0x5c000
	s_mov_b32 s47, 0x61000
	s_mov_b32 s48, 0x64000
	s_mov_b32 s49, 0x69000
	s_mov_b32 s50, 0x6c000
	s_mov_b32 s55, 0x71000
	s_mov_b32 s56, 0x76000
	s_mov_b32 s57, 0x79000
	s_mov_b32 s60, 0x7e000
	s_mov_b32 s62, 0x81000
	s_mov_b32 s63, 0x86000
	s_mov_b32 s64, 0x8b000
	s_mov_b32 s65, 0x8e000
	s_mov_b32 s69, 0x93000
	s_mov_b32 s70, 0x96000
	s_mov_b32 s71, 0x9b000
	s_mov_b32 s10, 0xa0000
	s_mov_b32 s73, 0xa3000
	s_waitcnt vmcnt(0)
	v_lshlrev_b32_e32 v78, 16, v136
	v_pk_fma_f32 v[140:141], v[70:71], v[78:79], v[66:67] op_sel_hi:[1,0,1]
	v_pk_fma_f32 v[78:79], v[68:69], v[78:79], v[64:65] op_sel_hi:[1,0,1]
	v_and_b32_e32 v136, 0xffff0000, v136
	v_pk_fma_f32 v[140:141], v[62:63], v[136:137], v[140:141] op_sel_hi:[1,0,1]
	v_pk_fma_f32 v[78:79], v[60:61], v[136:137], v[78:79] op_sel_hi:[1,0,1]
	v_lshlrev_b32_e32 v136, 16, v137
	v_pk_fma_f32 v[140:141], v[58:59], v[136:137], v[140:141] op_sel_hi:[1,0,1]
	v_pk_fma_f32 v[78:79], v[56:57], v[136:137], v[78:79] op_sel_hi:[1,0,1]
	v_and_b32_e32 v136, 0xffff0000, v137
	v_pk_fma_f32 v[140:141], v[54:55], v[136:137], v[140:141] op_sel_hi:[1,0,1]
	v_pk_fma_f32 v[78:79], v[52:53], v[136:137], v[78:79] op_sel_hi:[1,0,1]
	v_lshlrev_b32_e32 v136, 16, v138
	v_pk_fma_f32 v[140:141], v[50:51], v[136:137], v[140:141] op_sel_hi:[1,0,1]
	v_pk_fma_f32 v[78:79], v[48:49], v[136:137], v[78:79] op_sel_hi:[1,0,1]
	v_and_b32_e32 v136, 0xffff0000, v138
	v_pk_fma_f32 v[140:141], v[46:47], v[136:137], v[140:141] op_sel_hi:[1,0,1]
	v_pk_fma_f32 v[78:79], v[44:45], v[136:137], v[78:79] op_sel_hi:[1,0,1]
	v_lshlrev_b32_e32 v136, 16, v139
	v_pk_fma_f32 v[140:141], v[42:43], v[136:137], v[140:141] op_sel_hi:[1,0,1]
	v_pk_fma_f32 v[78:79], v[40:41], v[136:137], v[78:79] op_sel_hi:[1,0,1]
	v_and_b32_e32 v136, 0xffff0000, v139
	v_pk_fma_f32 v[138:139], v[38:39], v[136:137], v[140:141] op_sel_hi:[1,0,1]
	v_pk_fma_f32 v[78:79], v[36:37], v[136:137], v[78:79] op_sel_hi:[1,0,1]
	v_lshlrev_b32_e32 v136, 16, v72
	v_pk_fma_f32 v[138:139], v[34:35], v[136:137], v[138:139] op_sel_hi:[1,0,1]
	v_pk_fma_f32 v[78:79], v[32:33], v[136:137], v[78:79] op_sel_hi:[1,0,1]
	v_and_b32_e32 v72, 0xffff0000, v72
	v_pk_fma_f32 v[136:137], v[30:31], v[72:73], v[138:139] op_sel_hi:[1,0,1]
	v_pk_fma_f32 v[78:79], v[28:29], v[72:73], v[78:79] op_sel_hi:[1,0,1]
	v_lshlrev_b32_e32 v72, 16, v73
	v_pk_fma_f32 v[136:137], v[26:27], v[72:73], v[136:137] op_sel_hi:[1,0,1]
	v_pk_fma_f32 v[78:79], v[24:25], v[72:73], v[78:79] op_sel_hi:[1,0,1]
	v_and_b32_e32 v72, 0xffff0000, v73
	v_pk_fma_f32 v[136:137], v[22:23], v[72:73], v[136:137] op_sel_hi:[1,0,1]
	v_pk_fma_f32 v[72:73], v[20:21], v[72:73], v[78:79] op_sel_hi:[1,0,1]
	v_lshlrev_b32_e32 v78, 16, v74
	v_pk_fma_f32 v[136:137], v[18:19], v[78:79], v[136:137] op_sel_hi:[1,0,1]
	v_pk_fma_f32 v[72:73], v[16:17], v[78:79], v[72:73] op_sel_hi:[1,0,1]
	v_and_b32_e32 v74, 0xffff0000, v74
	v_pk_fma_f32 v[78:79], v[14:15], v[74:75], v[136:137] op_sel_hi:[1,0,1]
	v_pk_fma_f32 v[72:73], v[12:13], v[74:75], v[72:73] op_sel_hi:[1,0,1]
	v_lshlrev_b32_e32 v74, 16, v75
	v_pk_fma_f32 v[78:79], v[10:11], v[74:75], v[78:79] op_sel_hi:[1,0,1]
	v_pk_fma_f32 v[72:73], v[8:9], v[74:75], v[72:73] op_sel_hi:[1,0,1]
	v_and_b32_e32 v74, 0xffff0000, v75
	v_pk_fma_f32 v[72:73], v[4:5], v[74:75], v[72:73] op_sel_hi:[1,0,1]
	v_pk_fma_f32 v[78:79], v[6:7], v[74:75], v[78:79] op_sel_hi:[1,0,1]
	v_min_f32_e32 v74, 0, v72
	v_mul_f32_e64 v72, |v72|, s93
	v_exp_f32_e32 v72, v72
	s_nop 0
	v_add_f32_e32 v72, 1.0, v72
	v_log_f32_e32 v72, v72
	s_nop 0
	v_fmac_f32_e32 v74, 0xbf317218, v72
	v_min_f32_e32 v72, 0, v73
	v_mul_f32_e64 v73, |v73|, s93
	v_exp_f32_e32 v73, v73
	v_fma_f32 v85, v74, s2, 0
	v_add_f32_e32 v73, 1.0, v73
	v_log_f32_e32 v73, v73
	s_nop 0
	v_fmac_f32_e32 v72, 0xbf317218, v73
	v_mul_f32_e64 v73, |v78|, s93
	v_exp_f32_e32 v73, v73
	v_fma_f32 v91, v72, s2, 0
	v_min_f32_e32 v72, 0, v78
	v_add_f32_e32 v73, 1.0, v73
	v_log_f32_e32 v73, v73
	s_nop 0
	v_fmac_f32_e32 v72, 0xbf317218, v73
	v_mul_f32_e64 v73, |v79|, s93
	v_exp_f32_e32 v73, v73
	v_fma_f32 v163, v72, s2, 0
	v_min_f32_e32 v72, 0, v79
	v_mov_b32_e32 v79, 0x5000
	v_add_f32_e32 v73, 1.0, v73
	v_log_f32_e32 v73, v73
	global_load_dwordx4 v[144:147], v79, s[6:7] offset:512
	v_fmac_f32_e32 v72, 0xbf317218, v73
	v_fma_f32 v170, v72, s2, 0
	v_sub_f32_e32 v72, v130, v85
	v_mul_f32_e32 v72, 0x3fb8aa3b, v72
	v_exp_f32_e32 v142, v72
	v_sub_f32_e32 v72, v131, v91
	v_mul_f32_e32 v72, 0x3fb8aa3b, v72
	v_exp_f32_e32 v140, v72
	v_sub_f32_e32 v72, v128, v163
	v_mul_f32_e32 v72, 0x3fb8aa3b, v72
	v_exp_f32_e32 v78, v72
	v_sub_f32_e32 v72, v129, v170
	v_mul_f32_e32 v72, 0x3fb8aa3b, v72
	v_exp_f32_e32 v136, v72
	v_add_co_u32_e32 v72, vcc, s33, v76
	s_mov_b32 s2, 0x10000
	s_nop 0
	v_addc_co_u32_e32 v73, vcc, 0, v77, vcc
	global_load_dwordx2 v[138:139], v[72:73], off
	s_waitcnt vmcnt(1)
	v_lshlrev_b32_e32 v148, 16, v144
	global_load_dwordx4 v[72:75], v3, s[0:1] offset:16
	v_pk_fma_f32 v[150:151], v[70:71], v[148:149], v[66:67] op_sel_hi:[1,0,1]
	v_pk_fma_f32 v[148:149], v[68:69], v[148:149], v[64:65] op_sel_hi:[1,0,1]
	v_and_b32_e32 v144, 0xffff0000, v144
	v_pk_fma_f32 v[150:151], v[62:63], v[144:145], v[150:151] op_sel_hi:[1,0,1]
	v_pk_fma_f32 v[148:149], v[60:61], v[144:145], v[148:149] op_sel_hi:[1,0,1]
	v_lshlrev_b32_e32 v144, 16, v145
	v_pk_fma_f32 v[150:151], v[58:59], v[144:145], v[150:151] op_sel_hi:[1,0,1]
	v_pk_fma_f32 v[148:149], v[56:57], v[144:145], v[148:149] op_sel_hi:[1,0,1]
	v_and_b32_e32 v144, 0xffff0000, v145
	v_pk_fma_f32 v[150:151], v[54:55], v[144:145], v[150:151] op_sel_hi:[1,0,1]
	v_pk_fma_f32 v[144:145], v[52:53], v[144:145], v[148:149] op_sel_hi:[1,0,1]
	v_lshlrev_b32_e32 v148, 16, v146
	v_pk_fma_f32 v[150:151], v[50:51], v[148:149], v[150:151] op_sel_hi:[1,0,1]
	v_pk_fma_f32 v[144:145], v[48:49], v[148:149], v[144:145] op_sel_hi:[1,0,1]
	v_and_b32_e32 v146, 0xffff0000, v146
	v_pk_fma_f32 v[148:149], v[46:47], v[146:147], v[150:151] op_sel_hi:[1,0,1]
	v_pk_fma_f32 v[144:145], v[44:45], v[146:147], v[144:145] op_sel_hi:[1,0,1]
	v_lshlrev_b32_e32 v146, 16, v147
	v_pk_fma_f32 v[148:149], v[42:43], v[146:147], v[148:149] op_sel_hi:[1,0,1]
	v_pk_fma_f32 v[144:145], v[40:41], v[146:147], v[144:145] op_sel_hi:[1,0,1]
	v_and_b32_e32 v146, 0xffff0000, v147
	v_pk_fma_f32 v[148:149], v[38:39], v[146:147], v[148:149] op_sel_hi:[1,0,1]
	v_pk_fma_f32 v[144:145], v[36:37], v[146:147], v[144:145] op_sel_hi:[1,0,1]
	s_add_u32 s0, s6, 0x7c00
	s_addc_u32 s1, s7, 0
	s_waitcnt vmcnt(0)
	v_lshlrev_b32_e32 v146, 16, v72
	v_pk_fma_f32 v[148:149], v[34:35], v[146:147], v[148:149] op_sel_hi:[1,0,1]
	v_pk_fma_f32 v[144:145], v[32:33], v[146:147], v[144:145] op_sel_hi:[1,0,1]
	v_and_b32_e32 v72, 0xffff0000, v72
	v_pk_fma_f32 v[146:147], v[30:31], v[72:73], v[148:149] op_sel_hi:[1,0,1]
	v_pk_fma_f32 v[144:145], v[28:29], v[72:73], v[144:145] op_sel_hi:[1,0,1]
	v_lshlrev_b32_e32 v72, 16, v73
	v_pk_fma_f32 v[146:147], v[26:27], v[72:73], v[146:147] op_sel_hi:[1,0,1]
	v_pk_fma_f32 v[144:145], v[24:25], v[72:73], v[144:145] op_sel_hi:[1,0,1]
	v_and_b32_e32 v72, 0xffff0000, v73
	v_pk_fma_f32 v[146:147], v[22:23], v[72:73], v[146:147] op_sel_hi:[1,0,1]
	v_pk_fma_f32 v[72:73], v[20:21], v[72:73], v[144:145] op_sel_hi:[1,0,1]
	v_lshlrev_b32_e32 v144, 16, v74
	v_pk_fma_f32 v[146:147], v[18:19], v[144:145], v[146:147] op_sel_hi:[1,0,1]
	v_pk_fma_f32 v[72:73], v[16:17], v[144:145], v[72:73] op_sel_hi:[1,0,1]
	v_and_b32_e32 v74, 0xffff0000, v74
	v_pk_fma_f32 v[144:145], v[14:15], v[74:75], v[146:147] op_sel_hi:[1,0,1]
	v_pk_fma_f32 v[72:73], v[12:13], v[74:75], v[72:73] op_sel_hi:[1,0,1]
	v_lshlrev_b32_e32 v74, 16, v75
	v_pk_fma_f32 v[144:145], v[10:11], v[74:75], v[144:145] op_sel_hi:[1,0,1]
	v_pk_fma_f32 v[72:73], v[8:9], v[74:75], v[72:73] op_sel_hi:[1,0,1]
	v_and_b32_e32 v74, 0xffff0000, v75
	v_pk_fma_f32 v[72:73], v[4:5], v[74:75], v[72:73] op_sel_hi:[1,0,1]
	v_pk_fma_f32 v[144:145], v[6:7], v[74:75], v[144:145] op_sel_hi:[1,0,1]
	v_min_f32_e32 v74, 0, v72
	v_mul_f32_e64 v72, |v72|, s93
	v_exp_f32_e32 v72, v72
	v_and_b32_e32 v75, 0xffff0000, v138
	v_add_f32_e32 v72, 1.0, v72
	v_log_f32_e32 v72, v72
	s_nop 0
	v_fmac_f32_e32 v74, 0xbf317218, v72
	v_min_f32_e32 v72, 0, v73
	v_mul_f32_e64 v73, |v73|, s93
	v_exp_f32_e32 v73, v73
	v_fmac_f32_e32 v85, 0x3d800000, v74
	v_add_f32_e32 v73, 1.0, v73
	v_log_f32_e32 v73, v73
	s_nop 0
	v_fmac_f32_e32 v72, 0xbf317218, v73
	v_mul_f32_e64 v73, |v144|, s93
	v_exp_f32_e32 v73, v73
	v_fmac_f32_e32 v91, 0x3d800000, v72
	v_min_f32_e32 v72, 0, v144
	v_sub_f32_e32 v74, v131, v91
	v_add_f32_e32 v73, 1.0, v73
	v_log_f32_e32 v73, v73
	v_mul_f32_e32 v74, 0x3fb8aa3b, v74
	v_exp_f32_e32 v141, v74
	v_and_b32_e32 v74, 0xffff0000, v134
	v_fmac_f32_e32 v72, 0xbf317218, v73
	v_mul_f32_e64 v73, |v145|, s93
	v_exp_f32_e32 v73, v73
	v_fmac_f32_e32 v163, 0x3d800000, v72
	v_sub_f32_e32 v79, v128, v163
	v_mul_f32_e32 v79, 0x3fb8aa3b, v79
	v_add_f32_e32 v73, 1.0, v73
	v_log_f32_e32 v73, v73
	v_exp_f32_e32 v79, v79
	v_min_f32_e32 v72, 0, v145
	v_pk_mul_f32 v[74:75], v[140:141], v[74:75]
	v_fmac_f32_e32 v72, 0xbf317218, v73
	v_fmac_f32_e32 v170, 0x3d800000, v72
	v_sub_f32_e32 v72, v130, v85
	v_lshlrev_b32_e32 v141, 16, v139
	v_lshlrev_b32_e32 v140, 16, v135
	v_mul_f32_e32 v72, 0x3fb8aa3b, v72
	v_pk_mul_f32 v[78:79], v[78:79], v[140:141]
	v_mov_b32_e32 v140, 0x7000
	v_exp_f32_e32 v143, v72
	v_lshlrev_b32_e32 v72, 16, v134
	v_sub_f32_e32 v134, v129, v170
	global_load_dwordx4 v[144:147], v140, s[6:7] offset:3072
	v_mul_f32_e32 v134, 0x3fb8aa3b, v134
	v_exp_f32_e32 v137, v134
	v_lshlrev_b32_e32 v73, 16, v138
	v_and_b32_e32 v139, 0xffff0000, v139
	v_and_b32_e32 v138, 0xffff0000, v135
	v_pk_mul_f32 v[134:135], v[136:137], v[138:139]
	v_add_co_u32_e32 v136, vcc, s54, v76
	v_pk_mul_f32 v[72:73], v[142:143], v[72:73]
	s_nop 0
	v_addc_co_u32_e32 v137, vcc, 0, v77, vcc
	global_load_dwordx2 v[142:143], v[136:137], off offset:2560
	s_waitcnt vmcnt(1)
	v_lshlrev_b32_e32 v140, 16, v144
	global_load_dwordx4 v[136:139], v3, s[0:1] offset:16
	v_pk_fma_f32 v[148:149], v[70:71], v[140:141], v[66:67] op_sel_hi:[1,0,1]
	v_pk_fma_f32 v[140:141], v[68:69], v[140:141], v[64:65] op_sel_hi:[1,0,1]
	v_and_b32_e32 v144, 0xffff0000, v144
	v_pk_fma_f32 v[148:149], v[62:63], v[144:145], v[148:149] op_sel_hi:[1,0,1]
	v_pk_fma_f32 v[140:141], v[60:61], v[144:145], v[140:141] op_sel_hi:[1,0,1]
	v_lshlrev_b32_e32 v144, 16, v145
	v_pk_fma_f32 v[148:149], v[58:59], v[144:145], v[148:149] op_sel_hi:[1,0,1]
	v_pk_fma_f32 v[140:141], v[56:57], v[144:145], v[140:141] op_sel_hi:[1,0,1]
	v_and_b32_e32 v144, 0xffff0000, v145
	v_pk_fma_f32 v[148:149], v[54:55], v[144:145], v[148:149] op_sel_hi:[1,0,1]
	v_pk_fma_f32 v[140:141], v[52:53], v[144:145], v[140:141] op_sel_hi:[1,0,1]
	v_lshlrev_b32_e32 v144, 16, v146
	v_pk_fma_f32 v[148:149], v[50:51], v[144:145], v[148:149] op_sel_hi:[1,0,1]
	v_pk_fma_f32 v[140:141], v[48:49], v[144:145], v[140:141] op_sel_hi:[1,0,1]
	v_and_b32_e32 v144, 0xffff0000, v146
	v_pk_fma_f32 v[148:149], v[46:47], v[144:145], v[148:149] op_sel_hi:[1,0,1]
	v_pk_fma_f32 v[140:141], v[44:45], v[144:145], v[140:141] op_sel_hi:[1,0,1]
	v_lshlrev_b32_e32 v144, 16, v147
	v_pk_fma_f32 v[148:149], v[42:43], v[144:145], v[148:149] op_sel_hi:[1,0,1]
	v_pk_fma_f32 v[140:141], v[40:41], v[144:145], v[140:141] op_sel_hi:[1,0,1]
	v_and_b32_e32 v144, 0xffff0000, v147
	v_pk_fma_f32 v[146:147], v[38:39], v[144:145], v[148:149] op_sel_hi:[1,0,1]
	v_pk_fma_f32 v[140:141], v[36:37], v[144:145], v[140:141] op_sel_hi:[1,0,1]
	s_add_u32 s0, s6, 0xa600
	s_addc_u32 s1, s7, 0
	s_waitcnt vmcnt(0)
	v_lshlrev_b32_e32 v144, 16, v136
	v_pk_fma_f32 v[146:147], v[34:35], v[144:145], v[146:147] op_sel_hi:[1,0,1]
	v_pk_fma_f32 v[140:141], v[32:33], v[144:145], v[140:141] op_sel_hi:[1,0,1]
	v_and_b32_e32 v136, 0xffff0000, v136
	v_pk_fma_f32 v[144:145], v[30:31], v[136:137], v[146:147] op_sel_hi:[1,0,1]
	v_pk_fma_f32 v[140:141], v[28:29], v[136:137], v[140:141] op_sel_hi:[1,0,1]
	v_lshlrev_b32_e32 v136, 16, v137
	v_pk_fma_f32 v[144:145], v[26:27], v[136:137], v[144:145] op_sel_hi:[1,0,1]
	v_pk_fma_f32 v[140:141], v[24:25], v[136:137], v[140:141] op_sel_hi:[1,0,1]
	v_and_b32_e32 v136, 0xffff0000, v137
	v_pk_fma_f32 v[144:145], v[22:23], v[136:137], v[144:145] op_sel_hi:[1,0,1]
	v_pk_fma_f32 v[136:137], v[20:21], v[136:137], v[140:141] op_sel_hi:[1,0,1]
	v_lshlrev_b32_e32 v140, 16, v138
	v_pk_fma_f32 v[144:145], v[18:19], v[140:141], v[144:145] op_sel_hi:[1,0,1]
	v_pk_fma_f32 v[136:137], v[16:17], v[140:141], v[136:137] op_sel_hi:[1,0,1]
	v_and_b32_e32 v138, 0xffff0000, v138
	v_pk_fma_f32 v[140:141], v[14:15], v[138:139], v[144:145] op_sel_hi:[1,0,1]
	v_pk_fma_f32 v[136:137], v[12:13], v[138:139], v[136:137] op_sel_hi:[1,0,1]
	v_lshlrev_b32_e32 v138, 16, v139
	v_pk_fma_f32 v[140:141], v[10:11], v[138:139], v[140:141] op_sel_hi:[1,0,1]
	v_pk_fma_f32 v[136:137], v[8:9], v[138:139], v[136:137] op_sel_hi:[1,0,1]
	v_and_b32_e32 v138, 0xffff0000, v139
	v_pk_fma_f32 v[136:137], v[4:5], v[138:139], v[136:137] op_sel_hi:[1,0,1]
	v_pk_fma_f32 v[140:141], v[6:7], v[138:139], v[140:141] op_sel_hi:[1,0,1]
	v_min_f32_e32 v138, 0, v136
	v_mul_f32_e64 v136, |v136|, s93
	v_exp_f32_e32 v136, v136
	v_add_co_u32_e32 v146, vcc, s5, v76
	v_add_f32_e32 v136, 1.0, v136
	v_log_f32_e32 v136, v136
	v_addc_co_u32_e32 v147, vcc, 0, v77, vcc
	global_load_dwordx2 v[154:155], v[146:147], off offset:1024
	v_fmac_f32_e32 v138, 0xbf317218, v136
	v_min_f32_e32 v136, 0, v137
	v_mul_f32_e64 v137, |v137|, s93
	v_exp_f32_e32 v137, v137
	v_fmac_f32_e32 v85, 0x3d800000, v138
	global_load_dwordx4 v[146:149], v3, s[0:1] offset:16
	s_mov_b32 s0, 0xa000
	v_add_f32_e32 v137, 1.0, v137
	v_log_f32_e32 v137, v137
	s_nop 0
	v_fmac_f32_e32 v136, 0xbf317218, v137
	v_mul_f32_e64 v137, |v140|, s93
	v_exp_f32_e32 v137, v137
	v_fmac_f32_e32 v91, 0x3d800000, v136
	v_min_f32_e32 v136, 0, v140
	v_add_f32_e32 v137, 1.0, v137
	v_log_f32_e32 v137, v137
	s_nop 0
	v_fmac_f32_e32 v136, 0xbf317218, v137
	v_mul_f32_e64 v137, |v141|, s93
	v_exp_f32_e32 v137, v137
	v_fmac_f32_e32 v163, 0x3d800000, v136
	v_min_f32_e32 v136, 0, v141
	v_add_f32_e32 v137, 1.0, v137
	v_log_f32_e32 v137, v137
	s_nop 0
	v_fmac_f32_e32 v136, 0xbf317218, v137
	v_sub_f32_e32 v137, v131, v91
	v_mul_f32_e32 v137, 0x3fb8aa3b, v137
	v_exp_f32_e32 v138, v137
	v_sub_f32_e32 v137, v128, v163
	v_fmac_f32_e32 v170, 0x3d800000, v136
	v_mul_f32_e32 v137, 0x3fb8aa3b, v137
	v_exp_f32_e32 v140, v137
	v_sub_f32_e32 v137, v129, v170
	v_mul_f32_e32 v137, 0x3fb8aa3b, v137
	v_exp_f32_e32 v144, v137
	v_mov_b32_e32 v137, 0xa000
	global_load_dwordx4 v[150:153], v137, s[6:7] offset:1536
	v_sub_f32_e32 v136, v130, v85
	v_mul_f32_e32 v136, 0x3fb8aa3b, v136
	v_exp_f32_e32 v136, v136
	s_waitcnt vmcnt(0)
	v_lshlrev_b32_e32 v156, 16, v150
	v_pk_fma_f32 v[158:159], v[70:71], v[156:157], v[66:67] op_sel_hi:[1,0,1]
	v_pk_fma_f32 v[156:157], v[68:69], v[156:157], v[64:65] op_sel_hi:[1,0,1]
	v_and_b32_e32 v150, 0xffff0000, v150
	v_pk_fma_f32 v[158:159], v[62:63], v[150:151], v[158:159] op_sel_hi:[1,0,1]
	v_pk_fma_f32 v[156:157], v[60:61], v[150:151], v[156:157] op_sel_hi:[1,0,1]
	v_lshlrev_b32_e32 v150, 16, v151
	v_pk_fma_f32 v[158:159], v[58:59], v[150:151], v[158:159] op_sel_hi:[1,0,1]
	v_pk_fma_f32 v[156:157], v[56:57], v[150:151], v[156:157] op_sel_hi:[1,0,1]
	v_and_b32_e32 v150, 0xffff0000, v151
	v_pk_fma_f32 v[158:159], v[54:55], v[150:151], v[158:159] op_sel_hi:[1,0,1]
	v_pk_fma_f32 v[150:151], v[52:53], v[150:151], v[156:157] op_sel_hi:[1,0,1]
	v_lshlrev_b32_e32 v156, 16, v152
	v_pk_fma_f32 v[158:159], v[50:51], v[156:157], v[158:159] op_sel_hi:[1,0,1]
	v_pk_fma_f32 v[150:151], v[48:49], v[156:157], v[150:151] op_sel_hi:[1,0,1]
	v_and_b32_e32 v152, 0xffff0000, v152
	v_pk_fma_f32 v[156:157], v[46:47], v[152:153], v[158:159] op_sel_hi:[1,0,1]
	v_pk_fma_f32 v[150:151], v[44:45], v[152:153], v[150:151] op_sel_hi:[1,0,1]
	v_lshlrev_b32_e32 v152, 16, v153
	v_pk_fma_f32 v[156:157], v[42:43], v[152:153], v[156:157] op_sel_hi:[1,0,1]
	v_pk_fma_f32 v[150:151], v[40:41], v[152:153], v[150:151] op_sel_hi:[1,0,1]
	v_and_b32_e32 v152, 0xffff0000, v153
	v_pk_fma_f32 v[156:157], v[38:39], v[152:153], v[156:157] op_sel_hi:[1,0,1]
	v_pk_fma_f32 v[150:151], v[36:37], v[152:153], v[150:151] op_sel_hi:[1,0,1]
	v_lshlrev_b32_e32 v152, 16, v146
	v_pk_fma_f32 v[156:157], v[34:35], v[152:153], v[156:157] op_sel_hi:[1,0,1]
	v_pk_fma_f32 v[150:151], v[32:33], v[152:153], v[150:151] op_sel_hi:[1,0,1]
	v_and_b32_e32 v146, 0xffff0000, v146
	v_pk_fma_f32 v[152:153], v[30:31], v[146:147], v[156:157] op_sel_hi:[1,0,1]
	v_pk_fma_f32 v[150:151], v[28:29], v[146:147], v[150:151] op_sel_hi:[1,0,1]
	v_lshlrev_b32_e32 v146, 16, v147
	v_pk_fma_f32 v[152:153], v[26:27], v[146:147], v[152:153] op_sel_hi:[1,0,1]
	v_pk_fma_f32 v[150:151], v[24:25], v[146:147], v[150:151] op_sel_hi:[1,0,1]
	v_and_b32_e32 v146, 0xffff0000, v147
	v_pk_fma_f32 v[152:153], v[22:23], v[146:147], v[152:153] op_sel_hi:[1,0,1]
	v_pk_fma_f32 v[146:147], v[20:21], v[146:147], v[150:151] op_sel_hi:[1,0,1]
	v_lshlrev_b32_e32 v150, 16, v148
	v_pk_fma_f32 v[152:153], v[18:19], v[150:151], v[152:153] op_sel_hi:[1,0,1]
	v_pk_fma_f32 v[146:147], v[16:17], v[150:151], v[146:147] op_sel_hi:[1,0,1]
	v_and_b32_e32 v148, 0xffff0000, v148
	v_pk_fma_f32 v[150:151], v[14:15], v[148:149], v[152:153] op_sel_hi:[1,0,1]
	v_pk_fma_f32 v[146:147], v[12:13], v[148:149], v[146:147] op_sel_hi:[1,0,1]
	v_lshlrev_b32_e32 v148, 16, v149
	v_pk_fma_f32 v[150:151], v[10:11], v[148:149], v[150:151] op_sel_hi:[1,0,1]
	v_pk_fma_f32 v[146:147], v[8:9], v[148:149], v[146:147] op_sel_hi:[1,0,1]
	v_and_b32_e32 v148, 0xffff0000, v149
	v_pk_fma_f32 v[146:147], v[4:5], v[148:149], v[146:147] op_sel_hi:[1,0,1]
	v_pk_fma_f32 v[150:151], v[6:7], v[148:149], v[150:151] op_sel_hi:[1,0,1]
	v_mul_f32_e64 v139, |v146|, s93
	v_exp_f32_e32 v139, v139
	v_min_f32_e32 v137, 0, v146
	v_lshlrev_b32_e32 v146, 16, v142
	v_mov_b32_e32 v148, 0xd000
	v_add_f32_e32 v139, 1.0, v139
	v_log_f32_e32 v139, v139
	s_nop 0
	v_fmac_f32_e32 v137, 0xbf317218, v139
	v_mul_f32_e64 v139, |v147|, s93
	v_exp_f32_e32 v139, v139
	v_fmac_f32_e32 v85, 0x3d800000, v137
	v_min_f32_e32 v137, 0, v147
	v_lshlrev_b32_e32 v147, 16, v154
	v_add_f32_e32 v139, 1.0, v139
	v_log_f32_e32 v139, v139
	s_nop 0
	v_fmac_f32_e32 v137, 0xbf317218, v139
	v_mul_f32_e64 v139, |v150|, s93
	v_exp_f32_e32 v139, v139
	v_fmac_f32_e32 v91, 0x3d800000, v137
	v_min_f32_e32 v137, 0, v150
	v_add_f32_e32 v139, 1.0, v139
	v_log_f32_e32 v139, v139
	s_nop 0
	v_fmac_f32_e32 v137, 0xbf317218, v139
	v_mul_f32_e64 v139, |v151|, s93
	v_exp_f32_e32 v139, v139
	v_fmac_f32_e32 v163, 0x3d800000, v137
	v_min_f32_e32 v137, 0, v151
	v_sub_f32_e32 v141, v128, v163
	v_add_f32_e32 v139, 1.0, v139
	v_log_f32_e32 v139, v139
	v_mul_f32_e32 v141, 0x3fb8aa3b, v141
	v_exp_f32_e32 v141, v141
	v_fmac_f32_e32 v137, 0xbf317218, v139
	v_fmac_f32_e32 v170, 0x3d800000, v137
	v_sub_f32_e32 v137, v130, v85
	v_mul_f32_e32 v137, 0x3fb8aa3b, v137
	v_sub_f32_e32 v139, v131, v91
	v_exp_f32_e32 v137, v137
	v_mul_f32_e32 v139, 0x3fb8aa3b, v139
	v_exp_f32_e32 v139, v139
	v_pk_mul_f32 v[136:137], v[136:137], v[146:147]
	v_and_b32_e32 v147, 0xffff0000, v154
	v_and_b32_e32 v146, 0xffff0000, v142
	v_pk_mul_f32 v[138:139], v[138:139], v[146:147]
	v_lshlrev_b32_e32 v147, 16, v155
	v_lshlrev_b32_e32 v146, 16, v143
	v_pk_mul_f32 v[140:141], v[140:141], v[146:147]
	v_sub_f32_e32 v142, v129, v170
	v_and_b32_e32 v147, 0xffff0000, v155
	global_load_dwordx4 v[152:155], v148, s[6:7]
	v_mul_f32_e32 v142, 0x3fb8aa3b, v142
	v_exp_f32_e32 v145, v142
	v_and_b32_e32 v146, 0xffff0000, v143
	v_pk_mul_f32 v[142:143], v[144:145], v[146:147]
	v_add_co_u32_e32 v144, vcc, s0, v76
	s_add_u32 s0, s6, 0xd000
	s_nop 0
	v_addc_co_u32_e32 v145, vcc, 0, v77, vcc
	s_addc_u32 s1, s7, 0
	global_load_dwordx2 v[150:151], v[144:145], off offset:3584
	s_waitcnt vmcnt(1)
	v_lshlrev_b32_e32 v148, 16, v152
	global_load_dwordx4 v[144:147], v3, s[0:1] offset:16
	v_pk_fma_f32 v[156:157], v[70:71], v[148:149], v[66:67] op_sel_hi:[1,0,1]
	v_pk_fma_f32 v[148:149], v[68:69], v[148:149], v[64:65] op_sel_hi:[1,0,1]
	v_and_b32_e32 v152, 0xffff0000, v152
	v_pk_fma_f32 v[156:157], v[62:63], v[152:153], v[156:157] op_sel_hi:[1,0,1]
	v_pk_fma_f32 v[148:149], v[60:61], v[152:153], v[148:149] op_sel_hi:[1,0,1]
	v_lshlrev_b32_e32 v152, 16, v153
	v_pk_fma_f32 v[156:157], v[58:59], v[152:153], v[156:157] op_sel_hi:[1,0,1]
	v_pk_fma_f32 v[148:149], v[56:57], v[152:153], v[148:149] op_sel_hi:[1,0,1]
	v_and_b32_e32 v152, 0xffff0000, v153
	v_pk_fma_f32 v[156:157], v[54:55], v[152:153], v[156:157] op_sel_hi:[1,0,1]
	v_pk_fma_f32 v[148:149], v[52:53], v[152:153], v[148:149] op_sel_hi:[1,0,1]
	v_lshlrev_b32_e32 v152, 16, v154
	v_pk_fma_f32 v[156:157], v[50:51], v[152:153], v[156:157] op_sel_hi:[1,0,1]
	v_pk_fma_f32 v[148:149], v[48:49], v[152:153], v[148:149] op_sel_hi:[1,0,1]
	v_and_b32_e32 v152, 0xffff0000, v154
	v_pk_fma_f32 v[156:157], v[46:47], v[152:153], v[156:157] op_sel_hi:[1,0,1]
	v_pk_fma_f32 v[148:149], v[44:45], v[152:153], v[148:149] op_sel_hi:[1,0,1]
	v_lshlrev_b32_e32 v152, 16, v155
	v_pk_fma_f32 v[156:157], v[42:43], v[152:153], v[156:157] op_sel_hi:[1,0,1]
	v_pk_fma_f32 v[148:149], v[40:41], v[152:153], v[148:149] op_sel_hi:[1,0,1]
	v_and_b32_e32 v152, 0xffff0000, v155
	v_pk_fma_f32 v[154:155], v[38:39], v[152:153], v[156:157] op_sel_hi:[1,0,1]
	v_pk_fma_f32 v[148:149], v[36:37], v[152:153], v[148:149] op_sel_hi:[1,0,1]
	s_add_u32 s0, s6, 0xfa00
	s_addc_u32 s1, s7, 0
	s_waitcnt vmcnt(0)
	v_lshlrev_b32_e32 v152, 16, v144
	v_pk_fma_f32 v[154:155], v[34:35], v[152:153], v[154:155] op_sel_hi:[1,0,1]
	v_pk_fma_f32 v[148:149], v[32:33], v[152:153], v[148:149] op_sel_hi:[1,0,1]
	v_and_b32_e32 v144, 0xffff0000, v144
	v_pk_fma_f32 v[152:153], v[30:31], v[144:145], v[154:155] op_sel_hi:[1,0,1]
	v_pk_fma_f32 v[148:149], v[28:29], v[144:145], v[148:149] op_sel_hi:[1,0,1]
	v_lshlrev_b32_e32 v144, 16, v145
	v_pk_fma_f32 v[152:153], v[26:27], v[144:145], v[152:153] op_sel_hi:[1,0,1]
	v_pk_fma_f32 v[148:149], v[24:25], v[144:145], v[148:149] op_sel_hi:[1,0,1]
	v_and_b32_e32 v144, 0xffff0000, v145
	v_pk_fma_f32 v[152:153], v[22:23], v[144:145], v[152:153] op_sel_hi:[1,0,1]
	v_pk_fma_f32 v[144:145], v[20:21], v[144:145], v[148:149] op_sel_hi:[1,0,1]
	v_lshlrev_b32_e32 v148, 16, v146
	v_pk_fma_f32 v[152:153], v[18:19], v[148:149], v[152:153] op_sel_hi:[1,0,1]
	v_pk_fma_f32 v[144:145], v[16:17], v[148:149], v[144:145] op_sel_hi:[1,0,1]
	v_and_b32_e32 v146, 0xffff0000, v146
	v_pk_fma_f32 v[148:149], v[14:15], v[146:147], v[152:153] op_sel_hi:[1,0,1]
	v_pk_fma_f32 v[144:145], v[12:13], v[146:147], v[144:145] op_sel_hi:[1,0,1]
	v_lshlrev_b32_e32 v146, 16, v147
	v_pk_fma_f32 v[148:149], v[10:11], v[146:147], v[148:149] op_sel_hi:[1,0,1]
	v_pk_fma_f32 v[144:145], v[8:9], v[146:147], v[144:145] op_sel_hi:[1,0,1]
	v_and_b32_e32 v146, 0xffff0000, v147
	v_pk_fma_f32 v[144:145], v[4:5], v[146:147], v[144:145] op_sel_hi:[1,0,1]
	v_pk_fma_f32 v[148:149], v[6:7], v[146:147], v[148:149] op_sel_hi:[1,0,1]
	v_min_f32_e32 v146, 0, v144
	v_mul_f32_e64 v144, |v144|, s93
	v_exp_f32_e32 v144, v144
	v_add_co_u32_e32 v154, vcc, s11, v76
	v_add_f32_e32 v144, 1.0, v144
	v_log_f32_e32 v144, v144
	v_addc_co_u32_e32 v155, vcc, 0, v77, vcc
	global_load_dwordx2 v[164:165], v[154:155], off offset:2048
	v_fmac_f32_e32 v146, 0xbf317218, v144
	v_min_f32_e32 v144, 0, v145
	v_mul_f32_e64 v145, |v145|, s93
	v_exp_f32_e32 v145, v145
	v_fmac_f32_e32 v85, 0x3d800000, v146
	global_load_dwordx4 v[154:157], v3, s[0:1] offset:16
	s_add_u32 s0, s6, 0x12400
	v_add_f32_e32 v145, 1.0, v145
	v_log_f32_e32 v145, v145
	s_addc_u32 s1, s7, 0
	v_fmac_f32_e32 v144, 0xbf317218, v145
	v_mul_f32_e64 v145, |v148|, s93
	v_exp_f32_e32 v145, v145
	v_fmac_f32_e32 v91, 0x3d800000, v144
	v_min_f32_e32 v144, 0, v148
	v_add_f32_e32 v145, 1.0, v145
	v_log_f32_e32 v145, v145
	s_nop 0
	v_fmac_f32_e32 v144, 0xbf317218, v145
	v_mul_f32_e64 v145, |v149|, s93
	v_exp_f32_e32 v145, v145
	v_fmac_f32_e32 v163, 0x3d800000, v144
	v_min_f32_e32 v144, 0, v149
	v_add_f32_e32 v145, 1.0, v145
	v_log_f32_e32 v145, v145
	s_nop 0
	v_fmac_f32_e32 v144, 0xbf317218, v145
	v_sub_f32_e32 v145, v131, v91
	v_mul_f32_e32 v145, 0x3fb8aa3b, v145
	v_exp_f32_e32 v146, v145
	v_sub_f32_e32 v145, v128, v163
	v_fmac_f32_e32 v170, 0x3d800000, v144
	v_mul_f32_e32 v145, 0x3fb8aa3b, v145
	v_exp_f32_e32 v148, v145
	v_sub_f32_e32 v145, v129, v170
	v_mul_f32_e32 v145, 0x3fb8aa3b, v145
	v_exp_f32_e32 v152, v145
	v_mov_b32_e32 v145, 0xf000
	global_load_dwordx4 v[158:161], v145, s[6:7] offset:2560
	v_sub_f32_e32 v144, v130, v85
	v_mul_f32_e32 v144, 0x3fb8aa3b, v144
	v_exp_f32_e32 v144, v144
	s_waitcnt vmcnt(0)
	v_lshlrev_b32_e32 v162, 16, v158
	v_pk_fma_f32 v[166:167], v[70:71], v[162:163], v[66:67] op_sel_hi:[1,0,1]
	v_pk_fma_f32 v[168:169], v[68:69], v[162:163], v[64:65] op_sel_hi:[1,0,1]
	v_and_b32_e32 v158, 0xffff0000, v158
	v_pk_fma_f32 v[166:167], v[62:63], v[158:159], v[166:167] op_sel_hi:[1,0,1]
	v_pk_fma_f32 v[168:169], v[60:61], v[158:159], v[168:169] op_sel_hi:[1,0,1]
	v_lshlrev_b32_e32 v158, 16, v159
	v_pk_fma_f32 v[166:167], v[58:59], v[158:159], v[166:167] op_sel_hi:[1,0,1]
	v_pk_fma_f32 v[168:169], v[56:57], v[158:159], v[168:169] op_sel_hi:[1,0,1]
	v_and_b32_e32 v158, 0xffff0000, v159
	v_pk_fma_f32 v[166:167], v[54:55], v[158:159], v[166:167] op_sel_hi:[1,0,1]
	v_pk_fma_f32 v[158:159], v[52:53], v[158:159], v[168:169] op_sel_hi:[1,0,1]
	v_lshlrev_b32_e32 v162, 16, v160
	v_pk_fma_f32 v[166:167], v[50:51], v[162:163], v[166:167] op_sel_hi:[1,0,1]
	v_pk_fma_f32 v[158:159], v[48:49], v[162:163], v[158:159] op_sel_hi:[1,0,1]
	v_and_b32_e32 v160, 0xffff0000, v160
	v_pk_fma_f32 v[166:167], v[46:47], v[160:161], v[166:167] op_sel_hi:[1,0,1]
	v_pk_fma_f32 v[158:159], v[44:45], v[160:161], v[158:159] op_sel_hi:[1,0,1]
	v_lshlrev_b32_e32 v160, 16, v161
	v_pk_fma_f32 v[166:167], v[42:43], v[160:161], v[166:167] op_sel_hi:[1,0,1]
	v_pk_fma_f32 v[158:159], v[40:41], v[160:161], v[158:159] op_sel_hi:[1,0,1]
	v_and_b32_e32 v160, 0xffff0000, v161
	v_pk_fma_f32 v[166:167], v[38:39], v[160:161], v[166:167] op_sel_hi:[1,0,1]
	v_pk_fma_f32 v[158:159], v[36:37], v[160:161], v[158:159] op_sel_hi:[1,0,1]
	v_lshlrev_b32_e32 v160, 16, v154
	v_pk_fma_f32 v[166:167], v[34:35], v[160:161], v[166:167] op_sel_hi:[1,0,1]
	v_pk_fma_f32 v[158:159], v[32:33], v[160:161], v[158:159] op_sel_hi:[1,0,1]
	v_and_b32_e32 v154, 0xffff0000, v154
	v_pk_fma_f32 v[160:161], v[30:31], v[154:155], v[166:167] op_sel_hi:[1,0,1]
	v_pk_fma_f32 v[158:159], v[28:29], v[154:155], v[158:159] op_sel_hi:[1,0,1]
	v_lshlrev_b32_e32 v154, 16, v155
	v_pk_fma_f32 v[160:161], v[26:27], v[154:155], v[160:161] op_sel_hi:[1,0,1]
	v_pk_fma_f32 v[158:159], v[24:25], v[154:155], v[158:159] op_sel_hi:[1,0,1]
	v_and_b32_e32 v154, 0xffff0000, v155
	v_pk_fma_f32 v[160:161], v[22:23], v[154:155], v[160:161] op_sel_hi:[1,0,1]
	v_pk_fma_f32 v[154:155], v[20:21], v[154:155], v[158:159] op_sel_hi:[1,0,1]
	v_lshlrev_b32_e32 v158, 16, v156
	v_pk_fma_f32 v[160:161], v[18:19], v[158:159], v[160:161] op_sel_hi:[1,0,1]
	v_pk_fma_f32 v[154:155], v[16:17], v[158:159], v[154:155] op_sel_hi:[1,0,1]
	v_and_b32_e32 v156, 0xffff0000, v156
	v_pk_fma_f32 v[158:159], v[14:15], v[156:157], v[160:161] op_sel_hi:[1,0,1]
	v_pk_fma_f32 v[154:155], v[12:13], v[156:157], v[154:155] op_sel_hi:[1,0,1]
	v_lshlrev_b32_e32 v156, 16, v157
	v_pk_fma_f32 v[158:159], v[10:11], v[156:157], v[158:159] op_sel_hi:[1,0,1]
	v_pk_fma_f32 v[154:155], v[8:9], v[156:157], v[154:155] op_sel_hi:[1,0,1]
	v_and_b32_e32 v156, 0xffff0000, v157
	v_pk_fma_f32 v[154:155], v[4:5], v[156:157], v[154:155] op_sel_hi:[1,0,1]
	v_pk_fma_f32 v[158:159], v[6:7], v[156:157], v[158:159] op_sel_hi:[1,0,1]
	v_mul_f32_e64 v147, |v154|, s93
	v_exp_f32_e32 v147, v147
	v_min_f32_e32 v145, 0, v154
	v_lshlrev_b32_e32 v154, 16, v150
	v_add_f32_e32 v147, 1.0, v147
	v_log_f32_e32 v147, v147
	s_nop 0
	v_fmac_f32_e32 v145, 0xbf317218, v147
	v_mul_f32_e64 v147, |v155|, s93
	v_exp_f32_e32 v147, v147
	v_fmac_f32_e32 v85, 0x3d800000, v145
	v_min_f32_e32 v145, 0, v155
	v_lshlrev_b32_e32 v155, 16, v164
	v_add_f32_e32 v147, 1.0, v147
	v_log_f32_e32 v147, v147
	s_nop 0
	v_fmac_f32_e32 v145, 0xbf317218, v147
	v_mul_f32_e64 v147, |v158|, s93
	v_exp_f32_e32 v147, v147
	v_fmac_f32_e32 v91, 0x3d800000, v145
	v_min_f32_e32 v145, 0, v158
	v_mov_b32_e32 v158, 0x12000
	v_add_f32_e32 v147, 1.0, v147
	v_log_f32_e32 v147, v147
	s_nop 0
	v_fmac_f32_e32 v145, 0xbf317218, v147
	v_mul_f32_e64 v147, |v159|, s93
	v_exp_f32_e32 v147, v147
	v_fmac_f32_e32 v163, 0x3d800000, v145
	v_min_f32_e32 v145, 0, v159
	global_load_dwordx4 v[158:161], v158, s[6:7] offset:1024
	v_add_f32_e32 v147, 1.0, v147
	v_log_f32_e32 v147, v147
	v_sub_f32_e32 v149, v128, v163
	v_mul_f32_e32 v149, 0x3fb8aa3b, v149
	v_exp_f32_e32 v149, v149
	v_fmac_f32_e32 v145, 0xbf317218, v147
	v_fmac_f32_e32 v170, 0x3d800000, v145
	v_sub_f32_e32 v145, v130, v85
	v_mul_f32_e32 v145, 0x3fb8aa3b, v145
	v_exp_f32_e32 v145, v145
	v_sub_f32_e32 v147, v131, v91
	v_mul_f32_e32 v147, 0x3fb8aa3b, v147
	v_exp_f32_e32 v147, v147
	v_pk_mul_f32 v[144:145], v[144:145], v[154:155]
	v_and_b32_e32 v154, 0xffff0000, v150
	v_sub_f32_e32 v150, v129, v170
	v_mul_f32_e32 v150, 0x3fb8aa3b, v150
	v_exp_f32_e32 v153, v150
	v_and_b32_e32 v155, 0xffff0000, v164
	v_pk_mul_f32 v[146:147], v[146:147], v[154:155]
	v_lshlrev_b32_e32 v155, 16, v165
	v_lshlrev_b32_e32 v154, 16, v151
	v_pk_mul_f32 v[148:149], v[148:149], v[154:155]
	v_and_b32_e32 v155, 0xffff0000, v165
	v_and_b32_e32 v154, 0xffff0000, v151
	v_pk_mul_f32 v[150:151], v[152:153], v[154:155]
	global_load_dwordx4 v[154:157], v3, s[0:1] offset:16
	v_add_co_u32_e32 v152, vcc, s2, v76
	s_mov_b32 s0, 0x12000
	s_nop 0
	v_addc_co_u32_e32 v153, vcc, 0, v77, vcc
	global_load_dwordx2 v[152:153], v[152:153], off offset:512
	s_waitcnt vmcnt(2)
	v_lshlrev_b32_e32 v162, 16, v158
	v_pk_fma_f32 v[164:165], v[70:71], v[162:163], v[66:67] op_sel_hi:[1,0,1]
	v_pk_fma_f32 v[166:167], v[68:69], v[162:163], v[64:65] op_sel_hi:[1,0,1]
	v_and_b32_e32 v158, 0xffff0000, v158
	v_pk_fma_f32 v[164:165], v[62:63], v[158:159], v[164:165] op_sel_hi:[1,0,1]
	v_pk_fma_f32 v[166:167], v[60:61], v[158:159], v[166:167] op_sel_hi:[1,0,1]
	v_lshlrev_b32_e32 v158, 16, v159
	v_pk_fma_f32 v[164:165], v[58:59], v[158:159], v[164:165] op_sel_hi:[1,0,1]
	v_pk_fma_f32 v[166:167], v[56:57], v[158:159], v[166:167] op_sel_hi:[1,0,1]
	v_and_b32_e32 v158, 0xffff0000, v159
	v_pk_fma_f32 v[164:165], v[54:55], v[158:159], v[164:165] op_sel_hi:[1,0,1]
	v_pk_fma_f32 v[158:159], v[52:53], v[158:159], v[166:167] op_sel_hi:[1,0,1]
	v_lshlrev_b32_e32 v162, 16, v160
	v_pk_fma_f32 v[164:165], v[50:51], v[162:163], v[164:165] op_sel_hi:[1,0,1]
	v_pk_fma_f32 v[158:159], v[48:49], v[162:163], v[158:159] op_sel_hi:[1,0,1]
	v_and_b32_e32 v160, 0xffff0000, v160
	v_pk_fma_f32 v[164:165], v[46:47], v[160:161], v[164:165] op_sel_hi:[1,0,1]
	v_pk_fma_f32 v[158:159], v[44:45], v[160:161], v[158:159] op_sel_hi:[1,0,1]
	v_lshlrev_b32_e32 v160, 16, v161
	v_pk_fma_f32 v[164:165], v[42:43], v[160:161], v[164:165] op_sel_hi:[1,0,1]
	v_pk_fma_f32 v[158:159], v[40:41], v[160:161], v[158:159] op_sel_hi:[1,0,1]
	v_and_b32_e32 v160, 0xffff0000, v161
	v_pk_fma_f32 v[164:165], v[38:39], v[160:161], v[164:165] op_sel_hi:[1,0,1]
	v_pk_fma_f32 v[158:159], v[36:37], v[160:161], v[158:159] op_sel_hi:[1,0,1]
	s_waitcnt vmcnt(1)
	v_lshlrev_b32_e32 v160, 16, v154
	v_pk_fma_f32 v[164:165], v[34:35], v[160:161], v[164:165] op_sel_hi:[1,0,1]
	v_pk_fma_f32 v[158:159], v[32:33], v[160:161], v[158:159] op_sel_hi:[1,0,1]
	v_and_b32_e32 v154, 0xffff0000, v154
	v_pk_fma_f32 v[160:161], v[30:31], v[154:155], v[164:165] op_sel_hi:[1,0,1]
	v_pk_fma_f32 v[158:159], v[28:29], v[154:155], v[158:159] op_sel_hi:[1,0,1]
	v_lshlrev_b32_e32 v154, 16, v155
	v_pk_fma_f32 v[160:161], v[26:27], v[154:155], v[160:161] op_sel_hi:[1,0,1]
	v_pk_fma_f32 v[158:159], v[24:25], v[154:155], v[158:159] op_sel_hi:[1,0,1]
	v_and_b32_e32 v154, 0xffff0000, v155
	v_pk_fma_f32 v[160:161], v[22:23], v[154:155], v[160:161] op_sel_hi:[1,0,1]
	v_pk_fma_f32 v[154:155], v[20:21], v[154:155], v[158:159] op_sel_hi:[1,0,1]
	v_lshlrev_b32_e32 v158, 16, v156
	v_pk_fma_f32 v[160:161], v[18:19], v[158:159], v[160:161] op_sel_hi:[1,0,1]
	v_pk_fma_f32 v[154:155], v[16:17], v[158:159], v[154:155] op_sel_hi:[1,0,1]
	v_and_b32_e32 v156, 0xffff0000, v156
	v_pk_fma_f32 v[158:159], v[14:15], v[156:157], v[160:161] op_sel_hi:[1,0,1]
	v_pk_fma_f32 v[154:155], v[12:13], v[156:157], v[154:155] op_sel_hi:[1,0,1]
	v_lshlrev_b32_e32 v156, 16, v157
	v_pk_fma_f32 v[158:159], v[10:11], v[156:157], v[158:159] op_sel_hi:[1,0,1]
	v_pk_fma_f32 v[154:155], v[8:9], v[156:157], v[154:155] op_sel_hi:[1,0,1]
	v_and_b32_e32 v156, 0xffff0000, v157
	v_pk_fma_f32 v[154:155], v[4:5], v[156:157], v[154:155] op_sel_hi:[1,0,1]
	v_pk_fma_f32 v[158:159], v[6:7], v[156:157], v[158:159] op_sel_hi:[1,0,1]
	v_min_f32_e32 v156, 0, v154
	v_mul_f32_e64 v154, |v154|, s93
	v_exp_f32_e32 v154, v154
	v_add_co_u32_e32 v164, vcc, s0, v76
	s_add_u32 s0, s6, 0x14e00
	v_add_f32_e32 v154, 1.0, v154
	v_log_f32_e32 v154, v154
	v_addc_co_u32_e32 v165, vcc, 0, v77, vcc
	s_addc_u32 s1, s7, 0
	v_fmac_f32_e32 v156, 0xbf317218, v154
	v_min_f32_e32 v154, 0, v155
	v_mul_f32_e64 v155, |v155|, s93
	v_exp_f32_e32 v155, v155
	global_load_dwordx2 v[168:169], v[164:165], off offset:3072
	v_fmac_f32_e32 v85, 0x3d800000, v156
	global_load_dwordx4 v[164:167], v3, s[0:1] offset:16
	v_add_f32_e32 v155, 1.0, v155
	v_log_f32_e32 v155, v155
	s_add_u32 s0, s6, 0x17800
	s_addc_u32 s1, s7, 0
	v_fmac_f32_e32 v154, 0xbf317218, v155
	v_mul_f32_e64 v155, |v158|, s93
	v_exp_f32_e32 v155, v155
	v_fmac_f32_e32 v91, 0x3d800000, v154
	v_min_f32_e32 v154, 0, v158
	v_add_f32_e32 v155, 1.0, v155
	v_log_f32_e32 v155, v155
	s_nop 0
	v_fmac_f32_e32 v154, 0xbf317218, v155
	v_mul_f32_e64 v155, |v159|, s93
	v_exp_f32_e32 v155, v155
	v_fmac_f32_e32 v163, 0x3d800000, v154
	v_min_f32_e32 v154, 0, v159
	v_add_f32_e32 v155, 1.0, v155
	v_log_f32_e32 v155, v155
	s_nop 0
	v_fmac_f32_e32 v154, 0xbf317218, v155
	v_mov_b32_e32 v155, 0x14000
	global_load_dwordx4 v[172:175], v155, s[6:7] offset:3584
	v_fmac_f32_e32 v170, 0x3d800000, v154
	v_sub_f32_e32 v154, v130, v85
	v_mul_f32_e32 v154, 0x3fb8aa3b, v154
	v_exp_f32_e32 v160, v154
	v_sub_f32_e32 v154, v131, v91
	v_mul_f32_e32 v154, 0x3fb8aa3b, v154
	v_exp_f32_e32 v158, v154
	v_sub_f32_e32 v154, v128, v163
	v_mul_f32_e32 v154, 0x3fb8aa3b, v154
	v_exp_f32_e32 v156, v154
	v_sub_f32_e32 v154, v129, v170
	v_mul_f32_e32 v154, 0x3fb8aa3b, v154
	v_exp_f32_e32 v154, v154
	s_waitcnt vmcnt(0)
	v_lshlrev_b32_e32 v162, 16, v172
	v_pk_fma_f32 v[176:177], v[70:71], v[162:163], v[66:67] op_sel_hi:[1,0,1]
	v_pk_fma_f32 v[178:179], v[68:69], v[162:163], v[64:65] op_sel_hi:[1,0,1]
	v_and_b32_e32 v162, 0xffff0000, v172
	v_pk_fma_f32 v[176:177], v[62:63], v[162:163], v[176:177] op_sel_hi:[1,0,1]
	v_pk_fma_f32 v[178:179], v[60:61], v[162:163], v[178:179] op_sel_hi:[1,0,1]
	v_lshlrev_b32_e32 v162, 16, v173
	v_pk_fma_f32 v[176:177], v[58:59], v[162:163], v[176:177] op_sel_hi:[1,0,1]
	v_pk_fma_f32 v[178:179], v[56:57], v[162:163], v[178:179] op_sel_hi:[1,0,1]
	v_and_b32_e32 v162, 0xffff0000, v173
	v_pk_fma_f32 v[172:173], v[54:55], v[162:163], v[176:177] op_sel_hi:[1,0,1]
	v_pk_fma_f32 v[176:177], v[52:53], v[162:163], v[178:179] op_sel_hi:[1,0,1]
	v_lshlrev_b32_e32 v162, 16, v174
	v_pk_fma_f32 v[172:173], v[50:51], v[162:163], v[172:173] op_sel_hi:[1,0,1]
	v_pk_fma_f32 v[176:177], v[48:49], v[162:163], v[176:177] op_sel_hi:[1,0,1]
	v_and_b32_e32 v162, 0xffff0000, v174
	v_pk_fma_f32 v[172:173], v[46:47], v[162:163], v[172:173] op_sel_hi:[1,0,1]
	v_pk_fma_f32 v[176:177], v[44:45], v[162:163], v[176:177] op_sel_hi:[1,0,1]
	v_lshlrev_b32_e32 v162, 16, v175
	v_pk_fma_f32 v[172:173], v[42:43], v[162:163], v[172:173] op_sel_hi:[1,0,1]
	v_pk_fma_f32 v[176:177], v[40:41], v[162:163], v[176:177] op_sel_hi:[1,0,1]
	v_and_b32_e32 v162, 0xffff0000, v175
	v_pk_fma_f32 v[172:173], v[38:39], v[162:163], v[172:173] op_sel_hi:[1,0,1]
	v_pk_fma_f32 v[174:175], v[36:37], v[162:163], v[176:177] op_sel_hi:[1,0,1]
	v_lshlrev_b32_e32 v162, 16, v164
	v_pk_fma_f32 v[172:173], v[34:35], v[162:163], v[172:173] op_sel_hi:[1,0,1]
	v_pk_fma_f32 v[174:175], v[32:33], v[162:163], v[174:175] op_sel_hi:[1,0,1]
	v_and_b32_e32 v162, 0xffff0000, v164
	v_pk_fma_f32 v[172:173], v[30:31], v[162:163], v[172:173] op_sel_hi:[1,0,1]
	v_pk_fma_f32 v[174:175], v[28:29], v[162:163], v[174:175] op_sel_hi:[1,0,1]
	v_lshlrev_b32_e32 v162, 16, v165
	v_pk_fma_f32 v[172:173], v[26:27], v[162:163], v[172:173] op_sel_hi:[1,0,1]
	v_pk_fma_f32 v[174:175], v[24:25], v[162:163], v[174:175] op_sel_hi:[1,0,1]
	v_and_b32_e32 v162, 0xffff0000, v165
	v_pk_fma_f32 v[164:165], v[22:23], v[162:163], v[172:173] op_sel_hi:[1,0,1]
	v_pk_fma_f32 v[172:173], v[20:21], v[162:163], v[174:175] op_sel_hi:[1,0,1]
	v_lshlrev_b32_e32 v162, 16, v166
	v_pk_fma_f32 v[164:165], v[18:19], v[162:163], v[164:165] op_sel_hi:[1,0,1]
	v_pk_fma_f32 v[172:173], v[16:17], v[162:163], v[172:173] op_sel_hi:[1,0,1]
	v_and_b32_e32 v162, 0xffff0000, v166
	v_pk_fma_f32 v[164:165], v[14:15], v[162:163], v[164:165] op_sel_hi:[1,0,1]
	v_pk_fma_f32 v[172:173], v[12:13], v[162:163], v[172:173] op_sel_hi:[1,0,1]
	v_lshlrev_b32_e32 v162, 16, v167
	v_pk_fma_f32 v[164:165], v[10:11], v[162:163], v[164:165] op_sel_hi:[1,0,1]
	v_pk_fma_f32 v[172:173], v[8:9], v[162:163], v[172:173] op_sel_hi:[1,0,1]
	v_and_b32_e32 v162, 0xffff0000, v167
	v_pk_fma_f32 v[166:167], v[4:5], v[162:163], v[172:173] op_sel_hi:[1,0,1]
	v_pk_fma_f32 v[164:165], v[6:7], v[162:163], v[164:165] op_sel_hi:[1,0,1]
	v_mul_f32_e64 v157, |v166|, s93
	v_exp_f32_e32 v157, v157
	v_min_f32_e32 v155, 0, v166
	v_add_f32_e32 v157, 1.0, v157
	v_log_f32_e32 v157, v157
	s_nop 0
	v_fmac_f32_e32 v155, 0xbf317218, v157
	v_mul_f32_e64 v157, |v167|, s93
	v_exp_f32_e32 v157, v157
	v_fmac_f32_e32 v85, 0x3d800000, v155
	v_min_f32_e32 v155, 0, v167
	v_add_f32_e32 v157, 1.0, v157
	v_log_f32_e32 v157, v157
	s_nop 0
	v_fmac_f32_e32 v155, 0xbf317218, v157
	v_mul_f32_e64 v157, |v164|, s93
	v_exp_f32_e32 v157, v157
	v_fmac_f32_e32 v91, 0x3d800000, v155
	v_min_f32_e32 v155, 0, v164
	v_lshlrev_b32_e32 v164, 16, v152
	v_add_f32_e32 v157, 1.0, v157
	v_log_f32_e32 v157, v157
	s_nop 0
	v_fmac_f32_e32 v155, 0xbf317218, v157
	v_mul_f32_e64 v157, |v165|, s93
	v_exp_f32_e32 v157, v157
	v_fmac_f32_e32 v163, 0x3d800000, v155
	v_min_f32_e32 v155, 0, v165
	v_lshlrev_b32_e32 v165, 16, v168
	v_add_f32_e32 v157, 1.0, v157
	v_log_f32_e32 v157, v157
	s_nop 0
	v_fmac_f32_e32 v155, 0xbf317218, v157
	v_fmac_f32_e32 v170, 0x3d800000, v155
	v_sub_f32_e32 v155, v130, v85
	v_mul_f32_e32 v155, 0x3fb8aa3b, v155
	v_exp_f32_e32 v161, v155
	v_sub_f32_e32 v155, v131, v91
	v_mul_f32_e32 v155, 0x3fb8aa3b, v155
	v_exp_f32_e32 v159, v155
	v_pk_mul_f32 v[160:161], v[160:161], v[164:165]
	v_and_b32_e32 v164, 0xffff0000, v152
	v_sub_f32_e32 v152, v128, v163
	v_mul_f32_e32 v152, 0x3fb8aa3b, v152
	v_exp_f32_e32 v157, v152
	v_sub_f32_e32 v152, v129, v170
	v_mul_f32_e32 v152, 0x3fb8aa3b, v152
	v_exp_f32_e32 v155, v152
	v_and_b32_e32 v165, 0xffff0000, v168
	v_pk_mul_f32 v[158:159], v[158:159], v[164:165]
	v_lshlrev_b32_e32 v165, 16, v169
	v_lshlrev_b32_e32 v164, 16, v153
	v_pk_mul_f32 v[156:157], v[156:157], v[164:165]
	v_and_b32_e32 v165, 0xffff0000, v169
	v_and_b32_e32 v164, 0xffff0000, v153
	v_cvt_pk_bf16_f32 v152, v72, v73
	v_cvt_pk_bf16_f32 v72, v74, v75
	v_cvt_pk_bf16_f32 v73, v138, v139
	v_cvt_pk_bf16_f32 v74, v146, v147
	v_cvt_pk_bf16_f32 v75, v158, v159
	v_pk_mul_f32 v[164:165], v[154:155], v[164:165]
	global_store_dwordx4 v[132:133], v[72:75], off offset:16
	v_cvt_pk_bf16_f32 v153, v136, v137
	v_cvt_pk_bf16_f32 v154, v144, v145
	v_cvt_pk_bf16_f32 v72, v78, v79
	v_cvt_pk_bf16_f32 v73, v140, v141
	v_cvt_pk_bf16_f32 v74, v148, v149
	v_cvt_pk_bf16_f32 v75, v156, v157
	v_cvt_pk_bf16_f32 v155, v160, v161
	global_store_dwordx4 v[132:133], v[72:75], off offset:32
	global_store_dwordx4 v[132:133], v[152:155], off
	v_mov_b32_e32 v78, 0x17000
	v_cvt_pk_bf16_f32 v72, v134, v135
	v_cvt_pk_bf16_f32 v73, v142, v143
	v_cvt_pk_bf16_f32 v74, v150, v151
	v_cvt_pk_bf16_f32 v75, v164, v165
	global_store_dwordx4 v[132:133], v[72:75], off offset:48
	global_load_dwordx4 v[136:139], v78, s[6:7] offset:2048
	s_waitcnt vmcnt(0)
	v_lshlrev_b32_e32 v78, 16, v136
	v_add_co_u32_e32 v72, vcc, s18, v76
	v_pk_fma_f32 v[140:141], v[70:71], v[78:79], v[66:67] op_sel_hi:[1,0,1]
	s_nop 0
	v_addc_co_u32_e32 v73, vcc, 0, v77, vcc
	global_load_dwordx2 v[134:135], v[72:73], off offset:1536
	v_pk_fma_f32 v[78:79], v[68:69], v[78:79], v[64:65] op_sel_hi:[1,0,1]
	global_load_dwordx4 v[72:75], v3, s[0:1] offset:16
	v_and_b32_e32 v136, 0xffff0000, v136
	v_pk_fma_f32 v[140:141], v[62:63], v[136:137], v[140:141] op_sel_hi:[1,0,1]
	v_pk_fma_f32 v[78:79], v[60:61], v[136:137], v[78:79] op_sel_hi:[1,0,1]
	v_lshlrev_b32_e32 v136, 16, v137
	v_pk_fma_f32 v[140:141], v[58:59], v[136:137], v[140:141] op_sel_hi:[1,0,1]
	v_pk_fma_f32 v[78:79], v[56:57], v[136:137], v[78:79] op_sel_hi:[1,0,1]
	v_and_b32_e32 v136, 0xffff0000, v137
	v_pk_fma_f32 v[140:141], v[54:55], v[136:137], v[140:141] op_sel_hi:[1,0,1]
	v_pk_fma_f32 v[78:79], v[52:53], v[136:137], v[78:79] op_sel_hi:[1,0,1]
	v_lshlrev_b32_e32 v136, 16, v138
	v_pk_fma_f32 v[140:141], v[50:51], v[136:137], v[140:141] op_sel_hi:[1,0,1]
	v_pk_fma_f32 v[78:79], v[48:49], v[136:137], v[78:79] op_sel_hi:[1,0,1]
	v_and_b32_e32 v136, 0xffff0000, v138
	v_pk_fma_f32 v[140:141], v[46:47], v[136:137], v[140:141] op_sel_hi:[1,0,1]
	v_pk_fma_f32 v[78:79], v[44:45], v[136:137], v[78:79] op_sel_hi:[1,0,1]
	v_lshlrev_b32_e32 v136, 16, v139
	v_pk_fma_f32 v[140:141], v[42:43], v[136:137], v[140:141] op_sel_hi:[1,0,1]
	v_pk_fma_f32 v[78:79], v[40:41], v[136:137], v[78:79] op_sel_hi:[1,0,1]
	v_and_b32_e32 v136, 0xffff0000, v139
	v_pk_fma_f32 v[138:139], v[38:39], v[136:137], v[140:141] op_sel_hi:[1,0,1]
	v_pk_fma_f32 v[78:79], v[36:37], v[136:137], v[78:79] op_sel_hi:[1,0,1]
	s_add_u32 s0, s6, 0x1a200
	s_addc_u32 s1, s7, 0
	s_waitcnt vmcnt(0)
	v_lshlrev_b32_e32 v136, 16, v72
	v_pk_fma_f32 v[138:139], v[34:35], v[136:137], v[138:139] op_sel_hi:[1,0,1]
	v_pk_fma_f32 v[78:79], v[32:33], v[136:137], v[78:79] op_sel_hi:[1,0,1]
	v_and_b32_e32 v72, 0xffff0000, v72
	v_pk_fma_f32 v[136:137], v[30:31], v[72:73], v[138:139] op_sel_hi:[1,0,1]
	v_pk_fma_f32 v[78:79], v[28:29], v[72:73], v[78:79] op_sel_hi:[1,0,1]
	v_lshlrev_b32_e32 v72, 16, v73
	v_pk_fma_f32 v[136:137], v[26:27], v[72:73], v[136:137] op_sel_hi:[1,0,1]
	v_pk_fma_f32 v[78:79], v[24:25], v[72:73], v[78:79] op_sel_hi:[1,0,1]
	v_and_b32_e32 v72, 0xffff0000, v73
	v_pk_fma_f32 v[136:137], v[22:23], v[72:73], v[136:137] op_sel_hi:[1,0,1]
	v_pk_fma_f32 v[72:73], v[20:21], v[72:73], v[78:79] op_sel_hi:[1,0,1]
	v_lshlrev_b32_e32 v78, 16, v74
	v_pk_fma_f32 v[136:137], v[18:19], v[78:79], v[136:137] op_sel_hi:[1,0,1]
	v_pk_fma_f32 v[72:73], v[16:17], v[78:79], v[72:73] op_sel_hi:[1,0,1]
	v_and_b32_e32 v74, 0xffff0000, v74
	v_pk_fma_f32 v[78:79], v[14:15], v[74:75], v[136:137] op_sel_hi:[1,0,1]
	v_pk_fma_f32 v[72:73], v[12:13], v[74:75], v[72:73] op_sel_hi:[1,0,1]
	v_lshlrev_b32_e32 v74, 16, v75
	v_pk_fma_f32 v[78:79], v[10:11], v[74:75], v[78:79] op_sel_hi:[1,0,1]
	v_pk_fma_f32 v[72:73], v[8:9], v[74:75], v[72:73] op_sel_hi:[1,0,1]
	v_and_b32_e32 v74, 0xffff0000, v75
	v_pk_fma_f32 v[72:73], v[4:5], v[74:75], v[72:73] op_sel_hi:[1,0,1]
	v_pk_fma_f32 v[78:79], v[6:7], v[74:75], v[78:79] op_sel_hi:[1,0,1]
	v_min_f32_e32 v74, 0, v72
	v_mul_f32_e64 v72, |v72|, s93
	v_exp_f32_e32 v72, v72
	v_add_co_u32_e32 v138, vcc, s4, v76
	v_add_f32_e32 v72, 1.0, v72
	v_log_f32_e32 v72, v72
	v_addc_co_u32_e32 v139, vcc, 0, v77, vcc
	global_load_dwordx2 v[146:147], v[138:139], off
	v_fmac_f32_e32 v74, 0xbf317218, v72
	v_min_f32_e32 v72, 0, v73
	v_mul_f32_e64 v73, |v73|, s93
	v_exp_f32_e32 v73, v73
	v_fmac_f32_e32 v85, 0x3d800000, v74
	global_load_dwordx4 v[138:141], v3, s[0:1] offset:16
	s_mov_b32 s0, 0x1a000
	v_add_f32_e32 v73, 1.0, v73
	v_log_f32_e32 v73, v73
	s_nop 0
	v_fmac_f32_e32 v72, 0xbf317218, v73
	v_mul_f32_e64 v73, |v78|, s93
	v_exp_f32_e32 v73, v73
	v_fmac_f32_e32 v91, 0x3d800000, v72
	v_min_f32_e32 v72, 0, v78
	v_add_f32_e32 v73, 1.0, v73
	v_log_f32_e32 v73, v73
	s_nop 0
	v_fmac_f32_e32 v72, 0xbf317218, v73
	v_mul_f32_e64 v73, |v79|, s93
	v_exp_f32_e32 v73, v73
	v_fmac_f32_e32 v163, 0x3d800000, v72
	v_min_f32_e32 v72, 0, v79
	v_add_f32_e32 v73, 1.0, v73
	v_log_f32_e32 v73, v73
	s_nop 0
	v_fmac_f32_e32 v72, 0xbf317218, v73
	v_sub_f32_e32 v73, v131, v91
	v_mul_f32_e32 v73, 0x3fb8aa3b, v73
	v_exp_f32_e32 v74, v73
	v_sub_f32_e32 v73, v128, v163
	v_fmac_f32_e32 v170, 0x3d800000, v72
	v_mul_f32_e32 v73, 0x3fb8aa3b, v73
	v_exp_f32_e32 v78, v73
	v_sub_f32_e32 v73, v129, v170
	v_mul_f32_e32 v73, 0x3fb8aa3b, v73
	v_exp_f32_e32 v136, v73
	v_mov_b32_e32 v73, 0x1a000
	global_load_dwordx4 v[142:145], v73, s[6:7] offset:512
	v_sub_f32_e32 v72, v130, v85
	v_mul_f32_e32 v72, 0x3fb8aa3b, v72
	v_exp_f32_e32 v72, v72
	s_waitcnt vmcnt(0)
	v_lshlrev_b32_e32 v148, 16, v142
	v_pk_fma_f32 v[150:151], v[70:71], v[148:149], v[66:67] op_sel_hi:[1,0,1]
	v_pk_fma_f32 v[148:149], v[68:69], v[148:149], v[64:65] op_sel_hi:[1,0,1]
	v_and_b32_e32 v142, 0xffff0000, v142
	v_pk_fma_f32 v[150:151], v[62:63], v[142:143], v[150:151] op_sel_hi:[1,0,1]
	v_pk_fma_f32 v[148:149], v[60:61], v[142:143], v[148:149] op_sel_hi:[1,0,1]
	v_lshlrev_b32_e32 v142, 16, v143
	v_pk_fma_f32 v[150:151], v[58:59], v[142:143], v[150:151] op_sel_hi:[1,0,1]
	v_pk_fma_f32 v[148:149], v[56:57], v[142:143], v[148:149] op_sel_hi:[1,0,1]
	v_and_b32_e32 v142, 0xffff0000, v143
	v_pk_fma_f32 v[150:151], v[54:55], v[142:143], v[150:151] op_sel_hi:[1,0,1]
	v_pk_fma_f32 v[142:143], v[52:53], v[142:143], v[148:149] op_sel_hi:[1,0,1]
	v_lshlrev_b32_e32 v148, 16, v144
	v_pk_fma_f32 v[150:151], v[50:51], v[148:149], v[150:151] op_sel_hi:[1,0,1]
	v_pk_fma_f32 v[142:143], v[48:49], v[148:149], v[142:143] op_sel_hi:[1,0,1]
	v_and_b32_e32 v144, 0xffff0000, v144
	v_pk_fma_f32 v[148:149], v[46:47], v[144:145], v[150:151] op_sel_hi:[1,0,1]
	v_pk_fma_f32 v[142:143], v[44:45], v[144:145], v[142:143] op_sel_hi:[1,0,1]
	v_lshlrev_b32_e32 v144, 16, v145
	v_pk_fma_f32 v[148:149], v[42:43], v[144:145], v[148:149] op_sel_hi:[1,0,1]
	v_pk_fma_f32 v[142:143], v[40:41], v[144:145], v[142:143] op_sel_hi:[1,0,1]
	v_and_b32_e32 v144, 0xffff0000, v145
	v_pk_fma_f32 v[148:149], v[38:39], v[144:145], v[148:149] op_sel_hi:[1,0,1]
	v_pk_fma_f32 v[142:143], v[36:37], v[144:145], v[142:143] op_sel_hi:[1,0,1]
	v_lshlrev_b32_e32 v144, 16, v138
	v_pk_fma_f32 v[148:149], v[34:35], v[144:145], v[148:149] op_sel_hi:[1,0,1]
	v_pk_fma_f32 v[142:143], v[32:33], v[144:145], v[142:143] op_sel_hi:[1,0,1]
	v_and_b32_e32 v138, 0xffff0000, v138
	v_pk_fma_f32 v[144:145], v[30:31], v[138:139], v[148:149] op_sel_hi:[1,0,1]
	v_pk_fma_f32 v[142:143], v[28:29], v[138:139], v[142:143] op_sel_hi:[1,0,1]
	v_lshlrev_b32_e32 v138, 16, v139
	v_pk_fma_f32 v[144:145], v[26:27], v[138:139], v[144:145] op_sel_hi:[1,0,1]
	v_pk_fma_f32 v[142:143], v[24:25], v[138:139], v[142:143] op_sel_hi:[1,0,1]
	v_and_b32_e32 v138, 0xffff0000, v139
	v_pk_fma_f32 v[144:145], v[22:23], v[138:139], v[144:145] op_sel_hi:[1,0,1]
	v_pk_fma_f32 v[138:139], v[20:21], v[138:139], v[142:143] op_sel_hi:[1,0,1]
	v_lshlrev_b32_e32 v142, 16, v140
	v_pk_fma_f32 v[144:145], v[18:19], v[142:143], v[144:145] op_sel_hi:[1,0,1]
	v_pk_fma_f32 v[138:139], v[16:17], v[142:143], v[138:139] op_sel_hi:[1,0,1]
	v_and_b32_e32 v140, 0xffff0000, v140
	v_pk_fma_f32 v[142:143], v[14:15], v[140:141], v[144:145] op_sel_hi:[1,0,1]
	v_pk_fma_f32 v[138:139], v[12:13], v[140:141], v[138:139] op_sel_hi:[1,0,1]
	v_lshlrev_b32_e32 v140, 16, v141
	v_pk_fma_f32 v[142:143], v[10:11], v[140:141], v[142:143] op_sel_hi:[1,0,1]
	v_pk_fma_f32 v[138:139], v[8:9], v[140:141], v[138:139] op_sel_hi:[1,0,1]
	v_and_b32_e32 v140, 0xffff0000, v141
	v_pk_fma_f32 v[138:139], v[4:5], v[140:141], v[138:139] op_sel_hi:[1,0,1]
	v_pk_fma_f32 v[142:143], v[6:7], v[140:141], v[142:143] op_sel_hi:[1,0,1]
	v_mul_f32_e64 v75, |v138|, s93
	v_exp_f32_e32 v75, v75
	v_min_f32_e32 v73, 0, v138
	v_lshlrev_b32_e32 v138, 16, v134
	v_mov_b32_e32 v140, 0x1c000
	v_add_f32_e32 v75, 1.0, v75
	v_log_f32_e32 v75, v75
	s_nop 0
	v_fmac_f32_e32 v73, 0xbf317218, v75
	v_mul_f32_e64 v75, |v139|, s93
	v_exp_f32_e32 v75, v75
	v_fmac_f32_e32 v85, 0x3d800000, v73
	v_min_f32_e32 v73, 0, v139
	v_lshlrev_b32_e32 v139, 16, v146
	v_add_f32_e32 v75, 1.0, v75
	v_log_f32_e32 v75, v75
	s_nop 0
	v_fmac_f32_e32 v73, 0xbf317218, v75
	v_mul_f32_e64 v75, |v142|, s93
	v_exp_f32_e32 v75, v75
	v_fmac_f32_e32 v91, 0x3d800000, v73
	v_min_f32_e32 v73, 0, v142
	v_add_f32_e32 v75, 1.0, v75
	v_log_f32_e32 v75, v75
	s_nop 0
	v_fmac_f32_e32 v73, 0xbf317218, v75
	v_mul_f32_e64 v75, |v143|, s93
	v_exp_f32_e32 v75, v75
	v_fmac_f32_e32 v163, 0x3d800000, v73
	v_min_f32_e32 v73, 0, v143
	v_sub_f32_e32 v79, v128, v163
	v_add_f32_e32 v75, 1.0, v75
	v_log_f32_e32 v75, v75
	v_mul_f32_e32 v79, 0x3fb8aa3b, v79
	v_exp_f32_e32 v79, v79
	v_fmac_f32_e32 v73, 0xbf317218, v75
	v_fmac_f32_e32 v170, 0x3d800000, v73
	v_sub_f32_e32 v73, v130, v85
	v_mul_f32_e32 v73, 0x3fb8aa3b, v73
	v_sub_f32_e32 v75, v131, v91
	v_exp_f32_e32 v73, v73
	v_mul_f32_e32 v75, 0x3fb8aa3b, v75
	v_exp_f32_e32 v75, v75
	v_pk_mul_f32 v[72:73], v[72:73], v[138:139]
	v_and_b32_e32 v139, 0xffff0000, v146
	v_and_b32_e32 v138, 0xffff0000, v134
	v_pk_mul_f32 v[74:75], v[74:75], v[138:139]
	v_lshlrev_b32_e32 v139, 16, v147
	v_lshlrev_b32_e32 v138, 16, v135
	v_pk_mul_f32 v[78:79], v[78:79], v[138:139]
	v_sub_f32_e32 v134, v129, v170
	v_and_b32_e32 v139, 0xffff0000, v147
	global_load_dwordx4 v[144:147], v140, s[6:7] offset:3072
	v_mul_f32_e32 v134, 0x3fb8aa3b, v134
	v_exp_f32_e32 v137, v134
	v_and_b32_e32 v138, 0xffff0000, v135
	v_pk_mul_f32 v[134:135], v[136:137], v[138:139]
	v_add_co_u32_e32 v136, vcc, s0, v76
	s_add_u32 s0, s6, 0x1cc00
	s_nop 0
	v_addc_co_u32_e32 v137, vcc, 0, v77, vcc
	s_addc_u32 s1, s7, 0
	global_load_dwordx2 v[142:143], v[136:137], off offset:2560
	s_waitcnt vmcnt(1)
	v_lshlrev_b32_e32 v140, 16, v144
	global_load_dwordx4 v[136:139], v3, s[0:1] offset:16
	v_pk_fma_f32 v[148:149], v[70:71], v[140:141], v[66:67] op_sel_hi:[1,0,1]
	v_pk_fma_f32 v[140:141], v[68:69], v[140:141], v[64:65] op_sel_hi:[1,0,1]
	v_and_b32_e32 v144, 0xffff0000, v144
	v_pk_fma_f32 v[148:149], v[62:63], v[144:145], v[148:149] op_sel_hi:[1,0,1]
	v_pk_fma_f32 v[140:141], v[60:61], v[144:145], v[140:141] op_sel_hi:[1,0,1]
	v_lshlrev_b32_e32 v144, 16, v145
	v_pk_fma_f32 v[148:149], v[58:59], v[144:145], v[148:149] op_sel_hi:[1,0,1]
	v_pk_fma_f32 v[140:141], v[56:57], v[144:145], v[140:141] op_sel_hi:[1,0,1]
	v_and_b32_e32 v144, 0xffff0000, v145
	v_pk_fma_f32 v[148:149], v[54:55], v[144:145], v[148:149] op_sel_hi:[1,0,1]
	v_pk_fma_f32 v[140:141], v[52:53], v[144:145], v[140:141] op_sel_hi:[1,0,1]
	v_lshlrev_b32_e32 v144, 16, v146
	v_pk_fma_f32 v[148:149], v[50:51], v[144:145], v[148:149] op_sel_hi:[1,0,1]
	v_pk_fma_f32 v[140:141], v[48:49], v[144:145], v[140:141] op_sel_hi:[1,0,1]
	v_and_b32_e32 v144, 0xffff0000, v146
	v_pk_fma_f32 v[148:149], v[46:47], v[144:145], v[148:149] op_sel_hi:[1,0,1]
	v_pk_fma_f32 v[140:141], v[44:45], v[144:145], v[140:141] op_sel_hi:[1,0,1]
	v_lshlrev_b32_e32 v144, 16, v147
	v_pk_fma_f32 v[148:149], v[42:43], v[144:145], v[148:149] op_sel_hi:[1,0,1]
	v_pk_fma_f32 v[140:141], v[40:41], v[144:145], v[140:141] op_sel_hi:[1,0,1]
	v_and_b32_e32 v144, 0xffff0000, v147
	v_pk_fma_f32 v[146:147], v[38:39], v[144:145], v[148:149] op_sel_hi:[1,0,1]
	v_pk_fma_f32 v[140:141], v[36:37], v[144:145], v[140:141] op_sel_hi:[1,0,1]
	s_add_u32 s0, s6, 0x1f600
	s_addc_u32 s1, s7, 0
	s_waitcnt vmcnt(0)
	v_lshlrev_b32_e32 v144, 16, v136
	v_pk_fma_f32 v[146:147], v[34:35], v[144:145], v[146:147] op_sel_hi:[1,0,1]
	v_pk_fma_f32 v[140:141], v[32:33], v[144:145], v[140:141] op_sel_hi:[1,0,1]
	v_and_b32_e32 v136, 0xffff0000, v136
	v_pk_fma_f32 v[144:145], v[30:31], v[136:137], v[146:147] op_sel_hi:[1,0,1]
	v_pk_fma_f32 v[140:141], v[28:29], v[136:137], v[140:141] op_sel_hi:[1,0,1]
	v_lshlrev_b32_e32 v136, 16, v137
	v_pk_fma_f32 v[144:145], v[26:27], v[136:137], v[144:145] op_sel_hi:[1,0,1]
	v_pk_fma_f32 v[140:141], v[24:25], v[136:137], v[140:141] op_sel_hi:[1,0,1]
	v_and_b32_e32 v136, 0xffff0000, v137
	v_pk_fma_f32 v[144:145], v[22:23], v[136:137], v[144:145] op_sel_hi:[1,0,1]
	v_pk_fma_f32 v[136:137], v[20:21], v[136:137], v[140:141] op_sel_hi:[1,0,1]
	v_lshlrev_b32_e32 v140, 16, v138
	v_pk_fma_f32 v[144:145], v[18:19], v[140:141], v[144:145] op_sel_hi:[1,0,1]
	v_pk_fma_f32 v[136:137], v[16:17], v[140:141], v[136:137] op_sel_hi:[1,0,1]
	v_and_b32_e32 v138, 0xffff0000, v138
	v_pk_fma_f32 v[140:141], v[14:15], v[138:139], v[144:145] op_sel_hi:[1,0,1]
	v_pk_fma_f32 v[136:137], v[12:13], v[138:139], v[136:137] op_sel_hi:[1,0,1]
	v_lshlrev_b32_e32 v138, 16, v139
	v_pk_fma_f32 v[140:141], v[10:11], v[138:139], v[140:141] op_sel_hi:[1,0,1]
	v_pk_fma_f32 v[136:137], v[8:9], v[138:139], v[136:137] op_sel_hi:[1,0,1]
	v_and_b32_e32 v138, 0xffff0000, v139
	v_pk_fma_f32 v[136:137], v[4:5], v[138:139], v[136:137] op_sel_hi:[1,0,1]
	v_pk_fma_f32 v[140:141], v[6:7], v[138:139], v[140:141] op_sel_hi:[1,0,1]
	v_min_f32_e32 v138, 0, v136
	v_mul_f32_e64 v136, |v136|, s93
	v_exp_f32_e32 v136, v136
	v_add_co_u32_e32 v146, vcc, s19, v76
	v_add_f32_e32 v136, 1.0, v136
	v_log_f32_e32 v136, v136
	v_addc_co_u32_e32 v147, vcc, 0, v77, vcc
	global_load_dwordx2 v[154:155], v[146:147], off offset:1024
	v_fmac_f32_e32 v138, 0xbf317218, v136
	v_min_f32_e32 v136, 0, v137
	v_mul_f32_e64 v137, |v137|, s93
	v_exp_f32_e32 v137, v137
	v_fmac_f32_e32 v85, 0x3d800000, v138
	global_load_dwordx4 v[146:149], v3, s[0:1] offset:16
	s_mov_b32 s0, 0x1f000
	v_add_f32_e32 v137, 1.0, v137
	v_log_f32_e32 v137, v137
	s_nop 0
	v_fmac_f32_e32 v136, 0xbf317218, v137
	v_mul_f32_e64 v137, |v140|, s93
	v_exp_f32_e32 v137, v137
	v_fmac_f32_e32 v91, 0x3d800000, v136
	v_min_f32_e32 v136, 0, v140
	v_add_f32_e32 v137, 1.0, v137
	v_log_f32_e32 v137, v137
	s_nop 0
	v_fmac_f32_e32 v136, 0xbf317218, v137
	v_mul_f32_e64 v137, |v141|, s93
	v_exp_f32_e32 v137, v137
	v_fmac_f32_e32 v163, 0x3d800000, v136
	v_min_f32_e32 v136, 0, v141
	v_add_f32_e32 v137, 1.0, v137
	v_log_f32_e32 v137, v137
	s_nop 0
	v_fmac_f32_e32 v136, 0xbf317218, v137
	v_sub_f32_e32 v137, v131, v91
	v_mul_f32_e32 v137, 0x3fb8aa3b, v137
	v_exp_f32_e32 v138, v137
	v_sub_f32_e32 v137, v128, v163
	v_fmac_f32_e32 v170, 0x3d800000, v136
	v_mul_f32_e32 v137, 0x3fb8aa3b, v137
	v_exp_f32_e32 v140, v137
	v_sub_f32_e32 v137, v129, v170
	v_mul_f32_e32 v137, 0x3fb8aa3b, v137
	v_exp_f32_e32 v144, v137
	v_mov_b32_e32 v137, 0x1f000
	global_load_dwordx4 v[150:153], v137, s[6:7] offset:1536
	v_sub_f32_e32 v136, v130, v85
	v_mul_f32_e32 v136, 0x3fb8aa3b, v136
	v_exp_f32_e32 v136, v136
	s_waitcnt vmcnt(0)
	v_lshlrev_b32_e32 v156, 16, v150
	v_pk_fma_f32 v[158:159], v[70:71], v[156:157], v[66:67] op_sel_hi:[1,0,1]
	v_pk_fma_f32 v[156:157], v[68:69], v[156:157], v[64:65] op_sel_hi:[1,0,1]
	v_and_b32_e32 v150, 0xffff0000, v150
	v_pk_fma_f32 v[158:159], v[62:63], v[150:151], v[158:159] op_sel_hi:[1,0,1]
	v_pk_fma_f32 v[156:157], v[60:61], v[150:151], v[156:157] op_sel_hi:[1,0,1]
	v_lshlrev_b32_e32 v150, 16, v151
	v_pk_fma_f32 v[158:159], v[58:59], v[150:151], v[158:159] op_sel_hi:[1,0,1]
	v_pk_fma_f32 v[156:157], v[56:57], v[150:151], v[156:157] op_sel_hi:[1,0,1]
	v_and_b32_e32 v150, 0xffff0000, v151
	v_pk_fma_f32 v[158:159], v[54:55], v[150:151], v[158:159] op_sel_hi:[1,0,1]
	v_pk_fma_f32 v[150:151], v[52:53], v[150:151], v[156:157] op_sel_hi:[1,0,1]
	v_lshlrev_b32_e32 v156, 16, v152
	v_pk_fma_f32 v[158:159], v[50:51], v[156:157], v[158:159] op_sel_hi:[1,0,1]
	v_pk_fma_f32 v[150:151], v[48:49], v[156:157], v[150:151] op_sel_hi:[1,0,1]
	v_and_b32_e32 v152, 0xffff0000, v152
	v_pk_fma_f32 v[156:157], v[46:47], v[152:153], v[158:159] op_sel_hi:[1,0,1]
	v_pk_fma_f32 v[150:151], v[44:45], v[152:153], v[150:151] op_sel_hi:[1,0,1]
	v_lshlrev_b32_e32 v152, 16, v153
	v_pk_fma_f32 v[156:157], v[42:43], v[152:153], v[156:157] op_sel_hi:[1,0,1]
	v_pk_fma_f32 v[150:151], v[40:41], v[152:153], v[150:151] op_sel_hi:[1,0,1]
	v_and_b32_e32 v152, 0xffff0000, v153
	v_pk_fma_f32 v[156:157], v[38:39], v[152:153], v[156:157] op_sel_hi:[1,0,1]
	v_pk_fma_f32 v[150:151], v[36:37], v[152:153], v[150:151] op_sel_hi:[1,0,1]
	v_lshlrev_b32_e32 v152, 16, v146
	v_pk_fma_f32 v[156:157], v[34:35], v[152:153], v[156:157] op_sel_hi:[1,0,1]
	v_pk_fma_f32 v[150:151], v[32:33], v[152:153], v[150:151] op_sel_hi:[1,0,1]
	v_and_b32_e32 v146, 0xffff0000, v146
	v_pk_fma_f32 v[152:153], v[30:31], v[146:147], v[156:157] op_sel_hi:[1,0,1]
	v_pk_fma_f32 v[150:151], v[28:29], v[146:147], v[150:151] op_sel_hi:[1,0,1]
	v_lshlrev_b32_e32 v146, 16, v147
	v_pk_fma_f32 v[152:153], v[26:27], v[146:147], v[152:153] op_sel_hi:[1,0,1]
	v_pk_fma_f32 v[150:151], v[24:25], v[146:147], v[150:151] op_sel_hi:[1,0,1]
	v_and_b32_e32 v146, 0xffff0000, v147
	v_pk_fma_f32 v[152:153], v[22:23], v[146:147], v[152:153] op_sel_hi:[1,0,1]
	v_pk_fma_f32 v[146:147], v[20:21], v[146:147], v[150:151] op_sel_hi:[1,0,1]
	v_lshlrev_b32_e32 v150, 16, v148
	v_pk_fma_f32 v[152:153], v[18:19], v[150:151], v[152:153] op_sel_hi:[1,0,1]
	v_pk_fma_f32 v[146:147], v[16:17], v[150:151], v[146:147] op_sel_hi:[1,0,1]
	v_and_b32_e32 v148, 0xffff0000, v148
	v_pk_fma_f32 v[150:151], v[14:15], v[148:149], v[152:153] op_sel_hi:[1,0,1]
	v_pk_fma_f32 v[146:147], v[12:13], v[148:149], v[146:147] op_sel_hi:[1,0,1]
	v_lshlrev_b32_e32 v148, 16, v149
	v_pk_fma_f32 v[150:151], v[10:11], v[148:149], v[150:151] op_sel_hi:[1,0,1]
	v_pk_fma_f32 v[146:147], v[8:9], v[148:149], v[146:147] op_sel_hi:[1,0,1]
	v_and_b32_e32 v148, 0xffff0000, v149
	v_pk_fma_f32 v[146:147], v[4:5], v[148:149], v[146:147] op_sel_hi:[1,0,1]
	v_pk_fma_f32 v[150:151], v[6:7], v[148:149], v[150:151] op_sel_hi:[1,0,1]
	v_mul_f32_e64 v139, |v146|, s93
	v_exp_f32_e32 v139, v139
	v_min_f32_e32 v137, 0, v146
	v_lshlrev_b32_e32 v146, 16, v142
	v_mov_b32_e32 v148, 0x22000
	v_add_f32_e32 v139, 1.0, v139
	v_log_f32_e32 v139, v139
	s_nop 0
	v_fmac_f32_e32 v137, 0xbf317218, v139
	v_mul_f32_e64 v139, |v147|, s93
	v_exp_f32_e32 v139, v139
	v_fmac_f32_e32 v85, 0x3d800000, v137
	v_min_f32_e32 v137, 0, v147
	v_lshlrev_b32_e32 v147, 16, v154
	v_add_f32_e32 v139, 1.0, v139
	v_log_f32_e32 v139, v139
	s_nop 0
	v_fmac_f32_e32 v137, 0xbf317218, v139
	v_mul_f32_e64 v139, |v150|, s93
	v_exp_f32_e32 v139, v139
	v_fmac_f32_e32 v91, 0x3d800000, v137
	v_min_f32_e32 v137, 0, v150
	v_add_f32_e32 v139, 1.0, v139
	v_log_f32_e32 v139, v139
	s_nop 0
	v_fmac_f32_e32 v137, 0xbf317218, v139
	v_mul_f32_e64 v139, |v151|, s93
	v_exp_f32_e32 v139, v139
	v_fmac_f32_e32 v163, 0x3d800000, v137
	v_min_f32_e32 v137, 0, v151
	v_sub_f32_e32 v141, v128, v163
	v_add_f32_e32 v139, 1.0, v139
	v_log_f32_e32 v139, v139
	v_mul_f32_e32 v141, 0x3fb8aa3b, v141
	v_exp_f32_e32 v141, v141
	v_fmac_f32_e32 v137, 0xbf317218, v139
	v_fmac_f32_e32 v170, 0x3d800000, v137
	v_sub_f32_e32 v137, v130, v85
	v_mul_f32_e32 v137, 0x3fb8aa3b, v137
	v_sub_f32_e32 v139, v131, v91
	v_exp_f32_e32 v137, v137
	v_mul_f32_e32 v139, 0x3fb8aa3b, v139
	v_exp_f32_e32 v139, v139
	v_pk_mul_f32 v[136:137], v[136:137], v[146:147]
	v_and_b32_e32 v147, 0xffff0000, v154
	v_and_b32_e32 v146, 0xffff0000, v142
	v_pk_mul_f32 v[138:139], v[138:139], v[146:147]
	v_lshlrev_b32_e32 v147, 16, v155
	v_lshlrev_b32_e32 v146, 16, v143
	v_pk_mul_f32 v[140:141], v[140:141], v[146:147]
	v_sub_f32_e32 v142, v129, v170
	v_and_b32_e32 v147, 0xffff0000, v155
	global_load_dwordx4 v[152:155], v148, s[6:7]
	v_mul_f32_e32 v142, 0x3fb8aa3b, v142
	v_exp_f32_e32 v145, v142
	v_and_b32_e32 v146, 0xffff0000, v143
	v_pk_mul_f32 v[142:143], v[144:145], v[146:147]
	v_add_co_u32_e32 v144, vcc, s0, v76
	s_add_u32 s0, s6, 0x22000
	s_nop 0
	v_addc_co_u32_e32 v145, vcc, 0, v77, vcc
	s_addc_u32 s1, s7, 0
	global_load_dwordx2 v[150:151], v[144:145], off offset:3584
	s_waitcnt vmcnt(1)
	v_lshlrev_b32_e32 v148, 16, v152
	global_load_dwordx4 v[144:147], v3, s[0:1] offset:16
	v_pk_fma_f32 v[156:157], v[70:71], v[148:149], v[66:67] op_sel_hi:[1,0,1]
	v_pk_fma_f32 v[148:149], v[68:69], v[148:149], v[64:65] op_sel_hi:[1,0,1]
	v_and_b32_e32 v152, 0xffff0000, v152
	v_pk_fma_f32 v[156:157], v[62:63], v[152:153], v[156:157] op_sel_hi:[1,0,1]
	v_pk_fma_f32 v[148:149], v[60:61], v[152:153], v[148:149] op_sel_hi:[1,0,1]
	v_lshlrev_b32_e32 v152, 16, v153
	v_pk_fma_f32 v[156:157], v[58:59], v[152:153], v[156:157] op_sel_hi:[1,0,1]
	v_pk_fma_f32 v[148:149], v[56:57], v[152:153], v[148:149] op_sel_hi:[1,0,1]
	v_and_b32_e32 v152, 0xffff0000, v153
	v_pk_fma_f32 v[156:157], v[54:55], v[152:153], v[156:157] op_sel_hi:[1,0,1]
	v_pk_fma_f32 v[148:149], v[52:53], v[152:153], v[148:149] op_sel_hi:[1,0,1]
	v_lshlrev_b32_e32 v152, 16, v154
	v_pk_fma_f32 v[156:157], v[50:51], v[152:153], v[156:157] op_sel_hi:[1,0,1]
	v_pk_fma_f32 v[148:149], v[48:49], v[152:153], v[148:149] op_sel_hi:[1,0,1]
	v_and_b32_e32 v152, 0xffff0000, v154
	v_pk_fma_f32 v[156:157], v[46:47], v[152:153], v[156:157] op_sel_hi:[1,0,1]
	v_pk_fma_f32 v[148:149], v[44:45], v[152:153], v[148:149] op_sel_hi:[1,0,1]
	v_lshlrev_b32_e32 v152, 16, v155
	v_pk_fma_f32 v[156:157], v[42:43], v[152:153], v[156:157] op_sel_hi:[1,0,1]
	v_pk_fma_f32 v[148:149], v[40:41], v[152:153], v[148:149] op_sel_hi:[1,0,1]
	v_and_b32_e32 v152, 0xffff0000, v155
	v_pk_fma_f32 v[154:155], v[38:39], v[152:153], v[156:157] op_sel_hi:[1,0,1]
	v_pk_fma_f32 v[148:149], v[36:37], v[152:153], v[148:149] op_sel_hi:[1,0,1]
	s_add_u32 s0, s6, 0x24a00
	s_addc_u32 s1, s7, 0
	s_waitcnt vmcnt(0)
	v_lshlrev_b32_e32 v152, 16, v144
	v_pk_fma_f32 v[154:155], v[34:35], v[152:153], v[154:155] op_sel_hi:[1,0,1]
	v_pk_fma_f32 v[148:149], v[32:33], v[152:153], v[148:149] op_sel_hi:[1,0,1]
	v_and_b32_e32 v144, 0xffff0000, v144
	v_pk_fma_f32 v[152:153], v[30:31], v[144:145], v[154:155] op_sel_hi:[1,0,1]
	v_pk_fma_f32 v[148:149], v[28:29], v[144:145], v[148:149] op_sel_hi:[1,0,1]
	v_lshlrev_b32_e32 v144, 16, v145
	v_pk_fma_f32 v[152:153], v[26:27], v[144:145], v[152:153] op_sel_hi:[1,0,1]
	v_pk_fma_f32 v[148:149], v[24:25], v[144:145], v[148:149] op_sel_hi:[1,0,1]
	v_and_b32_e32 v144, 0xffff0000, v145
	v_pk_fma_f32 v[152:153], v[22:23], v[144:145], v[152:153] op_sel_hi:[1,0,1]
	v_pk_fma_f32 v[144:145], v[20:21], v[144:145], v[148:149] op_sel_hi:[1,0,1]
	v_lshlrev_b32_e32 v148, 16, v146
	v_pk_fma_f32 v[152:153], v[18:19], v[148:149], v[152:153] op_sel_hi:[1,0,1]
	v_pk_fma_f32 v[144:145], v[16:17], v[148:149], v[144:145] op_sel_hi:[1,0,1]
	v_and_b32_e32 v146, 0xffff0000, v146
	v_pk_fma_f32 v[148:149], v[14:15], v[146:147], v[152:153] op_sel_hi:[1,0,1]
	v_pk_fma_f32 v[144:145], v[12:13], v[146:147], v[144:145] op_sel_hi:[1,0,1]
	v_lshlrev_b32_e32 v146, 16, v147
	v_pk_fma_f32 v[148:149], v[10:11], v[146:147], v[148:149] op_sel_hi:[1,0,1]
	v_pk_fma_f32 v[144:145], v[8:9], v[146:147], v[144:145] op_sel_hi:[1,0,1]
	v_and_b32_e32 v146, 0xffff0000, v147
	v_pk_fma_f32 v[144:145], v[4:5], v[146:147], v[144:145] op_sel_hi:[1,0,1]
	v_pk_fma_f32 v[148:149], v[6:7], v[146:147], v[148:149] op_sel_hi:[1,0,1]
	v_min_f32_e32 v146, 0, v144
	v_mul_f32_e64 v144, |v144|, s93
	v_exp_f32_e32 v144, v144
	v_add_co_u32_e32 v154, vcc, s20, v76
	v_add_f32_e32 v144, 1.0, v144
	v_log_f32_e32 v144, v144
	v_addc_co_u32_e32 v155, vcc, 0, v77, vcc
	global_load_dwordx2 v[164:165], v[154:155], off offset:2048
	v_fmac_f32_e32 v146, 0xbf317218, v144
	v_min_f32_e32 v144, 0, v145
	v_mul_f32_e64 v145, |v145|, s93
	v_exp_f32_e32 v145, v145
	v_fmac_f32_e32 v85, 0x3d800000, v146
	global_load_dwordx4 v[154:157], v3, s[0:1] offset:16
	s_add_u32 s0, s6, 0x27400
	v_add_f32_e32 v145, 1.0, v145
	v_log_f32_e32 v145, v145
	s_addc_u32 s1, s7, 0
	v_fmac_f32_e32 v144, 0xbf317218, v145
	v_mul_f32_e64 v145, |v148|, s93
	v_exp_f32_e32 v145, v145
	v_fmac_f32_e32 v91, 0x3d800000, v144
	v_min_f32_e32 v144, 0, v148
	v_add_f32_e32 v145, 1.0, v145
	v_log_f32_e32 v145, v145
	s_nop 0
	v_fmac_f32_e32 v144, 0xbf317218, v145
	v_mul_f32_e64 v145, |v149|, s93
	v_exp_f32_e32 v145, v145
	v_fmac_f32_e32 v163, 0x3d800000, v144
	v_min_f32_e32 v144, 0, v149
	v_add_f32_e32 v145, 1.0, v145
	v_log_f32_e32 v145, v145
	s_nop 0
	v_fmac_f32_e32 v144, 0xbf317218, v145
	v_sub_f32_e32 v145, v131, v91
	v_mul_f32_e32 v145, 0x3fb8aa3b, v145
	v_exp_f32_e32 v146, v145
	v_sub_f32_e32 v145, v128, v163
	v_fmac_f32_e32 v170, 0x3d800000, v144
	v_mul_f32_e32 v145, 0x3fb8aa3b, v145
	v_exp_f32_e32 v148, v145
	v_sub_f32_e32 v145, v129, v170
	v_mul_f32_e32 v145, 0x3fb8aa3b, v145
	v_exp_f32_e32 v152, v145
	v_mov_b32_e32 v145, 0x24000
	global_load_dwordx4 v[158:161], v145, s[6:7] offset:2560
	v_sub_f32_e32 v144, v130, v85
	v_mul_f32_e32 v144, 0x3fb8aa3b, v144
	v_exp_f32_e32 v144, v144
	s_waitcnt vmcnt(0)
	v_lshlrev_b32_e32 v162, 16, v158
	v_pk_fma_f32 v[166:167], v[70:71], v[162:163], v[66:67] op_sel_hi:[1,0,1]
	v_pk_fma_f32 v[168:169], v[68:69], v[162:163], v[64:65] op_sel_hi:[1,0,1]
	v_and_b32_e32 v158, 0xffff0000, v158
	v_pk_fma_f32 v[166:167], v[62:63], v[158:159], v[166:167] op_sel_hi:[1,0,1]
	v_pk_fma_f32 v[168:169], v[60:61], v[158:159], v[168:169] op_sel_hi:[1,0,1]
	v_lshlrev_b32_e32 v158, 16, v159
	v_pk_fma_f32 v[166:167], v[58:59], v[158:159], v[166:167] op_sel_hi:[1,0,1]
	v_pk_fma_f32 v[168:169], v[56:57], v[158:159], v[168:169] op_sel_hi:[1,0,1]
	v_and_b32_e32 v158, 0xffff0000, v159
	v_pk_fma_f32 v[166:167], v[54:55], v[158:159], v[166:167] op_sel_hi:[1,0,1]
	v_pk_fma_f32 v[158:159], v[52:53], v[158:159], v[168:169] op_sel_hi:[1,0,1]
	v_lshlrev_b32_e32 v162, 16, v160
	v_pk_fma_f32 v[166:167], v[50:51], v[162:163], v[166:167] op_sel_hi:[1,0,1]
	v_pk_fma_f32 v[158:159], v[48:49], v[162:163], v[158:159] op_sel_hi:[1,0,1]
	v_and_b32_e32 v160, 0xffff0000, v160
	v_pk_fma_f32 v[166:167], v[46:47], v[160:161], v[166:167] op_sel_hi:[1,0,1]
	v_pk_fma_f32 v[158:159], v[44:45], v[160:161], v[158:159] op_sel_hi:[1,0,1]
	v_lshlrev_b32_e32 v160, 16, v161
	v_pk_fma_f32 v[166:167], v[42:43], v[160:161], v[166:167] op_sel_hi:[1,0,1]
	v_pk_fma_f32 v[158:159], v[40:41], v[160:161], v[158:159] op_sel_hi:[1,0,1]
	v_and_b32_e32 v160, 0xffff0000, v161
	v_pk_fma_f32 v[166:167], v[38:39], v[160:161], v[166:167] op_sel_hi:[1,0,1]
	v_pk_fma_f32 v[158:159], v[36:37], v[160:161], v[158:159] op_sel_hi:[1,0,1]
	v_lshlrev_b32_e32 v160, 16, v154
	v_pk_fma_f32 v[166:167], v[34:35], v[160:161], v[166:167] op_sel_hi:[1,0,1]
	v_pk_fma_f32 v[158:159], v[32:33], v[160:161], v[158:159] op_sel_hi:[1,0,1]
	v_and_b32_e32 v154, 0xffff0000, v154
	v_pk_fma_f32 v[160:161], v[30:31], v[154:155], v[166:167] op_sel_hi:[1,0,1]
	v_pk_fma_f32 v[158:159], v[28:29], v[154:155], v[158:159] op_sel_hi:[1,0,1]
	v_lshlrev_b32_e32 v154, 16, v155
	v_pk_fma_f32 v[160:161], v[26:27], v[154:155], v[160:161] op_sel_hi:[1,0,1]
	v_pk_fma_f32 v[158:159], v[24:25], v[154:155], v[158:159] op_sel_hi:[1,0,1]
	v_and_b32_e32 v154, 0xffff0000, v155
	v_pk_fma_f32 v[160:161], v[22:23], v[154:155], v[160:161] op_sel_hi:[1,0,1]
	v_pk_fma_f32 v[154:155], v[20:21], v[154:155], v[158:159] op_sel_hi:[1,0,1]
	v_lshlrev_b32_e32 v158, 16, v156
	v_pk_fma_f32 v[160:161], v[18:19], v[158:159], v[160:161] op_sel_hi:[1,0,1]
	v_pk_fma_f32 v[154:155], v[16:17], v[158:159], v[154:155] op_sel_hi:[1,0,1]
	v_and_b32_e32 v156, 0xffff0000, v156
	v_pk_fma_f32 v[158:159], v[14:15], v[156:157], v[160:161] op_sel_hi:[1,0,1]
	v_pk_fma_f32 v[154:155], v[12:13], v[156:157], v[154:155] op_sel_hi:[1,0,1]
	v_lshlrev_b32_e32 v156, 16, v157
	v_pk_fma_f32 v[158:159], v[10:11], v[156:157], v[158:159] op_sel_hi:[1,0,1]
	v_pk_fma_f32 v[154:155], v[8:9], v[156:157], v[154:155] op_sel_hi:[1,0,1]
	v_and_b32_e32 v156, 0xffff0000, v157
	v_pk_fma_f32 v[154:155], v[4:5], v[156:157], v[154:155] op_sel_hi:[1,0,1]
	v_pk_fma_f32 v[158:159], v[6:7], v[156:157], v[158:159] op_sel_hi:[1,0,1]
	v_mul_f32_e64 v147, |v154|, s93
	v_exp_f32_e32 v147, v147
	v_min_f32_e32 v145, 0, v154
	v_lshlrev_b32_e32 v154, 16, v150
	v_add_f32_e32 v147, 1.0, v147
	v_log_f32_e32 v147, v147
	s_nop 0
	v_fmac_f32_e32 v145, 0xbf317218, v147
	v_mul_f32_e64 v147, |v155|, s93
	v_exp_f32_e32 v147, v147
	v_fmac_f32_e32 v85, 0x3d800000, v145
	v_min_f32_e32 v145, 0, v155
	v_lshlrev_b32_e32 v155, 16, v164
	v_add_f32_e32 v147, 1.0, v147
	v_log_f32_e32 v147, v147
	s_nop 0
	v_fmac_f32_e32 v145, 0xbf317218, v147
	v_mul_f32_e64 v147, |v158|, s93
	v_exp_f32_e32 v147, v147
	v_fmac_f32_e32 v91, 0x3d800000, v145
	v_min_f32_e32 v145, 0, v158
	v_mov_b32_e32 v158, 0x27000
	v_add_f32_e32 v147, 1.0, v147
	v_log_f32_e32 v147, v147
	s_nop 0
	v_fmac_f32_e32 v145, 0xbf317218, v147
	v_mul_f32_e64 v147, |v159|, s93
	v_exp_f32_e32 v147, v147
	v_fmac_f32_e32 v163, 0x3d800000, v145
	v_min_f32_e32 v145, 0, v159
	global_load_dwordx4 v[158:161], v158, s[6:7] offset:1024
	v_add_f32_e32 v147, 1.0, v147
	v_log_f32_e32 v147, v147
	v_sub_f32_e32 v149, v128, v163
	v_mul_f32_e32 v149, 0x3fb8aa3b, v149
	v_exp_f32_e32 v149, v149
	v_fmac_f32_e32 v145, 0xbf317218, v147
	v_fmac_f32_e32 v170, 0x3d800000, v145
	v_sub_f32_e32 v145, v130, v85
	v_mul_f32_e32 v145, 0x3fb8aa3b, v145
	v_exp_f32_e32 v145, v145
	v_sub_f32_e32 v147, v131, v91
	v_mul_f32_e32 v147, 0x3fb8aa3b, v147
	v_exp_f32_e32 v147, v147
	v_pk_mul_f32 v[144:145], v[144:145], v[154:155]
	v_and_b32_e32 v154, 0xffff0000, v150
	v_sub_f32_e32 v150, v129, v170
	v_mul_f32_e32 v150, 0x3fb8aa3b, v150
	v_exp_f32_e32 v153, v150
	v_and_b32_e32 v155, 0xffff0000, v164
	v_pk_mul_f32 v[146:147], v[146:147], v[154:155]
	v_lshlrev_b32_e32 v155, 16, v165
	v_lshlrev_b32_e32 v154, 16, v151
	v_pk_mul_f32 v[148:149], v[148:149], v[154:155]
	v_and_b32_e32 v155, 0xffff0000, v165
	v_and_b32_e32 v154, 0xffff0000, v151
	v_pk_mul_f32 v[150:151], v[152:153], v[154:155]
	global_load_dwordx4 v[154:157], v3, s[0:1] offset:16
	v_add_co_u32_e32 v152, vcc, s21, v76
	s_mov_b32 s0, 0x27000
	s_nop 0
	v_addc_co_u32_e32 v153, vcc, 0, v77, vcc
	global_load_dwordx2 v[152:153], v[152:153], off offset:512
	s_waitcnt vmcnt(2)
	v_lshlrev_b32_e32 v162, 16, v158
	v_pk_fma_f32 v[164:165], v[70:71], v[162:163], v[66:67] op_sel_hi:[1,0,1]
	v_pk_fma_f32 v[166:167], v[68:69], v[162:163], v[64:65] op_sel_hi:[1,0,1]
	v_and_b32_e32 v158, 0xffff0000, v158
	v_pk_fma_f32 v[164:165], v[62:63], v[158:159], v[164:165] op_sel_hi:[1,0,1]
	v_pk_fma_f32 v[166:167], v[60:61], v[158:159], v[166:167] op_sel_hi:[1,0,1]
	v_lshlrev_b32_e32 v158, 16, v159
	v_pk_fma_f32 v[164:165], v[58:59], v[158:159], v[164:165] op_sel_hi:[1,0,1]
	v_pk_fma_f32 v[166:167], v[56:57], v[158:159], v[166:167] op_sel_hi:[1,0,1]
	v_and_b32_e32 v158, 0xffff0000, v159
	v_pk_fma_f32 v[164:165], v[54:55], v[158:159], v[164:165] op_sel_hi:[1,0,1]
	v_pk_fma_f32 v[158:159], v[52:53], v[158:159], v[166:167] op_sel_hi:[1,0,1]
	v_lshlrev_b32_e32 v162, 16, v160
	v_pk_fma_f32 v[164:165], v[50:51], v[162:163], v[164:165] op_sel_hi:[1,0,1]
	v_pk_fma_f32 v[158:159], v[48:49], v[162:163], v[158:159] op_sel_hi:[1,0,1]
	v_and_b32_e32 v160, 0xffff0000, v160
	v_pk_fma_f32 v[164:165], v[46:47], v[160:161], v[164:165] op_sel_hi:[1,0,1]
	v_pk_fma_f32 v[158:159], v[44:45], v[160:161], v[158:159] op_sel_hi:[1,0,1]
	v_lshlrev_b32_e32 v160, 16, v161
	v_pk_fma_f32 v[164:165], v[42:43], v[160:161], v[164:165] op_sel_hi:[1,0,1]
	v_pk_fma_f32 v[158:159], v[40:41], v[160:161], v[158:159] op_sel_hi:[1,0,1]
	v_and_b32_e32 v160, 0xffff0000, v161
	v_pk_fma_f32 v[164:165], v[38:39], v[160:161], v[164:165] op_sel_hi:[1,0,1]
	v_pk_fma_f32 v[158:159], v[36:37], v[160:161], v[158:159] op_sel_hi:[1,0,1]
	s_waitcnt vmcnt(1)
	v_lshlrev_b32_e32 v160, 16, v154
	v_pk_fma_f32 v[164:165], v[34:35], v[160:161], v[164:165] op_sel_hi:[1,0,1]
	v_pk_fma_f32 v[158:159], v[32:33], v[160:161], v[158:159] op_sel_hi:[1,0,1]
	v_and_b32_e32 v154, 0xffff0000, v154
	v_pk_fma_f32 v[160:161], v[30:31], v[154:155], v[164:165] op_sel_hi:[1,0,1]
	v_pk_fma_f32 v[158:159], v[28:29], v[154:155], v[158:159] op_sel_hi:[1,0,1]
	v_lshlrev_b32_e32 v154, 16, v155
	v_pk_fma_f32 v[160:161], v[26:27], v[154:155], v[160:161] op_sel_hi:[1,0,1]
	v_pk_fma_f32 v[158:159], v[24:25], v[154:155], v[158:159] op_sel_hi:[1,0,1]
	v_and_b32_e32 v154, 0xffff0000, v155
	v_pk_fma_f32 v[160:161], v[22:23], v[154:155], v[160:161] op_sel_hi:[1,0,1]
	v_pk_fma_f32 v[154:155], v[20:21], v[154:155], v[158:159] op_sel_hi:[1,0,1]
	v_lshlrev_b32_e32 v158, 16, v156
	v_pk_fma_f32 v[160:161], v[18:19], v[158:159], v[160:161] op_sel_hi:[1,0,1]
	v_pk_fma_f32 v[154:155], v[16:17], v[158:159], v[154:155] op_sel_hi:[1,0,1]
	v_and_b32_e32 v156, 0xffff0000, v156
	v_pk_fma_f32 v[158:159], v[14:15], v[156:157], v[160:161] op_sel_hi:[1,0,1]
	v_pk_fma_f32 v[154:155], v[12:13], v[156:157], v[154:155] op_sel_hi:[1,0,1]
	v_lshlrev_b32_e32 v156, 16, v157
	v_pk_fma_f32 v[158:159], v[10:11], v[156:157], v[158:159] op_sel_hi:[1,0,1]
	v_pk_fma_f32 v[154:155], v[8:9], v[156:157], v[154:155] op_sel_hi:[1,0,1]
	v_and_b32_e32 v156, 0xffff0000, v157
	v_pk_fma_f32 v[154:155], v[4:5], v[156:157], v[154:155] op_sel_hi:[1,0,1]
	v_pk_fma_f32 v[158:159], v[6:7], v[156:157], v[158:159] op_sel_hi:[1,0,1]
	v_min_f32_e32 v156, 0, v154
	v_mul_f32_e64 v154, |v154|, s93
	v_exp_f32_e32 v154, v154
	v_add_co_u32_e32 v164, vcc, s0, v76
	s_add_u32 s0, s6, 0x29e00
	v_add_f32_e32 v154, 1.0, v154
	v_log_f32_e32 v154, v154
	v_addc_co_u32_e32 v165, vcc, 0, v77, vcc
	s_addc_u32 s1, s7, 0
	v_fmac_f32_e32 v156, 0xbf317218, v154
	v_min_f32_e32 v154, 0, v155
	v_mul_f32_e64 v155, |v155|, s93
	v_exp_f32_e32 v155, v155
	global_load_dwordx2 v[168:169], v[164:165], off offset:3072
	v_fmac_f32_e32 v85, 0x3d800000, v156
	global_load_dwordx4 v[164:167], v3, s[0:1] offset:16
	v_add_f32_e32 v155, 1.0, v155
	v_log_f32_e32 v155, v155
	s_add_u32 s0, s6, 0x2c800
	s_addc_u32 s1, s7, 0
	v_fmac_f32_e32 v154, 0xbf317218, v155
	v_mul_f32_e64 v155, |v158|, s93
	v_exp_f32_e32 v155, v155
	v_fmac_f32_e32 v91, 0x3d800000, v154
	v_min_f32_e32 v154, 0, v158
	v_add_f32_e32 v155, 1.0, v155
	v_log_f32_e32 v155, v155
	s_nop 0
	v_fmac_f32_e32 v154, 0xbf317218, v155
	v_mul_f32_e64 v155, |v159|, s93
	v_exp_f32_e32 v155, v155
	v_fmac_f32_e32 v163, 0x3d800000, v154
	v_min_f32_e32 v154, 0, v159
	v_add_f32_e32 v155, 1.0, v155
	v_log_f32_e32 v155, v155
	s_nop 0
	v_fmac_f32_e32 v154, 0xbf317218, v155
	v_mov_b32_e32 v155, 0x29000
	global_load_dwordx4 v[172:175], v155, s[6:7] offset:3584
	v_fmac_f32_e32 v170, 0x3d800000, v154
	v_sub_f32_e32 v154, v130, v85
	v_mul_f32_e32 v154, 0x3fb8aa3b, v154
	v_exp_f32_e32 v160, v154
	v_sub_f32_e32 v154, v131, v91
	v_mul_f32_e32 v154, 0x3fb8aa3b, v154
	v_exp_f32_e32 v158, v154
	v_sub_f32_e32 v154, v128, v163
	v_mul_f32_e32 v154, 0x3fb8aa3b, v154
	v_exp_f32_e32 v156, v154
	v_sub_f32_e32 v154, v129, v170
	v_mul_f32_e32 v154, 0x3fb8aa3b, v154
	v_exp_f32_e32 v154, v154
	s_waitcnt vmcnt(0)
	v_lshlrev_b32_e32 v162, 16, v172
	v_pk_fma_f32 v[176:177], v[70:71], v[162:163], v[66:67] op_sel_hi:[1,0,1]
	v_pk_fma_f32 v[178:179], v[68:69], v[162:163], v[64:65] op_sel_hi:[1,0,1]
	v_and_b32_e32 v162, 0xffff0000, v172
	v_pk_fma_f32 v[176:177], v[62:63], v[162:163], v[176:177] op_sel_hi:[1,0,1]
	v_pk_fma_f32 v[178:179], v[60:61], v[162:163], v[178:179] op_sel_hi:[1,0,1]
	v_lshlrev_b32_e32 v162, 16, v173
	v_pk_fma_f32 v[176:177], v[58:59], v[162:163], v[176:177] op_sel_hi:[1,0,1]
	v_pk_fma_f32 v[178:179], v[56:57], v[162:163], v[178:179] op_sel_hi:[1,0,1]
	v_and_b32_e32 v162, 0xffff0000, v173
	v_pk_fma_f32 v[172:173], v[54:55], v[162:163], v[176:177] op_sel_hi:[1,0,1]
	v_pk_fma_f32 v[176:177], v[52:53], v[162:163], v[178:179] op_sel_hi:[1,0,1]
	v_lshlrev_b32_e32 v162, 16, v174
	v_pk_fma_f32 v[172:173], v[50:51], v[162:163], v[172:173] op_sel_hi:[1,0,1]
	v_pk_fma_f32 v[176:177], v[48:49], v[162:163], v[176:177] op_sel_hi:[1,0,1]
	v_and_b32_e32 v162, 0xffff0000, v174
	v_pk_fma_f32 v[172:173], v[46:47], v[162:163], v[172:173] op_sel_hi:[1,0,1]
	v_pk_fma_f32 v[176:177], v[44:45], v[162:163], v[176:177] op_sel_hi:[1,0,1]
	v_lshlrev_b32_e32 v162, 16, v175
	v_pk_fma_f32 v[172:173], v[42:43], v[162:163], v[172:173] op_sel_hi:[1,0,1]
	v_pk_fma_f32 v[176:177], v[40:41], v[162:163], v[176:177] op_sel_hi:[1,0,1]
	v_and_b32_e32 v162, 0xffff0000, v175
	v_pk_fma_f32 v[172:173], v[38:39], v[162:163], v[172:173] op_sel_hi:[1,0,1]
	v_pk_fma_f32 v[174:175], v[36:37], v[162:163], v[176:177] op_sel_hi:[1,0,1]
	v_lshlrev_b32_e32 v162, 16, v164
	v_pk_fma_f32 v[172:173], v[34:35], v[162:163], v[172:173] op_sel_hi:[1,0,1]
	v_pk_fma_f32 v[174:175], v[32:33], v[162:163], v[174:175] op_sel_hi:[1,0,1]
	v_and_b32_e32 v162, 0xffff0000, v164
	v_pk_fma_f32 v[172:173], v[30:31], v[162:163], v[172:173] op_sel_hi:[1,0,1]
	v_pk_fma_f32 v[174:175], v[28:29], v[162:163], v[174:175] op_sel_hi:[1,0,1]
	v_lshlrev_b32_e32 v162, 16, v165
	v_pk_fma_f32 v[172:173], v[26:27], v[162:163], v[172:173] op_sel_hi:[1,0,1]
	v_pk_fma_f32 v[174:175], v[24:25], v[162:163], v[174:175] op_sel_hi:[1,0,1]
	v_and_b32_e32 v162, 0xffff0000, v165
	v_pk_fma_f32 v[164:165], v[22:23], v[162:163], v[172:173] op_sel_hi:[1,0,1]
	v_pk_fma_f32 v[172:173], v[20:21], v[162:163], v[174:175] op_sel_hi:[1,0,1]
	v_lshlrev_b32_e32 v162, 16, v166
	v_pk_fma_f32 v[164:165], v[18:19], v[162:163], v[164:165] op_sel_hi:[1,0,1]
	v_pk_fma_f32 v[172:173], v[16:17], v[162:163], v[172:173] op_sel_hi:[1,0,1]
	v_and_b32_e32 v162, 0xffff0000, v166
	v_pk_fma_f32 v[164:165], v[14:15], v[162:163], v[164:165] op_sel_hi:[1,0,1]
	v_pk_fma_f32 v[172:173], v[12:13], v[162:163], v[172:173] op_sel_hi:[1,0,1]
	v_lshlrev_b32_e32 v162, 16, v167
	v_pk_fma_f32 v[164:165], v[10:11], v[162:163], v[164:165] op_sel_hi:[1,0,1]
	v_pk_fma_f32 v[172:173], v[8:9], v[162:163], v[172:173] op_sel_hi:[1,0,1]
	v_and_b32_e32 v162, 0xffff0000, v167
	v_pk_fma_f32 v[166:167], v[4:5], v[162:163], v[172:173] op_sel_hi:[1,0,1]
	v_pk_fma_f32 v[164:165], v[6:7], v[162:163], v[164:165] op_sel_hi:[1,0,1]
	v_mul_f32_e64 v157, |v166|, s93
	v_exp_f32_e32 v157, v157
	v_min_f32_e32 v155, 0, v166
	v_add_f32_e32 v157, 1.0, v157
	v_log_f32_e32 v157, v157
	s_nop 0
	v_fmac_f32_e32 v155, 0xbf317218, v157
	v_mul_f32_e64 v157, |v167|, s93
	v_exp_f32_e32 v157, v157
	v_fmac_f32_e32 v85, 0x3d800000, v155
	v_min_f32_e32 v155, 0, v167
	v_add_f32_e32 v157, 1.0, v157
	v_log_f32_e32 v157, v157
	s_nop 0
	v_fmac_f32_e32 v155, 0xbf317218, v157
	v_mul_f32_e64 v157, |v164|, s93
	v_exp_f32_e32 v157, v157
	v_fmac_f32_e32 v91, 0x3d800000, v155
	v_min_f32_e32 v155, 0, v164
	v_lshlrev_b32_e32 v164, 16, v152
	v_add_f32_e32 v157, 1.0, v157
	v_log_f32_e32 v157, v157
	s_nop 0
	v_fmac_f32_e32 v155, 0xbf317218, v157
	v_mul_f32_e64 v157, |v165|, s93
	v_exp_f32_e32 v157, v157
	v_fmac_f32_e32 v163, 0x3d800000, v155
	v_min_f32_e32 v155, 0, v165
	v_lshlrev_b32_e32 v165, 16, v168
	v_add_f32_e32 v157, 1.0, v157
	v_log_f32_e32 v157, v157
	s_nop 0
	v_fmac_f32_e32 v155, 0xbf317218, v157
	v_fmac_f32_e32 v170, 0x3d800000, v155
	v_sub_f32_e32 v155, v130, v85
	v_mul_f32_e32 v155, 0x3fb8aa3b, v155
	v_exp_f32_e32 v161, v155
	v_sub_f32_e32 v155, v131, v91
	v_mul_f32_e32 v155, 0x3fb8aa3b, v155
	v_exp_f32_e32 v159, v155
	v_pk_mul_f32 v[160:161], v[160:161], v[164:165]
	v_and_b32_e32 v164, 0xffff0000, v152
	v_sub_f32_e32 v152, v128, v163
	v_mul_f32_e32 v152, 0x3fb8aa3b, v152
	v_exp_f32_e32 v157, v152
	v_sub_f32_e32 v152, v129, v170
	v_mul_f32_e32 v152, 0x3fb8aa3b, v152
	v_exp_f32_e32 v155, v152
	v_and_b32_e32 v165, 0xffff0000, v168
	v_pk_mul_f32 v[158:159], v[158:159], v[164:165]
	v_lshlrev_b32_e32 v165, 16, v169
	v_lshlrev_b32_e32 v164, 16, v153
	v_pk_mul_f32 v[156:157], v[156:157], v[164:165]
	v_and_b32_e32 v165, 0xffff0000, v169
	v_and_b32_e32 v164, 0xffff0000, v153
	v_cvt_pk_bf16_f32 v152, v72, v73
	v_cvt_pk_bf16_f32 v72, v74, v75
	v_cvt_pk_bf16_f32 v73, v138, v139
	v_cvt_pk_bf16_f32 v74, v146, v147
	v_cvt_pk_bf16_f32 v75, v158, v159
	v_pk_mul_f32 v[164:165], v[154:155], v[164:165]
	global_store_dwordx4 v[132:133], v[72:75], off offset:528
	v_cvt_pk_bf16_f32 v153, v136, v137
	v_cvt_pk_bf16_f32 v154, v144, v145
	v_cvt_pk_bf16_f32 v72, v78, v79
	v_cvt_pk_bf16_f32 v73, v140, v141
	v_cvt_pk_bf16_f32 v74, v148, v149
	v_cvt_pk_bf16_f32 v75, v156, v157
	v_cvt_pk_bf16_f32 v155, v160, v161
	global_store_dwordx4 v[132:133], v[72:75], off offset:544
	global_store_dwordx4 v[132:133], v[152:155], off offset:512
	v_mov_b32_e32 v78, 0x2c000
	v_cvt_pk_bf16_f32 v72, v134, v135
	v_cvt_pk_bf16_f32 v73, v142, v143
	v_cvt_pk_bf16_f32 v74, v150, v151
	v_cvt_pk_bf16_f32 v75, v164, v165
	global_store_dwordx4 v[132:133], v[72:75], off offset:560
	global_load_dwordx4 v[136:139], v78, s[6:7] offset:2048
	s_waitcnt vmcnt(0)
	v_lshlrev_b32_e32 v78, 16, v136
	v_add_co_u32_e32 v72, vcc, s22, v76
	v_pk_fma_f32 v[140:141], v[70:71], v[78:79], v[66:67] op_sel_hi:[1,0,1]
	s_nop 0
	v_addc_co_u32_e32 v73, vcc, 0, v77, vcc
	global_load_dwordx2 v[134:135], v[72:73], off offset:1536
	v_pk_fma_f32 v[78:79], v[68:69], v[78:79], v[64:65] op_sel_hi:[1,0,1]
	global_load_dwordx4 v[72:75], v3, s[0:1] offset:16
	v_and_b32_e32 v136, 0xffff0000, v136
	v_pk_fma_f32 v[140:141], v[62:63], v[136:137], v[140:141] op_sel_hi:[1,0,1]
	v_pk_fma_f32 v[78:79], v[60:61], v[136:137], v[78:79] op_sel_hi:[1,0,1]
	v_lshlrev_b32_e32 v136, 16, v137
	v_pk_fma_f32 v[140:141], v[58:59], v[136:137], v[140:141] op_sel_hi:[1,0,1]
	v_pk_fma_f32 v[78:79], v[56:57], v[136:137], v[78:79] op_sel_hi:[1,0,1]
	v_and_b32_e32 v136, 0xffff0000, v137
	v_pk_fma_f32 v[140:141], v[54:55], v[136:137], v[140:141] op_sel_hi:[1,0,1]
	v_pk_fma_f32 v[78:79], v[52:53], v[136:137], v[78:79] op_sel_hi:[1,0,1]
	v_lshlrev_b32_e32 v136, 16, v138
	v_pk_fma_f32 v[140:141], v[50:51], v[136:137], v[140:141] op_sel_hi:[1,0,1]
	v_pk_fma_f32 v[78:79], v[48:49], v[136:137], v[78:79] op_sel_hi:[1,0,1]
	v_and_b32_e32 v136, 0xffff0000, v138
	v_pk_fma_f32 v[140:141], v[46:47], v[136:137], v[140:141] op_sel_hi:[1,0,1]
	v_pk_fma_f32 v[78:79], v[44:45], v[136:137], v[78:79] op_sel_hi:[1,0,1]
	v_lshlrev_b32_e32 v136, 16, v139
	v_pk_fma_f32 v[140:141], v[42:43], v[136:137], v[140:141] op_sel_hi:[1,0,1]
	v_pk_fma_f32 v[78:79], v[40:41], v[136:137], v[78:79] op_sel_hi:[1,0,1]
	v_and_b32_e32 v136, 0xffff0000, v139
	v_pk_fma_f32 v[138:139], v[38:39], v[136:137], v[140:141] op_sel_hi:[1,0,1]
	v_pk_fma_f32 v[78:79], v[36:37], v[136:137], v[78:79] op_sel_hi:[1,0,1]
	s_add_u32 s0, s6, 0x2f200
	s_addc_u32 s1, s7, 0
	s_waitcnt vmcnt(0)
	v_lshlrev_b32_e32 v136, 16, v72
	v_pk_fma_f32 v[138:139], v[34:35], v[136:137], v[138:139] op_sel_hi:[1,0,1]
	v_pk_fma_f32 v[78:79], v[32:33], v[136:137], v[78:79] op_sel_hi:[1,0,1]
	v_and_b32_e32 v72, 0xffff0000, v72
	v_pk_fma_f32 v[136:137], v[30:31], v[72:73], v[138:139] op_sel_hi:[1,0,1]
	v_pk_fma_f32 v[78:79], v[28:29], v[72:73], v[78:79] op_sel_hi:[1,0,1]
	v_lshlrev_b32_e32 v72, 16, v73
	v_pk_fma_f32 v[136:137], v[26:27], v[72:73], v[136:137] op_sel_hi:[1,0,1]
	v_pk_fma_f32 v[78:79], v[24:25], v[72:73], v[78:79] op_sel_hi:[1,0,1]
	v_and_b32_e32 v72, 0xffff0000, v73
	v_pk_fma_f32 v[136:137], v[22:23], v[72:73], v[136:137] op_sel_hi:[1,0,1]
	v_pk_fma_f32 v[72:73], v[20:21], v[72:73], v[78:79] op_sel_hi:[1,0,1]
	v_lshlrev_b32_e32 v78, 16, v74
	v_pk_fma_f32 v[136:137], v[18:19], v[78:79], v[136:137] op_sel_hi:[1,0,1]
	v_pk_fma_f32 v[72:73], v[16:17], v[78:79], v[72:73] op_sel_hi:[1,0,1]
	v_and_b32_e32 v74, 0xffff0000, v74
	v_pk_fma_f32 v[78:79], v[14:15], v[74:75], v[136:137] op_sel_hi:[1,0,1]
	v_pk_fma_f32 v[72:73], v[12:13], v[74:75], v[72:73] op_sel_hi:[1,0,1]
	v_lshlrev_b32_e32 v74, 16, v75
	v_pk_fma_f32 v[78:79], v[10:11], v[74:75], v[78:79] op_sel_hi:[1,0,1]
	v_pk_fma_f32 v[72:73], v[8:9], v[74:75], v[72:73] op_sel_hi:[1,0,1]
	v_and_b32_e32 v74, 0xffff0000, v75
	v_pk_fma_f32 v[72:73], v[4:5], v[74:75], v[72:73] op_sel_hi:[1,0,1]
	v_pk_fma_f32 v[78:79], v[6:7], v[74:75], v[78:79] op_sel_hi:[1,0,1]
	v_min_f32_e32 v74, 0, v72
	v_mul_f32_e64 v72, |v72|, s93
	v_exp_f32_e32 v72, v72
	v_add_co_u32_e32 v138, vcc, s23, v76
	v_add_f32_e32 v72, 1.0, v72
	v_log_f32_e32 v72, v72
	v_addc_co_u32_e32 v139, vcc, 0, v77, vcc
	global_load_dwordx2 v[146:147], v[138:139], off
	v_fmac_f32_e32 v74, 0xbf317218, v72
	v_min_f32_e32 v72, 0, v73
	v_mul_f32_e64 v73, |v73|, s93
	v_exp_f32_e32 v73, v73
	v_fmac_f32_e32 v85, 0x3d800000, v74
	global_load_dwordx4 v[138:141], v3, s[0:1] offset:16
	s_mov_b32 s0, 0x2f000
	v_add_f32_e32 v73, 1.0, v73
	v_log_f32_e32 v73, v73
	s_nop 0
	v_fmac_f32_e32 v72, 0xbf317218, v73
	v_mul_f32_e64 v73, |v78|, s93
	v_exp_f32_e32 v73, v73
	v_fmac_f32_e32 v91, 0x3d800000, v72
	v_min_f32_e32 v72, 0, v78
	v_add_f32_e32 v73, 1.0, v73
	v_log_f32_e32 v73, v73
	s_nop 0
	v_fmac_f32_e32 v72, 0xbf317218, v73
	v_mul_f32_e64 v73, |v79|, s93
	v_exp_f32_e32 v73, v73
	v_fmac_f32_e32 v163, 0x3d800000, v72
	v_min_f32_e32 v72, 0, v79
	v_add_f32_e32 v73, 1.0, v73
	v_log_f32_e32 v73, v73
	s_nop 0
	v_fmac_f32_e32 v72, 0xbf317218, v73
	v_sub_f32_e32 v73, v131, v91
	v_mul_f32_e32 v73, 0x3fb8aa3b, v73
	v_exp_f32_e32 v74, v73
	v_sub_f32_e32 v73, v128, v163
	v_fmac_f32_e32 v170, 0x3d800000, v72
	v_mul_f32_e32 v73, 0x3fb8aa3b, v73
	v_exp_f32_e32 v78, v73
	v_sub_f32_e32 v73, v129, v170
	v_mul_f32_e32 v73, 0x3fb8aa3b, v73
	v_exp_f32_e32 v136, v73
	v_mov_b32_e32 v73, 0x2f000
	global_load_dwordx4 v[142:145], v73, s[6:7] offset:512
	v_sub_f32_e32 v72, v130, v85
	v_mul_f32_e32 v72, 0x3fb8aa3b, v72
	v_exp_f32_e32 v72, v72
	s_waitcnt vmcnt(0)
	v_lshlrev_b32_e32 v148, 16, v142
	v_pk_fma_f32 v[150:151], v[70:71], v[148:149], v[66:67] op_sel_hi:[1,0,1]
	v_pk_fma_f32 v[148:149], v[68:69], v[148:149], v[64:65] op_sel_hi:[1,0,1]
	v_and_b32_e32 v142, 0xffff0000, v142
	v_pk_fma_f32 v[150:151], v[62:63], v[142:143], v[150:151] op_sel_hi:[1,0,1]
	v_pk_fma_f32 v[148:149], v[60:61], v[142:143], v[148:149] op_sel_hi:[1,0,1]
	v_lshlrev_b32_e32 v142, 16, v143
	v_pk_fma_f32 v[150:151], v[58:59], v[142:143], v[150:151] op_sel_hi:[1,0,1]
	v_pk_fma_f32 v[148:149], v[56:57], v[142:143], v[148:149] op_sel_hi:[1,0,1]
	v_and_b32_e32 v142, 0xffff0000, v143
	v_pk_fma_f32 v[150:151], v[54:55], v[142:143], v[150:151] op_sel_hi:[1,0,1]
	v_pk_fma_f32 v[142:143], v[52:53], v[142:143], v[148:149] op_sel_hi:[1,0,1]
	v_lshlrev_b32_e32 v148, 16, v144
	v_pk_fma_f32 v[150:151], v[50:51], v[148:149], v[150:151] op_sel_hi:[1,0,1]
	v_pk_fma_f32 v[142:143], v[48:49], v[148:149], v[142:143] op_sel_hi:[1,0,1]
	v_and_b32_e32 v144, 0xffff0000, v144
	v_pk_fma_f32 v[148:149], v[46:47], v[144:145], v[150:151] op_sel_hi:[1,0,1]
	v_pk_fma_f32 v[142:143], v[44:45], v[144:145], v[142:143] op_sel_hi:[1,0,1]
	v_lshlrev_b32_e32 v144, 16, v145
	v_pk_fma_f32 v[148:149], v[42:43], v[144:145], v[148:149] op_sel_hi:[1,0,1]
	v_pk_fma_f32 v[142:143], v[40:41], v[144:145], v[142:143] op_sel_hi:[1,0,1]
	v_and_b32_e32 v144, 0xffff0000, v145
	v_pk_fma_f32 v[148:149], v[38:39], v[144:145], v[148:149] op_sel_hi:[1,0,1]
	v_pk_fma_f32 v[142:143], v[36:37], v[144:145], v[142:143] op_sel_hi:[1,0,1]
	v_lshlrev_b32_e32 v144, 16, v138
	v_pk_fma_f32 v[148:149], v[34:35], v[144:145], v[148:149] op_sel_hi:[1,0,1]
	v_pk_fma_f32 v[142:143], v[32:33], v[144:145], v[142:143] op_sel_hi:[1,0,1]
	v_and_b32_e32 v138, 0xffff0000, v138
	v_pk_fma_f32 v[144:145], v[30:31], v[138:139], v[148:149] op_sel_hi:[1,0,1]
	v_pk_fma_f32 v[142:143], v[28:29], v[138:139], v[142:143] op_sel_hi:[1,0,1]
	v_lshlrev_b32_e32 v138, 16, v139
	v_pk_fma_f32 v[144:145], v[26:27], v[138:139], v[144:145] op_sel_hi:[1,0,1]
	v_pk_fma_f32 v[142:143], v[24:25], v[138:139], v[142:143] op_sel_hi:[1,0,1]
	v_and_b32_e32 v138, 0xffff0000, v139
	v_pk_fma_f32 v[144:145], v[22:23], v[138:139], v[144:145] op_sel_hi:[1,0,1]
	v_pk_fma_f32 v[138:139], v[20:21], v[138:139], v[142:143] op_sel_hi:[1,0,1]
	v_lshlrev_b32_e32 v142, 16, v140
	v_pk_fma_f32 v[144:145], v[18:19], v[142:143], v[144:145] op_sel_hi:[1,0,1]
	v_pk_fma_f32 v[138:139], v[16:17], v[142:143], v[138:139] op_sel_hi:[1,0,1]
	v_and_b32_e32 v140, 0xffff0000, v140
	v_pk_fma_f32 v[142:143], v[14:15], v[140:141], v[144:145] op_sel_hi:[1,0,1]
	v_pk_fma_f32 v[138:139], v[12:13], v[140:141], v[138:139] op_sel_hi:[1,0,1]
	v_lshlrev_b32_e32 v140, 16, v141
	v_pk_fma_f32 v[142:143], v[10:11], v[140:141], v[142:143] op_sel_hi:[1,0,1]
	v_pk_fma_f32 v[138:139], v[8:9], v[140:141], v[138:139] op_sel_hi:[1,0,1]
	v_and_b32_e32 v140, 0xffff0000, v141
	v_pk_fma_f32 v[138:139], v[4:5], v[140:141], v[138:139] op_sel_hi:[1,0,1]
	v_pk_fma_f32 v[142:143], v[6:7], v[140:141], v[142:143] op_sel_hi:[1,0,1]
	v_mul_f32_e64 v75, |v138|, s93
	v_exp_f32_e32 v75, v75
	v_min_f32_e32 v73, 0, v138
	v_lshlrev_b32_e32 v138, 16, v134
	v_mov_b32_e32 v140, 0x31000
	v_add_f32_e32 v75, 1.0, v75
	v_log_f32_e32 v75, v75
	s_nop 0
	v_fmac_f32_e32 v73, 0xbf317218, v75
	v_mul_f32_e64 v75, |v139|, s93
	v_exp_f32_e32 v75, v75
	v_fmac_f32_e32 v85, 0x3d800000, v73
	v_min_f32_e32 v73, 0, v139
	v_lshlrev_b32_e32 v139, 16, v146
	v_add_f32_e32 v75, 1.0, v75
	v_log_f32_e32 v75, v75
	s_nop 0
	v_fmac_f32_e32 v73, 0xbf317218, v75
	v_mul_f32_e64 v75, |v142|, s93
	v_exp_f32_e32 v75, v75
	v_fmac_f32_e32 v91, 0x3d800000, v73
	v_min_f32_e32 v73, 0, v142
	v_add_f32_e32 v75, 1.0, v75
	v_log_f32_e32 v75, v75
	s_nop 0
	v_fmac_f32_e32 v73, 0xbf317218, v75
	v_mul_f32_e64 v75, |v143|, s93
	v_exp_f32_e32 v75, v75
	v_fmac_f32_e32 v163, 0x3d800000, v73
	v_min_f32_e32 v73, 0, v143
	v_sub_f32_e32 v79, v128, v163
	v_add_f32_e32 v75, 1.0, v75
	v_log_f32_e32 v75, v75
	v_mul_f32_e32 v79, 0x3fb8aa3b, v79
	v_exp_f32_e32 v79, v79
	v_fmac_f32_e32 v73, 0xbf317218, v75
	v_fmac_f32_e32 v170, 0x3d800000, v73
	v_sub_f32_e32 v73, v130, v85
	v_mul_f32_e32 v73, 0x3fb8aa3b, v73
	v_sub_f32_e32 v75, v131, v91
	v_exp_f32_e32 v73, v73
	v_mul_f32_e32 v75, 0x3fb8aa3b, v75
	v_exp_f32_e32 v75, v75
	v_pk_mul_f32 v[72:73], v[72:73], v[138:139]
	v_and_b32_e32 v139, 0xffff0000, v146
	v_and_b32_e32 v138, 0xffff0000, v134
	v_pk_mul_f32 v[74:75], v[74:75], v[138:139]
	v_lshlrev_b32_e32 v139, 16, v147
	v_lshlrev_b32_e32 v138, 16, v135
	v_pk_mul_f32 v[78:79], v[78:79], v[138:139]
	v_sub_f32_e32 v134, v129, v170
	v_and_b32_e32 v139, 0xffff0000, v147
	global_load_dwordx4 v[144:147], v140, s[6:7] offset:3072
	v_mul_f32_e32 v134, 0x3fb8aa3b, v134
	v_exp_f32_e32 v137, v134
	v_and_b32_e32 v138, 0xffff0000, v135
	v_pk_mul_f32 v[134:135], v[136:137], v[138:139]
	v_add_co_u32_e32 v136, vcc, s0, v76
	s_add_u32 s0, s6, 0x31c00
	s_nop 0
	v_addc_co_u32_e32 v137, vcc, 0, v77, vcc
	s_addc_u32 s1, s7, 0
	global_load_dwordx2 v[142:143], v[136:137], off offset:2560
	s_waitcnt vmcnt(1)
	v_lshlrev_b32_e32 v140, 16, v144
	global_load_dwordx4 v[136:139], v3, s[0:1] offset:16
	v_pk_fma_f32 v[148:149], v[70:71], v[140:141], v[66:67] op_sel_hi:[1,0,1]
	v_pk_fma_f32 v[140:141], v[68:69], v[140:141], v[64:65] op_sel_hi:[1,0,1]
	v_and_b32_e32 v144, 0xffff0000, v144
	v_pk_fma_f32 v[148:149], v[62:63], v[144:145], v[148:149] op_sel_hi:[1,0,1]
	v_pk_fma_f32 v[140:141], v[60:61], v[144:145], v[140:141] op_sel_hi:[1,0,1]
	v_lshlrev_b32_e32 v144, 16, v145
	v_pk_fma_f32 v[148:149], v[58:59], v[144:145], v[148:149] op_sel_hi:[1,0,1]
	v_pk_fma_f32 v[140:141], v[56:57], v[144:145], v[140:141] op_sel_hi:[1,0,1]
	v_and_b32_e32 v144, 0xffff0000, v145
	v_pk_fma_f32 v[148:149], v[54:55], v[144:145], v[148:149] op_sel_hi:[1,0,1]
	v_pk_fma_f32 v[140:141], v[52:53], v[144:145], v[140:141] op_sel_hi:[1,0,1]
	v_lshlrev_b32_e32 v144, 16, v146
	v_pk_fma_f32 v[148:149], v[50:51], v[144:145], v[148:149] op_sel_hi:[1,0,1]
	v_pk_fma_f32 v[140:141], v[48:49], v[144:145], v[140:141] op_sel_hi:[1,0,1]
	v_and_b32_e32 v144, 0xffff0000, v146
	v_pk_fma_f32 v[148:149], v[46:47], v[144:145], v[148:149] op_sel_hi:[1,0,1]
	v_pk_fma_f32 v[140:141], v[44:45], v[144:145], v[140:141] op_sel_hi:[1,0,1]
	v_lshlrev_b32_e32 v144, 16, v147
	v_pk_fma_f32 v[148:149], v[42:43], v[144:145], v[148:149] op_sel_hi:[1,0,1]
	v_pk_fma_f32 v[140:141], v[40:41], v[144:145], v[140:141] op_sel_hi:[1,0,1]
	v_and_b32_e32 v144, 0xffff0000, v147
	v_pk_fma_f32 v[146:147], v[38:39], v[144:145], v[148:149] op_sel_hi:[1,0,1]
	v_pk_fma_f32 v[140:141], v[36:37], v[144:145], v[140:141] op_sel_hi:[1,0,1]
	s_add_u32 s0, s6, 0x34600
	s_addc_u32 s1, s7, 0
	s_waitcnt vmcnt(0)
	v_lshlrev_b32_e32 v144, 16, v136
	v_pk_fma_f32 v[146:147], v[34:35], v[144:145], v[146:147] op_sel_hi:[1,0,1]
	v_pk_fma_f32 v[140:141], v[32:33], v[144:145], v[140:141] op_sel_hi:[1,0,1]
	v_and_b32_e32 v136, 0xffff0000, v136
	v_pk_fma_f32 v[144:145], v[30:31], v[136:137], v[146:147] op_sel_hi:[1,0,1]
	v_pk_fma_f32 v[140:141], v[28:29], v[136:137], v[140:141] op_sel_hi:[1,0,1]
	v_lshlrev_b32_e32 v136, 16, v137
	v_pk_fma_f32 v[144:145], v[26:27], v[136:137], v[144:145] op_sel_hi:[1,0,1]
	v_pk_fma_f32 v[140:141], v[24:25], v[136:137], v[140:141] op_sel_hi:[1,0,1]
	v_and_b32_e32 v136, 0xffff0000, v137
	v_pk_fma_f32 v[144:145], v[22:23], v[136:137], v[144:145] op_sel_hi:[1,0,1]
	v_pk_fma_f32 v[136:137], v[20:21], v[136:137], v[140:141] op_sel_hi:[1,0,1]
	v_lshlrev_b32_e32 v140, 16, v138
	v_pk_fma_f32 v[144:145], v[18:19], v[140:141], v[144:145] op_sel_hi:[1,0,1]
	v_pk_fma_f32 v[136:137], v[16:17], v[140:141], v[136:137] op_sel_hi:[1,0,1]
	v_and_b32_e32 v138, 0xffff0000, v138
	v_pk_fma_f32 v[140:141], v[14:15], v[138:139], v[144:145] op_sel_hi:[1,0,1]
	v_pk_fma_f32 v[136:137], v[12:13], v[138:139], v[136:137] op_sel_hi:[1,0,1]
	v_lshlrev_b32_e32 v138, 16, v139
	v_pk_fma_f32 v[140:141], v[10:11], v[138:139], v[140:141] op_sel_hi:[1,0,1]
	v_pk_fma_f32 v[136:137], v[8:9], v[138:139], v[136:137] op_sel_hi:[1,0,1]
	v_and_b32_e32 v138, 0xffff0000, v139
	v_pk_fma_f32 v[136:137], v[4:5], v[138:139], v[136:137] op_sel_hi:[1,0,1]
	v_pk_fma_f32 v[140:141], v[6:7], v[138:139], v[140:141] op_sel_hi:[1,0,1]
	v_min_f32_e32 v138, 0, v136
	v_mul_f32_e64 v136, |v136|, s93
	v_exp_f32_e32 v136, v136
	v_add_co_u32_e32 v146, vcc, s24, v76
	v_add_f32_e32 v136, 1.0, v136
	v_log_f32_e32 v136, v136
	v_addc_co_u32_e32 v147, vcc, 0, v77, vcc
	global_load_dwordx2 v[154:155], v[146:147], off offset:1024
	v_fmac_f32_e32 v138, 0xbf317218, v136
	v_min_f32_e32 v136, 0, v137
	v_mul_f32_e64 v137, |v137|, s93
	v_exp_f32_e32 v137, v137
	v_fmac_f32_e32 v85, 0x3d800000, v138
	global_load_dwordx4 v[146:149], v3, s[0:1] offset:16
	s_mov_b32 s0, 0x34000
	v_add_f32_e32 v137, 1.0, v137
	v_log_f32_e32 v137, v137
	s_nop 0
	v_fmac_f32_e32 v136, 0xbf317218, v137
	v_mul_f32_e64 v137, |v140|, s93
	v_exp_f32_e32 v137, v137
	v_fmac_f32_e32 v91, 0x3d800000, v136
	v_min_f32_e32 v136, 0, v140
	v_add_f32_e32 v137, 1.0, v137
	v_log_f32_e32 v137, v137
	s_nop 0
	v_fmac_f32_e32 v136, 0xbf317218, v137
	v_mul_f32_e64 v137, |v141|, s93
	v_exp_f32_e32 v137, v137
	v_fmac_f32_e32 v163, 0x3d800000, v136
	v_min_f32_e32 v136, 0, v141
	v_add_f32_e32 v137, 1.0, v137
	v_log_f32_e32 v137, v137
	s_nop 0
	v_fmac_f32_e32 v136, 0xbf317218, v137
	v_sub_f32_e32 v137, v131, v91
	v_mul_f32_e32 v137, 0x3fb8aa3b, v137
	v_exp_f32_e32 v138, v137
	v_sub_f32_e32 v137, v128, v163
	v_fmac_f32_e32 v170, 0x3d800000, v136
	v_mul_f32_e32 v137, 0x3fb8aa3b, v137
	v_exp_f32_e32 v140, v137
	v_sub_f32_e32 v137, v129, v170
	v_mul_f32_e32 v137, 0x3fb8aa3b, v137
	v_exp_f32_e32 v144, v137
	v_mov_b32_e32 v137, 0x34000
	global_load_dwordx4 v[150:153], v137, s[6:7] offset:1536
	v_sub_f32_e32 v136, v130, v85
	v_mul_f32_e32 v136, 0x3fb8aa3b, v136
	v_exp_f32_e32 v136, v136
	s_waitcnt vmcnt(0)
	v_lshlrev_b32_e32 v156, 16, v150
	v_pk_fma_f32 v[158:159], v[70:71], v[156:157], v[66:67] op_sel_hi:[1,0,1]
	v_pk_fma_f32 v[156:157], v[68:69], v[156:157], v[64:65] op_sel_hi:[1,0,1]
	v_and_b32_e32 v150, 0xffff0000, v150
	v_pk_fma_f32 v[158:159], v[62:63], v[150:151], v[158:159] op_sel_hi:[1,0,1]
	v_pk_fma_f32 v[156:157], v[60:61], v[150:151], v[156:157] op_sel_hi:[1,0,1]
	v_lshlrev_b32_e32 v150, 16, v151
	v_pk_fma_f32 v[158:159], v[58:59], v[150:151], v[158:159] op_sel_hi:[1,0,1]
	v_pk_fma_f32 v[156:157], v[56:57], v[150:151], v[156:157] op_sel_hi:[1,0,1]
	v_and_b32_e32 v150, 0xffff0000, v151
	v_pk_fma_f32 v[158:159], v[54:55], v[150:151], v[158:159] op_sel_hi:[1,0,1]
	v_pk_fma_f32 v[150:151], v[52:53], v[150:151], v[156:157] op_sel_hi:[1,0,1]
	v_lshlrev_b32_e32 v156, 16, v152
	v_pk_fma_f32 v[158:159], v[50:51], v[156:157], v[158:159] op_sel_hi:[1,0,1]
	v_pk_fma_f32 v[150:151], v[48:49], v[156:157], v[150:151] op_sel_hi:[1,0,1]
	v_and_b32_e32 v152, 0xffff0000, v152
	v_pk_fma_f32 v[156:157], v[46:47], v[152:153], v[158:159] op_sel_hi:[1,0,1]
	v_pk_fma_f32 v[150:151], v[44:45], v[152:153], v[150:151] op_sel_hi:[1,0,1]
	v_lshlrev_b32_e32 v152, 16, v153
	v_pk_fma_f32 v[156:157], v[42:43], v[152:153], v[156:157] op_sel_hi:[1,0,1]
	v_pk_fma_f32 v[150:151], v[40:41], v[152:153], v[150:151] op_sel_hi:[1,0,1]
	v_and_b32_e32 v152, 0xffff0000, v153
	v_pk_fma_f32 v[156:157], v[38:39], v[152:153], v[156:157] op_sel_hi:[1,0,1]
	v_pk_fma_f32 v[150:151], v[36:37], v[152:153], v[150:151] op_sel_hi:[1,0,1]
	v_lshlrev_b32_e32 v152, 16, v146
	v_pk_fma_f32 v[156:157], v[34:35], v[152:153], v[156:157] op_sel_hi:[1,0,1]
	v_pk_fma_f32 v[150:151], v[32:33], v[152:153], v[150:151] op_sel_hi:[1,0,1]
	v_and_b32_e32 v146, 0xffff0000, v146
	v_pk_fma_f32 v[152:153], v[30:31], v[146:147], v[156:157] op_sel_hi:[1,0,1]
	v_pk_fma_f32 v[150:151], v[28:29], v[146:147], v[150:151] op_sel_hi:[1,0,1]
	v_lshlrev_b32_e32 v146, 16, v147
	v_pk_fma_f32 v[152:153], v[26:27], v[146:147], v[152:153] op_sel_hi:[1,0,1]
	v_pk_fma_f32 v[150:151], v[24:25], v[146:147], v[150:151] op_sel_hi:[1,0,1]
	v_and_b32_e32 v146, 0xffff0000, v147
	v_pk_fma_f32 v[152:153], v[22:23], v[146:147], v[152:153] op_sel_hi:[1,0,1]
	v_pk_fma_f32 v[146:147], v[20:21], v[146:147], v[150:151] op_sel_hi:[1,0,1]
	v_lshlrev_b32_e32 v150, 16, v148
	v_pk_fma_f32 v[152:153], v[18:19], v[150:151], v[152:153] op_sel_hi:[1,0,1]
	v_pk_fma_f32 v[146:147], v[16:17], v[150:151], v[146:147] op_sel_hi:[1,0,1]
	v_and_b32_e32 v148, 0xffff0000, v148
	v_pk_fma_f32 v[150:151], v[14:15], v[148:149], v[152:153] op_sel_hi:[1,0,1]
	v_pk_fma_f32 v[146:147], v[12:13], v[148:149], v[146:147] op_sel_hi:[1,0,1]
	v_lshlrev_b32_e32 v148, 16, v149
	v_pk_fma_f32 v[150:151], v[10:11], v[148:149], v[150:151] op_sel_hi:[1,0,1]
	v_pk_fma_f32 v[146:147], v[8:9], v[148:149], v[146:147] op_sel_hi:[1,0,1]
	v_and_b32_e32 v148, 0xffff0000, v149
	v_pk_fma_f32 v[146:147], v[4:5], v[148:149], v[146:147] op_sel_hi:[1,0,1]
	v_pk_fma_f32 v[150:151], v[6:7], v[148:149], v[150:151] op_sel_hi:[1,0,1]
	v_mul_f32_e64 v139, |v146|, s93
	v_exp_f32_e32 v139, v139
	v_min_f32_e32 v137, 0, v146
	v_lshlrev_b32_e32 v146, 16, v142
	v_mov_b32_e32 v148, 0x37000
	v_add_f32_e32 v139, 1.0, v139
	v_log_f32_e32 v139, v139
	s_nop 0
	v_fmac_f32_e32 v137, 0xbf317218, v139
	v_mul_f32_e64 v139, |v147|, s93
	v_exp_f32_e32 v139, v139
	v_fmac_f32_e32 v85, 0x3d800000, v137
	v_min_f32_e32 v137, 0, v147
	v_lshlrev_b32_e32 v147, 16, v154
	v_add_f32_e32 v139, 1.0, v139
	v_log_f32_e32 v139, v139
	s_nop 0
	v_fmac_f32_e32 v137, 0xbf317218, v139
	v_mul_f32_e64 v139, |v150|, s93
	v_exp_f32_e32 v139, v139
	v_fmac_f32_e32 v91, 0x3d800000, v137
	v_min_f32_e32 v137, 0, v150
	v_add_f32_e32 v139, 1.0, v139
	v_log_f32_e32 v139, v139
	s_nop 0
	v_fmac_f32_e32 v137, 0xbf317218, v139
	v_mul_f32_e64 v139, |v151|, s93
	v_exp_f32_e32 v139, v139
	v_fmac_f32_e32 v163, 0x3d800000, v137
	v_min_f32_e32 v137, 0, v151
	v_sub_f32_e32 v141, v128, v163
	v_add_f32_e32 v139, 1.0, v139
	v_log_f32_e32 v139, v139
	v_mul_f32_e32 v141, 0x3fb8aa3b, v141
	v_exp_f32_e32 v141, v141
	v_fmac_f32_e32 v137, 0xbf317218, v139
	v_fmac_f32_e32 v170, 0x3d800000, v137
	v_sub_f32_e32 v137, v130, v85
	v_mul_f32_e32 v137, 0x3fb8aa3b, v137
	v_sub_f32_e32 v139, v131, v91
	v_exp_f32_e32 v137, v137
	v_mul_f32_e32 v139, 0x3fb8aa3b, v139
	v_exp_f32_e32 v139, v139
	v_pk_mul_f32 v[136:137], v[136:137], v[146:147]
	v_and_b32_e32 v147, 0xffff0000, v154
	v_and_b32_e32 v146, 0xffff0000, v142
	v_pk_mul_f32 v[138:139], v[138:139], v[146:147]
	v_lshlrev_b32_e32 v147, 16, v155
	v_lshlrev_b32_e32 v146, 16, v143
	v_pk_mul_f32 v[140:141], v[140:141], v[146:147]
	v_sub_f32_e32 v142, v129, v170
	v_and_b32_e32 v147, 0xffff0000, v155
	global_load_dwordx4 v[152:155], v148, s[6:7]
	v_mul_f32_e32 v142, 0x3fb8aa3b, v142
	v_exp_f32_e32 v145, v142
	v_and_b32_e32 v146, 0xffff0000, v143
	v_pk_mul_f32 v[142:143], v[144:145], v[146:147]
	v_add_co_u32_e32 v144, vcc, s0, v76
	s_add_u32 s0, s6, 0x37000
	s_nop 0
	v_addc_co_u32_e32 v145, vcc, 0, v77, vcc
	s_addc_u32 s1, s7, 0
	global_load_dwordx2 v[150:151], v[144:145], off offset:3584
	s_waitcnt vmcnt(1)
	v_lshlrev_b32_e32 v148, 16, v152
	global_load_dwordx4 v[144:147], v3, s[0:1] offset:16
	v_pk_fma_f32 v[156:157], v[70:71], v[148:149], v[66:67] op_sel_hi:[1,0,1]
	v_pk_fma_f32 v[148:149], v[68:69], v[148:149], v[64:65] op_sel_hi:[1,0,1]
	v_and_b32_e32 v152, 0xffff0000, v152
	v_pk_fma_f32 v[156:157], v[62:63], v[152:153], v[156:157] op_sel_hi:[1,0,1]
	v_pk_fma_f32 v[148:149], v[60:61], v[152:153], v[148:149] op_sel_hi:[1,0,1]
	v_lshlrev_b32_e32 v152, 16, v153
	v_pk_fma_f32 v[156:157], v[58:59], v[152:153], v[156:157] op_sel_hi:[1,0,1]
	v_pk_fma_f32 v[148:149], v[56:57], v[152:153], v[148:149] op_sel_hi:[1,0,1]
	v_and_b32_e32 v152, 0xffff0000, v153
	v_pk_fma_f32 v[156:157], v[54:55], v[152:153], v[156:157] op_sel_hi:[1,0,1]
	v_pk_fma_f32 v[148:149], v[52:53], v[152:153], v[148:149] op_sel_hi:[1,0,1]
	v_lshlrev_b32_e32 v152, 16, v154
	v_pk_fma_f32 v[156:157], v[50:51], v[152:153], v[156:157] op_sel_hi:[1,0,1]
	v_pk_fma_f32 v[148:149], v[48:49], v[152:153], v[148:149] op_sel_hi:[1,0,1]
	v_and_b32_e32 v152, 0xffff0000, v154
	v_pk_fma_f32 v[156:157], v[46:47], v[152:153], v[156:157] op_sel_hi:[1,0,1]
	v_pk_fma_f32 v[148:149], v[44:45], v[152:153], v[148:149] op_sel_hi:[1,0,1]
	v_lshlrev_b32_e32 v152, 16, v155
	v_pk_fma_f32 v[156:157], v[42:43], v[152:153], v[156:157] op_sel_hi:[1,0,1]
	v_pk_fma_f32 v[148:149], v[40:41], v[152:153], v[148:149] op_sel_hi:[1,0,1]
	v_and_b32_e32 v152, 0xffff0000, v155
	v_pk_fma_f32 v[154:155], v[38:39], v[152:153], v[156:157] op_sel_hi:[1,0,1]
	v_pk_fma_f32 v[148:149], v[36:37], v[152:153], v[148:149] op_sel_hi:[1,0,1]
	s_add_u32 s0, s6, 0x39a00
	s_addc_u32 s1, s7, 0
	s_waitcnt vmcnt(0)
	v_lshlrev_b32_e32 v152, 16, v144
	v_pk_fma_f32 v[154:155], v[34:35], v[152:153], v[154:155] op_sel_hi:[1,0,1]
	v_pk_fma_f32 v[148:149], v[32:33], v[152:153], v[148:149] op_sel_hi:[1,0,1]
	v_and_b32_e32 v144, 0xffff0000, v144
	v_pk_fma_f32 v[152:153], v[30:31], v[144:145], v[154:155] op_sel_hi:[1,0,1]
	v_pk_fma_f32 v[148:149], v[28:29], v[144:145], v[148:149] op_sel_hi:[1,0,1]
	v_lshlrev_b32_e32 v144, 16, v145
	v_pk_fma_f32 v[152:153], v[26:27], v[144:145], v[152:153] op_sel_hi:[1,0,1]
	v_pk_fma_f32 v[148:149], v[24:25], v[144:145], v[148:149] op_sel_hi:[1,0,1]
	v_and_b32_e32 v144, 0xffff0000, v145
	v_pk_fma_f32 v[152:153], v[22:23], v[144:145], v[152:153] op_sel_hi:[1,0,1]
	v_pk_fma_f32 v[144:145], v[20:21], v[144:145], v[148:149] op_sel_hi:[1,0,1]
	v_lshlrev_b32_e32 v148, 16, v146
	v_pk_fma_f32 v[152:153], v[18:19], v[148:149], v[152:153] op_sel_hi:[1,0,1]
	v_pk_fma_f32 v[144:145], v[16:17], v[148:149], v[144:145] op_sel_hi:[1,0,1]
	v_and_b32_e32 v146, 0xffff0000, v146
	v_pk_fma_f32 v[148:149], v[14:15], v[146:147], v[152:153] op_sel_hi:[1,0,1]
	v_pk_fma_f32 v[144:145], v[12:13], v[146:147], v[144:145] op_sel_hi:[1,0,1]
	v_lshlrev_b32_e32 v146, 16, v147
	v_pk_fma_f32 v[148:149], v[10:11], v[146:147], v[148:149] op_sel_hi:[1,0,1]
	v_pk_fma_f32 v[144:145], v[8:9], v[146:147], v[144:145] op_sel_hi:[1,0,1]
	v_and_b32_e32 v146, 0xffff0000, v147
	v_pk_fma_f32 v[144:145], v[4:5], v[146:147], v[144:145] op_sel_hi:[1,0,1]
	v_pk_fma_f32 v[148:149], v[6:7], v[146:147], v[148:149] op_sel_hi:[1,0,1]
	v_min_f32_e32 v146, 0, v144
	v_mul_f32_e64 v144, |v144|, s93
	v_exp_f32_e32 v144, v144
	v_add_co_u32_e32 v154, vcc, s25, v76
	v_add_f32_e32 v144, 1.0, v144
	v_log_f32_e32 v144, v144
	v_addc_co_u32_e32 v155, vcc, 0, v77, vcc
	global_load_dwordx2 v[164:165], v[154:155], off offset:2048
	v_fmac_f32_e32 v146, 0xbf317218, v144
	v_min_f32_e32 v144, 0, v145
	v_mul_f32_e64 v145, |v145|, s93
	v_exp_f32_e32 v145, v145
	v_fmac_f32_e32 v85, 0x3d800000, v146
	global_load_dwordx4 v[154:157], v3, s[0:1] offset:16
	s_add_u32 s0, s6, 0x3c400
	v_add_f32_e32 v145, 1.0, v145
	v_log_f32_e32 v145, v145
	s_addc_u32 s1, s7, 0
	v_fmac_f32_e32 v144, 0xbf317218, v145
	v_mul_f32_e64 v145, |v148|, s93
	v_exp_f32_e32 v145, v145
	v_fmac_f32_e32 v91, 0x3d800000, v144
	v_min_f32_e32 v144, 0, v148
	v_add_f32_e32 v145, 1.0, v145
	v_log_f32_e32 v145, v145
	s_nop 0
	v_fmac_f32_e32 v144, 0xbf317218, v145
	v_mul_f32_e64 v145, |v149|, s93
	v_exp_f32_e32 v145, v145
	v_fmac_f32_e32 v163, 0x3d800000, v144
	v_min_f32_e32 v144, 0, v149
	v_add_f32_e32 v145, 1.0, v145
	v_log_f32_e32 v145, v145
	s_nop 0
	v_fmac_f32_e32 v144, 0xbf317218, v145
	v_sub_f32_e32 v145, v131, v91
	v_mul_f32_e32 v145, 0x3fb8aa3b, v145
	v_exp_f32_e32 v146, v145
	v_sub_f32_e32 v145, v128, v163
	v_fmac_f32_e32 v170, 0x3d800000, v144
	v_mul_f32_e32 v145, 0x3fb8aa3b, v145
	v_exp_f32_e32 v148, v145
	v_sub_f32_e32 v145, v129, v170
	v_mul_f32_e32 v145, 0x3fb8aa3b, v145
	v_exp_f32_e32 v152, v145
	v_mov_b32_e32 v145, 0x39000
	global_load_dwordx4 v[158:161], v145, s[6:7] offset:2560
	v_sub_f32_e32 v144, v130, v85
	v_mul_f32_e32 v144, 0x3fb8aa3b, v144
	v_exp_f32_e32 v144, v144
	s_waitcnt vmcnt(0)
	v_lshlrev_b32_e32 v162, 16, v158
	v_pk_fma_f32 v[166:167], v[70:71], v[162:163], v[66:67] op_sel_hi:[1,0,1]
	v_pk_fma_f32 v[168:169], v[68:69], v[162:163], v[64:65] op_sel_hi:[1,0,1]
	v_and_b32_e32 v158, 0xffff0000, v158
	v_pk_fma_f32 v[166:167], v[62:63], v[158:159], v[166:167] op_sel_hi:[1,0,1]
	v_pk_fma_f32 v[168:169], v[60:61], v[158:159], v[168:169] op_sel_hi:[1,0,1]
	v_lshlrev_b32_e32 v158, 16, v159
	v_pk_fma_f32 v[166:167], v[58:59], v[158:159], v[166:167] op_sel_hi:[1,0,1]
	v_pk_fma_f32 v[168:169], v[56:57], v[158:159], v[168:169] op_sel_hi:[1,0,1]
	v_and_b32_e32 v158, 0xffff0000, v159
	v_pk_fma_f32 v[166:167], v[54:55], v[158:159], v[166:167] op_sel_hi:[1,0,1]
	v_pk_fma_f32 v[158:159], v[52:53], v[158:159], v[168:169] op_sel_hi:[1,0,1]
	v_lshlrev_b32_e32 v162, 16, v160
	v_pk_fma_f32 v[166:167], v[50:51], v[162:163], v[166:167] op_sel_hi:[1,0,1]
	v_pk_fma_f32 v[158:159], v[48:49], v[162:163], v[158:159] op_sel_hi:[1,0,1]
	v_and_b32_e32 v160, 0xffff0000, v160
	v_pk_fma_f32 v[166:167], v[46:47], v[160:161], v[166:167] op_sel_hi:[1,0,1]
	v_pk_fma_f32 v[158:159], v[44:45], v[160:161], v[158:159] op_sel_hi:[1,0,1]
	v_lshlrev_b32_e32 v160, 16, v161
	v_pk_fma_f32 v[166:167], v[42:43], v[160:161], v[166:167] op_sel_hi:[1,0,1]
	v_pk_fma_f32 v[158:159], v[40:41], v[160:161], v[158:159] op_sel_hi:[1,0,1]
	v_and_b32_e32 v160, 0xffff0000, v161
	v_pk_fma_f32 v[166:167], v[38:39], v[160:161], v[166:167] op_sel_hi:[1,0,1]
	v_pk_fma_f32 v[158:159], v[36:37], v[160:161], v[158:159] op_sel_hi:[1,0,1]
	v_lshlrev_b32_e32 v160, 16, v154
	v_pk_fma_f32 v[166:167], v[34:35], v[160:161], v[166:167] op_sel_hi:[1,0,1]
	v_pk_fma_f32 v[158:159], v[32:33], v[160:161], v[158:159] op_sel_hi:[1,0,1]
	v_and_b32_e32 v154, 0xffff0000, v154
	v_pk_fma_f32 v[160:161], v[30:31], v[154:155], v[166:167] op_sel_hi:[1,0,1]
	v_pk_fma_f32 v[158:159], v[28:29], v[154:155], v[158:159] op_sel_hi:[1,0,1]
	v_lshlrev_b32_e32 v154, 16, v155
	v_pk_fma_f32 v[160:161], v[26:27], v[154:155], v[160:161] op_sel_hi:[1,0,1]
	v_pk_fma_f32 v[158:159], v[24:25], v[154:155], v[158:159] op_sel_hi:[1,0,1]
	v_and_b32_e32 v154, 0xffff0000, v155
	v_pk_fma_f32 v[160:161], v[22:23], v[154:155], v[160:161] op_sel_hi:[1,0,1]
	v_pk_fma_f32 v[154:155], v[20:21], v[154:155], v[158:159] op_sel_hi:[1,0,1]
	v_lshlrev_b32_e32 v158, 16, v156
	v_pk_fma_f32 v[160:161], v[18:19], v[158:159], v[160:161] op_sel_hi:[1,0,1]
	v_pk_fma_f32 v[154:155], v[16:17], v[158:159], v[154:155] op_sel_hi:[1,0,1]
	v_and_b32_e32 v156, 0xffff0000, v156
	v_pk_fma_f32 v[158:159], v[14:15], v[156:157], v[160:161] op_sel_hi:[1,0,1]
	v_pk_fma_f32 v[154:155], v[12:13], v[156:157], v[154:155] op_sel_hi:[1,0,1]
	v_lshlrev_b32_e32 v156, 16, v157
	v_pk_fma_f32 v[158:159], v[10:11], v[156:157], v[158:159] op_sel_hi:[1,0,1]
	v_pk_fma_f32 v[154:155], v[8:9], v[156:157], v[154:155] op_sel_hi:[1,0,1]
	v_and_b32_e32 v156, 0xffff0000, v157
	v_pk_fma_f32 v[154:155], v[4:5], v[156:157], v[154:155] op_sel_hi:[1,0,1]
	v_pk_fma_f32 v[158:159], v[6:7], v[156:157], v[158:159] op_sel_hi:[1,0,1]
	v_mul_f32_e64 v147, |v154|, s93
	v_exp_f32_e32 v147, v147
	v_min_f32_e32 v145, 0, v154
	v_lshlrev_b32_e32 v154, 16, v150
	v_add_f32_e32 v147, 1.0, v147
	v_log_f32_e32 v147, v147
	s_nop 0
	v_fmac_f32_e32 v145, 0xbf317218, v147
	v_mul_f32_e64 v147, |v155|, s93
	v_exp_f32_e32 v147, v147
	v_fmac_f32_e32 v85, 0x3d800000, v145
	v_min_f32_e32 v145, 0, v155
	v_lshlrev_b32_e32 v155, 16, v164
	v_add_f32_e32 v147, 1.0, v147
	v_log_f32_e32 v147, v147
	s_nop 0
	v_fmac_f32_e32 v145, 0xbf317218, v147
	v_mul_f32_e64 v147, |v158|, s93
	v_exp_f32_e32 v147, v147
	v_fmac_f32_e32 v91, 0x3d800000, v145
	v_min_f32_e32 v145, 0, v158
	v_mov_b32_e32 v158, 0x3c000
	v_add_f32_e32 v147, 1.0, v147
	v_log_f32_e32 v147, v147
	s_nop 0
	v_fmac_f32_e32 v145, 0xbf317218, v147
	v_mul_f32_e64 v147, |v159|, s93
	v_exp_f32_e32 v147, v147
	v_fmac_f32_e32 v163, 0x3d800000, v145
	v_min_f32_e32 v145, 0, v159
	global_load_dwordx4 v[158:161], v158, s[6:7] offset:1024
	v_add_f32_e32 v147, 1.0, v147
	v_log_f32_e32 v147, v147
	v_sub_f32_e32 v149, v128, v163
	v_mul_f32_e32 v149, 0x3fb8aa3b, v149
	v_exp_f32_e32 v149, v149
	v_fmac_f32_e32 v145, 0xbf317218, v147
	v_fmac_f32_e32 v170, 0x3d800000, v145
	v_sub_f32_e32 v145, v130, v85
	v_mul_f32_e32 v145, 0x3fb8aa3b, v145
	v_exp_f32_e32 v145, v145
	v_sub_f32_e32 v147, v131, v91
	v_mul_f32_e32 v147, 0x3fb8aa3b, v147
	v_exp_f32_e32 v147, v147
	v_pk_mul_f32 v[144:145], v[144:145], v[154:155]
	v_and_b32_e32 v154, 0xffff0000, v150
	v_sub_f32_e32 v150, v129, v170
	v_mul_f32_e32 v150, 0x3fb8aa3b, v150
	v_exp_f32_e32 v153, v150
	v_and_b32_e32 v155, 0xffff0000, v164
	v_pk_mul_f32 v[146:147], v[146:147], v[154:155]
	v_lshlrev_b32_e32 v155, 16, v165
	v_lshlrev_b32_e32 v154, 16, v151
	v_pk_mul_f32 v[148:149], v[148:149], v[154:155]
	v_and_b32_e32 v155, 0xffff0000, v165
	v_and_b32_e32 v154, 0xffff0000, v151
	v_pk_mul_f32 v[150:151], v[152:153], v[154:155]
	global_load_dwordx4 v[154:157], v3, s[0:1] offset:16
	v_add_co_u32_e32 v152, vcc, s26, v76
	s_mov_b32 s0, 0x3c000
	s_nop 0
	v_addc_co_u32_e32 v153, vcc, 0, v77, vcc
	global_load_dwordx2 v[152:153], v[152:153], off offset:512
	s_waitcnt vmcnt(2)
	v_lshlrev_b32_e32 v162, 16, v158
	v_pk_fma_f32 v[164:165], v[70:71], v[162:163], v[66:67] op_sel_hi:[1,0,1]
	v_pk_fma_f32 v[166:167], v[68:69], v[162:163], v[64:65] op_sel_hi:[1,0,1]
	v_and_b32_e32 v158, 0xffff0000, v158
	v_pk_fma_f32 v[164:165], v[62:63], v[158:159], v[164:165] op_sel_hi:[1,0,1]
	v_pk_fma_f32 v[166:167], v[60:61], v[158:159], v[166:167] op_sel_hi:[1,0,1]
	v_lshlrev_b32_e32 v158, 16, v159
	v_pk_fma_f32 v[164:165], v[58:59], v[158:159], v[164:165] op_sel_hi:[1,0,1]
	v_pk_fma_f32 v[166:167], v[56:57], v[158:159], v[166:167] op_sel_hi:[1,0,1]
	v_and_b32_e32 v158, 0xffff0000, v159
	v_pk_fma_f32 v[164:165], v[54:55], v[158:159], v[164:165] op_sel_hi:[1,0,1]
	v_pk_fma_f32 v[158:159], v[52:53], v[158:159], v[166:167] op_sel_hi:[1,0,1]
	v_lshlrev_b32_e32 v162, 16, v160
	v_pk_fma_f32 v[164:165], v[50:51], v[162:163], v[164:165] op_sel_hi:[1,0,1]
	v_pk_fma_f32 v[158:159], v[48:49], v[162:163], v[158:159] op_sel_hi:[1,0,1]
	v_and_b32_e32 v160, 0xffff0000, v160
	v_pk_fma_f32 v[164:165], v[46:47], v[160:161], v[164:165] op_sel_hi:[1,0,1]
	v_pk_fma_f32 v[158:159], v[44:45], v[160:161], v[158:159] op_sel_hi:[1,0,1]
	v_lshlrev_b32_e32 v160, 16, v161
	v_pk_fma_f32 v[164:165], v[42:43], v[160:161], v[164:165] op_sel_hi:[1,0,1]
	v_pk_fma_f32 v[158:159], v[40:41], v[160:161], v[158:159] op_sel_hi:[1,0,1]
	v_and_b32_e32 v160, 0xffff0000, v161
	v_pk_fma_f32 v[164:165], v[38:39], v[160:161], v[164:165] op_sel_hi:[1,0,1]
	v_pk_fma_f32 v[158:159], v[36:37], v[160:161], v[158:159] op_sel_hi:[1,0,1]
	s_waitcnt vmcnt(1)
	v_lshlrev_b32_e32 v160, 16, v154
	v_pk_fma_f32 v[164:165], v[34:35], v[160:161], v[164:165] op_sel_hi:[1,0,1]
	v_pk_fma_f32 v[158:159], v[32:33], v[160:161], v[158:159] op_sel_hi:[1,0,1]
	v_and_b32_e32 v154, 0xffff0000, v154
	v_pk_fma_f32 v[160:161], v[30:31], v[154:155], v[164:165] op_sel_hi:[1,0,1]
	v_pk_fma_f32 v[158:159], v[28:29], v[154:155], v[158:159] op_sel_hi:[1,0,1]
	v_lshlrev_b32_e32 v154, 16, v155
	v_pk_fma_f32 v[160:161], v[26:27], v[154:155], v[160:161] op_sel_hi:[1,0,1]
	v_pk_fma_f32 v[158:159], v[24:25], v[154:155], v[158:159] op_sel_hi:[1,0,1]
	v_and_b32_e32 v154, 0xffff0000, v155
	v_pk_fma_f32 v[160:161], v[22:23], v[154:155], v[160:161] op_sel_hi:[1,0,1]
	v_pk_fma_f32 v[154:155], v[20:21], v[154:155], v[158:159] op_sel_hi:[1,0,1]
	v_lshlrev_b32_e32 v158, 16, v156
	v_pk_fma_f32 v[160:161], v[18:19], v[158:159], v[160:161] op_sel_hi:[1,0,1]
	v_pk_fma_f32 v[154:155], v[16:17], v[158:159], v[154:155] op_sel_hi:[1,0,1]
	v_and_b32_e32 v156, 0xffff0000, v156
	v_pk_fma_f32 v[158:159], v[14:15], v[156:157], v[160:161] op_sel_hi:[1,0,1]
	v_pk_fma_f32 v[154:155], v[12:13], v[156:157], v[154:155] op_sel_hi:[1,0,1]
	v_lshlrev_b32_e32 v156, 16, v157
	v_pk_fma_f32 v[158:159], v[10:11], v[156:157], v[158:159] op_sel_hi:[1,0,1]
	v_pk_fma_f32 v[154:155], v[8:9], v[156:157], v[154:155] op_sel_hi:[1,0,1]
	v_and_b32_e32 v156, 0xffff0000, v157
	v_pk_fma_f32 v[154:155], v[4:5], v[156:157], v[154:155] op_sel_hi:[1,0,1]
	v_pk_fma_f32 v[158:159], v[6:7], v[156:157], v[158:159] op_sel_hi:[1,0,1]
	v_min_f32_e32 v156, 0, v154
	v_mul_f32_e64 v154, |v154|, s93
	v_exp_f32_e32 v154, v154
	v_add_co_u32_e32 v164, vcc, s0, v76
	s_add_u32 s0, s6, 0x3ee00
	v_add_f32_e32 v154, 1.0, v154
	v_log_f32_e32 v154, v154
	v_addc_co_u32_e32 v165, vcc, 0, v77, vcc
	s_addc_u32 s1, s7, 0
	v_fmac_f32_e32 v156, 0xbf317218, v154
	v_min_f32_e32 v154, 0, v155
	v_mul_f32_e64 v155, |v155|, s93
	v_exp_f32_e32 v155, v155
	global_load_dwordx2 v[168:169], v[164:165], off offset:3072
	v_fmac_f32_e32 v85, 0x3d800000, v156
	global_load_dwordx4 v[164:167], v3, s[0:1] offset:16
	v_add_f32_e32 v155, 1.0, v155
	v_log_f32_e32 v155, v155
	s_add_u32 s0, s6, 0x41800
	s_addc_u32 s1, s7, 0
	v_fmac_f32_e32 v154, 0xbf317218, v155
	v_mul_f32_e64 v155, |v158|, s93
	v_exp_f32_e32 v155, v155
	v_fmac_f32_e32 v91, 0x3d800000, v154
	v_min_f32_e32 v154, 0, v158
	v_add_f32_e32 v155, 1.0, v155
	v_log_f32_e32 v155, v155
	s_nop 0
	v_fmac_f32_e32 v154, 0xbf317218, v155
	v_mul_f32_e64 v155, |v159|, s93
	v_exp_f32_e32 v155, v155
	v_fmac_f32_e32 v163, 0x3d800000, v154
	v_min_f32_e32 v154, 0, v159
	v_add_f32_e32 v155, 1.0, v155
	v_log_f32_e32 v155, v155
	s_nop 0
	v_fmac_f32_e32 v154, 0xbf317218, v155
	v_mov_b32_e32 v155, 0x3e000
	global_load_dwordx4 v[172:175], v155, s[6:7] offset:3584
	v_fmac_f32_e32 v170, 0x3d800000, v154
	v_sub_f32_e32 v154, v130, v85
	v_mul_f32_e32 v154, 0x3fb8aa3b, v154
	v_exp_f32_e32 v160, v154
	v_sub_f32_e32 v154, v131, v91
	v_mul_f32_e32 v154, 0x3fb8aa3b, v154
	v_exp_f32_e32 v158, v154
	v_sub_f32_e32 v154, v128, v163
	v_mul_f32_e32 v154, 0x3fb8aa3b, v154
	v_exp_f32_e32 v156, v154
	v_sub_f32_e32 v154, v129, v170
	v_mul_f32_e32 v154, 0x3fb8aa3b, v154
	v_exp_f32_e32 v154, v154
	s_waitcnt vmcnt(0)
	v_lshlrev_b32_e32 v162, 16, v172
	v_pk_fma_f32 v[176:177], v[70:71], v[162:163], v[66:67] op_sel_hi:[1,0,1]
	v_pk_fma_f32 v[178:179], v[68:69], v[162:163], v[64:65] op_sel_hi:[1,0,1]
	v_and_b32_e32 v162, 0xffff0000, v172
	v_pk_fma_f32 v[176:177], v[62:63], v[162:163], v[176:177] op_sel_hi:[1,0,1]
	v_pk_fma_f32 v[178:179], v[60:61], v[162:163], v[178:179] op_sel_hi:[1,0,1]
	v_lshlrev_b32_e32 v162, 16, v173
	v_pk_fma_f32 v[176:177], v[58:59], v[162:163], v[176:177] op_sel_hi:[1,0,1]
	v_pk_fma_f32 v[178:179], v[56:57], v[162:163], v[178:179] op_sel_hi:[1,0,1]
	v_and_b32_e32 v162, 0xffff0000, v173
	v_pk_fma_f32 v[172:173], v[54:55], v[162:163], v[176:177] op_sel_hi:[1,0,1]
	v_pk_fma_f32 v[176:177], v[52:53], v[162:163], v[178:179] op_sel_hi:[1,0,1]
	v_lshlrev_b32_e32 v162, 16, v174
	v_pk_fma_f32 v[172:173], v[50:51], v[162:163], v[172:173] op_sel_hi:[1,0,1]
	v_pk_fma_f32 v[176:177], v[48:49], v[162:163], v[176:177] op_sel_hi:[1,0,1]
	v_and_b32_e32 v162, 0xffff0000, v174
	v_pk_fma_f32 v[172:173], v[46:47], v[162:163], v[172:173] op_sel_hi:[1,0,1]
	v_pk_fma_f32 v[176:177], v[44:45], v[162:163], v[176:177] op_sel_hi:[1,0,1]
	v_lshlrev_b32_e32 v162, 16, v175
	v_pk_fma_f32 v[172:173], v[42:43], v[162:163], v[172:173] op_sel_hi:[1,0,1]
	v_pk_fma_f32 v[176:177], v[40:41], v[162:163], v[176:177] op_sel_hi:[1,0,1]
	v_and_b32_e32 v162, 0xffff0000, v175
	v_pk_fma_f32 v[172:173], v[38:39], v[162:163], v[172:173] op_sel_hi:[1,0,1]
	v_pk_fma_f32 v[174:175], v[36:37], v[162:163], v[176:177] op_sel_hi:[1,0,1]
	v_lshlrev_b32_e32 v162, 16, v164
	v_pk_fma_f32 v[172:173], v[34:35], v[162:163], v[172:173] op_sel_hi:[1,0,1]
	v_pk_fma_f32 v[174:175], v[32:33], v[162:163], v[174:175] op_sel_hi:[1,0,1]
	v_and_b32_e32 v162, 0xffff0000, v164
	v_pk_fma_f32 v[172:173], v[30:31], v[162:163], v[172:173] op_sel_hi:[1,0,1]
	v_pk_fma_f32 v[174:175], v[28:29], v[162:163], v[174:175] op_sel_hi:[1,0,1]
	v_lshlrev_b32_e32 v162, 16, v165
	v_pk_fma_f32 v[172:173], v[26:27], v[162:163], v[172:173] op_sel_hi:[1,0,1]
	v_pk_fma_f32 v[174:175], v[24:25], v[162:163], v[174:175] op_sel_hi:[1,0,1]
	v_and_b32_e32 v162, 0xffff0000, v165
	v_pk_fma_f32 v[164:165], v[22:23], v[162:163], v[172:173] op_sel_hi:[1,0,1]
	v_pk_fma_f32 v[172:173], v[20:21], v[162:163], v[174:175] op_sel_hi:[1,0,1]
	v_lshlrev_b32_e32 v162, 16, v166
	v_pk_fma_f32 v[164:165], v[18:19], v[162:163], v[164:165] op_sel_hi:[1,0,1]
	v_pk_fma_f32 v[172:173], v[16:17], v[162:163], v[172:173] op_sel_hi:[1,0,1]
	v_and_b32_e32 v162, 0xffff0000, v166
	v_pk_fma_f32 v[164:165], v[14:15], v[162:163], v[164:165] op_sel_hi:[1,0,1]
	v_pk_fma_f32 v[172:173], v[12:13], v[162:163], v[172:173] op_sel_hi:[1,0,1]
	v_lshlrev_b32_e32 v162, 16, v167
	v_pk_fma_f32 v[164:165], v[10:11], v[162:163], v[164:165] op_sel_hi:[1,0,1]
	v_pk_fma_f32 v[172:173], v[8:9], v[162:163], v[172:173] op_sel_hi:[1,0,1]
	v_and_b32_e32 v162, 0xffff0000, v167
	v_pk_fma_f32 v[166:167], v[4:5], v[162:163], v[172:173] op_sel_hi:[1,0,1]
	v_pk_fma_f32 v[164:165], v[6:7], v[162:163], v[164:165] op_sel_hi:[1,0,1]
	v_mul_f32_e64 v157, |v166|, s93
	v_exp_f32_e32 v157, v157
	v_min_f32_e32 v155, 0, v166
	v_add_f32_e32 v157, 1.0, v157
	v_log_f32_e32 v157, v157
	s_nop 0
	v_fmac_f32_e32 v155, 0xbf317218, v157
	v_mul_f32_e64 v157, |v167|, s93
	v_exp_f32_e32 v157, v157
	v_fmac_f32_e32 v85, 0x3d800000, v155
	v_min_f32_e32 v155, 0, v167
	v_add_f32_e32 v157, 1.0, v157
	v_log_f32_e32 v157, v157
	s_nop 0
	v_fmac_f32_e32 v155, 0xbf317218, v157
	v_mul_f32_e64 v157, |v164|, s93
	v_exp_f32_e32 v157, v157
	v_fmac_f32_e32 v91, 0x3d800000, v155
	v_min_f32_e32 v155, 0, v164
	v_lshlrev_b32_e32 v164, 16, v152
	v_add_f32_e32 v157, 1.0, v157
	v_log_f32_e32 v157, v157
	s_nop 0
	v_fmac_f32_e32 v155, 0xbf317218, v157
	v_mul_f32_e64 v157, |v165|, s93
	v_exp_f32_e32 v157, v157
	v_fmac_f32_e32 v163, 0x3d800000, v155
	v_min_f32_e32 v155, 0, v165
	v_lshlrev_b32_e32 v165, 16, v168
	v_add_f32_e32 v157, 1.0, v157
	v_log_f32_e32 v157, v157
	s_nop 0
	v_fmac_f32_e32 v155, 0xbf317218, v157
	v_fmac_f32_e32 v170, 0x3d800000, v155
	v_sub_f32_e32 v155, v130, v85
	v_mul_f32_e32 v155, 0x3fb8aa3b, v155
	v_exp_f32_e32 v161, v155
	v_sub_f32_e32 v155, v131, v91
	v_mul_f32_e32 v155, 0x3fb8aa3b, v155
	v_exp_f32_e32 v159, v155
	v_pk_mul_f32 v[160:161], v[160:161], v[164:165]
	v_and_b32_e32 v164, 0xffff0000, v152
	v_sub_f32_e32 v152, v128, v163
	v_mul_f32_e32 v152, 0x3fb8aa3b, v152
	v_exp_f32_e32 v157, v152
	v_sub_f32_e32 v152, v129, v170
	v_mul_f32_e32 v152, 0x3fb8aa3b, v152
	v_exp_f32_e32 v155, v152
	v_and_b32_e32 v165, 0xffff0000, v168
	v_pk_mul_f32 v[158:159], v[158:159], v[164:165]
	v_lshlrev_b32_e32 v165, 16, v169
	v_lshlrev_b32_e32 v164, 16, v153
	v_pk_mul_f32 v[156:157], v[156:157], v[164:165]
	v_and_b32_e32 v165, 0xffff0000, v169
	v_and_b32_e32 v164, 0xffff0000, v153
	v_cvt_pk_bf16_f32 v152, v72, v73
	v_cvt_pk_bf16_f32 v72, v74, v75
	v_cvt_pk_bf16_f32 v73, v138, v139
	v_cvt_pk_bf16_f32 v74, v146, v147
	v_cvt_pk_bf16_f32 v75, v158, v159
	v_pk_mul_f32 v[164:165], v[154:155], v[164:165]
	global_store_dwordx4 v[132:133], v[72:75], off offset:1040
	v_cvt_pk_bf16_f32 v153, v136, v137
	v_cvt_pk_bf16_f32 v154, v144, v145
	v_cvt_pk_bf16_f32 v72, v78, v79
	v_cvt_pk_bf16_f32 v73, v140, v141
	v_cvt_pk_bf16_f32 v74, v148, v149
	v_cvt_pk_bf16_f32 v75, v156, v157
	v_cvt_pk_bf16_f32 v155, v160, v161
	global_store_dwordx4 v[132:133], v[72:75], off offset:1056
	global_store_dwordx4 v[132:133], v[152:155], off offset:1024
	v_mov_b32_e32 v78, 0x41000
	v_cvt_pk_bf16_f32 v72, v134, v135
	v_cvt_pk_bf16_f32 v73, v142, v143
	v_cvt_pk_bf16_f32 v74, v150, v151
	v_cvt_pk_bf16_f32 v75, v164, v165
	global_store_dwordx4 v[132:133], v[72:75], off offset:1072
	global_load_dwordx4 v[136:139], v78, s[6:7] offset:2048
	s_waitcnt vmcnt(0)
	v_lshlrev_b32_e32 v78, 16, v136
	v_add_co_u32_e32 v72, vcc, s27, v76
	v_pk_fma_f32 v[140:141], v[70:71], v[78:79], v[66:67] op_sel_hi:[1,0,1]
	s_nop 0
	v_addc_co_u32_e32 v73, vcc, 0, v77, vcc
	global_load_dwordx2 v[134:135], v[72:73], off offset:1536
	v_pk_fma_f32 v[78:79], v[68:69], v[78:79], v[64:65] op_sel_hi:[1,0,1]
	global_load_dwordx4 v[72:75], v3, s[0:1] offset:16
	v_and_b32_e32 v136, 0xffff0000, v136
	v_pk_fma_f32 v[140:141], v[62:63], v[136:137], v[140:141] op_sel_hi:[1,0,1]
	v_pk_fma_f32 v[78:79], v[60:61], v[136:137], v[78:79] op_sel_hi:[1,0,1]
	v_lshlrev_b32_e32 v136, 16, v137
	v_pk_fma_f32 v[140:141], v[58:59], v[136:137], v[140:141] op_sel_hi:[1,0,1]
	v_pk_fma_f32 v[78:79], v[56:57], v[136:137], v[78:79] op_sel_hi:[1,0,1]
	v_and_b32_e32 v136, 0xffff0000, v137
	v_pk_fma_f32 v[140:141], v[54:55], v[136:137], v[140:141] op_sel_hi:[1,0,1]
	v_pk_fma_f32 v[78:79], v[52:53], v[136:137], v[78:79] op_sel_hi:[1,0,1]
	v_lshlrev_b32_e32 v136, 16, v138
	v_pk_fma_f32 v[140:141], v[50:51], v[136:137], v[140:141] op_sel_hi:[1,0,1]
	v_pk_fma_f32 v[78:79], v[48:49], v[136:137], v[78:79] op_sel_hi:[1,0,1]
	v_and_b32_e32 v136, 0xffff0000, v138
	v_pk_fma_f32 v[140:141], v[46:47], v[136:137], v[140:141] op_sel_hi:[1,0,1]
	v_pk_fma_f32 v[78:79], v[44:45], v[136:137], v[78:79] op_sel_hi:[1,0,1]
	v_lshlrev_b32_e32 v136, 16, v139
	v_pk_fma_f32 v[140:141], v[42:43], v[136:137], v[140:141] op_sel_hi:[1,0,1]
	v_pk_fma_f32 v[78:79], v[40:41], v[136:137], v[78:79] op_sel_hi:[1,0,1]
	v_and_b32_e32 v136, 0xffff0000, v139
	v_pk_fma_f32 v[138:139], v[38:39], v[136:137], v[140:141] op_sel_hi:[1,0,1]
	v_pk_fma_f32 v[78:79], v[36:37], v[136:137], v[78:79] op_sel_hi:[1,0,1]
	s_add_u32 s0, s6, 0x44200
	s_addc_u32 s1, s7, 0
	s_waitcnt vmcnt(0)
	v_lshlrev_b32_e32 v136, 16, v72
	v_pk_fma_f32 v[138:139], v[34:35], v[136:137], v[138:139] op_sel_hi:[1,0,1]
	v_pk_fma_f32 v[78:79], v[32:33], v[136:137], v[78:79] op_sel_hi:[1,0,1]
	v_and_b32_e32 v72, 0xffff0000, v72
	v_pk_fma_f32 v[136:137], v[30:31], v[72:73], v[138:139] op_sel_hi:[1,0,1]
	v_pk_fma_f32 v[78:79], v[28:29], v[72:73], v[78:79] op_sel_hi:[1,0,1]
	v_lshlrev_b32_e32 v72, 16, v73
	v_pk_fma_f32 v[136:137], v[26:27], v[72:73], v[136:137] op_sel_hi:[1,0,1]
	v_pk_fma_f32 v[78:79], v[24:25], v[72:73], v[78:79] op_sel_hi:[1,0,1]
	v_and_b32_e32 v72, 0xffff0000, v73
	v_pk_fma_f32 v[136:137], v[22:23], v[72:73], v[136:137] op_sel_hi:[1,0,1]
	v_pk_fma_f32 v[72:73], v[20:21], v[72:73], v[78:79] op_sel_hi:[1,0,1]
	v_lshlrev_b32_e32 v78, 16, v74
	v_pk_fma_f32 v[136:137], v[18:19], v[78:79], v[136:137] op_sel_hi:[1,0,1]
	v_pk_fma_f32 v[72:73], v[16:17], v[78:79], v[72:73] op_sel_hi:[1,0,1]
	v_and_b32_e32 v74, 0xffff0000, v74
	v_pk_fma_f32 v[78:79], v[14:15], v[74:75], v[136:137] op_sel_hi:[1,0,1]
	v_pk_fma_f32 v[72:73], v[12:13], v[74:75], v[72:73] op_sel_hi:[1,0,1]
	v_lshlrev_b32_e32 v74, 16, v75
	v_pk_fma_f32 v[78:79], v[10:11], v[74:75], v[78:79] op_sel_hi:[1,0,1]
	v_pk_fma_f32 v[72:73], v[8:9], v[74:75], v[72:73] op_sel_hi:[1,0,1]
	v_and_b32_e32 v74, 0xffff0000, v75
	v_pk_fma_f32 v[72:73], v[4:5], v[74:75], v[72:73] op_sel_hi:[1,0,1]
	v_pk_fma_f32 v[78:79], v[6:7], v[74:75], v[78:79] op_sel_hi:[1,0,1]
	v_min_f32_e32 v74, 0, v72
	v_mul_f32_e64 v72, |v72|, s93
	v_exp_f32_e32 v72, v72
	v_add_co_u32_e32 v138, vcc, s28, v76
	v_add_f32_e32 v72, 1.0, v72
	v_log_f32_e32 v72, v72
	v_addc_co_u32_e32 v139, vcc, 0, v77, vcc
	global_load_dwordx2 v[146:147], v[138:139], off
	v_fmac_f32_e32 v74, 0xbf317218, v72
	v_min_f32_e32 v72, 0, v73
	v_mul_f32_e64 v73, |v73|, s93
	v_exp_f32_e32 v73, v73
	v_fmac_f32_e32 v85, 0x3d800000, v74
	global_load_dwordx4 v[138:141], v3, s[0:1] offset:16
	s_mov_b32 s0, 0x44000
	v_add_f32_e32 v73, 1.0, v73
	v_log_f32_e32 v73, v73
	s_nop 0
	v_fmac_f32_e32 v72, 0xbf317218, v73
	v_mul_f32_e64 v73, |v78|, s93
	v_exp_f32_e32 v73, v73
	v_fmac_f32_e32 v91, 0x3d800000, v72
	v_min_f32_e32 v72, 0, v78
	v_add_f32_e32 v73, 1.0, v73
	v_log_f32_e32 v73, v73
	s_nop 0
	v_fmac_f32_e32 v72, 0xbf317218, v73
	v_mul_f32_e64 v73, |v79|, s93
	v_exp_f32_e32 v73, v73
	v_fmac_f32_e32 v163, 0x3d800000, v72
	v_min_f32_e32 v72, 0, v79
	v_add_f32_e32 v73, 1.0, v73
	v_log_f32_e32 v73, v73
	s_nop 0
	v_fmac_f32_e32 v72, 0xbf317218, v73
	v_sub_f32_e32 v73, v131, v91
	v_mul_f32_e32 v73, 0x3fb8aa3b, v73
	v_exp_f32_e32 v74, v73
	v_sub_f32_e32 v73, v128, v163
	v_fmac_f32_e32 v170, 0x3d800000, v72
	v_mul_f32_e32 v73, 0x3fb8aa3b, v73
	v_exp_f32_e32 v78, v73
	v_sub_f32_e32 v73, v129, v170
	v_mul_f32_e32 v73, 0x3fb8aa3b, v73
	v_exp_f32_e32 v136, v73
	v_mov_b32_e32 v73, 0x44000
	global_load_dwordx4 v[142:145], v73, s[6:7] offset:512
	v_sub_f32_e32 v72, v130, v85
	v_mul_f32_e32 v72, 0x3fb8aa3b, v72
	v_exp_f32_e32 v72, v72
	s_waitcnt vmcnt(0)
	v_lshlrev_b32_e32 v148, 16, v142
	v_pk_fma_f32 v[150:151], v[70:71], v[148:149], v[66:67] op_sel_hi:[1,0,1]
	v_pk_fma_f32 v[148:149], v[68:69], v[148:149], v[64:65] op_sel_hi:[1,0,1]
	v_and_b32_e32 v142, 0xffff0000, v142
	v_pk_fma_f32 v[150:151], v[62:63], v[142:143], v[150:151] op_sel_hi:[1,0,1]
	v_pk_fma_f32 v[148:149], v[60:61], v[142:143], v[148:149] op_sel_hi:[1,0,1]
	v_lshlrev_b32_e32 v142, 16, v143
	v_pk_fma_f32 v[150:151], v[58:59], v[142:143], v[150:151] op_sel_hi:[1,0,1]
	v_pk_fma_f32 v[148:149], v[56:57], v[142:143], v[148:149] op_sel_hi:[1,0,1]
	v_and_b32_e32 v142, 0xffff0000, v143
	v_pk_fma_f32 v[150:151], v[54:55], v[142:143], v[150:151] op_sel_hi:[1,0,1]
	v_pk_fma_f32 v[142:143], v[52:53], v[142:143], v[148:149] op_sel_hi:[1,0,1]
	v_lshlrev_b32_e32 v148, 16, v144
	v_pk_fma_f32 v[150:151], v[50:51], v[148:149], v[150:151] op_sel_hi:[1,0,1]
	v_pk_fma_f32 v[142:143], v[48:49], v[148:149], v[142:143] op_sel_hi:[1,0,1]
	v_and_b32_e32 v144, 0xffff0000, v144
	v_pk_fma_f32 v[148:149], v[46:47], v[144:145], v[150:151] op_sel_hi:[1,0,1]
	v_pk_fma_f32 v[142:143], v[44:45], v[144:145], v[142:143] op_sel_hi:[1,0,1]
	v_lshlrev_b32_e32 v144, 16, v145
	v_pk_fma_f32 v[148:149], v[42:43], v[144:145], v[148:149] op_sel_hi:[1,0,1]
	v_pk_fma_f32 v[142:143], v[40:41], v[144:145], v[142:143] op_sel_hi:[1,0,1]
	v_and_b32_e32 v144, 0xffff0000, v145
	v_pk_fma_f32 v[148:149], v[38:39], v[144:145], v[148:149] op_sel_hi:[1,0,1]
	v_pk_fma_f32 v[142:143], v[36:37], v[144:145], v[142:143] op_sel_hi:[1,0,1]
	v_lshlrev_b32_e32 v144, 16, v138
	v_pk_fma_f32 v[148:149], v[34:35], v[144:145], v[148:149] op_sel_hi:[1,0,1]
	v_pk_fma_f32 v[142:143], v[32:33], v[144:145], v[142:143] op_sel_hi:[1,0,1]
	v_and_b32_e32 v138, 0xffff0000, v138
	v_pk_fma_f32 v[144:145], v[30:31], v[138:139], v[148:149] op_sel_hi:[1,0,1]
	v_pk_fma_f32 v[142:143], v[28:29], v[138:139], v[142:143] op_sel_hi:[1,0,1]
	v_lshlrev_b32_e32 v138, 16, v139
	v_pk_fma_f32 v[144:145], v[26:27], v[138:139], v[144:145] op_sel_hi:[1,0,1]
	v_pk_fma_f32 v[142:143], v[24:25], v[138:139], v[142:143] op_sel_hi:[1,0,1]
	v_and_b32_e32 v138, 0xffff0000, v139
	v_pk_fma_f32 v[144:145], v[22:23], v[138:139], v[144:145] op_sel_hi:[1,0,1]
	v_pk_fma_f32 v[138:139], v[20:21], v[138:139], v[142:143] op_sel_hi:[1,0,1]
	v_lshlrev_b32_e32 v142, 16, v140
	v_pk_fma_f32 v[144:145], v[18:19], v[142:143], v[144:145] op_sel_hi:[1,0,1]
	v_pk_fma_f32 v[138:139], v[16:17], v[142:143], v[138:139] op_sel_hi:[1,0,1]
	v_and_b32_e32 v140, 0xffff0000, v140
	v_pk_fma_f32 v[142:143], v[14:15], v[140:141], v[144:145] op_sel_hi:[1,0,1]
	v_pk_fma_f32 v[138:139], v[12:13], v[140:141], v[138:139] op_sel_hi:[1,0,1]
	v_lshlrev_b32_e32 v140, 16, v141
	v_pk_fma_f32 v[142:143], v[10:11], v[140:141], v[142:143] op_sel_hi:[1,0,1]
	v_pk_fma_f32 v[138:139], v[8:9], v[140:141], v[138:139] op_sel_hi:[1,0,1]
	v_and_b32_e32 v140, 0xffff0000, v141
	v_pk_fma_f32 v[138:139], v[4:5], v[140:141], v[138:139] op_sel_hi:[1,0,1]
	v_pk_fma_f32 v[142:143], v[6:7], v[140:141], v[142:143] op_sel_hi:[1,0,1]
	v_mul_f32_e64 v75, |v138|, s93
	v_exp_f32_e32 v75, v75
	v_min_f32_e32 v73, 0, v138
	v_lshlrev_b32_e32 v138, 16, v134
	v_mov_b32_e32 v140, 0x46000
	v_add_f32_e32 v75, 1.0, v75
	v_log_f32_e32 v75, v75
	s_nop 0
	v_fmac_f32_e32 v73, 0xbf317218, v75
	v_mul_f32_e64 v75, |v139|, s93
	v_exp_f32_e32 v75, v75
	v_fmac_f32_e32 v85, 0x3d800000, v73
	v_min_f32_e32 v73, 0, v139
	v_lshlrev_b32_e32 v139, 16, v146
	v_add_f32_e32 v75, 1.0, v75
	v_log_f32_e32 v75, v75
	s_nop 0
	v_fmac_f32_e32 v73, 0xbf317218, v75
	v_mul_f32_e64 v75, |v142|, s93
	v_exp_f32_e32 v75, v75
	v_fmac_f32_e32 v91, 0x3d800000, v73
	v_min_f32_e32 v73, 0, v142
	v_add_f32_e32 v75, 1.0, v75
	v_log_f32_e32 v75, v75
	s_nop 0
	v_fmac_f32_e32 v73, 0xbf317218, v75
	v_mul_f32_e64 v75, |v143|, s93
	v_exp_f32_e32 v75, v75
	v_fmac_f32_e32 v163, 0x3d800000, v73
	v_min_f32_e32 v73, 0, v143
	v_sub_f32_e32 v79, v128, v163
	v_add_f32_e32 v75, 1.0, v75
	v_log_f32_e32 v75, v75
	v_mul_f32_e32 v79, 0x3fb8aa3b, v79
	v_exp_f32_e32 v79, v79
	v_fmac_f32_e32 v73, 0xbf317218, v75
	v_fmac_f32_e32 v170, 0x3d800000, v73
	v_sub_f32_e32 v73, v130, v85
	v_mul_f32_e32 v73, 0x3fb8aa3b, v73
	v_sub_f32_e32 v75, v131, v91
	v_exp_f32_e32 v73, v73
	v_mul_f32_e32 v75, 0x3fb8aa3b, v75
	v_exp_f32_e32 v75, v75
	v_pk_mul_f32 v[72:73], v[72:73], v[138:139]
	v_and_b32_e32 v139, 0xffff0000, v146
	v_and_b32_e32 v138, 0xffff0000, v134
	v_pk_mul_f32 v[74:75], v[74:75], v[138:139]
	v_lshlrev_b32_e32 v139, 16, v147
	v_lshlrev_b32_e32 v138, 16, v135
	v_pk_mul_f32 v[78:79], v[78:79], v[138:139]
	v_sub_f32_e32 v134, v129, v170
	v_and_b32_e32 v139, 0xffff0000, v147
	global_load_dwordx4 v[144:147], v140, s[6:7] offset:3072
	v_mul_f32_e32 v134, 0x3fb8aa3b, v134
	v_exp_f32_e32 v137, v134
	v_and_b32_e32 v138, 0xffff0000, v135
	v_pk_mul_f32 v[134:135], v[136:137], v[138:139]
	v_add_co_u32_e32 v136, vcc, s0, v76
	s_add_u32 s0, s6, 0x46c00
	s_nop 0
	v_addc_co_u32_e32 v137, vcc, 0, v77, vcc
	s_addc_u32 s1, s7, 0
	global_load_dwordx2 v[142:143], v[136:137], off offset:2560
	s_waitcnt vmcnt(1)
	v_lshlrev_b32_e32 v140, 16, v144
	global_load_dwordx4 v[136:139], v3, s[0:1] offset:16
	v_pk_fma_f32 v[148:149], v[70:71], v[140:141], v[66:67] op_sel_hi:[1,0,1]
	v_pk_fma_f32 v[140:141], v[68:69], v[140:141], v[64:65] op_sel_hi:[1,0,1]
	v_and_b32_e32 v144, 0xffff0000, v144
	v_pk_fma_f32 v[148:149], v[62:63], v[144:145], v[148:149] op_sel_hi:[1,0,1]
	v_pk_fma_f32 v[140:141], v[60:61], v[144:145], v[140:141] op_sel_hi:[1,0,1]
	v_lshlrev_b32_e32 v144, 16, v145
	v_pk_fma_f32 v[148:149], v[58:59], v[144:145], v[148:149] op_sel_hi:[1,0,1]
	v_pk_fma_f32 v[140:141], v[56:57], v[144:145], v[140:141] op_sel_hi:[1,0,1]
	v_and_b32_e32 v144, 0xffff0000, v145
	v_pk_fma_f32 v[148:149], v[54:55], v[144:145], v[148:149] op_sel_hi:[1,0,1]
	v_pk_fma_f32 v[140:141], v[52:53], v[144:145], v[140:141] op_sel_hi:[1,0,1]
	v_lshlrev_b32_e32 v144, 16, v146
	v_pk_fma_f32 v[148:149], v[50:51], v[144:145], v[148:149] op_sel_hi:[1,0,1]
	v_pk_fma_f32 v[140:141], v[48:49], v[144:145], v[140:141] op_sel_hi:[1,0,1]
	v_and_b32_e32 v144, 0xffff0000, v146
	v_pk_fma_f32 v[148:149], v[46:47], v[144:145], v[148:149] op_sel_hi:[1,0,1]
	v_pk_fma_f32 v[140:141], v[44:45], v[144:145], v[140:141] op_sel_hi:[1,0,1]
	v_lshlrev_b32_e32 v144, 16, v147
	v_pk_fma_f32 v[148:149], v[42:43], v[144:145], v[148:149] op_sel_hi:[1,0,1]
	v_pk_fma_f32 v[140:141], v[40:41], v[144:145], v[140:141] op_sel_hi:[1,0,1]
	v_and_b32_e32 v144, 0xffff0000, v147
	v_pk_fma_f32 v[146:147], v[38:39], v[144:145], v[148:149] op_sel_hi:[1,0,1]
	v_pk_fma_f32 v[140:141], v[36:37], v[144:145], v[140:141] op_sel_hi:[1,0,1]
	s_add_u32 s0, s6, 0x49600
	s_addc_u32 s1, s7, 0
	s_waitcnt vmcnt(0)
	v_lshlrev_b32_e32 v144, 16, v136
	v_pk_fma_f32 v[146:147], v[34:35], v[144:145], v[146:147] op_sel_hi:[1,0,1]
	v_pk_fma_f32 v[140:141], v[32:33], v[144:145], v[140:141] op_sel_hi:[1,0,1]
	v_and_b32_e32 v136, 0xffff0000, v136
	v_pk_fma_f32 v[144:145], v[30:31], v[136:137], v[146:147] op_sel_hi:[1,0,1]
	v_pk_fma_f32 v[140:141], v[28:29], v[136:137], v[140:141] op_sel_hi:[1,0,1]
	v_lshlrev_b32_e32 v136, 16, v137
	v_pk_fma_f32 v[144:145], v[26:27], v[136:137], v[144:145] op_sel_hi:[1,0,1]
	v_pk_fma_f32 v[140:141], v[24:25], v[136:137], v[140:141] op_sel_hi:[1,0,1]
	v_and_b32_e32 v136, 0xffff0000, v137
	v_pk_fma_f32 v[144:145], v[22:23], v[136:137], v[144:145] op_sel_hi:[1,0,1]
	v_pk_fma_f32 v[136:137], v[20:21], v[136:137], v[140:141] op_sel_hi:[1,0,1]
	v_lshlrev_b32_e32 v140, 16, v138
	v_pk_fma_f32 v[144:145], v[18:19], v[140:141], v[144:145] op_sel_hi:[1,0,1]
	v_pk_fma_f32 v[136:137], v[16:17], v[140:141], v[136:137] op_sel_hi:[1,0,1]
	v_and_b32_e32 v138, 0xffff0000, v138
	v_pk_fma_f32 v[140:141], v[14:15], v[138:139], v[144:145] op_sel_hi:[1,0,1]
	v_pk_fma_f32 v[136:137], v[12:13], v[138:139], v[136:137] op_sel_hi:[1,0,1]
	v_lshlrev_b32_e32 v138, 16, v139
	v_pk_fma_f32 v[140:141], v[10:11], v[138:139], v[140:141] op_sel_hi:[1,0,1]
	v_pk_fma_f32 v[136:137], v[8:9], v[138:139], v[136:137] op_sel_hi:[1,0,1]
	v_and_b32_e32 v138, 0xffff0000, v139
	v_pk_fma_f32 v[136:137], v[4:5], v[138:139], v[136:137] op_sel_hi:[1,0,1]
	v_pk_fma_f32 v[140:141], v[6:7], v[138:139], v[140:141] op_sel_hi:[1,0,1]
	v_min_f32_e32 v138, 0, v136
	v_mul_f32_e64 v136, |v136|, s93
	v_exp_f32_e32 v136, v136
	v_add_co_u32_e32 v146, vcc, s29, v76
	v_add_f32_e32 v136, 1.0, v136
	v_log_f32_e32 v136, v136
	v_addc_co_u32_e32 v147, vcc, 0, v77, vcc
	global_load_dwordx2 v[154:155], v[146:147], off offset:1024
	v_fmac_f32_e32 v138, 0xbf317218, v136
	v_min_f32_e32 v136, 0, v137
	v_mul_f32_e64 v137, |v137|, s93
	v_exp_f32_e32 v137, v137
	v_fmac_f32_e32 v85, 0x3d800000, v138
	global_load_dwordx4 v[146:149], v3, s[0:1] offset:16
	s_mov_b32 s0, 0x49000
	v_add_f32_e32 v137, 1.0, v137
	v_log_f32_e32 v137, v137
	s_nop 0
	v_fmac_f32_e32 v136, 0xbf317218, v137
	v_mul_f32_e64 v137, |v140|, s93
	v_exp_f32_e32 v137, v137
	v_fmac_f32_e32 v91, 0x3d800000, v136
	v_min_f32_e32 v136, 0, v140
	v_add_f32_e32 v137, 1.0, v137
	v_log_f32_e32 v137, v137
	s_nop 0
	v_fmac_f32_e32 v136, 0xbf317218, v137
	v_mul_f32_e64 v137, |v141|, s93
	v_exp_f32_e32 v137, v137
	v_fmac_f32_e32 v163, 0x3d800000, v136
	v_min_f32_e32 v136, 0, v141
	v_add_f32_e32 v137, 1.0, v137
	v_log_f32_e32 v137, v137
	s_nop 0
	v_fmac_f32_e32 v136, 0xbf317218, v137
	v_sub_f32_e32 v137, v131, v91
	v_mul_f32_e32 v137, 0x3fb8aa3b, v137
	v_exp_f32_e32 v138, v137
	v_sub_f32_e32 v137, v128, v163
	v_fmac_f32_e32 v170, 0x3d800000, v136
	v_mul_f32_e32 v137, 0x3fb8aa3b, v137
	v_exp_f32_e32 v140, v137
	v_sub_f32_e32 v137, v129, v170
	v_mul_f32_e32 v137, 0x3fb8aa3b, v137
	v_exp_f32_e32 v144, v137
	v_mov_b32_e32 v137, 0x49000
	global_load_dwordx4 v[150:153], v137, s[6:7] offset:1536
	v_sub_f32_e32 v136, v130, v85
	v_mul_f32_e32 v136, 0x3fb8aa3b, v136
	v_exp_f32_e32 v136, v136
	s_waitcnt vmcnt(0)
	v_lshlrev_b32_e32 v156, 16, v150
	v_pk_fma_f32 v[158:159], v[70:71], v[156:157], v[66:67] op_sel_hi:[1,0,1]
	v_pk_fma_f32 v[156:157], v[68:69], v[156:157], v[64:65] op_sel_hi:[1,0,1]
	v_and_b32_e32 v150, 0xffff0000, v150
	v_pk_fma_f32 v[158:159], v[62:63], v[150:151], v[158:159] op_sel_hi:[1,0,1]
	v_pk_fma_f32 v[156:157], v[60:61], v[150:151], v[156:157] op_sel_hi:[1,0,1]
	v_lshlrev_b32_e32 v150, 16, v151
	v_pk_fma_f32 v[158:159], v[58:59], v[150:151], v[158:159] op_sel_hi:[1,0,1]
	v_pk_fma_f32 v[156:157], v[56:57], v[150:151], v[156:157] op_sel_hi:[1,0,1]
	v_and_b32_e32 v150, 0xffff0000, v151
	v_pk_fma_f32 v[158:159], v[54:55], v[150:151], v[158:159] op_sel_hi:[1,0,1]
	v_pk_fma_f32 v[150:151], v[52:53], v[150:151], v[156:157] op_sel_hi:[1,0,1]
	v_lshlrev_b32_e32 v156, 16, v152
	v_pk_fma_f32 v[158:159], v[50:51], v[156:157], v[158:159] op_sel_hi:[1,0,1]
	v_pk_fma_f32 v[150:151], v[48:49], v[156:157], v[150:151] op_sel_hi:[1,0,1]
	v_and_b32_e32 v152, 0xffff0000, v152
	v_pk_fma_f32 v[156:157], v[46:47], v[152:153], v[158:159] op_sel_hi:[1,0,1]
	v_pk_fma_f32 v[150:151], v[44:45], v[152:153], v[150:151] op_sel_hi:[1,0,1]
	v_lshlrev_b32_e32 v152, 16, v153
	v_pk_fma_f32 v[156:157], v[42:43], v[152:153], v[156:157] op_sel_hi:[1,0,1]
	v_pk_fma_f32 v[150:151], v[40:41], v[152:153], v[150:151] op_sel_hi:[1,0,1]
	v_and_b32_e32 v152, 0xffff0000, v153
	v_pk_fma_f32 v[156:157], v[38:39], v[152:153], v[156:157] op_sel_hi:[1,0,1]
	v_pk_fma_f32 v[150:151], v[36:37], v[152:153], v[150:151] op_sel_hi:[1,0,1]
	v_lshlrev_b32_e32 v152, 16, v146
	v_pk_fma_f32 v[156:157], v[34:35], v[152:153], v[156:157] op_sel_hi:[1,0,1]
	v_pk_fma_f32 v[150:151], v[32:33], v[152:153], v[150:151] op_sel_hi:[1,0,1]
	v_and_b32_e32 v146, 0xffff0000, v146
	v_pk_fma_f32 v[152:153], v[30:31], v[146:147], v[156:157] op_sel_hi:[1,0,1]
	v_pk_fma_f32 v[150:151], v[28:29], v[146:147], v[150:151] op_sel_hi:[1,0,1]
	v_lshlrev_b32_e32 v146, 16, v147
	v_pk_fma_f32 v[152:153], v[26:27], v[146:147], v[152:153] op_sel_hi:[1,0,1]
	v_pk_fma_f32 v[150:151], v[24:25], v[146:147], v[150:151] op_sel_hi:[1,0,1]
	v_and_b32_e32 v146, 0xffff0000, v147
	v_pk_fma_f32 v[152:153], v[22:23], v[146:147], v[152:153] op_sel_hi:[1,0,1]
	v_pk_fma_f32 v[146:147], v[20:21], v[146:147], v[150:151] op_sel_hi:[1,0,1]
	v_lshlrev_b32_e32 v150, 16, v148
	v_pk_fma_f32 v[152:153], v[18:19], v[150:151], v[152:153] op_sel_hi:[1,0,1]
	v_pk_fma_f32 v[146:147], v[16:17], v[150:151], v[146:147] op_sel_hi:[1,0,1]
	v_and_b32_e32 v148, 0xffff0000, v148
	v_pk_fma_f32 v[150:151], v[14:15], v[148:149], v[152:153] op_sel_hi:[1,0,1]
	v_pk_fma_f32 v[146:147], v[12:13], v[148:149], v[146:147] op_sel_hi:[1,0,1]
	v_lshlrev_b32_e32 v148, 16, v149
	v_pk_fma_f32 v[150:151], v[10:11], v[148:149], v[150:151] op_sel_hi:[1,0,1]
	v_pk_fma_f32 v[146:147], v[8:9], v[148:149], v[146:147] op_sel_hi:[1,0,1]
	v_and_b32_e32 v148, 0xffff0000, v149
	v_pk_fma_f32 v[146:147], v[4:5], v[148:149], v[146:147] op_sel_hi:[1,0,1]
	v_pk_fma_f32 v[150:151], v[6:7], v[148:149], v[150:151] op_sel_hi:[1,0,1]
	v_mul_f32_e64 v139, |v146|, s93
	v_exp_f32_e32 v139, v139
	v_min_f32_e32 v137, 0, v146
	v_lshlrev_b32_e32 v146, 16, v142
	v_mov_b32_e32 v148, 0x4c000
	v_add_f32_e32 v139, 1.0, v139
	v_log_f32_e32 v139, v139
	s_nop 0
	v_fmac_f32_e32 v137, 0xbf317218, v139
	v_mul_f32_e64 v139, |v147|, s93
	v_exp_f32_e32 v139, v139
	v_fmac_f32_e32 v85, 0x3d800000, v137
	v_min_f32_e32 v137, 0, v147
	v_lshlrev_b32_e32 v147, 16, v154
	v_add_f32_e32 v139, 1.0, v139
	v_log_f32_e32 v139, v139
	s_nop 0
	v_fmac_f32_e32 v137, 0xbf317218, v139
	v_mul_f32_e64 v139, |v150|, s93
	v_exp_f32_e32 v139, v139
	v_fmac_f32_e32 v91, 0x3d800000, v137
	v_min_f32_e32 v137, 0, v150
	v_add_f32_e32 v139, 1.0, v139
	v_log_f32_e32 v139, v139
	s_nop 0
	v_fmac_f32_e32 v137, 0xbf317218, v139
	v_mul_f32_e64 v139, |v151|, s93
	v_exp_f32_e32 v139, v139
	v_fmac_f32_e32 v163, 0x3d800000, v137
	v_min_f32_e32 v137, 0, v151
	v_sub_f32_e32 v141, v128, v163
	v_add_f32_e32 v139, 1.0, v139
	v_log_f32_e32 v139, v139
	v_mul_f32_e32 v141, 0x3fb8aa3b, v141
	v_exp_f32_e32 v141, v141
	v_fmac_f32_e32 v137, 0xbf317218, v139
	v_fmac_f32_e32 v170, 0x3d800000, v137
	v_sub_f32_e32 v137, v130, v85
	v_mul_f32_e32 v137, 0x3fb8aa3b, v137
	v_sub_f32_e32 v139, v131, v91
	v_exp_f32_e32 v137, v137
	v_mul_f32_e32 v139, 0x3fb8aa3b, v139
	v_exp_f32_e32 v139, v139
	v_pk_mul_f32 v[136:137], v[136:137], v[146:147]
	v_and_b32_e32 v147, 0xffff0000, v154
	v_and_b32_e32 v146, 0xffff0000, v142
	v_pk_mul_f32 v[138:139], v[138:139], v[146:147]
	v_lshlrev_b32_e32 v147, 16, v155
	v_lshlrev_b32_e32 v146, 16, v143
	v_pk_mul_f32 v[140:141], v[140:141], v[146:147]
	v_sub_f32_e32 v142, v129, v170
	v_and_b32_e32 v147, 0xffff0000, v155
	global_load_dwordx4 v[152:155], v148, s[6:7]
	v_mul_f32_e32 v142, 0x3fb8aa3b, v142
	v_exp_f32_e32 v145, v142
	v_and_b32_e32 v146, 0xffff0000, v143
	v_pk_mul_f32 v[142:143], v[144:145], v[146:147]
	v_add_co_u32_e32 v144, vcc, s0, v76
	s_add_u32 s0, s6, 0x4c000
	s_nop 0
	v_addc_co_u32_e32 v145, vcc, 0, v77, vcc
	s_addc_u32 s1, s7, 0
	global_load_dwordx2 v[150:151], v[144:145], off offset:3584
	s_waitcnt vmcnt(1)
	v_lshlrev_b32_e32 v148, 16, v152
	global_load_dwordx4 v[144:147], v3, s[0:1] offset:16
	v_pk_fma_f32 v[156:157], v[70:71], v[148:149], v[66:67] op_sel_hi:[1,0,1]
	v_pk_fma_f32 v[148:149], v[68:69], v[148:149], v[64:65] op_sel_hi:[1,0,1]
	v_and_b32_e32 v152, 0xffff0000, v152
	v_pk_fma_f32 v[156:157], v[62:63], v[152:153], v[156:157] op_sel_hi:[1,0,1]
	v_pk_fma_f32 v[148:149], v[60:61], v[152:153], v[148:149] op_sel_hi:[1,0,1]
	v_lshlrev_b32_e32 v152, 16, v153
	v_pk_fma_f32 v[156:157], v[58:59], v[152:153], v[156:157] op_sel_hi:[1,0,1]
	v_pk_fma_f32 v[148:149], v[56:57], v[152:153], v[148:149] op_sel_hi:[1,0,1]
	v_and_b32_e32 v152, 0xffff0000, v153
	v_pk_fma_f32 v[156:157], v[54:55], v[152:153], v[156:157] op_sel_hi:[1,0,1]
	v_pk_fma_f32 v[148:149], v[52:53], v[152:153], v[148:149] op_sel_hi:[1,0,1]
	v_lshlrev_b32_e32 v152, 16, v154
	v_pk_fma_f32 v[156:157], v[50:51], v[152:153], v[156:157] op_sel_hi:[1,0,1]
	v_pk_fma_f32 v[148:149], v[48:49], v[152:153], v[148:149] op_sel_hi:[1,0,1]
	v_and_b32_e32 v152, 0xffff0000, v154
	v_pk_fma_f32 v[156:157], v[46:47], v[152:153], v[156:157] op_sel_hi:[1,0,1]
	v_pk_fma_f32 v[148:149], v[44:45], v[152:153], v[148:149] op_sel_hi:[1,0,1]
	v_lshlrev_b32_e32 v152, 16, v155
	v_pk_fma_f32 v[156:157], v[42:43], v[152:153], v[156:157] op_sel_hi:[1,0,1]
	v_pk_fma_f32 v[148:149], v[40:41], v[152:153], v[148:149] op_sel_hi:[1,0,1]
	v_and_b32_e32 v152, 0xffff0000, v155
	v_pk_fma_f32 v[154:155], v[38:39], v[152:153], v[156:157] op_sel_hi:[1,0,1]
	v_pk_fma_f32 v[148:149], v[36:37], v[152:153], v[148:149] op_sel_hi:[1,0,1]
	s_add_u32 s0, s6, 0x4ea00
	s_addc_u32 s1, s7, 0
	s_waitcnt vmcnt(0)
	v_lshlrev_b32_e32 v152, 16, v144
	v_pk_fma_f32 v[154:155], v[34:35], v[152:153], v[154:155] op_sel_hi:[1,0,1]
	v_pk_fma_f32 v[148:149], v[32:33], v[152:153], v[148:149] op_sel_hi:[1,0,1]
	v_and_b32_e32 v144, 0xffff0000, v144
	v_pk_fma_f32 v[152:153], v[30:31], v[144:145], v[154:155] op_sel_hi:[1,0,1]
	v_pk_fma_f32 v[148:149], v[28:29], v[144:145], v[148:149] op_sel_hi:[1,0,1]
	v_lshlrev_b32_e32 v144, 16, v145
	v_pk_fma_f32 v[152:153], v[26:27], v[144:145], v[152:153] op_sel_hi:[1,0,1]
	v_pk_fma_f32 v[148:149], v[24:25], v[144:145], v[148:149] op_sel_hi:[1,0,1]
	v_and_b32_e32 v144, 0xffff0000, v145
	v_pk_fma_f32 v[152:153], v[22:23], v[144:145], v[152:153] op_sel_hi:[1,0,1]
	v_pk_fma_f32 v[144:145], v[20:21], v[144:145], v[148:149] op_sel_hi:[1,0,1]
	v_lshlrev_b32_e32 v148, 16, v146
	v_pk_fma_f32 v[152:153], v[18:19], v[148:149], v[152:153] op_sel_hi:[1,0,1]
	v_pk_fma_f32 v[144:145], v[16:17], v[148:149], v[144:145] op_sel_hi:[1,0,1]
	v_and_b32_e32 v146, 0xffff0000, v146
	v_pk_fma_f32 v[148:149], v[14:15], v[146:147], v[152:153] op_sel_hi:[1,0,1]
	v_pk_fma_f32 v[144:145], v[12:13], v[146:147], v[144:145] op_sel_hi:[1,0,1]
	v_lshlrev_b32_e32 v146, 16, v147
	v_pk_fma_f32 v[148:149], v[10:11], v[146:147], v[148:149] op_sel_hi:[1,0,1]
	v_pk_fma_f32 v[144:145], v[8:9], v[146:147], v[144:145] op_sel_hi:[1,0,1]
	v_and_b32_e32 v146, 0xffff0000, v147
	v_pk_fma_f32 v[144:145], v[4:5], v[146:147], v[144:145] op_sel_hi:[1,0,1]
	v_pk_fma_f32 v[148:149], v[6:7], v[146:147], v[148:149] op_sel_hi:[1,0,1]
	v_min_f32_e32 v146, 0, v144
	v_mul_f32_e64 v144, |v144|, s93
	v_exp_f32_e32 v144, v144
	v_add_co_u32_e32 v154, vcc, s30, v76
	v_add_f32_e32 v144, 1.0, v144
	v_log_f32_e32 v144, v144
	v_addc_co_u32_e32 v155, vcc, 0, v77, vcc
	global_load_dwordx2 v[164:165], v[154:155], off offset:2048
	v_fmac_f32_e32 v146, 0xbf317218, v144
	v_min_f32_e32 v144, 0, v145
	v_mul_f32_e64 v145, |v145|, s93
	v_exp_f32_e32 v145, v145
	v_fmac_f32_e32 v85, 0x3d800000, v146
	global_load_dwordx4 v[154:157], v3, s[0:1] offset:16
	s_add_u32 s0, s6, 0x51400
	v_add_f32_e32 v145, 1.0, v145
	v_log_f32_e32 v145, v145
	s_addc_u32 s1, s7, 0
	v_fmac_f32_e32 v144, 0xbf317218, v145
	v_mul_f32_e64 v145, |v148|, s93
	v_exp_f32_e32 v145, v145
	v_fmac_f32_e32 v91, 0x3d800000, v144
	v_min_f32_e32 v144, 0, v148
	v_add_f32_e32 v145, 1.0, v145
	v_log_f32_e32 v145, v145
	s_nop 0
	v_fmac_f32_e32 v144, 0xbf317218, v145
	v_mul_f32_e64 v145, |v149|, s93
	v_exp_f32_e32 v145, v145
	v_fmac_f32_e32 v163, 0x3d800000, v144
	v_min_f32_e32 v144, 0, v149
	v_add_f32_e32 v145, 1.0, v145
	v_log_f32_e32 v145, v145
	s_nop 0
	v_fmac_f32_e32 v144, 0xbf317218, v145
	v_sub_f32_e32 v145, v131, v91
	v_mul_f32_e32 v145, 0x3fb8aa3b, v145
	v_exp_f32_e32 v146, v145
	v_sub_f32_e32 v145, v128, v163
	v_fmac_f32_e32 v170, 0x3d800000, v144
	v_mul_f32_e32 v145, 0x3fb8aa3b, v145
	v_exp_f32_e32 v148, v145
	v_sub_f32_e32 v145, v129, v170
	v_mul_f32_e32 v145, 0x3fb8aa3b, v145
	v_exp_f32_e32 v152, v145
	v_mov_b32_e32 v145, 0x4e000
	global_load_dwordx4 v[158:161], v145, s[6:7] offset:2560
	v_sub_f32_e32 v144, v130, v85
	v_mul_f32_e32 v144, 0x3fb8aa3b, v144
	v_exp_f32_e32 v144, v144
	s_waitcnt vmcnt(0)
	v_lshlrev_b32_e32 v162, 16, v158
	v_pk_fma_f32 v[166:167], v[70:71], v[162:163], v[66:67] op_sel_hi:[1,0,1]
	v_pk_fma_f32 v[168:169], v[68:69], v[162:163], v[64:65] op_sel_hi:[1,0,1]
	v_and_b32_e32 v158, 0xffff0000, v158
	v_pk_fma_f32 v[166:167], v[62:63], v[158:159], v[166:167] op_sel_hi:[1,0,1]
	v_pk_fma_f32 v[168:169], v[60:61], v[158:159], v[168:169] op_sel_hi:[1,0,1]
	v_lshlrev_b32_e32 v158, 16, v159
	v_pk_fma_f32 v[166:167], v[58:59], v[158:159], v[166:167] op_sel_hi:[1,0,1]
	v_pk_fma_f32 v[168:169], v[56:57], v[158:159], v[168:169] op_sel_hi:[1,0,1]
	v_and_b32_e32 v158, 0xffff0000, v159
	v_pk_fma_f32 v[166:167], v[54:55], v[158:159], v[166:167] op_sel_hi:[1,0,1]
	v_pk_fma_f32 v[158:159], v[52:53], v[158:159], v[168:169] op_sel_hi:[1,0,1]
	v_lshlrev_b32_e32 v162, 16, v160
	v_pk_fma_f32 v[166:167], v[50:51], v[162:163], v[166:167] op_sel_hi:[1,0,1]
	v_pk_fma_f32 v[158:159], v[48:49], v[162:163], v[158:159] op_sel_hi:[1,0,1]
	v_and_b32_e32 v160, 0xffff0000, v160
	v_pk_fma_f32 v[166:167], v[46:47], v[160:161], v[166:167] op_sel_hi:[1,0,1]
	v_pk_fma_f32 v[158:159], v[44:45], v[160:161], v[158:159] op_sel_hi:[1,0,1]
	v_lshlrev_b32_e32 v160, 16, v161
	v_pk_fma_f32 v[166:167], v[42:43], v[160:161], v[166:167] op_sel_hi:[1,0,1]
	v_pk_fma_f32 v[158:159], v[40:41], v[160:161], v[158:159] op_sel_hi:[1,0,1]
	v_and_b32_e32 v160, 0xffff0000, v161
	v_pk_fma_f32 v[166:167], v[38:39], v[160:161], v[166:167] op_sel_hi:[1,0,1]
	v_pk_fma_f32 v[158:159], v[36:37], v[160:161], v[158:159] op_sel_hi:[1,0,1]
	v_lshlrev_b32_e32 v160, 16, v154
	v_pk_fma_f32 v[166:167], v[34:35], v[160:161], v[166:167] op_sel_hi:[1,0,1]
	v_pk_fma_f32 v[158:159], v[32:33], v[160:161], v[158:159] op_sel_hi:[1,0,1]
	v_and_b32_e32 v154, 0xffff0000, v154
	v_pk_fma_f32 v[160:161], v[30:31], v[154:155], v[166:167] op_sel_hi:[1,0,1]
	v_pk_fma_f32 v[158:159], v[28:29], v[154:155], v[158:159] op_sel_hi:[1,0,1]
	v_lshlrev_b32_e32 v154, 16, v155
	v_pk_fma_f32 v[160:161], v[26:27], v[154:155], v[160:161] op_sel_hi:[1,0,1]
	v_pk_fma_f32 v[158:159], v[24:25], v[154:155], v[158:159] op_sel_hi:[1,0,1]
	v_and_b32_e32 v154, 0xffff0000, v155
	v_pk_fma_f32 v[160:161], v[22:23], v[154:155], v[160:161] op_sel_hi:[1,0,1]
	v_pk_fma_f32 v[154:155], v[20:21], v[154:155], v[158:159] op_sel_hi:[1,0,1]
	v_lshlrev_b32_e32 v158, 16, v156
	v_pk_fma_f32 v[160:161], v[18:19], v[158:159], v[160:161] op_sel_hi:[1,0,1]
	v_pk_fma_f32 v[154:155], v[16:17], v[158:159], v[154:155] op_sel_hi:[1,0,1]
	v_and_b32_e32 v156, 0xffff0000, v156
	v_pk_fma_f32 v[158:159], v[14:15], v[156:157], v[160:161] op_sel_hi:[1,0,1]
	v_pk_fma_f32 v[154:155], v[12:13], v[156:157], v[154:155] op_sel_hi:[1,0,1]
	v_lshlrev_b32_e32 v156, 16, v157
	v_pk_fma_f32 v[158:159], v[10:11], v[156:157], v[158:159] op_sel_hi:[1,0,1]
	v_pk_fma_f32 v[154:155], v[8:9], v[156:157], v[154:155] op_sel_hi:[1,0,1]
	v_and_b32_e32 v156, 0xffff0000, v157
	v_pk_fma_f32 v[154:155], v[4:5], v[156:157], v[154:155] op_sel_hi:[1,0,1]
	v_pk_fma_f32 v[158:159], v[6:7], v[156:157], v[158:159] op_sel_hi:[1,0,1]
	v_mul_f32_e64 v147, |v154|, s93
	v_exp_f32_e32 v147, v147
	v_min_f32_e32 v145, 0, v154
	v_lshlrev_b32_e32 v154, 16, v150
	v_add_f32_e32 v147, 1.0, v147
	v_log_f32_e32 v147, v147
	s_nop 0
	v_fmac_f32_e32 v145, 0xbf317218, v147
	v_mul_f32_e64 v147, |v155|, s93
	v_exp_f32_e32 v147, v147
	v_fmac_f32_e32 v85, 0x3d800000, v145
	v_min_f32_e32 v145, 0, v155
	v_lshlrev_b32_e32 v155, 16, v164
	v_add_f32_e32 v147, 1.0, v147
	v_log_f32_e32 v147, v147
	s_nop 0
	v_fmac_f32_e32 v145, 0xbf317218, v147
	v_mul_f32_e64 v147, |v158|, s93
	v_exp_f32_e32 v147, v147
	v_fmac_f32_e32 v91, 0x3d800000, v145
	v_min_f32_e32 v145, 0, v158
	v_mov_b32_e32 v158, 0x51000
	v_add_f32_e32 v147, 1.0, v147
	v_log_f32_e32 v147, v147
	s_nop 0
	v_fmac_f32_e32 v145, 0xbf317218, v147
	v_mul_f32_e64 v147, |v159|, s93
	v_exp_f32_e32 v147, v147
	v_fmac_f32_e32 v163, 0x3d800000, v145
	v_min_f32_e32 v145, 0, v159
	global_load_dwordx4 v[158:161], v158, s[6:7] offset:1024
	v_add_f32_e32 v147, 1.0, v147
	v_log_f32_e32 v147, v147
	v_sub_f32_e32 v149, v128, v163
	v_mul_f32_e32 v149, 0x3fb8aa3b, v149
	v_exp_f32_e32 v149, v149
	v_fmac_f32_e32 v145, 0xbf317218, v147
	v_fmac_f32_e32 v170, 0x3d800000, v145
	v_sub_f32_e32 v145, v130, v85
	v_mul_f32_e32 v145, 0x3fb8aa3b, v145
	v_exp_f32_e32 v145, v145
	v_sub_f32_e32 v147, v131, v91
	v_mul_f32_e32 v147, 0x3fb8aa3b, v147
	v_exp_f32_e32 v147, v147
	v_pk_mul_f32 v[144:145], v[144:145], v[154:155]
	v_and_b32_e32 v154, 0xffff0000, v150
	v_sub_f32_e32 v150, v129, v170
	v_mul_f32_e32 v150, 0x3fb8aa3b, v150
	v_exp_f32_e32 v153, v150
	v_and_b32_e32 v155, 0xffff0000, v164
	v_pk_mul_f32 v[146:147], v[146:147], v[154:155]
	v_lshlrev_b32_e32 v155, 16, v165
	v_lshlrev_b32_e32 v154, 16, v151
	v_pk_mul_f32 v[148:149], v[148:149], v[154:155]
	v_and_b32_e32 v155, 0xffff0000, v165
	v_and_b32_e32 v154, 0xffff0000, v151
	v_pk_mul_f32 v[150:151], v[152:153], v[154:155]
	global_load_dwordx4 v[154:157], v3, s[0:1] offset:16
	v_add_co_u32_e32 v152, vcc, s31, v76
	s_mov_b32 s0, 0x51000
	s_nop 0
	v_addc_co_u32_e32 v153, vcc, 0, v77, vcc
	global_load_dwordx2 v[152:153], v[152:153], off offset:512
	s_waitcnt vmcnt(2)
	v_lshlrev_b32_e32 v162, 16, v158
	v_pk_fma_f32 v[164:165], v[70:71], v[162:163], v[66:67] op_sel_hi:[1,0,1]
	v_pk_fma_f32 v[166:167], v[68:69], v[162:163], v[64:65] op_sel_hi:[1,0,1]
	v_and_b32_e32 v158, 0xffff0000, v158
	v_pk_fma_f32 v[164:165], v[62:63], v[158:159], v[164:165] op_sel_hi:[1,0,1]
	v_pk_fma_f32 v[166:167], v[60:61], v[158:159], v[166:167] op_sel_hi:[1,0,1]
	v_lshlrev_b32_e32 v158, 16, v159
	v_pk_fma_f32 v[164:165], v[58:59], v[158:159], v[164:165] op_sel_hi:[1,0,1]
	v_pk_fma_f32 v[166:167], v[56:57], v[158:159], v[166:167] op_sel_hi:[1,0,1]
	v_and_b32_e32 v158, 0xffff0000, v159
	v_pk_fma_f32 v[164:165], v[54:55], v[158:159], v[164:165] op_sel_hi:[1,0,1]
	v_pk_fma_f32 v[158:159], v[52:53], v[158:159], v[166:167] op_sel_hi:[1,0,1]
	v_lshlrev_b32_e32 v162, 16, v160
	v_pk_fma_f32 v[164:165], v[50:51], v[162:163], v[164:165] op_sel_hi:[1,0,1]
	v_pk_fma_f32 v[158:159], v[48:49], v[162:163], v[158:159] op_sel_hi:[1,0,1]
	v_and_b32_e32 v160, 0xffff0000, v160
	v_pk_fma_f32 v[164:165], v[46:47], v[160:161], v[164:165] op_sel_hi:[1,0,1]
	v_pk_fma_f32 v[158:159], v[44:45], v[160:161], v[158:159] op_sel_hi:[1,0,1]
	v_lshlrev_b32_e32 v160, 16, v161
	v_pk_fma_f32 v[164:165], v[42:43], v[160:161], v[164:165] op_sel_hi:[1,0,1]
	v_pk_fma_f32 v[158:159], v[40:41], v[160:161], v[158:159] op_sel_hi:[1,0,1]
	v_and_b32_e32 v160, 0xffff0000, v161
	v_pk_fma_f32 v[164:165], v[38:39], v[160:161], v[164:165] op_sel_hi:[1,0,1]
	v_pk_fma_f32 v[158:159], v[36:37], v[160:161], v[158:159] op_sel_hi:[1,0,1]
	s_waitcnt vmcnt(1)
	v_lshlrev_b32_e32 v160, 16, v154
	v_pk_fma_f32 v[164:165], v[34:35], v[160:161], v[164:165] op_sel_hi:[1,0,1]
	v_pk_fma_f32 v[158:159], v[32:33], v[160:161], v[158:159] op_sel_hi:[1,0,1]
	v_and_b32_e32 v154, 0xffff0000, v154
	v_pk_fma_f32 v[160:161], v[30:31], v[154:155], v[164:165] op_sel_hi:[1,0,1]
	v_pk_fma_f32 v[158:159], v[28:29], v[154:155], v[158:159] op_sel_hi:[1,0,1]
	v_lshlrev_b32_e32 v154, 16, v155
	v_pk_fma_f32 v[160:161], v[26:27], v[154:155], v[160:161] op_sel_hi:[1,0,1]
	v_pk_fma_f32 v[158:159], v[24:25], v[154:155], v[158:159] op_sel_hi:[1,0,1]
	v_and_b32_e32 v154, 0xffff0000, v155
	v_pk_fma_f32 v[160:161], v[22:23], v[154:155], v[160:161] op_sel_hi:[1,0,1]
	v_pk_fma_f32 v[154:155], v[20:21], v[154:155], v[158:159] op_sel_hi:[1,0,1]
	v_lshlrev_b32_e32 v158, 16, v156
	v_pk_fma_f32 v[160:161], v[18:19], v[158:159], v[160:161] op_sel_hi:[1,0,1]
	v_pk_fma_f32 v[154:155], v[16:17], v[158:159], v[154:155] op_sel_hi:[1,0,1]
	v_and_b32_e32 v156, 0xffff0000, v156
	v_pk_fma_f32 v[158:159], v[14:15], v[156:157], v[160:161] op_sel_hi:[1,0,1]
	v_pk_fma_f32 v[154:155], v[12:13], v[156:157], v[154:155] op_sel_hi:[1,0,1]
	v_lshlrev_b32_e32 v156, 16, v157
	v_pk_fma_f32 v[158:159], v[10:11], v[156:157], v[158:159] op_sel_hi:[1,0,1]
	v_pk_fma_f32 v[154:155], v[8:9], v[156:157], v[154:155] op_sel_hi:[1,0,1]
	v_and_b32_e32 v156, 0xffff0000, v157
	v_pk_fma_f32 v[154:155], v[4:5], v[156:157], v[154:155] op_sel_hi:[1,0,1]
	v_pk_fma_f32 v[158:159], v[6:7], v[156:157], v[158:159] op_sel_hi:[1,0,1]
	v_min_f32_e32 v156, 0, v154
	v_mul_f32_e64 v154, |v154|, s93
	v_exp_f32_e32 v154, v154
	v_add_co_u32_e32 v164, vcc, s0, v76
	s_add_u32 s0, s6, 0x53e00
	v_add_f32_e32 v154, 1.0, v154
	v_log_f32_e32 v154, v154
	v_addc_co_u32_e32 v165, vcc, 0, v77, vcc
	s_addc_u32 s1, s7, 0
	v_fmac_f32_e32 v156, 0xbf317218, v154
	v_min_f32_e32 v154, 0, v155
	v_mul_f32_e64 v155, |v155|, s93
	v_exp_f32_e32 v155, v155
	global_load_dwordx2 v[168:169], v[164:165], off offset:3072
	v_fmac_f32_e32 v85, 0x3d800000, v156
	global_load_dwordx4 v[164:167], v3, s[0:1] offset:16
	v_add_f32_e32 v155, 1.0, v155
	v_log_f32_e32 v155, v155
	s_add_u32 s0, s6, 0x56800
	s_addc_u32 s1, s7, 0
	v_fmac_f32_e32 v154, 0xbf317218, v155
	v_mul_f32_e64 v155, |v158|, s93
	v_exp_f32_e32 v155, v155
	v_fmac_f32_e32 v91, 0x3d800000, v154
	v_min_f32_e32 v154, 0, v158
	v_add_f32_e32 v155, 1.0, v155
	v_log_f32_e32 v155, v155
	s_nop 0
	v_fmac_f32_e32 v154, 0xbf317218, v155
	v_mul_f32_e64 v155, |v159|, s93
	v_exp_f32_e32 v155, v155
	v_fmac_f32_e32 v163, 0x3d800000, v154
	v_min_f32_e32 v154, 0, v159
	v_add_f32_e32 v155, 1.0, v155
	v_log_f32_e32 v155, v155
	s_nop 0
	v_fmac_f32_e32 v154, 0xbf317218, v155
	v_mov_b32_e32 v155, 0x53000
	global_load_dwordx4 v[172:175], v155, s[6:7] offset:3584
	v_fmac_f32_e32 v170, 0x3d800000, v154
	v_sub_f32_e32 v154, v130, v85
	v_mul_f32_e32 v154, 0x3fb8aa3b, v154
	v_exp_f32_e32 v160, v154
	v_sub_f32_e32 v154, v131, v91
	v_mul_f32_e32 v154, 0x3fb8aa3b, v154
	v_exp_f32_e32 v158, v154
	v_sub_f32_e32 v154, v128, v163
	v_mul_f32_e32 v154, 0x3fb8aa3b, v154
	v_exp_f32_e32 v156, v154
	v_sub_f32_e32 v154, v129, v170
	v_mul_f32_e32 v154, 0x3fb8aa3b, v154
	v_exp_f32_e32 v154, v154
	s_waitcnt vmcnt(0)
	v_lshlrev_b32_e32 v162, 16, v172
	v_pk_fma_f32 v[176:177], v[70:71], v[162:163], v[66:67] op_sel_hi:[1,0,1]
	v_pk_fma_f32 v[178:179], v[68:69], v[162:163], v[64:65] op_sel_hi:[1,0,1]
	v_and_b32_e32 v162, 0xffff0000, v172
	v_pk_fma_f32 v[176:177], v[62:63], v[162:163], v[176:177] op_sel_hi:[1,0,1]
	v_pk_fma_f32 v[178:179], v[60:61], v[162:163], v[178:179] op_sel_hi:[1,0,1]
	v_lshlrev_b32_e32 v162, 16, v173
	v_pk_fma_f32 v[176:177], v[58:59], v[162:163], v[176:177] op_sel_hi:[1,0,1]
	v_pk_fma_f32 v[178:179], v[56:57], v[162:163], v[178:179] op_sel_hi:[1,0,1]
	v_and_b32_e32 v162, 0xffff0000, v173
	v_pk_fma_f32 v[172:173], v[54:55], v[162:163], v[176:177] op_sel_hi:[1,0,1]
	v_pk_fma_f32 v[176:177], v[52:53], v[162:163], v[178:179] op_sel_hi:[1,0,1]
	v_lshlrev_b32_e32 v162, 16, v174
	v_pk_fma_f32 v[172:173], v[50:51], v[162:163], v[172:173] op_sel_hi:[1,0,1]
	v_pk_fma_f32 v[176:177], v[48:49], v[162:163], v[176:177] op_sel_hi:[1,0,1]
	v_and_b32_e32 v162, 0xffff0000, v174
	v_pk_fma_f32 v[172:173], v[46:47], v[162:163], v[172:173] op_sel_hi:[1,0,1]
	v_pk_fma_f32 v[176:177], v[44:45], v[162:163], v[176:177] op_sel_hi:[1,0,1]
	v_lshlrev_b32_e32 v162, 16, v175
	v_pk_fma_f32 v[172:173], v[42:43], v[162:163], v[172:173] op_sel_hi:[1,0,1]
	v_pk_fma_f32 v[176:177], v[40:41], v[162:163], v[176:177] op_sel_hi:[1,0,1]
	v_and_b32_e32 v162, 0xffff0000, v175
	v_pk_fma_f32 v[172:173], v[38:39], v[162:163], v[172:173] op_sel_hi:[1,0,1]
	v_pk_fma_f32 v[174:175], v[36:37], v[162:163], v[176:177] op_sel_hi:[1,0,1]
	v_lshlrev_b32_e32 v162, 16, v164
	v_pk_fma_f32 v[172:173], v[34:35], v[162:163], v[172:173] op_sel_hi:[1,0,1]
	v_pk_fma_f32 v[174:175], v[32:33], v[162:163], v[174:175] op_sel_hi:[1,0,1]
	v_and_b32_e32 v162, 0xffff0000, v164
	v_pk_fma_f32 v[172:173], v[30:31], v[162:163], v[172:173] op_sel_hi:[1,0,1]
	v_pk_fma_f32 v[174:175], v[28:29], v[162:163], v[174:175] op_sel_hi:[1,0,1]
	v_lshlrev_b32_e32 v162, 16, v165
	v_pk_fma_f32 v[172:173], v[26:27], v[162:163], v[172:173] op_sel_hi:[1,0,1]
	v_pk_fma_f32 v[174:175], v[24:25], v[162:163], v[174:175] op_sel_hi:[1,0,1]
	v_and_b32_e32 v162, 0xffff0000, v165
	v_pk_fma_f32 v[164:165], v[22:23], v[162:163], v[172:173] op_sel_hi:[1,0,1]
	v_pk_fma_f32 v[172:173], v[20:21], v[162:163], v[174:175] op_sel_hi:[1,0,1]
	v_lshlrev_b32_e32 v162, 16, v166
	v_pk_fma_f32 v[164:165], v[18:19], v[162:163], v[164:165] op_sel_hi:[1,0,1]
	v_pk_fma_f32 v[172:173], v[16:17], v[162:163], v[172:173] op_sel_hi:[1,0,1]
	v_and_b32_e32 v162, 0xffff0000, v166
	v_pk_fma_f32 v[164:165], v[14:15], v[162:163], v[164:165] op_sel_hi:[1,0,1]
	v_pk_fma_f32 v[172:173], v[12:13], v[162:163], v[172:173] op_sel_hi:[1,0,1]
	v_lshlrev_b32_e32 v162, 16, v167
	v_pk_fma_f32 v[164:165], v[10:11], v[162:163], v[164:165] op_sel_hi:[1,0,1]
	v_pk_fma_f32 v[172:173], v[8:9], v[162:163], v[172:173] op_sel_hi:[1,0,1]
	v_and_b32_e32 v162, 0xffff0000, v167
	v_pk_fma_f32 v[166:167], v[4:5], v[162:163], v[172:173] op_sel_hi:[1,0,1]
	v_pk_fma_f32 v[164:165], v[6:7], v[162:163], v[164:165] op_sel_hi:[1,0,1]
	v_mul_f32_e64 v157, |v166|, s93
	v_exp_f32_e32 v157, v157
	v_min_f32_e32 v155, 0, v166
	v_add_f32_e32 v157, 1.0, v157
	v_log_f32_e32 v157, v157
	s_nop 0
	v_fmac_f32_e32 v155, 0xbf317218, v157
	v_mul_f32_e64 v157, |v167|, s93
	v_exp_f32_e32 v157, v157
	v_fmac_f32_e32 v85, 0x3d800000, v155
	v_min_f32_e32 v155, 0, v167
	v_add_f32_e32 v157, 1.0, v157
	v_log_f32_e32 v157, v157
	s_nop 0
	v_fmac_f32_e32 v155, 0xbf317218, v157
	v_mul_f32_e64 v157, |v164|, s93
	v_exp_f32_e32 v157, v157
	v_fmac_f32_e32 v91, 0x3d800000, v155
	v_min_f32_e32 v155, 0, v164
	v_lshlrev_b32_e32 v164, 16, v152
	v_add_f32_e32 v157, 1.0, v157
	v_log_f32_e32 v157, v157
	s_nop 0
	v_fmac_f32_e32 v155, 0xbf317218, v157
	v_mul_f32_e64 v157, |v165|, s93
	v_exp_f32_e32 v157, v157
	v_fmac_f32_e32 v163, 0x3d800000, v155
	v_min_f32_e32 v155, 0, v165
	v_lshlrev_b32_e32 v165, 16, v168
	v_add_f32_e32 v157, 1.0, v157
	v_log_f32_e32 v157, v157
	s_nop 0
	v_fmac_f32_e32 v155, 0xbf317218, v157
	v_fmac_f32_e32 v170, 0x3d800000, v155
	v_sub_f32_e32 v155, v130, v85
	v_mul_f32_e32 v155, 0x3fb8aa3b, v155
	v_exp_f32_e32 v161, v155
	v_sub_f32_e32 v155, v131, v91
	v_mul_f32_e32 v155, 0x3fb8aa3b, v155
	v_exp_f32_e32 v159, v155
	v_pk_mul_f32 v[160:161], v[160:161], v[164:165]
	v_and_b32_e32 v164, 0xffff0000, v152
	v_sub_f32_e32 v152, v128, v163
	v_mul_f32_e32 v152, 0x3fb8aa3b, v152
	v_exp_f32_e32 v157, v152
	v_sub_f32_e32 v152, v129, v170
	v_mul_f32_e32 v152, 0x3fb8aa3b, v152
	v_exp_f32_e32 v155, v152
	v_and_b32_e32 v165, 0xffff0000, v168
	v_pk_mul_f32 v[158:159], v[158:159], v[164:165]
	v_lshlrev_b32_e32 v165, 16, v169
	v_lshlrev_b32_e32 v164, 16, v153
	v_pk_mul_f32 v[156:157], v[156:157], v[164:165]
	v_and_b32_e32 v165, 0xffff0000, v169
	v_and_b32_e32 v164, 0xffff0000, v153
	v_cvt_pk_bf16_f32 v152, v72, v73
	v_cvt_pk_bf16_f32 v72, v74, v75
	v_cvt_pk_bf16_f32 v73, v138, v139
	v_cvt_pk_bf16_f32 v74, v146, v147
	v_cvt_pk_bf16_f32 v75, v158, v159
	v_pk_mul_f32 v[164:165], v[154:155], v[164:165]
	global_store_dwordx4 v[132:133], v[72:75], off offset:1552
	v_cvt_pk_bf16_f32 v153, v136, v137
	v_cvt_pk_bf16_f32 v154, v144, v145
	v_cvt_pk_bf16_f32 v72, v78, v79
	v_cvt_pk_bf16_f32 v73, v140, v141
	v_cvt_pk_bf16_f32 v74, v148, v149
	v_cvt_pk_bf16_f32 v75, v156, v157
	v_cvt_pk_bf16_f32 v155, v160, v161
	global_store_dwordx4 v[132:133], v[72:75], off offset:1568
	global_store_dwordx4 v[132:133], v[152:155], off offset:1536
	v_mov_b32_e32 v78, 0x56000
	v_cvt_pk_bf16_f32 v72, v134, v135
	v_cvt_pk_bf16_f32 v73, v142, v143
	v_cvt_pk_bf16_f32 v74, v150, v151
	v_cvt_pk_bf16_f32 v75, v164, v165
	global_store_dwordx4 v[132:133], v[72:75], off offset:1584
	global_load_dwordx4 v[136:139], v78, s[6:7] offset:2048
	s_waitcnt vmcnt(0)
	v_lshlrev_b32_e32 v78, 16, v136
	v_add_co_u32_e32 v72, vcc, s34, v76
	v_pk_fma_f32 v[140:141], v[70:71], v[78:79], v[66:67] op_sel_hi:[1,0,1]
	s_nop 0
	v_addc_co_u32_e32 v73, vcc, 0, v77, vcc
	global_load_dwordx2 v[134:135], v[72:73], off offset:1536
	v_pk_fma_f32 v[78:79], v[68:69], v[78:79], v[64:65] op_sel_hi:[1,0,1]
	global_load_dwordx4 v[72:75], v3, s[0:1] offset:16
	v_and_b32_e32 v136, 0xffff0000, v136
	v_pk_fma_f32 v[140:141], v[62:63], v[136:137], v[140:141] op_sel_hi:[1,0,1]
	v_pk_fma_f32 v[78:79], v[60:61], v[136:137], v[78:79] op_sel_hi:[1,0,1]
	v_lshlrev_b32_e32 v136, 16, v137
	v_pk_fma_f32 v[140:141], v[58:59], v[136:137], v[140:141] op_sel_hi:[1,0,1]
	v_pk_fma_f32 v[78:79], v[56:57], v[136:137], v[78:79] op_sel_hi:[1,0,1]
	v_and_b32_e32 v136, 0xffff0000, v137
	v_pk_fma_f32 v[140:141], v[54:55], v[136:137], v[140:141] op_sel_hi:[1,0,1]
	v_pk_fma_f32 v[78:79], v[52:53], v[136:137], v[78:79] op_sel_hi:[1,0,1]
	v_lshlrev_b32_e32 v136, 16, v138
	v_pk_fma_f32 v[140:141], v[50:51], v[136:137], v[140:141] op_sel_hi:[1,0,1]
	v_pk_fma_f32 v[78:79], v[48:49], v[136:137], v[78:79] op_sel_hi:[1,0,1]
	v_and_b32_e32 v136, 0xffff0000, v138
	v_pk_fma_f32 v[140:141], v[46:47], v[136:137], v[140:141] op_sel_hi:[1,0,1]
	v_pk_fma_f32 v[78:79], v[44:45], v[136:137], v[78:79] op_sel_hi:[1,0,1]
	v_lshlrev_b32_e32 v136, 16, v139
	v_pk_fma_f32 v[140:141], v[42:43], v[136:137], v[140:141] op_sel_hi:[1,0,1]
	v_pk_fma_f32 v[78:79], v[40:41], v[136:137], v[78:79] op_sel_hi:[1,0,1]
	v_and_b32_e32 v136, 0xffff0000, v139
	v_pk_fma_f32 v[138:139], v[38:39], v[136:137], v[140:141] op_sel_hi:[1,0,1]
	v_pk_fma_f32 v[78:79], v[36:37], v[136:137], v[78:79] op_sel_hi:[1,0,1]
	s_add_u32 s0, s6, 0x59200
	s_addc_u32 s1, s7, 0
	s_waitcnt vmcnt(0)
	v_lshlrev_b32_e32 v136, 16, v72
	v_pk_fma_f32 v[138:139], v[34:35], v[136:137], v[138:139] op_sel_hi:[1,0,1]
	v_pk_fma_f32 v[78:79], v[32:33], v[136:137], v[78:79] op_sel_hi:[1,0,1]
	v_and_b32_e32 v72, 0xffff0000, v72
	v_pk_fma_f32 v[136:137], v[30:31], v[72:73], v[138:139] op_sel_hi:[1,0,1]
	v_pk_fma_f32 v[78:79], v[28:29], v[72:73], v[78:79] op_sel_hi:[1,0,1]
	v_lshlrev_b32_e32 v72, 16, v73
	v_pk_fma_f32 v[136:137], v[26:27], v[72:73], v[136:137] op_sel_hi:[1,0,1]
	v_pk_fma_f32 v[78:79], v[24:25], v[72:73], v[78:79] op_sel_hi:[1,0,1]
	v_and_b32_e32 v72, 0xffff0000, v73
	v_pk_fma_f32 v[136:137], v[22:23], v[72:73], v[136:137] op_sel_hi:[1,0,1]
	v_pk_fma_f32 v[72:73], v[20:21], v[72:73], v[78:79] op_sel_hi:[1,0,1]
	v_lshlrev_b32_e32 v78, 16, v74
	v_pk_fma_f32 v[136:137], v[18:19], v[78:79], v[136:137] op_sel_hi:[1,0,1]
	v_pk_fma_f32 v[72:73], v[16:17], v[78:79], v[72:73] op_sel_hi:[1,0,1]
	v_and_b32_e32 v74, 0xffff0000, v74
	v_pk_fma_f32 v[78:79], v[14:15], v[74:75], v[136:137] op_sel_hi:[1,0,1]
	v_pk_fma_f32 v[72:73], v[12:13], v[74:75], v[72:73] op_sel_hi:[1,0,1]
	v_lshlrev_b32_e32 v74, 16, v75
	v_pk_fma_f32 v[78:79], v[10:11], v[74:75], v[78:79] op_sel_hi:[1,0,1]
	v_pk_fma_f32 v[72:73], v[8:9], v[74:75], v[72:73] op_sel_hi:[1,0,1]
	v_and_b32_e32 v74, 0xffff0000, v75
	v_pk_fma_f32 v[72:73], v[4:5], v[74:75], v[72:73] op_sel_hi:[1,0,1]
	v_pk_fma_f32 v[78:79], v[6:7], v[74:75], v[78:79] op_sel_hi:[1,0,1]
	v_min_f32_e32 v74, 0, v72
	v_mul_f32_e64 v72, |v72|, s93
	v_exp_f32_e32 v72, v72
	v_add_co_u32_e32 v138, vcc, s35, v76
	v_add_f32_e32 v72, 1.0, v72
	v_log_f32_e32 v72, v72
	v_addc_co_u32_e32 v139, vcc, 0, v77, vcc
	global_load_dwordx2 v[146:147], v[138:139], off
	v_fmac_f32_e32 v74, 0xbf317218, v72
	v_min_f32_e32 v72, 0, v73
	v_mul_f32_e64 v73, |v73|, s93
	v_exp_f32_e32 v73, v73
	v_fmac_f32_e32 v85, 0x3d800000, v74
	global_load_dwordx4 v[138:141], v3, s[0:1] offset:16
	s_mov_b32 s0, 0x59000
	v_add_f32_e32 v73, 1.0, v73
	v_log_f32_e32 v73, v73
	s_nop 0
	v_fmac_f32_e32 v72, 0xbf317218, v73
	v_mul_f32_e64 v73, |v78|, s93
	v_exp_f32_e32 v73, v73
	v_fmac_f32_e32 v91, 0x3d800000, v72
	v_min_f32_e32 v72, 0, v78
	v_add_f32_e32 v73, 1.0, v73
	v_log_f32_e32 v73, v73
	s_nop 0
	v_fmac_f32_e32 v72, 0xbf317218, v73
	v_mul_f32_e64 v73, |v79|, s93
	v_exp_f32_e32 v73, v73
	v_fmac_f32_e32 v163, 0x3d800000, v72
	v_min_f32_e32 v72, 0, v79
	v_add_f32_e32 v73, 1.0, v73
	v_log_f32_e32 v73, v73
	s_nop 0
	v_fmac_f32_e32 v72, 0xbf317218, v73
	v_sub_f32_e32 v73, v131, v91
	v_mul_f32_e32 v73, 0x3fb8aa3b, v73
	v_exp_f32_e32 v74, v73
	v_sub_f32_e32 v73, v128, v163
	v_fmac_f32_e32 v170, 0x3d800000, v72
	v_mul_f32_e32 v73, 0x3fb8aa3b, v73
	v_exp_f32_e32 v78, v73
	v_sub_f32_e32 v73, v129, v170
	v_mul_f32_e32 v73, 0x3fb8aa3b, v73
	v_exp_f32_e32 v136, v73
	v_mov_b32_e32 v73, 0x59000
	global_load_dwordx4 v[142:145], v73, s[6:7] offset:512
	v_sub_f32_e32 v72, v130, v85
	v_mul_f32_e32 v72, 0x3fb8aa3b, v72
	v_exp_f32_e32 v72, v72
	s_waitcnt vmcnt(0)
	v_lshlrev_b32_e32 v148, 16, v142
	v_pk_fma_f32 v[150:151], v[70:71], v[148:149], v[66:67] op_sel_hi:[1,0,1]
	v_pk_fma_f32 v[148:149], v[68:69], v[148:149], v[64:65] op_sel_hi:[1,0,1]
	v_and_b32_e32 v142, 0xffff0000, v142
	v_pk_fma_f32 v[150:151], v[62:63], v[142:143], v[150:151] op_sel_hi:[1,0,1]
	v_pk_fma_f32 v[148:149], v[60:61], v[142:143], v[148:149] op_sel_hi:[1,0,1]
	v_lshlrev_b32_e32 v142, 16, v143
	v_pk_fma_f32 v[150:151], v[58:59], v[142:143], v[150:151] op_sel_hi:[1,0,1]
	v_pk_fma_f32 v[148:149], v[56:57], v[142:143], v[148:149] op_sel_hi:[1,0,1]
	v_and_b32_e32 v142, 0xffff0000, v143
	v_pk_fma_f32 v[150:151], v[54:55], v[142:143], v[150:151] op_sel_hi:[1,0,1]
	v_pk_fma_f32 v[142:143], v[52:53], v[142:143], v[148:149] op_sel_hi:[1,0,1]
	v_lshlrev_b32_e32 v148, 16, v144
	v_pk_fma_f32 v[150:151], v[50:51], v[148:149], v[150:151] op_sel_hi:[1,0,1]
	v_pk_fma_f32 v[142:143], v[48:49], v[148:149], v[142:143] op_sel_hi:[1,0,1]
	v_and_b32_e32 v144, 0xffff0000, v144
	v_pk_fma_f32 v[148:149], v[46:47], v[144:145], v[150:151] op_sel_hi:[1,0,1]
	v_pk_fma_f32 v[142:143], v[44:45], v[144:145], v[142:143] op_sel_hi:[1,0,1]
	v_lshlrev_b32_e32 v144, 16, v145
	v_pk_fma_f32 v[148:149], v[42:43], v[144:145], v[148:149] op_sel_hi:[1,0,1]
	v_pk_fma_f32 v[142:143], v[40:41], v[144:145], v[142:143] op_sel_hi:[1,0,1]
	v_and_b32_e32 v144, 0xffff0000, v145
	v_pk_fma_f32 v[148:149], v[38:39], v[144:145], v[148:149] op_sel_hi:[1,0,1]
	v_pk_fma_f32 v[142:143], v[36:37], v[144:145], v[142:143] op_sel_hi:[1,0,1]
	v_lshlrev_b32_e32 v144, 16, v138
	v_pk_fma_f32 v[148:149], v[34:35], v[144:145], v[148:149] op_sel_hi:[1,0,1]
	v_pk_fma_f32 v[142:143], v[32:33], v[144:145], v[142:143] op_sel_hi:[1,0,1]
	v_and_b32_e32 v138, 0xffff0000, v138
	v_pk_fma_f32 v[144:145], v[30:31], v[138:139], v[148:149] op_sel_hi:[1,0,1]
	v_pk_fma_f32 v[142:143], v[28:29], v[138:139], v[142:143] op_sel_hi:[1,0,1]
	v_lshlrev_b32_e32 v138, 16, v139
	v_pk_fma_f32 v[144:145], v[26:27], v[138:139], v[144:145] op_sel_hi:[1,0,1]
	v_pk_fma_f32 v[142:143], v[24:25], v[138:139], v[142:143] op_sel_hi:[1,0,1]
	v_and_b32_e32 v138, 0xffff0000, v139
	v_pk_fma_f32 v[144:145], v[22:23], v[138:139], v[144:145] op_sel_hi:[1,0,1]
	v_pk_fma_f32 v[138:139], v[20:21], v[138:139], v[142:143] op_sel_hi:[1,0,1]
	v_lshlrev_b32_e32 v142, 16, v140
	v_pk_fma_f32 v[144:145], v[18:19], v[142:143], v[144:145] op_sel_hi:[1,0,1]
	v_pk_fma_f32 v[138:139], v[16:17], v[142:143], v[138:139] op_sel_hi:[1,0,1]
	v_and_b32_e32 v140, 0xffff0000, v140
	v_pk_fma_f32 v[142:143], v[14:15], v[140:141], v[144:145] op_sel_hi:[1,0,1]
	v_pk_fma_f32 v[138:139], v[12:13], v[140:141], v[138:139] op_sel_hi:[1,0,1]
	v_lshlrev_b32_e32 v140, 16, v141
	v_pk_fma_f32 v[142:143], v[10:11], v[140:141], v[142:143] op_sel_hi:[1,0,1]
	v_pk_fma_f32 v[138:139], v[8:9], v[140:141], v[138:139] op_sel_hi:[1,0,1]
	v_and_b32_e32 v140, 0xffff0000, v141
	v_pk_fma_f32 v[138:139], v[4:5], v[140:141], v[138:139] op_sel_hi:[1,0,1]
	v_pk_fma_f32 v[142:143], v[6:7], v[140:141], v[142:143] op_sel_hi:[1,0,1]
	v_mul_f32_e64 v75, |v138|, s93
	v_exp_f32_e32 v75, v75
	v_min_f32_e32 v73, 0, v138
	v_lshlrev_b32_e32 v138, 16, v134
	v_mov_b32_e32 v140, 0x5b000
	v_add_f32_e32 v75, 1.0, v75
	v_log_f32_e32 v75, v75
	s_nop 0
	v_fmac_f32_e32 v73, 0xbf317218, v75
	v_mul_f32_e64 v75, |v139|, s93
	v_exp_f32_e32 v75, v75
	v_fmac_f32_e32 v85, 0x3d800000, v73
	v_min_f32_e32 v73, 0, v139
	v_lshlrev_b32_e32 v139, 16, v146
	v_add_f32_e32 v75, 1.0, v75
	v_log_f32_e32 v75, v75
	s_nop 0
	v_fmac_f32_e32 v73, 0xbf317218, v75
	v_mul_f32_e64 v75, |v142|, s93
	v_exp_f32_e32 v75, v75
	v_fmac_f32_e32 v91, 0x3d800000, v73
	v_min_f32_e32 v73, 0, v142
	v_add_f32_e32 v75, 1.0, v75
	v_log_f32_e32 v75, v75
	s_nop 0
	v_fmac_f32_e32 v73, 0xbf317218, v75
	v_mul_f32_e64 v75, |v143|, s93
	v_exp_f32_e32 v75, v75
	v_fmac_f32_e32 v163, 0x3d800000, v73
	v_min_f32_e32 v73, 0, v143
	v_sub_f32_e32 v79, v128, v163
	v_add_f32_e32 v75, 1.0, v75
	v_log_f32_e32 v75, v75
	v_mul_f32_e32 v79, 0x3fb8aa3b, v79
	v_exp_f32_e32 v79, v79
	v_fmac_f32_e32 v73, 0xbf317218, v75
	v_fmac_f32_e32 v170, 0x3d800000, v73
	v_sub_f32_e32 v73, v130, v85
	v_mul_f32_e32 v73, 0x3fb8aa3b, v73
	v_sub_f32_e32 v75, v131, v91
	v_exp_f32_e32 v73, v73
	v_mul_f32_e32 v75, 0x3fb8aa3b, v75
	v_exp_f32_e32 v75, v75
	v_pk_mul_f32 v[72:73], v[72:73], v[138:139]
	v_and_b32_e32 v139, 0xffff0000, v146
	v_and_b32_e32 v138, 0xffff0000, v134
	v_pk_mul_f32 v[74:75], v[74:75], v[138:139]
	v_lshlrev_b32_e32 v139, 16, v147
	v_lshlrev_b32_e32 v138, 16, v135
	v_pk_mul_f32 v[78:79], v[78:79], v[138:139]
	v_sub_f32_e32 v134, v129, v170
	v_and_b32_e32 v139, 0xffff0000, v147
	global_load_dwordx4 v[144:147], v140, s[6:7] offset:3072
	v_mul_f32_e32 v134, 0x3fb8aa3b, v134
	v_exp_f32_e32 v137, v134
	v_and_b32_e32 v138, 0xffff0000, v135
	v_pk_mul_f32 v[134:135], v[136:137], v[138:139]
	v_add_co_u32_e32 v136, vcc, s0, v76
	s_add_u32 s0, s6, 0x5bc00
	s_nop 0
	v_addc_co_u32_e32 v137, vcc, 0, v77, vcc
	s_addc_u32 s1, s7, 0
	global_load_dwordx2 v[142:143], v[136:137], off offset:2560
	s_waitcnt vmcnt(1)
	v_lshlrev_b32_e32 v140, 16, v144
	global_load_dwordx4 v[136:139], v3, s[0:1] offset:16
	v_pk_fma_f32 v[148:149], v[70:71], v[140:141], v[66:67] op_sel_hi:[1,0,1]
	v_pk_fma_f32 v[140:141], v[68:69], v[140:141], v[64:65] op_sel_hi:[1,0,1]
	v_and_b32_e32 v144, 0xffff0000, v144
	v_pk_fma_f32 v[148:149], v[62:63], v[144:145], v[148:149] op_sel_hi:[1,0,1]
	v_pk_fma_f32 v[140:141], v[60:61], v[144:145], v[140:141] op_sel_hi:[1,0,1]
	v_lshlrev_b32_e32 v144, 16, v145
	v_pk_fma_f32 v[148:149], v[58:59], v[144:145], v[148:149] op_sel_hi:[1,0,1]
	v_pk_fma_f32 v[140:141], v[56:57], v[144:145], v[140:141] op_sel_hi:[1,0,1]
	v_and_b32_e32 v144, 0xffff0000, v145
	v_pk_fma_f32 v[148:149], v[54:55], v[144:145], v[148:149] op_sel_hi:[1,0,1]
	v_pk_fma_f32 v[140:141], v[52:53], v[144:145], v[140:141] op_sel_hi:[1,0,1]
	v_lshlrev_b32_e32 v144, 16, v146
	v_pk_fma_f32 v[148:149], v[50:51], v[144:145], v[148:149] op_sel_hi:[1,0,1]
	v_pk_fma_f32 v[140:141], v[48:49], v[144:145], v[140:141] op_sel_hi:[1,0,1]
	v_and_b32_e32 v144, 0xffff0000, v146
	v_pk_fma_f32 v[148:149], v[46:47], v[144:145], v[148:149] op_sel_hi:[1,0,1]
	v_pk_fma_f32 v[140:141], v[44:45], v[144:145], v[140:141] op_sel_hi:[1,0,1]
	v_lshlrev_b32_e32 v144, 16, v147
	v_pk_fma_f32 v[148:149], v[42:43], v[144:145], v[148:149] op_sel_hi:[1,0,1]
	v_pk_fma_f32 v[140:141], v[40:41], v[144:145], v[140:141] op_sel_hi:[1,0,1]
	v_and_b32_e32 v144, 0xffff0000, v147
	v_pk_fma_f32 v[146:147], v[38:39], v[144:145], v[148:149] op_sel_hi:[1,0,1]
	v_pk_fma_f32 v[140:141], v[36:37], v[144:145], v[140:141] op_sel_hi:[1,0,1]
	s_add_u32 s0, s6, 0x5e600
	s_addc_u32 s1, s7, 0
	s_waitcnt vmcnt(0)
	v_lshlrev_b32_e32 v144, 16, v136
	v_pk_fma_f32 v[146:147], v[34:35], v[144:145], v[146:147] op_sel_hi:[1,0,1]
	v_pk_fma_f32 v[140:141], v[32:33], v[144:145], v[140:141] op_sel_hi:[1,0,1]
	v_and_b32_e32 v136, 0xffff0000, v136
	v_pk_fma_f32 v[144:145], v[30:31], v[136:137], v[146:147] op_sel_hi:[1,0,1]
	v_pk_fma_f32 v[140:141], v[28:29], v[136:137], v[140:141] op_sel_hi:[1,0,1]
	v_lshlrev_b32_e32 v136, 16, v137
	v_pk_fma_f32 v[144:145], v[26:27], v[136:137], v[144:145] op_sel_hi:[1,0,1]
	v_pk_fma_f32 v[140:141], v[24:25], v[136:137], v[140:141] op_sel_hi:[1,0,1]
	v_and_b32_e32 v136, 0xffff0000, v137
	v_pk_fma_f32 v[144:145], v[22:23], v[136:137], v[144:145] op_sel_hi:[1,0,1]
	v_pk_fma_f32 v[136:137], v[20:21], v[136:137], v[140:141] op_sel_hi:[1,0,1]
	v_lshlrev_b32_e32 v140, 16, v138
	v_pk_fma_f32 v[144:145], v[18:19], v[140:141], v[144:145] op_sel_hi:[1,0,1]
	v_pk_fma_f32 v[136:137], v[16:17], v[140:141], v[136:137] op_sel_hi:[1,0,1]
	v_and_b32_e32 v138, 0xffff0000, v138
	v_pk_fma_f32 v[140:141], v[14:15], v[138:139], v[144:145] op_sel_hi:[1,0,1]
	v_pk_fma_f32 v[136:137], v[12:13], v[138:139], v[136:137] op_sel_hi:[1,0,1]
	v_lshlrev_b32_e32 v138, 16, v139
	v_pk_fma_f32 v[140:141], v[10:11], v[138:139], v[140:141] op_sel_hi:[1,0,1]
	v_pk_fma_f32 v[136:137], v[8:9], v[138:139], v[136:137] op_sel_hi:[1,0,1]
	v_and_b32_e32 v138, 0xffff0000, v139
	v_pk_fma_f32 v[136:137], v[4:5], v[138:139], v[136:137] op_sel_hi:[1,0,1]
	v_pk_fma_f32 v[140:141], v[6:7], v[138:139], v[140:141] op_sel_hi:[1,0,1]
	v_min_f32_e32 v138, 0, v136
	v_mul_f32_e64 v136, |v136|, s93
	v_exp_f32_e32 v136, v136
	v_add_co_u32_e32 v146, vcc, s46, v76
	v_add_f32_e32 v136, 1.0, v136
	v_log_f32_e32 v136, v136
	v_addc_co_u32_e32 v147, vcc, 0, v77, vcc
	global_load_dwordx2 v[154:155], v[146:147], off offset:1024
	v_fmac_f32_e32 v138, 0xbf317218, v136
	v_min_f32_e32 v136, 0, v137
	v_mul_f32_e64 v137, |v137|, s93
	v_exp_f32_e32 v137, v137
	v_fmac_f32_e32 v85, 0x3d800000, v138
	global_load_dwordx4 v[146:149], v3, s[0:1] offset:16
	s_mov_b32 s0, 0x5e000
	v_add_f32_e32 v137, 1.0, v137
	v_log_f32_e32 v137, v137
	s_nop 0
	v_fmac_f32_e32 v136, 0xbf317218, v137
	v_mul_f32_e64 v137, |v140|, s93
	v_exp_f32_e32 v137, v137
	v_fmac_f32_e32 v91, 0x3d800000, v136
	v_min_f32_e32 v136, 0, v140
	v_add_f32_e32 v137, 1.0, v137
	v_log_f32_e32 v137, v137
	s_nop 0
	v_fmac_f32_e32 v136, 0xbf317218, v137
	v_mul_f32_e64 v137, |v141|, s93
	v_exp_f32_e32 v137, v137
	v_fmac_f32_e32 v163, 0x3d800000, v136
	v_min_f32_e32 v136, 0, v141
	v_add_f32_e32 v137, 1.0, v137
	v_log_f32_e32 v137, v137
	s_nop 0
	v_fmac_f32_e32 v136, 0xbf317218, v137
	v_sub_f32_e32 v137, v131, v91
	v_mul_f32_e32 v137, 0x3fb8aa3b, v137
	v_exp_f32_e32 v138, v137
	v_sub_f32_e32 v137, v128, v163
	v_fmac_f32_e32 v170, 0x3d800000, v136
	v_mul_f32_e32 v137, 0x3fb8aa3b, v137
	v_exp_f32_e32 v140, v137
	v_sub_f32_e32 v137, v129, v170
	v_mul_f32_e32 v137, 0x3fb8aa3b, v137
	v_exp_f32_e32 v144, v137
	v_mov_b32_e32 v137, 0x5e000
	global_load_dwordx4 v[150:153], v137, s[6:7] offset:1536
	v_sub_f32_e32 v136, v130, v85
	v_mul_f32_e32 v136, 0x3fb8aa3b, v136
	v_exp_f32_e32 v136, v136
	s_waitcnt vmcnt(0)
	v_lshlrev_b32_e32 v156, 16, v150
	v_pk_fma_f32 v[158:159], v[70:71], v[156:157], v[66:67] op_sel_hi:[1,0,1]
	v_pk_fma_f32 v[156:157], v[68:69], v[156:157], v[64:65] op_sel_hi:[1,0,1]
	v_and_b32_e32 v150, 0xffff0000, v150
	v_pk_fma_f32 v[158:159], v[62:63], v[150:151], v[158:159] op_sel_hi:[1,0,1]
	v_pk_fma_f32 v[156:157], v[60:61], v[150:151], v[156:157] op_sel_hi:[1,0,1]
	v_lshlrev_b32_e32 v150, 16, v151
	v_pk_fma_f32 v[158:159], v[58:59], v[150:151], v[158:159] op_sel_hi:[1,0,1]
	v_pk_fma_f32 v[156:157], v[56:57], v[150:151], v[156:157] op_sel_hi:[1,0,1]
	v_and_b32_e32 v150, 0xffff0000, v151
	v_pk_fma_f32 v[158:159], v[54:55], v[150:151], v[158:159] op_sel_hi:[1,0,1]
	v_pk_fma_f32 v[150:151], v[52:53], v[150:151], v[156:157] op_sel_hi:[1,0,1]
	v_lshlrev_b32_e32 v156, 16, v152
	v_pk_fma_f32 v[158:159], v[50:51], v[156:157], v[158:159] op_sel_hi:[1,0,1]
	v_pk_fma_f32 v[150:151], v[48:49], v[156:157], v[150:151] op_sel_hi:[1,0,1]
	v_and_b32_e32 v152, 0xffff0000, v152
	v_pk_fma_f32 v[156:157], v[46:47], v[152:153], v[158:159] op_sel_hi:[1,0,1]
	v_pk_fma_f32 v[150:151], v[44:45], v[152:153], v[150:151] op_sel_hi:[1,0,1]
	v_lshlrev_b32_e32 v152, 16, v153
	v_pk_fma_f32 v[156:157], v[42:43], v[152:153], v[156:157] op_sel_hi:[1,0,1]
	v_pk_fma_f32 v[150:151], v[40:41], v[152:153], v[150:151] op_sel_hi:[1,0,1]
	v_and_b32_e32 v152, 0xffff0000, v153
	v_pk_fma_f32 v[156:157], v[38:39], v[152:153], v[156:157] op_sel_hi:[1,0,1]
	v_pk_fma_f32 v[150:151], v[36:37], v[152:153], v[150:151] op_sel_hi:[1,0,1]
	v_lshlrev_b32_e32 v152, 16, v146
	v_pk_fma_f32 v[156:157], v[34:35], v[152:153], v[156:157] op_sel_hi:[1,0,1]
	v_pk_fma_f32 v[150:151], v[32:33], v[152:153], v[150:151] op_sel_hi:[1,0,1]
	v_and_b32_e32 v146, 0xffff0000, v146
	v_pk_fma_f32 v[152:153], v[30:31], v[146:147], v[156:157] op_sel_hi:[1,0,1]
	v_pk_fma_f32 v[150:151], v[28:29], v[146:147], v[150:151] op_sel_hi:[1,0,1]
	v_lshlrev_b32_e32 v146, 16, v147
	v_pk_fma_f32 v[152:153], v[26:27], v[146:147], v[152:153] op_sel_hi:[1,0,1]
	v_pk_fma_f32 v[150:151], v[24:25], v[146:147], v[150:151] op_sel_hi:[1,0,1]
	v_and_b32_e32 v146, 0xffff0000, v147
	v_pk_fma_f32 v[152:153], v[22:23], v[146:147], v[152:153] op_sel_hi:[1,0,1]
	v_pk_fma_f32 v[146:147], v[20:21], v[146:147], v[150:151] op_sel_hi:[1,0,1]
	v_lshlrev_b32_e32 v150, 16, v148
	v_pk_fma_f32 v[152:153], v[18:19], v[150:151], v[152:153] op_sel_hi:[1,0,1]
	v_pk_fma_f32 v[146:147], v[16:17], v[150:151], v[146:147] op_sel_hi:[1,0,1]
	v_and_b32_e32 v148, 0xffff0000, v148
	v_pk_fma_f32 v[150:151], v[14:15], v[148:149], v[152:153] op_sel_hi:[1,0,1]
	v_pk_fma_f32 v[146:147], v[12:13], v[148:149], v[146:147] op_sel_hi:[1,0,1]
	v_lshlrev_b32_e32 v148, 16, v149
	v_pk_fma_f32 v[150:151], v[10:11], v[148:149], v[150:151] op_sel_hi:[1,0,1]
	v_pk_fma_f32 v[146:147], v[8:9], v[148:149], v[146:147] op_sel_hi:[1,0,1]
	v_and_b32_e32 v148, 0xffff0000, v149
	v_pk_fma_f32 v[146:147], v[4:5], v[148:149], v[146:147] op_sel_hi:[1,0,1]
	v_pk_fma_f32 v[150:151], v[6:7], v[148:149], v[150:151] op_sel_hi:[1,0,1]
	v_mul_f32_e64 v139, |v146|, s93
	v_exp_f32_e32 v139, v139
	v_min_f32_e32 v137, 0, v146
	v_lshlrev_b32_e32 v146, 16, v142
	v_mov_b32_e32 v148, 0x61000
	v_add_f32_e32 v139, 1.0, v139
	v_log_f32_e32 v139, v139
	s_nop 0
	v_fmac_f32_e32 v137, 0xbf317218, v139
	v_mul_f32_e64 v139, |v147|, s93
	v_exp_f32_e32 v139, v139
	v_fmac_f32_e32 v85, 0x3d800000, v137
	v_min_f32_e32 v137, 0, v147
	v_lshlrev_b32_e32 v147, 16, v154
	v_add_f32_e32 v139, 1.0, v139
	v_log_f32_e32 v139, v139
	s_nop 0
	v_fmac_f32_e32 v137, 0xbf317218, v139
	v_mul_f32_e64 v139, |v150|, s93
	v_exp_f32_e32 v139, v139
	v_fmac_f32_e32 v91, 0x3d800000, v137
	v_min_f32_e32 v137, 0, v150
	v_add_f32_e32 v139, 1.0, v139
	v_log_f32_e32 v139, v139
	s_nop 0
	v_fmac_f32_e32 v137, 0xbf317218, v139
	v_mul_f32_e64 v139, |v151|, s93
	v_exp_f32_e32 v139, v139
	v_fmac_f32_e32 v163, 0x3d800000, v137
	v_min_f32_e32 v137, 0, v151
	v_sub_f32_e32 v141, v128, v163
	v_add_f32_e32 v139, 1.0, v139
	v_log_f32_e32 v139, v139
	v_mul_f32_e32 v141, 0x3fb8aa3b, v141
	v_exp_f32_e32 v141, v141
	v_fmac_f32_e32 v137, 0xbf317218, v139
	v_fmac_f32_e32 v170, 0x3d800000, v137
	v_sub_f32_e32 v137, v130, v85
	v_mul_f32_e32 v137, 0x3fb8aa3b, v137
	v_sub_f32_e32 v139, v131, v91
	v_exp_f32_e32 v137, v137
	v_mul_f32_e32 v139, 0x3fb8aa3b, v139
	v_exp_f32_e32 v139, v139
	v_pk_mul_f32 v[136:137], v[136:137], v[146:147]
	v_and_b32_e32 v147, 0xffff0000, v154
	v_and_b32_e32 v146, 0xffff0000, v142
	v_pk_mul_f32 v[138:139], v[138:139], v[146:147]
	v_lshlrev_b32_e32 v147, 16, v155
	v_lshlrev_b32_e32 v146, 16, v143
	v_pk_mul_f32 v[140:141], v[140:141], v[146:147]
	v_sub_f32_e32 v142, v129, v170
	v_and_b32_e32 v147, 0xffff0000, v155
	global_load_dwordx4 v[152:155], v148, s[6:7]
	v_mul_f32_e32 v142, 0x3fb8aa3b, v142
	v_exp_f32_e32 v145, v142
	v_and_b32_e32 v146, 0xffff0000, v143
	v_pk_mul_f32 v[142:143], v[144:145], v[146:147]
	v_add_co_u32_e32 v144, vcc, s0, v76
	s_add_u32 s0, s6, 0x61000
	s_nop 0
	v_addc_co_u32_e32 v145, vcc, 0, v77, vcc
	s_addc_u32 s1, s7, 0
	global_load_dwordx2 v[150:151], v[144:145], off offset:3584
	s_waitcnt vmcnt(1)
	v_lshlrev_b32_e32 v148, 16, v152
	global_load_dwordx4 v[144:147], v3, s[0:1] offset:16
	v_pk_fma_f32 v[156:157], v[70:71], v[148:149], v[66:67] op_sel_hi:[1,0,1]
	v_pk_fma_f32 v[148:149], v[68:69], v[148:149], v[64:65] op_sel_hi:[1,0,1]
	v_and_b32_e32 v152, 0xffff0000, v152
	v_pk_fma_f32 v[156:157], v[62:63], v[152:153], v[156:157] op_sel_hi:[1,0,1]
	v_pk_fma_f32 v[148:149], v[60:61], v[152:153], v[148:149] op_sel_hi:[1,0,1]
	v_lshlrev_b32_e32 v152, 16, v153
	v_pk_fma_f32 v[156:157], v[58:59], v[152:153], v[156:157] op_sel_hi:[1,0,1]
	v_pk_fma_f32 v[148:149], v[56:57], v[152:153], v[148:149] op_sel_hi:[1,0,1]
	v_and_b32_e32 v152, 0xffff0000, v153
	v_pk_fma_f32 v[156:157], v[54:55], v[152:153], v[156:157] op_sel_hi:[1,0,1]
	v_pk_fma_f32 v[148:149], v[52:53], v[152:153], v[148:149] op_sel_hi:[1,0,1]
	v_lshlrev_b32_e32 v152, 16, v154
	v_pk_fma_f32 v[156:157], v[50:51], v[152:153], v[156:157] op_sel_hi:[1,0,1]
	v_pk_fma_f32 v[148:149], v[48:49], v[152:153], v[148:149] op_sel_hi:[1,0,1]
	v_and_b32_e32 v152, 0xffff0000, v154
	v_pk_fma_f32 v[156:157], v[46:47], v[152:153], v[156:157] op_sel_hi:[1,0,1]
	v_pk_fma_f32 v[148:149], v[44:45], v[152:153], v[148:149] op_sel_hi:[1,0,1]
	v_lshlrev_b32_e32 v152, 16, v155
	v_pk_fma_f32 v[156:157], v[42:43], v[152:153], v[156:157] op_sel_hi:[1,0,1]
	v_pk_fma_f32 v[148:149], v[40:41], v[152:153], v[148:149] op_sel_hi:[1,0,1]
	v_and_b32_e32 v152, 0xffff0000, v155
	v_pk_fma_f32 v[154:155], v[38:39], v[152:153], v[156:157] op_sel_hi:[1,0,1]
	v_pk_fma_f32 v[148:149], v[36:37], v[152:153], v[148:149] op_sel_hi:[1,0,1]
	s_add_u32 s0, s6, 0x63a00
	s_addc_u32 s1, s7, 0
	s_waitcnt vmcnt(0)
	v_lshlrev_b32_e32 v152, 16, v144
	v_pk_fma_f32 v[154:155], v[34:35], v[152:153], v[154:155] op_sel_hi:[1,0,1]
	v_pk_fma_f32 v[148:149], v[32:33], v[152:153], v[148:149] op_sel_hi:[1,0,1]
	v_and_b32_e32 v144, 0xffff0000, v144
	v_pk_fma_f32 v[152:153], v[30:31], v[144:145], v[154:155] op_sel_hi:[1,0,1]
	v_pk_fma_f32 v[148:149], v[28:29], v[144:145], v[148:149] op_sel_hi:[1,0,1]
	v_lshlrev_b32_e32 v144, 16, v145
	v_pk_fma_f32 v[152:153], v[26:27], v[144:145], v[152:153] op_sel_hi:[1,0,1]
	v_pk_fma_f32 v[148:149], v[24:25], v[144:145], v[148:149] op_sel_hi:[1,0,1]
	v_and_b32_e32 v144, 0xffff0000, v145
	v_pk_fma_f32 v[152:153], v[22:23], v[144:145], v[152:153] op_sel_hi:[1,0,1]
	v_pk_fma_f32 v[144:145], v[20:21], v[144:145], v[148:149] op_sel_hi:[1,0,1]
	v_lshlrev_b32_e32 v148, 16, v146
	v_pk_fma_f32 v[152:153], v[18:19], v[148:149], v[152:153] op_sel_hi:[1,0,1]
	v_pk_fma_f32 v[144:145], v[16:17], v[148:149], v[144:145] op_sel_hi:[1,0,1]
	v_and_b32_e32 v146, 0xffff0000, v146
	v_pk_fma_f32 v[148:149], v[14:15], v[146:147], v[152:153] op_sel_hi:[1,0,1]
	v_pk_fma_f32 v[144:145], v[12:13], v[146:147], v[144:145] op_sel_hi:[1,0,1]
	v_lshlrev_b32_e32 v146, 16, v147
	v_pk_fma_f32 v[148:149], v[10:11], v[146:147], v[148:149] op_sel_hi:[1,0,1]
	v_pk_fma_f32 v[144:145], v[8:9], v[146:147], v[144:145] op_sel_hi:[1,0,1]
	v_and_b32_e32 v146, 0xffff0000, v147
	v_pk_fma_f32 v[144:145], v[4:5], v[146:147], v[144:145] op_sel_hi:[1,0,1]
	v_pk_fma_f32 v[148:149], v[6:7], v[146:147], v[148:149] op_sel_hi:[1,0,1]
	v_min_f32_e32 v146, 0, v144
	v_mul_f32_e64 v144, |v144|, s93
	v_exp_f32_e32 v144, v144
	v_add_co_u32_e32 v154, vcc, s47, v76
	v_add_f32_e32 v144, 1.0, v144
	v_log_f32_e32 v144, v144
	v_addc_co_u32_e32 v155, vcc, 0, v77, vcc
	global_load_dwordx2 v[164:165], v[154:155], off offset:2048
	v_fmac_f32_e32 v146, 0xbf317218, v144
	v_min_f32_e32 v144, 0, v145
	v_mul_f32_e64 v145, |v145|, s93
	v_exp_f32_e32 v145, v145
	v_fmac_f32_e32 v85, 0x3d800000, v146
	global_load_dwordx4 v[154:157], v3, s[0:1] offset:16
	s_add_u32 s0, s6, 0x66400
	v_add_f32_e32 v145, 1.0, v145
	v_log_f32_e32 v145, v145
	s_addc_u32 s1, s7, 0
	v_fmac_f32_e32 v144, 0xbf317218, v145
	v_mul_f32_e64 v145, |v148|, s93
	v_exp_f32_e32 v145, v145
	v_fmac_f32_e32 v91, 0x3d800000, v144
	v_min_f32_e32 v144, 0, v148
	v_add_f32_e32 v145, 1.0, v145
	v_log_f32_e32 v145, v145
	s_nop 0
	v_fmac_f32_e32 v144, 0xbf317218, v145
	v_mul_f32_e64 v145, |v149|, s93
	v_exp_f32_e32 v145, v145
	v_fmac_f32_e32 v163, 0x3d800000, v144
	v_min_f32_e32 v144, 0, v149
	v_add_f32_e32 v145, 1.0, v145
	v_log_f32_e32 v145, v145
	s_nop 0
	v_fmac_f32_e32 v144, 0xbf317218, v145
	v_sub_f32_e32 v145, v131, v91
	v_mul_f32_e32 v145, 0x3fb8aa3b, v145
	v_exp_f32_e32 v146, v145
	v_sub_f32_e32 v145, v128, v163
	v_fmac_f32_e32 v170, 0x3d800000, v144
	v_mul_f32_e32 v145, 0x3fb8aa3b, v145
	v_exp_f32_e32 v148, v145
	v_sub_f32_e32 v145, v129, v170
	v_mul_f32_e32 v145, 0x3fb8aa3b, v145
	v_exp_f32_e32 v152, v145
	v_mov_b32_e32 v145, 0x63000
	global_load_dwordx4 v[158:161], v145, s[6:7] offset:2560
	v_sub_f32_e32 v144, v130, v85
	v_mul_f32_e32 v144, 0x3fb8aa3b, v144
	v_exp_f32_e32 v144, v144
	s_waitcnt vmcnt(0)
	v_lshlrev_b32_e32 v162, 16, v158
	v_pk_fma_f32 v[166:167], v[70:71], v[162:163], v[66:67] op_sel_hi:[1,0,1]
	v_pk_fma_f32 v[168:169], v[68:69], v[162:163], v[64:65] op_sel_hi:[1,0,1]
	v_and_b32_e32 v158, 0xffff0000, v158
	v_pk_fma_f32 v[166:167], v[62:63], v[158:159], v[166:167] op_sel_hi:[1,0,1]
	v_pk_fma_f32 v[168:169], v[60:61], v[158:159], v[168:169] op_sel_hi:[1,0,1]
	v_lshlrev_b32_e32 v158, 16, v159
	v_pk_fma_f32 v[166:167], v[58:59], v[158:159], v[166:167] op_sel_hi:[1,0,1]
	v_pk_fma_f32 v[168:169], v[56:57], v[158:159], v[168:169] op_sel_hi:[1,0,1]
	v_and_b32_e32 v158, 0xffff0000, v159
	v_pk_fma_f32 v[166:167], v[54:55], v[158:159], v[166:167] op_sel_hi:[1,0,1]
	v_pk_fma_f32 v[158:159], v[52:53], v[158:159], v[168:169] op_sel_hi:[1,0,1]
	v_lshlrev_b32_e32 v162, 16, v160
	v_pk_fma_f32 v[166:167], v[50:51], v[162:163], v[166:167] op_sel_hi:[1,0,1]
	v_pk_fma_f32 v[158:159], v[48:49], v[162:163], v[158:159] op_sel_hi:[1,0,1]
	v_and_b32_e32 v160, 0xffff0000, v160
	v_pk_fma_f32 v[166:167], v[46:47], v[160:161], v[166:167] op_sel_hi:[1,0,1]
	v_pk_fma_f32 v[158:159], v[44:45], v[160:161], v[158:159] op_sel_hi:[1,0,1]
	v_lshlrev_b32_e32 v160, 16, v161
	v_pk_fma_f32 v[166:167], v[42:43], v[160:161], v[166:167] op_sel_hi:[1,0,1]
	v_pk_fma_f32 v[158:159], v[40:41], v[160:161], v[158:159] op_sel_hi:[1,0,1]
	v_and_b32_e32 v160, 0xffff0000, v161
	v_pk_fma_f32 v[166:167], v[38:39], v[160:161], v[166:167] op_sel_hi:[1,0,1]
	v_pk_fma_f32 v[158:159], v[36:37], v[160:161], v[158:159] op_sel_hi:[1,0,1]
	v_lshlrev_b32_e32 v160, 16, v154
	v_pk_fma_f32 v[166:167], v[34:35], v[160:161], v[166:167] op_sel_hi:[1,0,1]
	v_pk_fma_f32 v[158:159], v[32:33], v[160:161], v[158:159] op_sel_hi:[1,0,1]
	v_and_b32_e32 v154, 0xffff0000, v154
	v_pk_fma_f32 v[160:161], v[30:31], v[154:155], v[166:167] op_sel_hi:[1,0,1]
	v_pk_fma_f32 v[158:159], v[28:29], v[154:155], v[158:159] op_sel_hi:[1,0,1]
	v_lshlrev_b32_e32 v154, 16, v155
	v_pk_fma_f32 v[160:161], v[26:27], v[154:155], v[160:161] op_sel_hi:[1,0,1]
	v_pk_fma_f32 v[158:159], v[24:25], v[154:155], v[158:159] op_sel_hi:[1,0,1]
	v_and_b32_e32 v154, 0xffff0000, v155
	v_pk_fma_f32 v[160:161], v[22:23], v[154:155], v[160:161] op_sel_hi:[1,0,1]
	v_pk_fma_f32 v[154:155], v[20:21], v[154:155], v[158:159] op_sel_hi:[1,0,1]
	v_lshlrev_b32_e32 v158, 16, v156
	v_pk_fma_f32 v[160:161], v[18:19], v[158:159], v[160:161] op_sel_hi:[1,0,1]
	v_pk_fma_f32 v[154:155], v[16:17], v[158:159], v[154:155] op_sel_hi:[1,0,1]
	v_and_b32_e32 v156, 0xffff0000, v156
	v_pk_fma_f32 v[158:159], v[14:15], v[156:157], v[160:161] op_sel_hi:[1,0,1]
	v_pk_fma_f32 v[154:155], v[12:13], v[156:157], v[154:155] op_sel_hi:[1,0,1]
	v_lshlrev_b32_e32 v156, 16, v157
	v_pk_fma_f32 v[158:159], v[10:11], v[156:157], v[158:159] op_sel_hi:[1,0,1]
	v_pk_fma_f32 v[154:155], v[8:9], v[156:157], v[154:155] op_sel_hi:[1,0,1]
	v_and_b32_e32 v156, 0xffff0000, v157
	v_pk_fma_f32 v[154:155], v[4:5], v[156:157], v[154:155] op_sel_hi:[1,0,1]
	v_pk_fma_f32 v[158:159], v[6:7], v[156:157], v[158:159] op_sel_hi:[1,0,1]
	v_mul_f32_e64 v147, |v154|, s93
	v_exp_f32_e32 v147, v147
	v_min_f32_e32 v145, 0, v154
	v_lshlrev_b32_e32 v154, 16, v150
	v_add_f32_e32 v147, 1.0, v147
	v_log_f32_e32 v147, v147
	s_nop 0
	v_fmac_f32_e32 v145, 0xbf317218, v147
	v_mul_f32_e64 v147, |v155|, s93
	v_exp_f32_e32 v147, v147
	v_fmac_f32_e32 v85, 0x3d800000, v145
	v_min_f32_e32 v145, 0, v155
	v_lshlrev_b32_e32 v155, 16, v164
	v_add_f32_e32 v147, 1.0, v147
	v_log_f32_e32 v147, v147
	s_nop 0
	v_fmac_f32_e32 v145, 0xbf317218, v147
	v_mul_f32_e64 v147, |v158|, s93
	v_exp_f32_e32 v147, v147
	v_fmac_f32_e32 v91, 0x3d800000, v145
	v_min_f32_e32 v145, 0, v158
	v_mov_b32_e32 v158, 0x66000
	v_add_f32_e32 v147, 1.0, v147
	v_log_f32_e32 v147, v147
	s_nop 0
	v_fmac_f32_e32 v145, 0xbf317218, v147
	v_mul_f32_e64 v147, |v159|, s93
	v_exp_f32_e32 v147, v147
	v_fmac_f32_e32 v163, 0x3d800000, v145
	v_min_f32_e32 v145, 0, v159
	global_load_dwordx4 v[158:161], v158, s[6:7] offset:1024
	v_add_f32_e32 v147, 1.0, v147
	v_log_f32_e32 v147, v147
	v_sub_f32_e32 v149, v128, v163
	v_mul_f32_e32 v149, 0x3fb8aa3b, v149
	v_exp_f32_e32 v149, v149
	v_fmac_f32_e32 v145, 0xbf317218, v147
	v_fmac_f32_e32 v170, 0x3d800000, v145
	v_sub_f32_e32 v145, v130, v85
	v_mul_f32_e32 v145, 0x3fb8aa3b, v145
	v_exp_f32_e32 v145, v145
	v_sub_f32_e32 v147, v131, v91
	v_mul_f32_e32 v147, 0x3fb8aa3b, v147
	v_exp_f32_e32 v147, v147
	v_pk_mul_f32 v[144:145], v[144:145], v[154:155]
	v_and_b32_e32 v154, 0xffff0000, v150
	v_sub_f32_e32 v150, v129, v170
	v_mul_f32_e32 v150, 0x3fb8aa3b, v150
	v_exp_f32_e32 v153, v150
	v_and_b32_e32 v155, 0xffff0000, v164
	v_pk_mul_f32 v[146:147], v[146:147], v[154:155]
	v_lshlrev_b32_e32 v155, 16, v165
	v_lshlrev_b32_e32 v154, 16, v151
	v_pk_mul_f32 v[148:149], v[148:149], v[154:155]
	v_and_b32_e32 v155, 0xffff0000, v165
	v_and_b32_e32 v154, 0xffff0000, v151
	v_pk_mul_f32 v[150:151], v[152:153], v[154:155]
	global_load_dwordx4 v[154:157], v3, s[0:1] offset:16
	v_add_co_u32_e32 v152, vcc, s48, v76
	s_mov_b32 s0, 0x66000
	s_nop 0
	v_addc_co_u32_e32 v153, vcc, 0, v77, vcc
	global_load_dwordx2 v[152:153], v[152:153], off offset:512
	s_waitcnt vmcnt(2)
	v_lshlrev_b32_e32 v162, 16, v158
	v_pk_fma_f32 v[164:165], v[70:71], v[162:163], v[66:67] op_sel_hi:[1,0,1]
	v_pk_fma_f32 v[166:167], v[68:69], v[162:163], v[64:65] op_sel_hi:[1,0,1]
	v_and_b32_e32 v158, 0xffff0000, v158
	v_pk_fma_f32 v[164:165], v[62:63], v[158:159], v[164:165] op_sel_hi:[1,0,1]
	v_pk_fma_f32 v[166:167], v[60:61], v[158:159], v[166:167] op_sel_hi:[1,0,1]
	v_lshlrev_b32_e32 v158, 16, v159
	v_pk_fma_f32 v[164:165], v[58:59], v[158:159], v[164:165] op_sel_hi:[1,0,1]
	v_pk_fma_f32 v[166:167], v[56:57], v[158:159], v[166:167] op_sel_hi:[1,0,1]
	v_and_b32_e32 v158, 0xffff0000, v159
	v_pk_fma_f32 v[164:165], v[54:55], v[158:159], v[164:165] op_sel_hi:[1,0,1]
	v_pk_fma_f32 v[158:159], v[52:53], v[158:159], v[166:167] op_sel_hi:[1,0,1]
	v_lshlrev_b32_e32 v162, 16, v160
	v_pk_fma_f32 v[164:165], v[50:51], v[162:163], v[164:165] op_sel_hi:[1,0,1]
	v_pk_fma_f32 v[158:159], v[48:49], v[162:163], v[158:159] op_sel_hi:[1,0,1]
	v_and_b32_e32 v160, 0xffff0000, v160
	v_pk_fma_f32 v[164:165], v[46:47], v[160:161], v[164:165] op_sel_hi:[1,0,1]
	v_pk_fma_f32 v[158:159], v[44:45], v[160:161], v[158:159] op_sel_hi:[1,0,1]
	v_lshlrev_b32_e32 v160, 16, v161
	v_pk_fma_f32 v[164:165], v[42:43], v[160:161], v[164:165] op_sel_hi:[1,0,1]
	v_pk_fma_f32 v[158:159], v[40:41], v[160:161], v[158:159] op_sel_hi:[1,0,1]
	v_and_b32_e32 v160, 0xffff0000, v161
	v_pk_fma_f32 v[164:165], v[38:39], v[160:161], v[164:165] op_sel_hi:[1,0,1]
	v_pk_fma_f32 v[158:159], v[36:37], v[160:161], v[158:159] op_sel_hi:[1,0,1]
	s_waitcnt vmcnt(1)
	v_lshlrev_b32_e32 v160, 16, v154
	v_pk_fma_f32 v[164:165], v[34:35], v[160:161], v[164:165] op_sel_hi:[1,0,1]
	v_pk_fma_f32 v[158:159], v[32:33], v[160:161], v[158:159] op_sel_hi:[1,0,1]
	v_and_b32_e32 v154, 0xffff0000, v154
	v_pk_fma_f32 v[160:161], v[30:31], v[154:155], v[164:165] op_sel_hi:[1,0,1]
	v_pk_fma_f32 v[158:159], v[28:29], v[154:155], v[158:159] op_sel_hi:[1,0,1]
	v_lshlrev_b32_e32 v154, 16, v155
	v_pk_fma_f32 v[160:161], v[26:27], v[154:155], v[160:161] op_sel_hi:[1,0,1]
	v_pk_fma_f32 v[158:159], v[24:25], v[154:155], v[158:159] op_sel_hi:[1,0,1]
	v_and_b32_e32 v154, 0xffff0000, v155
	v_pk_fma_f32 v[160:161], v[22:23], v[154:155], v[160:161] op_sel_hi:[1,0,1]
	v_pk_fma_f32 v[154:155], v[20:21], v[154:155], v[158:159] op_sel_hi:[1,0,1]
	v_lshlrev_b32_e32 v158, 16, v156
	v_pk_fma_f32 v[160:161], v[18:19], v[158:159], v[160:161] op_sel_hi:[1,0,1]
	v_pk_fma_f32 v[154:155], v[16:17], v[158:159], v[154:155] op_sel_hi:[1,0,1]
	v_and_b32_e32 v156, 0xffff0000, v156
	v_pk_fma_f32 v[158:159], v[14:15], v[156:157], v[160:161] op_sel_hi:[1,0,1]
	v_pk_fma_f32 v[154:155], v[12:13], v[156:157], v[154:155] op_sel_hi:[1,0,1]
	v_lshlrev_b32_e32 v156, 16, v157
	v_pk_fma_f32 v[158:159], v[10:11], v[156:157], v[158:159] op_sel_hi:[1,0,1]
	v_pk_fma_f32 v[154:155], v[8:9], v[156:157], v[154:155] op_sel_hi:[1,0,1]
	v_and_b32_e32 v156, 0xffff0000, v157
	v_pk_fma_f32 v[154:155], v[4:5], v[156:157], v[154:155] op_sel_hi:[1,0,1]
	v_pk_fma_f32 v[158:159], v[6:7], v[156:157], v[158:159] op_sel_hi:[1,0,1]
	v_min_f32_e32 v156, 0, v154
	v_mul_f32_e64 v154, |v154|, s93
	v_exp_f32_e32 v154, v154
	v_add_co_u32_e32 v164, vcc, s0, v76
	s_add_u32 s0, s6, 0x68e00
	v_add_f32_e32 v154, 1.0, v154
	v_log_f32_e32 v154, v154
	v_addc_co_u32_e32 v165, vcc, 0, v77, vcc
	s_addc_u32 s1, s7, 0
	v_fmac_f32_e32 v156, 0xbf317218, v154
	v_min_f32_e32 v154, 0, v155
	v_mul_f32_e64 v155, |v155|, s93
	v_exp_f32_e32 v155, v155
	global_load_dwordx2 v[168:169], v[164:165], off offset:3072
	v_fmac_f32_e32 v85, 0x3d800000, v156
	global_load_dwordx4 v[164:167], v3, s[0:1] offset:16
	v_add_f32_e32 v155, 1.0, v155
	v_log_f32_e32 v155, v155
	s_add_u32 s0, s6, 0x6b800
	s_addc_u32 s1, s7, 0
	v_fmac_f32_e32 v154, 0xbf317218, v155
	v_mul_f32_e64 v155, |v158|, s93
	v_exp_f32_e32 v155, v155
	v_fmac_f32_e32 v91, 0x3d800000, v154
	v_min_f32_e32 v154, 0, v158
	v_add_f32_e32 v155, 1.0, v155
	v_log_f32_e32 v155, v155
	s_nop 0
	v_fmac_f32_e32 v154, 0xbf317218, v155
	v_mul_f32_e64 v155, |v159|, s93
	v_exp_f32_e32 v155, v155
	v_fmac_f32_e32 v163, 0x3d800000, v154
	v_min_f32_e32 v154, 0, v159
	v_add_f32_e32 v155, 1.0, v155
	v_log_f32_e32 v155, v155
	s_nop 0
	v_fmac_f32_e32 v154, 0xbf317218, v155
	v_mov_b32_e32 v155, 0x68000
	global_load_dwordx4 v[172:175], v155, s[6:7] offset:3584
	v_fmac_f32_e32 v170, 0x3d800000, v154
	v_sub_f32_e32 v154, v130, v85
	v_mul_f32_e32 v154, 0x3fb8aa3b, v154
	v_exp_f32_e32 v160, v154
	v_sub_f32_e32 v154, v131, v91
	v_mul_f32_e32 v154, 0x3fb8aa3b, v154
	v_exp_f32_e32 v158, v154
	v_sub_f32_e32 v154, v128, v163
	v_mul_f32_e32 v154, 0x3fb8aa3b, v154
	v_exp_f32_e32 v156, v154
	v_sub_f32_e32 v154, v129, v170
	v_mul_f32_e32 v154, 0x3fb8aa3b, v154
	v_exp_f32_e32 v154, v154
	s_waitcnt vmcnt(0)
	v_lshlrev_b32_e32 v162, 16, v172
	v_pk_fma_f32 v[176:177], v[70:71], v[162:163], v[66:67] op_sel_hi:[1,0,1]
	v_pk_fma_f32 v[178:179], v[68:69], v[162:163], v[64:65] op_sel_hi:[1,0,1]
	v_and_b32_e32 v162, 0xffff0000, v172
	v_pk_fma_f32 v[176:177], v[62:63], v[162:163], v[176:177] op_sel_hi:[1,0,1]
	v_pk_fma_f32 v[178:179], v[60:61], v[162:163], v[178:179] op_sel_hi:[1,0,1]
	v_lshlrev_b32_e32 v162, 16, v173
	v_pk_fma_f32 v[176:177], v[58:59], v[162:163], v[176:177] op_sel_hi:[1,0,1]
	v_pk_fma_f32 v[178:179], v[56:57], v[162:163], v[178:179] op_sel_hi:[1,0,1]
	v_and_b32_e32 v162, 0xffff0000, v173
	v_pk_fma_f32 v[172:173], v[54:55], v[162:163], v[176:177] op_sel_hi:[1,0,1]
	v_pk_fma_f32 v[176:177], v[52:53], v[162:163], v[178:179] op_sel_hi:[1,0,1]
	v_lshlrev_b32_e32 v162, 16, v174
	v_pk_fma_f32 v[172:173], v[50:51], v[162:163], v[172:173] op_sel_hi:[1,0,1]
	v_pk_fma_f32 v[176:177], v[48:49], v[162:163], v[176:177] op_sel_hi:[1,0,1]
	v_and_b32_e32 v162, 0xffff0000, v174
	v_pk_fma_f32 v[172:173], v[46:47], v[162:163], v[172:173] op_sel_hi:[1,0,1]
	v_pk_fma_f32 v[176:177], v[44:45], v[162:163], v[176:177] op_sel_hi:[1,0,1]
	v_lshlrev_b32_e32 v162, 16, v175
	v_pk_fma_f32 v[172:173], v[42:43], v[162:163], v[172:173] op_sel_hi:[1,0,1]
	v_pk_fma_f32 v[176:177], v[40:41], v[162:163], v[176:177] op_sel_hi:[1,0,1]
	v_and_b32_e32 v162, 0xffff0000, v175
	v_pk_fma_f32 v[172:173], v[38:39], v[162:163], v[172:173] op_sel_hi:[1,0,1]
	v_pk_fma_f32 v[174:175], v[36:37], v[162:163], v[176:177] op_sel_hi:[1,0,1]
	v_lshlrev_b32_e32 v162, 16, v164
	v_pk_fma_f32 v[172:173], v[34:35], v[162:163], v[172:173] op_sel_hi:[1,0,1]
	v_pk_fma_f32 v[174:175], v[32:33], v[162:163], v[174:175] op_sel_hi:[1,0,1]
	v_and_b32_e32 v162, 0xffff0000, v164
	v_pk_fma_f32 v[172:173], v[30:31], v[162:163], v[172:173] op_sel_hi:[1,0,1]
	v_pk_fma_f32 v[174:175], v[28:29], v[162:163], v[174:175] op_sel_hi:[1,0,1]
	v_lshlrev_b32_e32 v162, 16, v165
	v_pk_fma_f32 v[172:173], v[26:27], v[162:163], v[172:173] op_sel_hi:[1,0,1]
	v_pk_fma_f32 v[174:175], v[24:25], v[162:163], v[174:175] op_sel_hi:[1,0,1]
	v_and_b32_e32 v162, 0xffff0000, v165
	v_pk_fma_f32 v[164:165], v[22:23], v[162:163], v[172:173] op_sel_hi:[1,0,1]
	v_pk_fma_f32 v[172:173], v[20:21], v[162:163], v[174:175] op_sel_hi:[1,0,1]
	v_lshlrev_b32_e32 v162, 16, v166
	v_pk_fma_f32 v[164:165], v[18:19], v[162:163], v[164:165] op_sel_hi:[1,0,1]
	v_pk_fma_f32 v[172:173], v[16:17], v[162:163], v[172:173] op_sel_hi:[1,0,1]
	v_and_b32_e32 v162, 0xffff0000, v166
	v_pk_fma_f32 v[164:165], v[14:15], v[162:163], v[164:165] op_sel_hi:[1,0,1]
	v_pk_fma_f32 v[172:173], v[12:13], v[162:163], v[172:173] op_sel_hi:[1,0,1]
	v_lshlrev_b32_e32 v162, 16, v167
	v_pk_fma_f32 v[164:165], v[10:11], v[162:163], v[164:165] op_sel_hi:[1,0,1]
	v_pk_fma_f32 v[172:173], v[8:9], v[162:163], v[172:173] op_sel_hi:[1,0,1]
	v_and_b32_e32 v162, 0xffff0000, v167
	v_pk_fma_f32 v[166:167], v[4:5], v[162:163], v[172:173] op_sel_hi:[1,0,1]
	v_pk_fma_f32 v[164:165], v[6:7], v[162:163], v[164:165] op_sel_hi:[1,0,1]
	v_mul_f32_e64 v157, |v166|, s93
	v_exp_f32_e32 v157, v157
	v_min_f32_e32 v155, 0, v166
	v_add_f32_e32 v157, 1.0, v157
	v_log_f32_e32 v157, v157
	s_nop 0
	v_fmac_f32_e32 v155, 0xbf317218, v157
	v_mul_f32_e64 v157, |v167|, s93
	v_exp_f32_e32 v157, v157
	v_fmac_f32_e32 v85, 0x3d800000, v155
	v_min_f32_e32 v155, 0, v167
	v_add_f32_e32 v157, 1.0, v157
	v_log_f32_e32 v157, v157
	s_nop 0
	v_fmac_f32_e32 v155, 0xbf317218, v157
	v_mul_f32_e64 v157, |v164|, s93
	v_exp_f32_e32 v157, v157
	v_fmac_f32_e32 v91, 0x3d800000, v155
	v_min_f32_e32 v155, 0, v164
	v_lshlrev_b32_e32 v164, 16, v152
	v_add_f32_e32 v157, 1.0, v157
	v_log_f32_e32 v157, v157
	s_nop 0
	v_fmac_f32_e32 v155, 0xbf317218, v157
	v_mul_f32_e64 v157, |v165|, s93
	v_exp_f32_e32 v157, v157
	v_fmac_f32_e32 v163, 0x3d800000, v155
	v_min_f32_e32 v155, 0, v165
	v_lshlrev_b32_e32 v165, 16, v168
	v_add_f32_e32 v157, 1.0, v157
	v_log_f32_e32 v157, v157
	s_nop 0
	v_fmac_f32_e32 v155, 0xbf317218, v157
	v_fmac_f32_e32 v170, 0x3d800000, v155
	v_sub_f32_e32 v155, v130, v85
	v_mul_f32_e32 v155, 0x3fb8aa3b, v155
	v_exp_f32_e32 v161, v155
	v_sub_f32_e32 v155, v131, v91
	v_mul_f32_e32 v155, 0x3fb8aa3b, v155
	v_exp_f32_e32 v159, v155
	v_pk_mul_f32 v[160:161], v[160:161], v[164:165]
	v_and_b32_e32 v164, 0xffff0000, v152
	v_sub_f32_e32 v152, v128, v163
	v_mul_f32_e32 v152, 0x3fb8aa3b, v152
	v_exp_f32_e32 v157, v152
	v_sub_f32_e32 v152, v129, v170
	v_mul_f32_e32 v152, 0x3fb8aa3b, v152
	v_exp_f32_e32 v155, v152
	v_and_b32_e32 v165, 0xffff0000, v168
	v_pk_mul_f32 v[158:159], v[158:159], v[164:165]
	v_lshlrev_b32_e32 v165, 16, v169
	v_lshlrev_b32_e32 v164, 16, v153
	v_pk_mul_f32 v[156:157], v[156:157], v[164:165]
	v_and_b32_e32 v165, 0xffff0000, v169
	v_and_b32_e32 v164, 0xffff0000, v153
	v_cvt_pk_bf16_f32 v152, v72, v73
	v_cvt_pk_bf16_f32 v72, v74, v75
	v_cvt_pk_bf16_f32 v73, v138, v139
	v_cvt_pk_bf16_f32 v74, v146, v147
	v_cvt_pk_bf16_f32 v75, v158, v159
	v_pk_mul_f32 v[164:165], v[154:155], v[164:165]
	global_store_dwordx4 v[132:133], v[72:75], off offset:2064
	v_cvt_pk_bf16_f32 v153, v136, v137
	v_cvt_pk_bf16_f32 v154, v144, v145
	v_cvt_pk_bf16_f32 v72, v78, v79
	v_cvt_pk_bf16_f32 v73, v140, v141
	v_cvt_pk_bf16_f32 v74, v148, v149
	v_cvt_pk_bf16_f32 v75, v156, v157
	v_cvt_pk_bf16_f32 v155, v160, v161
	global_store_dwordx4 v[132:133], v[72:75], off offset:2080
	global_store_dwordx4 v[132:133], v[152:155], off offset:2048
	v_mov_b32_e32 v78, 0x6b000
	v_cvt_pk_bf16_f32 v72, v134, v135
	v_cvt_pk_bf16_f32 v73, v142, v143
	v_cvt_pk_bf16_f32 v74, v150, v151
	v_cvt_pk_bf16_f32 v75, v164, v165
	global_store_dwordx4 v[132:133], v[72:75], off offset:2096
	global_load_dwordx4 v[136:139], v78, s[6:7] offset:2048
	s_waitcnt vmcnt(0)
	v_lshlrev_b32_e32 v78, 16, v136
	v_add_co_u32_e32 v72, vcc, s49, v76
	v_pk_fma_f32 v[140:141], v[70:71], v[78:79], v[66:67] op_sel_hi:[1,0,1]
	s_nop 0
	v_addc_co_u32_e32 v73, vcc, 0, v77, vcc
	global_load_dwordx2 v[134:135], v[72:73], off offset:1536
	v_pk_fma_f32 v[78:79], v[68:69], v[78:79], v[64:65] op_sel_hi:[1,0,1]
	global_load_dwordx4 v[72:75], v3, s[0:1] offset:16
	v_and_b32_e32 v136, 0xffff0000, v136
	v_pk_fma_f32 v[140:141], v[62:63], v[136:137], v[140:141] op_sel_hi:[1,0,1]
	v_pk_fma_f32 v[78:79], v[60:61], v[136:137], v[78:79] op_sel_hi:[1,0,1]
	v_lshlrev_b32_e32 v136, 16, v137
	v_pk_fma_f32 v[140:141], v[58:59], v[136:137], v[140:141] op_sel_hi:[1,0,1]
	v_pk_fma_f32 v[78:79], v[56:57], v[136:137], v[78:79] op_sel_hi:[1,0,1]
	v_and_b32_e32 v136, 0xffff0000, v137
	v_pk_fma_f32 v[140:141], v[54:55], v[136:137], v[140:141] op_sel_hi:[1,0,1]
	v_pk_fma_f32 v[78:79], v[52:53], v[136:137], v[78:79] op_sel_hi:[1,0,1]
	v_lshlrev_b32_e32 v136, 16, v138
	v_pk_fma_f32 v[140:141], v[50:51], v[136:137], v[140:141] op_sel_hi:[1,0,1]
	v_pk_fma_f32 v[78:79], v[48:49], v[136:137], v[78:79] op_sel_hi:[1,0,1]
	v_and_b32_e32 v136, 0xffff0000, v138
	v_pk_fma_f32 v[140:141], v[46:47], v[136:137], v[140:141] op_sel_hi:[1,0,1]
	v_pk_fma_f32 v[78:79], v[44:45], v[136:137], v[78:79] op_sel_hi:[1,0,1]
	v_lshlrev_b32_e32 v136, 16, v139
	v_pk_fma_f32 v[140:141], v[42:43], v[136:137], v[140:141] op_sel_hi:[1,0,1]
	v_pk_fma_f32 v[78:79], v[40:41], v[136:137], v[78:79] op_sel_hi:[1,0,1]
	v_and_b32_e32 v136, 0xffff0000, v139
	v_pk_fma_f32 v[138:139], v[38:39], v[136:137], v[140:141] op_sel_hi:[1,0,1]
	v_pk_fma_f32 v[78:79], v[36:37], v[136:137], v[78:79] op_sel_hi:[1,0,1]
	s_add_u32 s0, s6, 0x6e200
	s_addc_u32 s1, s7, 0
	s_waitcnt vmcnt(0)
	v_lshlrev_b32_e32 v136, 16, v72
	v_pk_fma_f32 v[138:139], v[34:35], v[136:137], v[138:139] op_sel_hi:[1,0,1]
	v_pk_fma_f32 v[78:79], v[32:33], v[136:137], v[78:79] op_sel_hi:[1,0,1]
	v_and_b32_e32 v72, 0xffff0000, v72
	v_pk_fma_f32 v[136:137], v[30:31], v[72:73], v[138:139] op_sel_hi:[1,0,1]
	v_pk_fma_f32 v[78:79], v[28:29], v[72:73], v[78:79] op_sel_hi:[1,0,1]
	v_lshlrev_b32_e32 v72, 16, v73
	v_pk_fma_f32 v[136:137], v[26:27], v[72:73], v[136:137] op_sel_hi:[1,0,1]
	v_pk_fma_f32 v[78:79], v[24:25], v[72:73], v[78:79] op_sel_hi:[1,0,1]
	v_and_b32_e32 v72, 0xffff0000, v73
	v_pk_fma_f32 v[136:137], v[22:23], v[72:73], v[136:137] op_sel_hi:[1,0,1]
	v_pk_fma_f32 v[72:73], v[20:21], v[72:73], v[78:79] op_sel_hi:[1,0,1]
	v_lshlrev_b32_e32 v78, 16, v74
	v_pk_fma_f32 v[136:137], v[18:19], v[78:79], v[136:137] op_sel_hi:[1,0,1]
	v_pk_fma_f32 v[72:73], v[16:17], v[78:79], v[72:73] op_sel_hi:[1,0,1]
	v_and_b32_e32 v74, 0xffff0000, v74
	v_pk_fma_f32 v[78:79], v[14:15], v[74:75], v[136:137] op_sel_hi:[1,0,1]
	v_pk_fma_f32 v[72:73], v[12:13], v[74:75], v[72:73] op_sel_hi:[1,0,1]
	v_lshlrev_b32_e32 v74, 16, v75
	v_pk_fma_f32 v[78:79], v[10:11], v[74:75], v[78:79] op_sel_hi:[1,0,1]
	v_pk_fma_f32 v[72:73], v[8:9], v[74:75], v[72:73] op_sel_hi:[1,0,1]
	v_and_b32_e32 v74, 0xffff0000, v75
	v_pk_fma_f32 v[72:73], v[4:5], v[74:75], v[72:73] op_sel_hi:[1,0,1]
	v_pk_fma_f32 v[78:79], v[6:7], v[74:75], v[78:79] op_sel_hi:[1,0,1]
	v_min_f32_e32 v74, 0, v72
	v_mul_f32_e64 v72, |v72|, s93
	v_exp_f32_e32 v72, v72
	v_add_co_u32_e32 v138, vcc, s50, v76
	v_add_f32_e32 v72, 1.0, v72
	v_log_f32_e32 v72, v72
	v_addc_co_u32_e32 v139, vcc, 0, v77, vcc
	global_load_dwordx2 v[146:147], v[138:139], off
	v_fmac_f32_e32 v74, 0xbf317218, v72
	v_min_f32_e32 v72, 0, v73
	v_mul_f32_e64 v73, |v73|, s93
	v_exp_f32_e32 v73, v73
	v_fmac_f32_e32 v85, 0x3d800000, v74
	global_load_dwordx4 v[138:141], v3, s[0:1] offset:16
	s_mov_b32 s0, 0x6e000
	v_add_f32_e32 v73, 1.0, v73
	v_log_f32_e32 v73, v73
	s_nop 0
	v_fmac_f32_e32 v72, 0xbf317218, v73
	v_mul_f32_e64 v73, |v78|, s93
	v_exp_f32_e32 v73, v73
	v_fmac_f32_e32 v91, 0x3d800000, v72
	v_min_f32_e32 v72, 0, v78
	v_add_f32_e32 v73, 1.0, v73
	v_log_f32_e32 v73, v73
	s_nop 0
	v_fmac_f32_e32 v72, 0xbf317218, v73
	v_mul_f32_e64 v73, |v79|, s93
	v_exp_f32_e32 v73, v73
	v_fmac_f32_e32 v163, 0x3d800000, v72
	v_min_f32_e32 v72, 0, v79
	v_add_f32_e32 v73, 1.0, v73
	v_log_f32_e32 v73, v73
	s_nop 0
	v_fmac_f32_e32 v72, 0xbf317218, v73
	v_sub_f32_e32 v73, v131, v91
	v_mul_f32_e32 v73, 0x3fb8aa3b, v73
	v_exp_f32_e32 v74, v73
	v_sub_f32_e32 v73, v128, v163
	v_fmac_f32_e32 v170, 0x3d800000, v72
	v_mul_f32_e32 v73, 0x3fb8aa3b, v73
	v_exp_f32_e32 v78, v73
	v_sub_f32_e32 v73, v129, v170
	v_mul_f32_e32 v73, 0x3fb8aa3b, v73
	v_exp_f32_e32 v136, v73
	v_mov_b32_e32 v73, 0x6e000
	global_load_dwordx4 v[142:145], v73, s[6:7] offset:512
	v_sub_f32_e32 v72, v130, v85
	v_mul_f32_e32 v72, 0x3fb8aa3b, v72
	v_exp_f32_e32 v72, v72
	s_waitcnt vmcnt(0)
	v_lshlrev_b32_e32 v148, 16, v142
	v_pk_fma_f32 v[150:151], v[70:71], v[148:149], v[66:67] op_sel_hi:[1,0,1]
	v_pk_fma_f32 v[148:149], v[68:69], v[148:149], v[64:65] op_sel_hi:[1,0,1]
	v_and_b32_e32 v142, 0xffff0000, v142
	v_pk_fma_f32 v[150:151], v[62:63], v[142:143], v[150:151] op_sel_hi:[1,0,1]
	v_pk_fma_f32 v[148:149], v[60:61], v[142:143], v[148:149] op_sel_hi:[1,0,1]
	v_lshlrev_b32_e32 v142, 16, v143
	v_pk_fma_f32 v[150:151], v[58:59], v[142:143], v[150:151] op_sel_hi:[1,0,1]
	v_pk_fma_f32 v[148:149], v[56:57], v[142:143], v[148:149] op_sel_hi:[1,0,1]
	v_and_b32_e32 v142, 0xffff0000, v143
	v_pk_fma_f32 v[150:151], v[54:55], v[142:143], v[150:151] op_sel_hi:[1,0,1]
	v_pk_fma_f32 v[142:143], v[52:53], v[142:143], v[148:149] op_sel_hi:[1,0,1]
	v_lshlrev_b32_e32 v148, 16, v144
	v_pk_fma_f32 v[150:151], v[50:51], v[148:149], v[150:151] op_sel_hi:[1,0,1]
	v_pk_fma_f32 v[142:143], v[48:49], v[148:149], v[142:143] op_sel_hi:[1,0,1]
	v_and_b32_e32 v144, 0xffff0000, v144
	v_pk_fma_f32 v[148:149], v[46:47], v[144:145], v[150:151] op_sel_hi:[1,0,1]
	v_pk_fma_f32 v[142:143], v[44:45], v[144:145], v[142:143] op_sel_hi:[1,0,1]
	v_lshlrev_b32_e32 v144, 16, v145
	v_pk_fma_f32 v[148:149], v[42:43], v[144:145], v[148:149] op_sel_hi:[1,0,1]
	v_pk_fma_f32 v[142:143], v[40:41], v[144:145], v[142:143] op_sel_hi:[1,0,1]
	v_and_b32_e32 v144, 0xffff0000, v145
	v_pk_fma_f32 v[148:149], v[38:39], v[144:145], v[148:149] op_sel_hi:[1,0,1]
	v_pk_fma_f32 v[142:143], v[36:37], v[144:145], v[142:143] op_sel_hi:[1,0,1]
	v_lshlrev_b32_e32 v144, 16, v138
	v_pk_fma_f32 v[148:149], v[34:35], v[144:145], v[148:149] op_sel_hi:[1,0,1]
	v_pk_fma_f32 v[142:143], v[32:33], v[144:145], v[142:143] op_sel_hi:[1,0,1]
	v_and_b32_e32 v138, 0xffff0000, v138
	v_pk_fma_f32 v[144:145], v[30:31], v[138:139], v[148:149] op_sel_hi:[1,0,1]
	v_pk_fma_f32 v[142:143], v[28:29], v[138:139], v[142:143] op_sel_hi:[1,0,1]
	v_lshlrev_b32_e32 v138, 16, v139
	v_pk_fma_f32 v[144:145], v[26:27], v[138:139], v[144:145] op_sel_hi:[1,0,1]
	v_pk_fma_f32 v[142:143], v[24:25], v[138:139], v[142:143] op_sel_hi:[1,0,1]
	v_and_b32_e32 v138, 0xffff0000, v139
	v_pk_fma_f32 v[144:145], v[22:23], v[138:139], v[144:145] op_sel_hi:[1,0,1]
	v_pk_fma_f32 v[138:139], v[20:21], v[138:139], v[142:143] op_sel_hi:[1,0,1]
	v_lshlrev_b32_e32 v142, 16, v140
	v_pk_fma_f32 v[144:145], v[18:19], v[142:143], v[144:145] op_sel_hi:[1,0,1]
	v_pk_fma_f32 v[138:139], v[16:17], v[142:143], v[138:139] op_sel_hi:[1,0,1]
	v_and_b32_e32 v140, 0xffff0000, v140
	v_pk_fma_f32 v[142:143], v[14:15], v[140:141], v[144:145] op_sel_hi:[1,0,1]
	v_pk_fma_f32 v[138:139], v[12:13], v[140:141], v[138:139] op_sel_hi:[1,0,1]
	v_lshlrev_b32_e32 v140, 16, v141
	v_pk_fma_f32 v[142:143], v[10:11], v[140:141], v[142:143] op_sel_hi:[1,0,1]
	v_pk_fma_f32 v[138:139], v[8:9], v[140:141], v[138:139] op_sel_hi:[1,0,1]
	v_and_b32_e32 v140, 0xffff0000, v141
	v_pk_fma_f32 v[138:139], v[4:5], v[140:141], v[138:139] op_sel_hi:[1,0,1]
	v_pk_fma_f32 v[142:143], v[6:7], v[140:141], v[142:143] op_sel_hi:[1,0,1]
	v_mul_f32_e64 v75, |v138|, s93
	v_exp_f32_e32 v75, v75
	v_min_f32_e32 v73, 0, v138
	v_lshlrev_b32_e32 v138, 16, v134
	v_mov_b32_e32 v140, 0x70000
	v_add_f32_e32 v75, 1.0, v75
	v_log_f32_e32 v75, v75
	s_nop 0
	v_fmac_f32_e32 v73, 0xbf317218, v75
	v_mul_f32_e64 v75, |v139|, s93
	v_exp_f32_e32 v75, v75
	v_fmac_f32_e32 v85, 0x3d800000, v73
	v_min_f32_e32 v73, 0, v139
	v_lshlrev_b32_e32 v139, 16, v146
	v_add_f32_e32 v75, 1.0, v75
	v_log_f32_e32 v75, v75
	s_nop 0
	v_fmac_f32_e32 v73, 0xbf317218, v75
	v_mul_f32_e64 v75, |v142|, s93
	v_exp_f32_e32 v75, v75
	v_fmac_f32_e32 v91, 0x3d800000, v73
	v_min_f32_e32 v73, 0, v142
	v_add_f32_e32 v75, 1.0, v75
	v_log_f32_e32 v75, v75
	s_nop 0
	v_fmac_f32_e32 v73, 0xbf317218, v75
	v_mul_f32_e64 v75, |v143|, s93
	v_exp_f32_e32 v75, v75
	v_fmac_f32_e32 v163, 0x3d800000, v73
	v_min_f32_e32 v73, 0, v143
	v_sub_f32_e32 v79, v128, v163
	v_add_f32_e32 v75, 1.0, v75
	v_log_f32_e32 v75, v75
	v_mul_f32_e32 v79, 0x3fb8aa3b, v79
	v_exp_f32_e32 v79, v79
	v_fmac_f32_e32 v73, 0xbf317218, v75
	v_fmac_f32_e32 v170, 0x3d800000, v73
	v_sub_f32_e32 v73, v130, v85
	v_mul_f32_e32 v73, 0x3fb8aa3b, v73
	v_sub_f32_e32 v75, v131, v91
	v_exp_f32_e32 v73, v73
	v_mul_f32_e32 v75, 0x3fb8aa3b, v75
	v_exp_f32_e32 v75, v75
	v_pk_mul_f32 v[72:73], v[72:73], v[138:139]
	v_and_b32_e32 v139, 0xffff0000, v146
	v_and_b32_e32 v138, 0xffff0000, v134
	v_pk_mul_f32 v[74:75], v[74:75], v[138:139]
	v_lshlrev_b32_e32 v139, 16, v147
	v_lshlrev_b32_e32 v138, 16, v135
	v_pk_mul_f32 v[78:79], v[78:79], v[138:139]
	v_sub_f32_e32 v134, v129, v170
	v_and_b32_e32 v139, 0xffff0000, v147
	global_load_dwordx4 v[144:147], v140, s[6:7] offset:3072
	v_mul_f32_e32 v134, 0x3fb8aa3b, v134
	v_exp_f32_e32 v137, v134
	v_and_b32_e32 v138, 0xffff0000, v135
	v_pk_mul_f32 v[134:135], v[136:137], v[138:139]
	v_add_co_u32_e32 v136, vcc, s0, v76
	s_add_u32 s0, s6, 0x70c00
	s_nop 0
	v_addc_co_u32_e32 v137, vcc, 0, v77, vcc
	s_addc_u32 s1, s7, 0
	global_load_dwordx2 v[142:143], v[136:137], off offset:2560
	s_waitcnt vmcnt(1)
	v_lshlrev_b32_e32 v140, 16, v144
	global_load_dwordx4 v[136:139], v3, s[0:1] offset:16
	v_pk_fma_f32 v[148:149], v[70:71], v[140:141], v[66:67] op_sel_hi:[1,0,1]
	v_pk_fma_f32 v[140:141], v[68:69], v[140:141], v[64:65] op_sel_hi:[1,0,1]
	v_and_b32_e32 v144, 0xffff0000, v144
	v_pk_fma_f32 v[148:149], v[62:63], v[144:145], v[148:149] op_sel_hi:[1,0,1]
	v_pk_fma_f32 v[140:141], v[60:61], v[144:145], v[140:141] op_sel_hi:[1,0,1]
	v_lshlrev_b32_e32 v144, 16, v145
	v_pk_fma_f32 v[148:149], v[58:59], v[144:145], v[148:149] op_sel_hi:[1,0,1]
	v_pk_fma_f32 v[140:141], v[56:57], v[144:145], v[140:141] op_sel_hi:[1,0,1]
	v_and_b32_e32 v144, 0xffff0000, v145
	v_pk_fma_f32 v[148:149], v[54:55], v[144:145], v[148:149] op_sel_hi:[1,0,1]
	v_pk_fma_f32 v[140:141], v[52:53], v[144:145], v[140:141] op_sel_hi:[1,0,1]
	v_lshlrev_b32_e32 v144, 16, v146
	v_pk_fma_f32 v[148:149], v[50:51], v[144:145], v[148:149] op_sel_hi:[1,0,1]
	v_pk_fma_f32 v[140:141], v[48:49], v[144:145], v[140:141] op_sel_hi:[1,0,1]
	v_and_b32_e32 v144, 0xffff0000, v146
	v_pk_fma_f32 v[148:149], v[46:47], v[144:145], v[148:149] op_sel_hi:[1,0,1]
	v_pk_fma_f32 v[140:141], v[44:45], v[144:145], v[140:141] op_sel_hi:[1,0,1]
	v_lshlrev_b32_e32 v144, 16, v147
	v_pk_fma_f32 v[148:149], v[42:43], v[144:145], v[148:149] op_sel_hi:[1,0,1]
	v_pk_fma_f32 v[140:141], v[40:41], v[144:145], v[140:141] op_sel_hi:[1,0,1]
	v_and_b32_e32 v144, 0xffff0000, v147
	v_pk_fma_f32 v[146:147], v[38:39], v[144:145], v[148:149] op_sel_hi:[1,0,1]
	v_pk_fma_f32 v[140:141], v[36:37], v[144:145], v[140:141] op_sel_hi:[1,0,1]
	s_add_u32 s0, s6, 0x73600
	s_addc_u32 s1, s7, 0
	s_waitcnt vmcnt(0)
	v_lshlrev_b32_e32 v144, 16, v136
	v_pk_fma_f32 v[146:147], v[34:35], v[144:145], v[146:147] op_sel_hi:[1,0,1]
	v_pk_fma_f32 v[140:141], v[32:33], v[144:145], v[140:141] op_sel_hi:[1,0,1]
	v_and_b32_e32 v136, 0xffff0000, v136
	v_pk_fma_f32 v[144:145], v[30:31], v[136:137], v[146:147] op_sel_hi:[1,0,1]
	v_pk_fma_f32 v[140:141], v[28:29], v[136:137], v[140:141] op_sel_hi:[1,0,1]
	v_lshlrev_b32_e32 v136, 16, v137
	v_pk_fma_f32 v[144:145], v[26:27], v[136:137], v[144:145] op_sel_hi:[1,0,1]
	v_pk_fma_f32 v[140:141], v[24:25], v[136:137], v[140:141] op_sel_hi:[1,0,1]
	v_and_b32_e32 v136, 0xffff0000, v137
	v_pk_fma_f32 v[144:145], v[22:23], v[136:137], v[144:145] op_sel_hi:[1,0,1]
	v_pk_fma_f32 v[136:137], v[20:21], v[136:137], v[140:141] op_sel_hi:[1,0,1]
	v_lshlrev_b32_e32 v140, 16, v138
	v_pk_fma_f32 v[144:145], v[18:19], v[140:141], v[144:145] op_sel_hi:[1,0,1]
	v_pk_fma_f32 v[136:137], v[16:17], v[140:141], v[136:137] op_sel_hi:[1,0,1]
	v_and_b32_e32 v138, 0xffff0000, v138
	v_pk_fma_f32 v[140:141], v[14:15], v[138:139], v[144:145] op_sel_hi:[1,0,1]
	v_pk_fma_f32 v[136:137], v[12:13], v[138:139], v[136:137] op_sel_hi:[1,0,1]
	v_lshlrev_b32_e32 v138, 16, v139
	v_pk_fma_f32 v[140:141], v[10:11], v[138:139], v[140:141] op_sel_hi:[1,0,1]
	v_pk_fma_f32 v[136:137], v[8:9], v[138:139], v[136:137] op_sel_hi:[1,0,1]
	v_and_b32_e32 v138, 0xffff0000, v139
	v_pk_fma_f32 v[136:137], v[4:5], v[138:139], v[136:137] op_sel_hi:[1,0,1]
	v_pk_fma_f32 v[140:141], v[6:7], v[138:139], v[140:141] op_sel_hi:[1,0,1]
	v_min_f32_e32 v138, 0, v136
	v_mul_f32_e64 v136, |v136|, s93
	v_exp_f32_e32 v136, v136
	v_add_co_u32_e32 v146, vcc, s55, v76
	v_add_f32_e32 v136, 1.0, v136
	v_log_f32_e32 v136, v136
	v_addc_co_u32_e32 v147, vcc, 0, v77, vcc
	global_load_dwordx2 v[154:155], v[146:147], off offset:1024
	v_fmac_f32_e32 v138, 0xbf317218, v136
	v_min_f32_e32 v136, 0, v137
	v_mul_f32_e64 v137, |v137|, s93
	v_exp_f32_e32 v137, v137
	v_fmac_f32_e32 v85, 0x3d800000, v138
	global_load_dwordx4 v[146:149], v3, s[0:1] offset:16
	s_mov_b32 s0, 0x73000
	v_add_f32_e32 v137, 1.0, v137
	v_log_f32_e32 v137, v137
	s_nop 0
	v_fmac_f32_e32 v136, 0xbf317218, v137
	v_mul_f32_e64 v137, |v140|, s93
	v_exp_f32_e32 v137, v137
	v_fmac_f32_e32 v91, 0x3d800000, v136
	v_min_f32_e32 v136, 0, v140
	v_add_f32_e32 v137, 1.0, v137
	v_log_f32_e32 v137, v137
	s_nop 0
	v_fmac_f32_e32 v136, 0xbf317218, v137
	v_mul_f32_e64 v137, |v141|, s93
	v_exp_f32_e32 v137, v137
	v_fmac_f32_e32 v163, 0x3d800000, v136
	v_min_f32_e32 v136, 0, v141
	v_add_f32_e32 v137, 1.0, v137
	v_log_f32_e32 v137, v137
	s_nop 0
	v_fmac_f32_e32 v136, 0xbf317218, v137
	v_sub_f32_e32 v137, v131, v91
	v_mul_f32_e32 v137, 0x3fb8aa3b, v137
	v_exp_f32_e32 v138, v137
	v_sub_f32_e32 v137, v128, v163
	v_fmac_f32_e32 v170, 0x3d800000, v136
	v_mul_f32_e32 v137, 0x3fb8aa3b, v137
	v_exp_f32_e32 v140, v137
	v_sub_f32_e32 v137, v129, v170
	v_mul_f32_e32 v137, 0x3fb8aa3b, v137
	v_exp_f32_e32 v144, v137
	v_mov_b32_e32 v137, 0x73000
	global_load_dwordx4 v[150:153], v137, s[6:7] offset:1536
	v_sub_f32_e32 v136, v130, v85
	v_mul_f32_e32 v136, 0x3fb8aa3b, v136
	v_exp_f32_e32 v136, v136
	s_waitcnt vmcnt(0)
	v_lshlrev_b32_e32 v156, 16, v150
	v_pk_fma_f32 v[158:159], v[70:71], v[156:157], v[66:67] op_sel_hi:[1,0,1]
	v_pk_fma_f32 v[156:157], v[68:69], v[156:157], v[64:65] op_sel_hi:[1,0,1]
	v_and_b32_e32 v150, 0xffff0000, v150
	v_pk_fma_f32 v[158:159], v[62:63], v[150:151], v[158:159] op_sel_hi:[1,0,1]
	v_pk_fma_f32 v[156:157], v[60:61], v[150:151], v[156:157] op_sel_hi:[1,0,1]
	v_lshlrev_b32_e32 v150, 16, v151
	v_pk_fma_f32 v[158:159], v[58:59], v[150:151], v[158:159] op_sel_hi:[1,0,1]
	v_pk_fma_f32 v[156:157], v[56:57], v[150:151], v[156:157] op_sel_hi:[1,0,1]
	v_and_b32_e32 v150, 0xffff0000, v151
	v_pk_fma_f32 v[158:159], v[54:55], v[150:151], v[158:159] op_sel_hi:[1,0,1]
	v_pk_fma_f32 v[150:151], v[52:53], v[150:151], v[156:157] op_sel_hi:[1,0,1]
	v_lshlrev_b32_e32 v156, 16, v152
	v_pk_fma_f32 v[158:159], v[50:51], v[156:157], v[158:159] op_sel_hi:[1,0,1]
	v_pk_fma_f32 v[150:151], v[48:49], v[156:157], v[150:151] op_sel_hi:[1,0,1]
	v_and_b32_e32 v152, 0xffff0000, v152
	v_pk_fma_f32 v[156:157], v[46:47], v[152:153], v[158:159] op_sel_hi:[1,0,1]
	v_pk_fma_f32 v[150:151], v[44:45], v[152:153], v[150:151] op_sel_hi:[1,0,1]
	v_lshlrev_b32_e32 v152, 16, v153
	v_pk_fma_f32 v[156:157], v[42:43], v[152:153], v[156:157] op_sel_hi:[1,0,1]
	v_pk_fma_f32 v[150:151], v[40:41], v[152:153], v[150:151] op_sel_hi:[1,0,1]
	v_and_b32_e32 v152, 0xffff0000, v153
	v_pk_fma_f32 v[156:157], v[38:39], v[152:153], v[156:157] op_sel_hi:[1,0,1]
	v_pk_fma_f32 v[150:151], v[36:37], v[152:153], v[150:151] op_sel_hi:[1,0,1]
	v_lshlrev_b32_e32 v152, 16, v146
	v_pk_fma_f32 v[156:157], v[34:35], v[152:153], v[156:157] op_sel_hi:[1,0,1]
	v_pk_fma_f32 v[150:151], v[32:33], v[152:153], v[150:151] op_sel_hi:[1,0,1]
	v_and_b32_e32 v146, 0xffff0000, v146
	v_pk_fma_f32 v[152:153], v[30:31], v[146:147], v[156:157] op_sel_hi:[1,0,1]
	v_pk_fma_f32 v[150:151], v[28:29], v[146:147], v[150:151] op_sel_hi:[1,0,1]
	v_lshlrev_b32_e32 v146, 16, v147
	v_pk_fma_f32 v[152:153], v[26:27], v[146:147], v[152:153] op_sel_hi:[1,0,1]
	v_pk_fma_f32 v[150:151], v[24:25], v[146:147], v[150:151] op_sel_hi:[1,0,1]
	v_and_b32_e32 v146, 0xffff0000, v147
	v_pk_fma_f32 v[152:153], v[22:23], v[146:147], v[152:153] op_sel_hi:[1,0,1]
	v_pk_fma_f32 v[146:147], v[20:21], v[146:147], v[150:151] op_sel_hi:[1,0,1]
	v_lshlrev_b32_e32 v150, 16, v148
	v_pk_fma_f32 v[152:153], v[18:19], v[150:151], v[152:153] op_sel_hi:[1,0,1]
	v_pk_fma_f32 v[146:147], v[16:17], v[150:151], v[146:147] op_sel_hi:[1,0,1]
	v_and_b32_e32 v148, 0xffff0000, v148
	v_pk_fma_f32 v[150:151], v[14:15], v[148:149], v[152:153] op_sel_hi:[1,0,1]
	v_pk_fma_f32 v[146:147], v[12:13], v[148:149], v[146:147] op_sel_hi:[1,0,1]
	v_lshlrev_b32_e32 v148, 16, v149
	v_pk_fma_f32 v[150:151], v[10:11], v[148:149], v[150:151] op_sel_hi:[1,0,1]
	v_pk_fma_f32 v[146:147], v[8:9], v[148:149], v[146:147] op_sel_hi:[1,0,1]
	v_and_b32_e32 v148, 0xffff0000, v149
	v_pk_fma_f32 v[146:147], v[4:5], v[148:149], v[146:147] op_sel_hi:[1,0,1]
	v_pk_fma_f32 v[150:151], v[6:7], v[148:149], v[150:151] op_sel_hi:[1,0,1]
	v_mul_f32_e64 v139, |v146|, s93
	v_exp_f32_e32 v139, v139
	v_min_f32_e32 v137, 0, v146
	v_lshlrev_b32_e32 v146, 16, v142
	v_mov_b32_e32 v148, 0x76000
	v_add_f32_e32 v139, 1.0, v139
	v_log_f32_e32 v139, v139
	s_nop 0
	v_fmac_f32_e32 v137, 0xbf317218, v139
	v_mul_f32_e64 v139, |v147|, s93
	v_exp_f32_e32 v139, v139
	v_fmac_f32_e32 v85, 0x3d800000, v137
	v_min_f32_e32 v137, 0, v147
	v_lshlrev_b32_e32 v147, 16, v154
	v_add_f32_e32 v139, 1.0, v139
	v_log_f32_e32 v139, v139
	s_nop 0
	v_fmac_f32_e32 v137, 0xbf317218, v139
	v_mul_f32_e64 v139, |v150|, s93
	v_exp_f32_e32 v139, v139
	v_fmac_f32_e32 v91, 0x3d800000, v137
	v_min_f32_e32 v137, 0, v150
	v_add_f32_e32 v139, 1.0, v139
	v_log_f32_e32 v139, v139
	s_nop 0
	v_fmac_f32_e32 v137, 0xbf317218, v139
	v_mul_f32_e64 v139, |v151|, s93
	v_exp_f32_e32 v139, v139
	v_fmac_f32_e32 v163, 0x3d800000, v137
	v_min_f32_e32 v137, 0, v151
	v_sub_f32_e32 v141, v128, v163
	v_add_f32_e32 v139, 1.0, v139
	v_log_f32_e32 v139, v139
	v_mul_f32_e32 v141, 0x3fb8aa3b, v141
	v_exp_f32_e32 v141, v141
	v_fmac_f32_e32 v137, 0xbf317218, v139
	v_fmac_f32_e32 v170, 0x3d800000, v137
	v_sub_f32_e32 v137, v130, v85
	v_mul_f32_e32 v137, 0x3fb8aa3b, v137
	v_sub_f32_e32 v139, v131, v91
	v_exp_f32_e32 v137, v137
	v_mul_f32_e32 v139, 0x3fb8aa3b, v139
	v_exp_f32_e32 v139, v139
	v_pk_mul_f32 v[136:137], v[136:137], v[146:147]
	v_and_b32_e32 v147, 0xffff0000, v154
	v_and_b32_e32 v146, 0xffff0000, v142
	v_pk_mul_f32 v[138:139], v[138:139], v[146:147]
	v_lshlrev_b32_e32 v147, 16, v155
	v_lshlrev_b32_e32 v146, 16, v143
	v_pk_mul_f32 v[140:141], v[140:141], v[146:147]
	v_sub_f32_e32 v142, v129, v170
	v_and_b32_e32 v147, 0xffff0000, v155
	global_load_dwordx4 v[152:155], v148, s[6:7]
	v_mul_f32_e32 v142, 0x3fb8aa3b, v142
	v_exp_f32_e32 v145, v142
	v_and_b32_e32 v146, 0xffff0000, v143
	v_pk_mul_f32 v[142:143], v[144:145], v[146:147]
	v_add_co_u32_e32 v144, vcc, s0, v76
	s_add_u32 s0, s6, 0x76000
	s_nop 0
	v_addc_co_u32_e32 v145, vcc, 0, v77, vcc
	s_addc_u32 s1, s7, 0
	global_load_dwordx2 v[150:151], v[144:145], off offset:3584
	s_waitcnt vmcnt(1)
	v_lshlrev_b32_e32 v148, 16, v152
	global_load_dwordx4 v[144:147], v3, s[0:1] offset:16
	v_pk_fma_f32 v[156:157], v[70:71], v[148:149], v[66:67] op_sel_hi:[1,0,1]
	v_pk_fma_f32 v[148:149], v[68:69], v[148:149], v[64:65] op_sel_hi:[1,0,1]
	v_and_b32_e32 v152, 0xffff0000, v152
	v_pk_fma_f32 v[156:157], v[62:63], v[152:153], v[156:157] op_sel_hi:[1,0,1]
	v_pk_fma_f32 v[148:149], v[60:61], v[152:153], v[148:149] op_sel_hi:[1,0,1]
	v_lshlrev_b32_e32 v152, 16, v153
	v_pk_fma_f32 v[156:157], v[58:59], v[152:153], v[156:157] op_sel_hi:[1,0,1]
	v_pk_fma_f32 v[148:149], v[56:57], v[152:153], v[148:149] op_sel_hi:[1,0,1]
	v_and_b32_e32 v152, 0xffff0000, v153
	v_pk_fma_f32 v[156:157], v[54:55], v[152:153], v[156:157] op_sel_hi:[1,0,1]
	v_pk_fma_f32 v[148:149], v[52:53], v[152:153], v[148:149] op_sel_hi:[1,0,1]
	v_lshlrev_b32_e32 v152, 16, v154
	v_pk_fma_f32 v[156:157], v[50:51], v[152:153], v[156:157] op_sel_hi:[1,0,1]
	v_pk_fma_f32 v[148:149], v[48:49], v[152:153], v[148:149] op_sel_hi:[1,0,1]
	v_and_b32_e32 v152, 0xffff0000, v154
	v_pk_fma_f32 v[156:157], v[46:47], v[152:153], v[156:157] op_sel_hi:[1,0,1]
	v_pk_fma_f32 v[148:149], v[44:45], v[152:153], v[148:149] op_sel_hi:[1,0,1]
	v_lshlrev_b32_e32 v152, 16, v155
	v_pk_fma_f32 v[156:157], v[42:43], v[152:153], v[156:157] op_sel_hi:[1,0,1]
	v_pk_fma_f32 v[148:149], v[40:41], v[152:153], v[148:149] op_sel_hi:[1,0,1]
	v_and_b32_e32 v152, 0xffff0000, v155
	v_pk_fma_f32 v[154:155], v[38:39], v[152:153], v[156:157] op_sel_hi:[1,0,1]
	v_pk_fma_f32 v[148:149], v[36:37], v[152:153], v[148:149] op_sel_hi:[1,0,1]
	s_add_u32 s0, s6, 0x78a00
	s_addc_u32 s1, s7, 0
	s_waitcnt vmcnt(0)
	v_lshlrev_b32_e32 v152, 16, v144
	v_pk_fma_f32 v[154:155], v[34:35], v[152:153], v[154:155] op_sel_hi:[1,0,1]
	v_pk_fma_f32 v[148:149], v[32:33], v[152:153], v[148:149] op_sel_hi:[1,0,1]
	v_and_b32_e32 v144, 0xffff0000, v144
	v_pk_fma_f32 v[152:153], v[30:31], v[144:145], v[154:155] op_sel_hi:[1,0,1]
	v_pk_fma_f32 v[148:149], v[28:29], v[144:145], v[148:149] op_sel_hi:[1,0,1]
	v_lshlrev_b32_e32 v144, 16, v145
	v_pk_fma_f32 v[152:153], v[26:27], v[144:145], v[152:153] op_sel_hi:[1,0,1]
	v_pk_fma_f32 v[148:149], v[24:25], v[144:145], v[148:149] op_sel_hi:[1,0,1]
	v_and_b32_e32 v144, 0xffff0000, v145
	v_pk_fma_f32 v[152:153], v[22:23], v[144:145], v[152:153] op_sel_hi:[1,0,1]
	v_pk_fma_f32 v[144:145], v[20:21], v[144:145], v[148:149] op_sel_hi:[1,0,1]
	v_lshlrev_b32_e32 v148, 16, v146
	v_pk_fma_f32 v[152:153], v[18:19], v[148:149], v[152:153] op_sel_hi:[1,0,1]
	v_pk_fma_f32 v[144:145], v[16:17], v[148:149], v[144:145] op_sel_hi:[1,0,1]
	v_and_b32_e32 v146, 0xffff0000, v146
	v_pk_fma_f32 v[148:149], v[14:15], v[146:147], v[152:153] op_sel_hi:[1,0,1]
	v_pk_fma_f32 v[144:145], v[12:13], v[146:147], v[144:145] op_sel_hi:[1,0,1]
	v_lshlrev_b32_e32 v146, 16, v147
	v_pk_fma_f32 v[148:149], v[10:11], v[146:147], v[148:149] op_sel_hi:[1,0,1]
	v_pk_fma_f32 v[144:145], v[8:9], v[146:147], v[144:145] op_sel_hi:[1,0,1]
	v_and_b32_e32 v146, 0xffff0000, v147
	v_pk_fma_f32 v[144:145], v[4:5], v[146:147], v[144:145] op_sel_hi:[1,0,1]
	v_pk_fma_f32 v[148:149], v[6:7], v[146:147], v[148:149] op_sel_hi:[1,0,1]
	v_min_f32_e32 v146, 0, v144
	v_mul_f32_e64 v144, |v144|, s93
	v_exp_f32_e32 v144, v144
	v_add_co_u32_e32 v154, vcc, s56, v76
	v_add_f32_e32 v144, 1.0, v144
	v_log_f32_e32 v144, v144
	v_addc_co_u32_e32 v155, vcc, 0, v77, vcc
	global_load_dwordx2 v[164:165], v[154:155], off offset:2048
	v_fmac_f32_e32 v146, 0xbf317218, v144
	v_min_f32_e32 v144, 0, v145
	v_mul_f32_e64 v145, |v145|, s93
	v_exp_f32_e32 v145, v145
	v_fmac_f32_e32 v85, 0x3d800000, v146
	global_load_dwordx4 v[154:157], v3, s[0:1] offset:16
	s_add_u32 s0, s6, 0x7b400
	v_add_f32_e32 v145, 1.0, v145
	v_log_f32_e32 v145, v145
	s_addc_u32 s1, s7, 0
	v_fmac_f32_e32 v144, 0xbf317218, v145
	v_mul_f32_e64 v145, |v148|, s93
	v_exp_f32_e32 v145, v145
	v_fmac_f32_e32 v91, 0x3d800000, v144
	v_min_f32_e32 v144, 0, v148
	v_add_f32_e32 v145, 1.0, v145
	v_log_f32_e32 v145, v145
	s_nop 0
	v_fmac_f32_e32 v144, 0xbf317218, v145
	v_mul_f32_e64 v145, |v149|, s93
	v_exp_f32_e32 v145, v145
	v_fmac_f32_e32 v163, 0x3d800000, v144
	v_min_f32_e32 v144, 0, v149
	v_add_f32_e32 v145, 1.0, v145
	v_log_f32_e32 v145, v145
	s_nop 0
	v_fmac_f32_e32 v144, 0xbf317218, v145
	v_sub_f32_e32 v145, v131, v91
	v_mul_f32_e32 v145, 0x3fb8aa3b, v145
	v_exp_f32_e32 v146, v145
	v_sub_f32_e32 v145, v128, v163
	v_fmac_f32_e32 v170, 0x3d800000, v144
	v_mul_f32_e32 v145, 0x3fb8aa3b, v145
	v_exp_f32_e32 v148, v145
	v_sub_f32_e32 v145, v129, v170
	v_mul_f32_e32 v145, 0x3fb8aa3b, v145
	v_exp_f32_e32 v152, v145
	v_mov_b32_e32 v145, 0x78000
	global_load_dwordx4 v[158:161], v145, s[6:7] offset:2560
	v_sub_f32_e32 v144, v130, v85
	v_mul_f32_e32 v144, 0x3fb8aa3b, v144
	v_exp_f32_e32 v144, v144
	s_waitcnt vmcnt(0)
	v_lshlrev_b32_e32 v162, 16, v158
	v_pk_fma_f32 v[166:167], v[70:71], v[162:163], v[66:67] op_sel_hi:[1,0,1]
	v_pk_fma_f32 v[168:169], v[68:69], v[162:163], v[64:65] op_sel_hi:[1,0,1]
	v_and_b32_e32 v158, 0xffff0000, v158
	v_pk_fma_f32 v[166:167], v[62:63], v[158:159], v[166:167] op_sel_hi:[1,0,1]
	v_pk_fma_f32 v[168:169], v[60:61], v[158:159], v[168:169] op_sel_hi:[1,0,1]
	v_lshlrev_b32_e32 v158, 16, v159
	v_pk_fma_f32 v[166:167], v[58:59], v[158:159], v[166:167] op_sel_hi:[1,0,1]
	v_pk_fma_f32 v[168:169], v[56:57], v[158:159], v[168:169] op_sel_hi:[1,0,1]
	v_and_b32_e32 v158, 0xffff0000, v159
	v_pk_fma_f32 v[166:167], v[54:55], v[158:159], v[166:167] op_sel_hi:[1,0,1]
	v_pk_fma_f32 v[158:159], v[52:53], v[158:159], v[168:169] op_sel_hi:[1,0,1]
	v_lshlrev_b32_e32 v162, 16, v160
	v_pk_fma_f32 v[166:167], v[50:51], v[162:163], v[166:167] op_sel_hi:[1,0,1]
	v_pk_fma_f32 v[158:159], v[48:49], v[162:163], v[158:159] op_sel_hi:[1,0,1]
	v_and_b32_e32 v160, 0xffff0000, v160
	v_pk_fma_f32 v[166:167], v[46:47], v[160:161], v[166:167] op_sel_hi:[1,0,1]
	v_pk_fma_f32 v[158:159], v[44:45], v[160:161], v[158:159] op_sel_hi:[1,0,1]
	v_lshlrev_b32_e32 v160, 16, v161
	v_pk_fma_f32 v[166:167], v[42:43], v[160:161], v[166:167] op_sel_hi:[1,0,1]
	v_pk_fma_f32 v[158:159], v[40:41], v[160:161], v[158:159] op_sel_hi:[1,0,1]
	v_and_b32_e32 v160, 0xffff0000, v161
	v_pk_fma_f32 v[166:167], v[38:39], v[160:161], v[166:167] op_sel_hi:[1,0,1]
	v_pk_fma_f32 v[158:159], v[36:37], v[160:161], v[158:159] op_sel_hi:[1,0,1]
	v_lshlrev_b32_e32 v160, 16, v154
	v_pk_fma_f32 v[166:167], v[34:35], v[160:161], v[166:167] op_sel_hi:[1,0,1]
	v_pk_fma_f32 v[158:159], v[32:33], v[160:161], v[158:159] op_sel_hi:[1,0,1]
	v_and_b32_e32 v154, 0xffff0000, v154
	v_pk_fma_f32 v[160:161], v[30:31], v[154:155], v[166:167] op_sel_hi:[1,0,1]
	v_pk_fma_f32 v[158:159], v[28:29], v[154:155], v[158:159] op_sel_hi:[1,0,1]
	v_lshlrev_b32_e32 v154, 16, v155
	v_pk_fma_f32 v[160:161], v[26:27], v[154:155], v[160:161] op_sel_hi:[1,0,1]
	v_pk_fma_f32 v[158:159], v[24:25], v[154:155], v[158:159] op_sel_hi:[1,0,1]
	v_and_b32_e32 v154, 0xffff0000, v155
	v_pk_fma_f32 v[160:161], v[22:23], v[154:155], v[160:161] op_sel_hi:[1,0,1]
	v_pk_fma_f32 v[154:155], v[20:21], v[154:155], v[158:159] op_sel_hi:[1,0,1]
	v_lshlrev_b32_e32 v158, 16, v156
	v_pk_fma_f32 v[160:161], v[18:19], v[158:159], v[160:161] op_sel_hi:[1,0,1]
	v_pk_fma_f32 v[154:155], v[16:17], v[158:159], v[154:155] op_sel_hi:[1,0,1]
	v_and_b32_e32 v156, 0xffff0000, v156
	v_pk_fma_f32 v[158:159], v[14:15], v[156:157], v[160:161] op_sel_hi:[1,0,1]
	v_pk_fma_f32 v[154:155], v[12:13], v[156:157], v[154:155] op_sel_hi:[1,0,1]
	v_lshlrev_b32_e32 v156, 16, v157
	v_pk_fma_f32 v[158:159], v[10:11], v[156:157], v[158:159] op_sel_hi:[1,0,1]
	v_pk_fma_f32 v[154:155], v[8:9], v[156:157], v[154:155] op_sel_hi:[1,0,1]
	v_and_b32_e32 v156, 0xffff0000, v157
	v_pk_fma_f32 v[154:155], v[4:5], v[156:157], v[154:155] op_sel_hi:[1,0,1]
	v_pk_fma_f32 v[158:159], v[6:7], v[156:157], v[158:159] op_sel_hi:[1,0,1]
	v_mul_f32_e64 v147, |v154|, s93
	v_exp_f32_e32 v147, v147
	v_min_f32_e32 v145, 0, v154
	v_lshlrev_b32_e32 v154, 16, v150
	v_add_f32_e32 v147, 1.0, v147
	v_log_f32_e32 v147, v147
	s_nop 0
	v_fmac_f32_e32 v145, 0xbf317218, v147
	v_mul_f32_e64 v147, |v155|, s93
	v_exp_f32_e32 v147, v147
	v_fmac_f32_e32 v85, 0x3d800000, v145
	v_min_f32_e32 v145, 0, v155
	v_lshlrev_b32_e32 v155, 16, v164
	v_add_f32_e32 v147, 1.0, v147
	v_log_f32_e32 v147, v147
	s_nop 0
	v_fmac_f32_e32 v145, 0xbf317218, v147
	v_mul_f32_e64 v147, |v158|, s93
	v_exp_f32_e32 v147, v147
	v_fmac_f32_e32 v91, 0x3d800000, v145
	v_min_f32_e32 v145, 0, v158
	v_mov_b32_e32 v158, 0x7b000
	v_add_f32_e32 v147, 1.0, v147
	v_log_f32_e32 v147, v147
	s_nop 0
	v_fmac_f32_e32 v145, 0xbf317218, v147
	v_mul_f32_e64 v147, |v159|, s93
	v_exp_f32_e32 v147, v147
	v_fmac_f32_e32 v163, 0x3d800000, v145
	v_min_f32_e32 v145, 0, v159
	global_load_dwordx4 v[158:161], v158, s[6:7] offset:1024
	v_add_f32_e32 v147, 1.0, v147
	v_log_f32_e32 v147, v147
	v_sub_f32_e32 v149, v128, v163
	v_mul_f32_e32 v149, 0x3fb8aa3b, v149
	v_exp_f32_e32 v149, v149
	v_fmac_f32_e32 v145, 0xbf317218, v147
	v_fmac_f32_e32 v170, 0x3d800000, v145
	v_sub_f32_e32 v145, v130, v85
	v_mul_f32_e32 v145, 0x3fb8aa3b, v145
	v_exp_f32_e32 v145, v145
	v_sub_f32_e32 v147, v131, v91
	v_mul_f32_e32 v147, 0x3fb8aa3b, v147
	v_exp_f32_e32 v147, v147
	v_pk_mul_f32 v[144:145], v[144:145], v[154:155]
	v_and_b32_e32 v154, 0xffff0000, v150
	v_sub_f32_e32 v150, v129, v170
	v_mul_f32_e32 v150, 0x3fb8aa3b, v150
	v_exp_f32_e32 v153, v150
	v_and_b32_e32 v155, 0xffff0000, v164
	v_pk_mul_f32 v[146:147], v[146:147], v[154:155]
	v_lshlrev_b32_e32 v155, 16, v165
	v_lshlrev_b32_e32 v154, 16, v151
	v_pk_mul_f32 v[148:149], v[148:149], v[154:155]
	v_and_b32_e32 v155, 0xffff0000, v165
	v_and_b32_e32 v154, 0xffff0000, v151
	v_pk_mul_f32 v[150:151], v[152:153], v[154:155]
	global_load_dwordx4 v[154:157], v3, s[0:1] offset:16
	v_add_co_u32_e32 v152, vcc, s57, v76
	s_mov_b32 s0, 0x7b000
	s_nop 0
	v_addc_co_u32_e32 v153, vcc, 0, v77, vcc
	global_load_dwordx2 v[152:153], v[152:153], off offset:512
	s_waitcnt vmcnt(2)
	v_lshlrev_b32_e32 v162, 16, v158
	v_pk_fma_f32 v[164:165], v[70:71], v[162:163], v[66:67] op_sel_hi:[1,0,1]
	v_pk_fma_f32 v[166:167], v[68:69], v[162:163], v[64:65] op_sel_hi:[1,0,1]
	v_and_b32_e32 v158, 0xffff0000, v158
	v_pk_fma_f32 v[164:165], v[62:63], v[158:159], v[164:165] op_sel_hi:[1,0,1]
	v_pk_fma_f32 v[166:167], v[60:61], v[158:159], v[166:167] op_sel_hi:[1,0,1]
	v_lshlrev_b32_e32 v158, 16, v159
	v_pk_fma_f32 v[164:165], v[58:59], v[158:159], v[164:165] op_sel_hi:[1,0,1]
	v_pk_fma_f32 v[166:167], v[56:57], v[158:159], v[166:167] op_sel_hi:[1,0,1]
	v_and_b32_e32 v158, 0xffff0000, v159
	v_pk_fma_f32 v[164:165], v[54:55], v[158:159], v[164:165] op_sel_hi:[1,0,1]
	v_pk_fma_f32 v[158:159], v[52:53], v[158:159], v[166:167] op_sel_hi:[1,0,1]
	v_lshlrev_b32_e32 v162, 16, v160
	v_pk_fma_f32 v[164:165], v[50:51], v[162:163], v[164:165] op_sel_hi:[1,0,1]
	v_pk_fma_f32 v[158:159], v[48:49], v[162:163], v[158:159] op_sel_hi:[1,0,1]
	v_and_b32_e32 v160, 0xffff0000, v160
	v_pk_fma_f32 v[164:165], v[46:47], v[160:161], v[164:165] op_sel_hi:[1,0,1]
	v_pk_fma_f32 v[158:159], v[44:45], v[160:161], v[158:159] op_sel_hi:[1,0,1]
	v_lshlrev_b32_e32 v160, 16, v161
	v_pk_fma_f32 v[164:165], v[42:43], v[160:161], v[164:165] op_sel_hi:[1,0,1]
	v_pk_fma_f32 v[158:159], v[40:41], v[160:161], v[158:159] op_sel_hi:[1,0,1]
	v_and_b32_e32 v160, 0xffff0000, v161
	v_pk_fma_f32 v[164:165], v[38:39], v[160:161], v[164:165] op_sel_hi:[1,0,1]
	v_pk_fma_f32 v[158:159], v[36:37], v[160:161], v[158:159] op_sel_hi:[1,0,1]
	s_waitcnt vmcnt(1)
	v_lshlrev_b32_e32 v160, 16, v154
	v_pk_fma_f32 v[164:165], v[34:35], v[160:161], v[164:165] op_sel_hi:[1,0,1]
	v_pk_fma_f32 v[158:159], v[32:33], v[160:161], v[158:159] op_sel_hi:[1,0,1]
	v_and_b32_e32 v154, 0xffff0000, v154
	v_pk_fma_f32 v[160:161], v[30:31], v[154:155], v[164:165] op_sel_hi:[1,0,1]
	v_pk_fma_f32 v[158:159], v[28:29], v[154:155], v[158:159] op_sel_hi:[1,0,1]
	v_lshlrev_b32_e32 v154, 16, v155
	v_pk_fma_f32 v[160:161], v[26:27], v[154:155], v[160:161] op_sel_hi:[1,0,1]
	v_pk_fma_f32 v[158:159], v[24:25], v[154:155], v[158:159] op_sel_hi:[1,0,1]
	v_and_b32_e32 v154, 0xffff0000, v155
	v_pk_fma_f32 v[160:161], v[22:23], v[154:155], v[160:161] op_sel_hi:[1,0,1]
	v_pk_fma_f32 v[154:155], v[20:21], v[154:155], v[158:159] op_sel_hi:[1,0,1]
	v_lshlrev_b32_e32 v158, 16, v156
	v_pk_fma_f32 v[160:161], v[18:19], v[158:159], v[160:161] op_sel_hi:[1,0,1]
	v_pk_fma_f32 v[154:155], v[16:17], v[158:159], v[154:155] op_sel_hi:[1,0,1]
	v_and_b32_e32 v156, 0xffff0000, v156
	v_pk_fma_f32 v[158:159], v[14:15], v[156:157], v[160:161] op_sel_hi:[1,0,1]
	v_pk_fma_f32 v[154:155], v[12:13], v[156:157], v[154:155] op_sel_hi:[1,0,1]
	v_lshlrev_b32_e32 v156, 16, v157
	v_pk_fma_f32 v[158:159], v[10:11], v[156:157], v[158:159] op_sel_hi:[1,0,1]
	v_pk_fma_f32 v[154:155], v[8:9], v[156:157], v[154:155] op_sel_hi:[1,0,1]
	v_and_b32_e32 v156, 0xffff0000, v157
	v_pk_fma_f32 v[154:155], v[4:5], v[156:157], v[154:155] op_sel_hi:[1,0,1]
	v_pk_fma_f32 v[158:159], v[6:7], v[156:157], v[158:159] op_sel_hi:[1,0,1]
	v_min_f32_e32 v156, 0, v154
	v_mul_f32_e64 v154, |v154|, s93
	v_exp_f32_e32 v154, v154
	v_add_co_u32_e32 v164, vcc, s0, v76
	s_add_u32 s0, s6, 0x7de00
	v_add_f32_e32 v154, 1.0, v154
	v_log_f32_e32 v154, v154
	v_addc_co_u32_e32 v165, vcc, 0, v77, vcc
	s_addc_u32 s1, s7, 0
	v_fmac_f32_e32 v156, 0xbf317218, v154
	v_min_f32_e32 v154, 0, v155
	v_mul_f32_e64 v155, |v155|, s93
	v_exp_f32_e32 v155, v155
	global_load_dwordx2 v[168:169], v[164:165], off offset:3072
	v_fmac_f32_e32 v85, 0x3d800000, v156
	global_load_dwordx4 v[164:167], v3, s[0:1] offset:16
	v_add_f32_e32 v155, 1.0, v155
	v_log_f32_e32 v155, v155
	s_add_u32 s0, s6, 0x80800
	s_addc_u32 s1, s7, 0
	v_fmac_f32_e32 v154, 0xbf317218, v155
	v_mul_f32_e64 v155, |v158|, s93
	v_exp_f32_e32 v155, v155
	v_fmac_f32_e32 v91, 0x3d800000, v154
	v_min_f32_e32 v154, 0, v158
	v_add_f32_e32 v155, 1.0, v155
	v_log_f32_e32 v155, v155
	s_nop 0
	v_fmac_f32_e32 v154, 0xbf317218, v155
	v_mul_f32_e64 v155, |v159|, s93
	v_exp_f32_e32 v155, v155
	v_fmac_f32_e32 v163, 0x3d800000, v154
	v_min_f32_e32 v154, 0, v159
	v_add_f32_e32 v155, 1.0, v155
	v_log_f32_e32 v155, v155
	s_nop 0
	v_fmac_f32_e32 v154, 0xbf317218, v155
	v_mov_b32_e32 v155, 0x7d000
	global_load_dwordx4 v[172:175], v155, s[6:7] offset:3584
	v_fmac_f32_e32 v170, 0x3d800000, v154
	v_sub_f32_e32 v154, v130, v85
	v_mul_f32_e32 v154, 0x3fb8aa3b, v154
	v_exp_f32_e32 v160, v154
	v_sub_f32_e32 v154, v131, v91
	v_mul_f32_e32 v154, 0x3fb8aa3b, v154
	v_exp_f32_e32 v158, v154
	v_sub_f32_e32 v154, v128, v163
	v_mul_f32_e32 v154, 0x3fb8aa3b, v154
	v_exp_f32_e32 v156, v154
	v_sub_f32_e32 v154, v129, v170
	v_mul_f32_e32 v154, 0x3fb8aa3b, v154
	v_exp_f32_e32 v154, v154
	s_waitcnt vmcnt(0)
	v_lshlrev_b32_e32 v162, 16, v172
	v_pk_fma_f32 v[176:177], v[70:71], v[162:163], v[66:67] op_sel_hi:[1,0,1]
	v_pk_fma_f32 v[178:179], v[68:69], v[162:163], v[64:65] op_sel_hi:[1,0,1]
	v_and_b32_e32 v162, 0xffff0000, v172
	v_pk_fma_f32 v[176:177], v[62:63], v[162:163], v[176:177] op_sel_hi:[1,0,1]
	v_pk_fma_f32 v[178:179], v[60:61], v[162:163], v[178:179] op_sel_hi:[1,0,1]
	v_lshlrev_b32_e32 v162, 16, v173
	v_pk_fma_f32 v[176:177], v[58:59], v[162:163], v[176:177] op_sel_hi:[1,0,1]
	v_pk_fma_f32 v[178:179], v[56:57], v[162:163], v[178:179] op_sel_hi:[1,0,1]
	v_and_b32_e32 v162, 0xffff0000, v173
	v_pk_fma_f32 v[172:173], v[54:55], v[162:163], v[176:177] op_sel_hi:[1,0,1]
	v_pk_fma_f32 v[176:177], v[52:53], v[162:163], v[178:179] op_sel_hi:[1,0,1]
	v_lshlrev_b32_e32 v162, 16, v174
	v_pk_fma_f32 v[172:173], v[50:51], v[162:163], v[172:173] op_sel_hi:[1,0,1]
	v_pk_fma_f32 v[176:177], v[48:49], v[162:163], v[176:177] op_sel_hi:[1,0,1]
	v_and_b32_e32 v162, 0xffff0000, v174
	v_pk_fma_f32 v[172:173], v[46:47], v[162:163], v[172:173] op_sel_hi:[1,0,1]
	v_pk_fma_f32 v[176:177], v[44:45], v[162:163], v[176:177] op_sel_hi:[1,0,1]
	v_lshlrev_b32_e32 v162, 16, v175
	v_pk_fma_f32 v[172:173], v[42:43], v[162:163], v[172:173] op_sel_hi:[1,0,1]
	v_pk_fma_f32 v[176:177], v[40:41], v[162:163], v[176:177] op_sel_hi:[1,0,1]
	v_and_b32_e32 v162, 0xffff0000, v175
	v_pk_fma_f32 v[172:173], v[38:39], v[162:163], v[172:173] op_sel_hi:[1,0,1]
	v_pk_fma_f32 v[174:175], v[36:37], v[162:163], v[176:177] op_sel_hi:[1,0,1]
	v_lshlrev_b32_e32 v162, 16, v164
	v_pk_fma_f32 v[172:173], v[34:35], v[162:163], v[172:173] op_sel_hi:[1,0,1]
	v_pk_fma_f32 v[174:175], v[32:33], v[162:163], v[174:175] op_sel_hi:[1,0,1]
	v_and_b32_e32 v162, 0xffff0000, v164
	v_pk_fma_f32 v[172:173], v[30:31], v[162:163], v[172:173] op_sel_hi:[1,0,1]
	v_pk_fma_f32 v[174:175], v[28:29], v[162:163], v[174:175] op_sel_hi:[1,0,1]
	v_lshlrev_b32_e32 v162, 16, v165
	v_pk_fma_f32 v[172:173], v[26:27], v[162:163], v[172:173] op_sel_hi:[1,0,1]
	v_pk_fma_f32 v[174:175], v[24:25], v[162:163], v[174:175] op_sel_hi:[1,0,1]
	v_and_b32_e32 v162, 0xffff0000, v165
	v_pk_fma_f32 v[164:165], v[22:23], v[162:163], v[172:173] op_sel_hi:[1,0,1]
	v_pk_fma_f32 v[172:173], v[20:21], v[162:163], v[174:175] op_sel_hi:[1,0,1]
	v_lshlrev_b32_e32 v162, 16, v166
	v_pk_fma_f32 v[164:165], v[18:19], v[162:163], v[164:165] op_sel_hi:[1,0,1]
	v_pk_fma_f32 v[172:173], v[16:17], v[162:163], v[172:173] op_sel_hi:[1,0,1]
	v_and_b32_e32 v162, 0xffff0000, v166
	v_pk_fma_f32 v[164:165], v[14:15], v[162:163], v[164:165] op_sel_hi:[1,0,1]
	v_pk_fma_f32 v[172:173], v[12:13], v[162:163], v[172:173] op_sel_hi:[1,0,1]
	v_lshlrev_b32_e32 v162, 16, v167
	v_pk_fma_f32 v[164:165], v[10:11], v[162:163], v[164:165] op_sel_hi:[1,0,1]
	v_pk_fma_f32 v[172:173], v[8:9], v[162:163], v[172:173] op_sel_hi:[1,0,1]
	v_and_b32_e32 v162, 0xffff0000, v167
	v_pk_fma_f32 v[166:167], v[4:5], v[162:163], v[172:173] op_sel_hi:[1,0,1]
	v_pk_fma_f32 v[164:165], v[6:7], v[162:163], v[164:165] op_sel_hi:[1,0,1]
	v_mul_f32_e64 v157, |v166|, s93
	v_exp_f32_e32 v157, v157
	v_min_f32_e32 v155, 0, v166
	v_add_f32_e32 v157, 1.0, v157
	v_log_f32_e32 v157, v157
	s_nop 0
	v_fmac_f32_e32 v155, 0xbf317218, v157
	v_mul_f32_e64 v157, |v167|, s93
	v_exp_f32_e32 v157, v157
	v_fmac_f32_e32 v85, 0x3d800000, v155
	v_min_f32_e32 v155, 0, v167
	v_add_f32_e32 v157, 1.0, v157
	v_log_f32_e32 v157, v157
	s_nop 0
	v_fmac_f32_e32 v155, 0xbf317218, v157
	v_mul_f32_e64 v157, |v164|, s93
	v_exp_f32_e32 v157, v157
	v_fmac_f32_e32 v91, 0x3d800000, v155
	v_min_f32_e32 v155, 0, v164
	v_lshlrev_b32_e32 v164, 16, v152
	v_add_f32_e32 v157, 1.0, v157
	v_log_f32_e32 v157, v157
	s_nop 0
	v_fmac_f32_e32 v155, 0xbf317218, v157
	v_mul_f32_e64 v157, |v165|, s93
	v_exp_f32_e32 v157, v157
	v_fmac_f32_e32 v163, 0x3d800000, v155
	v_min_f32_e32 v155, 0, v165
	v_lshlrev_b32_e32 v165, 16, v168
	v_add_f32_e32 v157, 1.0, v157
	v_log_f32_e32 v157, v157
	s_nop 0
	v_fmac_f32_e32 v155, 0xbf317218, v157
	v_fmac_f32_e32 v170, 0x3d800000, v155
	v_sub_f32_e32 v155, v130, v85
	v_mul_f32_e32 v155, 0x3fb8aa3b, v155
	v_exp_f32_e32 v161, v155
	v_sub_f32_e32 v155, v131, v91
	v_mul_f32_e32 v155, 0x3fb8aa3b, v155
	v_exp_f32_e32 v159, v155
	v_pk_mul_f32 v[160:161], v[160:161], v[164:165]
	v_and_b32_e32 v164, 0xffff0000, v152
	v_sub_f32_e32 v152, v128, v163
	v_mul_f32_e32 v152, 0x3fb8aa3b, v152
	v_exp_f32_e32 v157, v152
	v_sub_f32_e32 v152, v129, v170
	v_mul_f32_e32 v152, 0x3fb8aa3b, v152
	v_exp_f32_e32 v155, v152
	v_and_b32_e32 v165, 0xffff0000, v168
	v_pk_mul_f32 v[158:159], v[158:159], v[164:165]
	v_lshlrev_b32_e32 v165, 16, v169
	v_lshlrev_b32_e32 v164, 16, v153
	v_pk_mul_f32 v[156:157], v[156:157], v[164:165]
	v_and_b32_e32 v165, 0xffff0000, v169
	v_and_b32_e32 v164, 0xffff0000, v153
	v_cvt_pk_bf16_f32 v152, v72, v73
	v_cvt_pk_bf16_f32 v72, v74, v75
	v_cvt_pk_bf16_f32 v73, v138, v139
	v_cvt_pk_bf16_f32 v74, v146, v147
	v_cvt_pk_bf16_f32 v75, v158, v159
	v_pk_mul_f32 v[164:165], v[154:155], v[164:165]
	global_store_dwordx4 v[132:133], v[72:75], off offset:2576
	v_cvt_pk_bf16_f32 v153, v136, v137
	v_cvt_pk_bf16_f32 v154, v144, v145
	v_cvt_pk_bf16_f32 v72, v78, v79
	v_cvt_pk_bf16_f32 v73, v140, v141
	v_cvt_pk_bf16_f32 v74, v148, v149
	v_cvt_pk_bf16_f32 v75, v156, v157
	v_cvt_pk_bf16_f32 v155, v160, v161
	global_store_dwordx4 v[132:133], v[72:75], off offset:2592
	global_store_dwordx4 v[132:133], v[152:155], off offset:2560
	v_mov_b32_e32 v78, 0x80000
	v_cvt_pk_bf16_f32 v72, v134, v135
	v_cvt_pk_bf16_f32 v73, v142, v143
	v_cvt_pk_bf16_f32 v74, v150, v151
	v_cvt_pk_bf16_f32 v75, v164, v165
	global_store_dwordx4 v[132:133], v[72:75], off offset:2608
	global_load_dwordx4 v[136:139], v78, s[6:7] offset:2048
	s_waitcnt vmcnt(0)
	v_lshlrev_b32_e32 v78, 16, v136
	v_add_co_u32_e32 v72, vcc, s60, v76
	v_pk_fma_f32 v[140:141], v[70:71], v[78:79], v[66:67] op_sel_hi:[1,0,1]
	s_nop 0
	v_addc_co_u32_e32 v73, vcc, 0, v77, vcc
	global_load_dwordx2 v[134:135], v[72:73], off offset:1536
	v_pk_fma_f32 v[78:79], v[68:69], v[78:79], v[64:65] op_sel_hi:[1,0,1]
	global_load_dwordx4 v[72:75], v3, s[0:1] offset:16
	v_and_b32_e32 v136, 0xffff0000, v136
	v_pk_fma_f32 v[140:141], v[62:63], v[136:137], v[140:141] op_sel_hi:[1,0,1]
	v_pk_fma_f32 v[78:79], v[60:61], v[136:137], v[78:79] op_sel_hi:[1,0,1]
	v_lshlrev_b32_e32 v136, 16, v137
	v_pk_fma_f32 v[140:141], v[58:59], v[136:137], v[140:141] op_sel_hi:[1,0,1]
	v_pk_fma_f32 v[78:79], v[56:57], v[136:137], v[78:79] op_sel_hi:[1,0,1]
	v_and_b32_e32 v136, 0xffff0000, v137
	v_pk_fma_f32 v[140:141], v[54:55], v[136:137], v[140:141] op_sel_hi:[1,0,1]
	v_pk_fma_f32 v[78:79], v[52:53], v[136:137], v[78:79] op_sel_hi:[1,0,1]
	v_lshlrev_b32_e32 v136, 16, v138
	v_pk_fma_f32 v[140:141], v[50:51], v[136:137], v[140:141] op_sel_hi:[1,0,1]
	v_pk_fma_f32 v[78:79], v[48:49], v[136:137], v[78:79] op_sel_hi:[1,0,1]
	v_and_b32_e32 v136, 0xffff0000, v138
	v_pk_fma_f32 v[140:141], v[46:47], v[136:137], v[140:141] op_sel_hi:[1,0,1]
	v_pk_fma_f32 v[78:79], v[44:45], v[136:137], v[78:79] op_sel_hi:[1,0,1]
	v_lshlrev_b32_e32 v136, 16, v139
	v_pk_fma_f32 v[140:141], v[42:43], v[136:137], v[140:141] op_sel_hi:[1,0,1]
	v_pk_fma_f32 v[78:79], v[40:41], v[136:137], v[78:79] op_sel_hi:[1,0,1]
	v_and_b32_e32 v136, 0xffff0000, v139
	v_pk_fma_f32 v[138:139], v[38:39], v[136:137], v[140:141] op_sel_hi:[1,0,1]
	v_pk_fma_f32 v[78:79], v[36:37], v[136:137], v[78:79] op_sel_hi:[1,0,1]
	s_add_u32 s0, s6, 0x83200
	s_addc_u32 s1, s7, 0
	s_waitcnt vmcnt(0)
	v_lshlrev_b32_e32 v136, 16, v72
	v_pk_fma_f32 v[138:139], v[34:35], v[136:137], v[138:139] op_sel_hi:[1,0,1]
	v_pk_fma_f32 v[78:79], v[32:33], v[136:137], v[78:79] op_sel_hi:[1,0,1]
	v_and_b32_e32 v72, 0xffff0000, v72
	v_pk_fma_f32 v[136:137], v[30:31], v[72:73], v[138:139] op_sel_hi:[1,0,1]
	v_pk_fma_f32 v[78:79], v[28:29], v[72:73], v[78:79] op_sel_hi:[1,0,1]
	v_lshlrev_b32_e32 v72, 16, v73
	v_pk_fma_f32 v[136:137], v[26:27], v[72:73], v[136:137] op_sel_hi:[1,0,1]
	v_pk_fma_f32 v[78:79], v[24:25], v[72:73], v[78:79] op_sel_hi:[1,0,1]
	v_and_b32_e32 v72, 0xffff0000, v73
	v_pk_fma_f32 v[136:137], v[22:23], v[72:73], v[136:137] op_sel_hi:[1,0,1]
	v_pk_fma_f32 v[72:73], v[20:21], v[72:73], v[78:79] op_sel_hi:[1,0,1]
	v_lshlrev_b32_e32 v78, 16, v74
	v_pk_fma_f32 v[136:137], v[18:19], v[78:79], v[136:137] op_sel_hi:[1,0,1]
	v_pk_fma_f32 v[72:73], v[16:17], v[78:79], v[72:73] op_sel_hi:[1,0,1]
	v_and_b32_e32 v74, 0xffff0000, v74
	v_pk_fma_f32 v[78:79], v[14:15], v[74:75], v[136:137] op_sel_hi:[1,0,1]
	v_pk_fma_f32 v[72:73], v[12:13], v[74:75], v[72:73] op_sel_hi:[1,0,1]
	v_lshlrev_b32_e32 v74, 16, v75
	v_pk_fma_f32 v[78:79], v[10:11], v[74:75], v[78:79] op_sel_hi:[1,0,1]
	v_pk_fma_f32 v[72:73], v[8:9], v[74:75], v[72:73] op_sel_hi:[1,0,1]
	v_and_b32_e32 v74, 0xffff0000, v75
	v_pk_fma_f32 v[72:73], v[4:5], v[74:75], v[72:73] op_sel_hi:[1,0,1]
	v_pk_fma_f32 v[78:79], v[6:7], v[74:75], v[78:79] op_sel_hi:[1,0,1]
	v_min_f32_e32 v74, 0, v72
	v_mul_f32_e64 v72, |v72|, s93
	v_exp_f32_e32 v72, v72
	v_add_co_u32_e32 v138, vcc, s62, v76
	v_add_f32_e32 v72, 1.0, v72
	v_log_f32_e32 v72, v72
	v_addc_co_u32_e32 v139, vcc, 0, v77, vcc
	global_load_dwordx2 v[146:147], v[138:139], off
	v_fmac_f32_e32 v74, 0xbf317218, v72
	v_min_f32_e32 v72, 0, v73
	v_mul_f32_e64 v73, |v73|, s93
	v_exp_f32_e32 v73, v73
	v_fmac_f32_e32 v85, 0x3d800000, v74
	global_load_dwordx4 v[138:141], v3, s[0:1] offset:16
	s_mov_b32 s0, 0x83000
	v_add_f32_e32 v73, 1.0, v73
	v_log_f32_e32 v73, v73
	s_nop 0
	v_fmac_f32_e32 v72, 0xbf317218, v73
	v_mul_f32_e64 v73, |v78|, s93
	v_exp_f32_e32 v73, v73
	v_fmac_f32_e32 v91, 0x3d800000, v72
	v_min_f32_e32 v72, 0, v78
	v_add_f32_e32 v73, 1.0, v73
	v_log_f32_e32 v73, v73
	s_nop 0
	v_fmac_f32_e32 v72, 0xbf317218, v73
	v_mul_f32_e64 v73, |v79|, s93
	v_exp_f32_e32 v73, v73
	v_fmac_f32_e32 v163, 0x3d800000, v72
	v_min_f32_e32 v72, 0, v79
	v_add_f32_e32 v73, 1.0, v73
	v_log_f32_e32 v73, v73
	s_nop 0
	v_fmac_f32_e32 v72, 0xbf317218, v73
	v_sub_f32_e32 v73, v131, v91
	v_mul_f32_e32 v73, 0x3fb8aa3b, v73
	v_exp_f32_e32 v74, v73
	v_sub_f32_e32 v73, v128, v163
	v_fmac_f32_e32 v170, 0x3d800000, v72
	v_mul_f32_e32 v73, 0x3fb8aa3b, v73
	v_exp_f32_e32 v78, v73
	v_sub_f32_e32 v73, v129, v170
	v_mul_f32_e32 v73, 0x3fb8aa3b, v73
	v_exp_f32_e32 v136, v73
	v_mov_b32_e32 v73, 0x83000
	global_load_dwordx4 v[142:145], v73, s[6:7] offset:512
	v_sub_f32_e32 v72, v130, v85
	v_mul_f32_e32 v72, 0x3fb8aa3b, v72
	v_exp_f32_e32 v72, v72
	s_waitcnt vmcnt(0)
	v_lshlrev_b32_e32 v148, 16, v142
	v_pk_fma_f32 v[150:151], v[70:71], v[148:149], v[66:67] op_sel_hi:[1,0,1]
	v_pk_fma_f32 v[148:149], v[68:69], v[148:149], v[64:65] op_sel_hi:[1,0,1]
	v_and_b32_e32 v142, 0xffff0000, v142
	v_pk_fma_f32 v[150:151], v[62:63], v[142:143], v[150:151] op_sel_hi:[1,0,1]
	v_pk_fma_f32 v[148:149], v[60:61], v[142:143], v[148:149] op_sel_hi:[1,0,1]
	v_lshlrev_b32_e32 v142, 16, v143
	v_pk_fma_f32 v[150:151], v[58:59], v[142:143], v[150:151] op_sel_hi:[1,0,1]
	v_pk_fma_f32 v[148:149], v[56:57], v[142:143], v[148:149] op_sel_hi:[1,0,1]
	v_and_b32_e32 v142, 0xffff0000, v143
	v_pk_fma_f32 v[150:151], v[54:55], v[142:143], v[150:151] op_sel_hi:[1,0,1]
	v_pk_fma_f32 v[142:143], v[52:53], v[142:143], v[148:149] op_sel_hi:[1,0,1]
	v_lshlrev_b32_e32 v148, 16, v144
	v_pk_fma_f32 v[150:151], v[50:51], v[148:149], v[150:151] op_sel_hi:[1,0,1]
	v_pk_fma_f32 v[142:143], v[48:49], v[148:149], v[142:143] op_sel_hi:[1,0,1]
	v_and_b32_e32 v144, 0xffff0000, v144
	v_pk_fma_f32 v[148:149], v[46:47], v[144:145], v[150:151] op_sel_hi:[1,0,1]
	v_pk_fma_f32 v[142:143], v[44:45], v[144:145], v[142:143] op_sel_hi:[1,0,1]
	v_lshlrev_b32_e32 v144, 16, v145
	v_pk_fma_f32 v[148:149], v[42:43], v[144:145], v[148:149] op_sel_hi:[1,0,1]
	v_pk_fma_f32 v[142:143], v[40:41], v[144:145], v[142:143] op_sel_hi:[1,0,1]
	v_and_b32_e32 v144, 0xffff0000, v145
	v_pk_fma_f32 v[148:149], v[38:39], v[144:145], v[148:149] op_sel_hi:[1,0,1]
	v_pk_fma_f32 v[142:143], v[36:37], v[144:145], v[142:143] op_sel_hi:[1,0,1]
	v_lshlrev_b32_e32 v144, 16, v138
	v_pk_fma_f32 v[148:149], v[34:35], v[144:145], v[148:149] op_sel_hi:[1,0,1]
	v_pk_fma_f32 v[142:143], v[32:33], v[144:145], v[142:143] op_sel_hi:[1,0,1]
	v_and_b32_e32 v138, 0xffff0000, v138
	v_pk_fma_f32 v[144:145], v[30:31], v[138:139], v[148:149] op_sel_hi:[1,0,1]
	v_pk_fma_f32 v[142:143], v[28:29], v[138:139], v[142:143] op_sel_hi:[1,0,1]
	v_lshlrev_b32_e32 v138, 16, v139
	v_pk_fma_f32 v[144:145], v[26:27], v[138:139], v[144:145] op_sel_hi:[1,0,1]
	v_pk_fma_f32 v[142:143], v[24:25], v[138:139], v[142:143] op_sel_hi:[1,0,1]
	v_and_b32_e32 v138, 0xffff0000, v139
	v_pk_fma_f32 v[144:145], v[22:23], v[138:139], v[144:145] op_sel_hi:[1,0,1]
	v_pk_fma_f32 v[138:139], v[20:21], v[138:139], v[142:143] op_sel_hi:[1,0,1]
	v_lshlrev_b32_e32 v142, 16, v140
	v_pk_fma_f32 v[144:145], v[18:19], v[142:143], v[144:145] op_sel_hi:[1,0,1]
	v_pk_fma_f32 v[138:139], v[16:17], v[142:143], v[138:139] op_sel_hi:[1,0,1]
	v_and_b32_e32 v140, 0xffff0000, v140
	v_pk_fma_f32 v[142:143], v[14:15], v[140:141], v[144:145] op_sel_hi:[1,0,1]
	v_pk_fma_f32 v[138:139], v[12:13], v[140:141], v[138:139] op_sel_hi:[1,0,1]
	v_lshlrev_b32_e32 v140, 16, v141
	v_pk_fma_f32 v[142:143], v[10:11], v[140:141], v[142:143] op_sel_hi:[1,0,1]
	v_pk_fma_f32 v[138:139], v[8:9], v[140:141], v[138:139] op_sel_hi:[1,0,1]
	v_and_b32_e32 v140, 0xffff0000, v141
	v_pk_fma_f32 v[138:139], v[4:5], v[140:141], v[138:139] op_sel_hi:[1,0,1]
	v_pk_fma_f32 v[142:143], v[6:7], v[140:141], v[142:143] op_sel_hi:[1,0,1]
	v_mul_f32_e64 v75, |v138|, s93
	v_exp_f32_e32 v75, v75
	v_min_f32_e32 v73, 0, v138
	v_lshlrev_b32_e32 v138, 16, v134
	v_mov_b32_e32 v140, 0x85000
	v_add_f32_e32 v75, 1.0, v75
	v_log_f32_e32 v75, v75
	s_nop 0
	v_fmac_f32_e32 v73, 0xbf317218, v75
	v_mul_f32_e64 v75, |v139|, s93
	v_exp_f32_e32 v75, v75
	v_fmac_f32_e32 v85, 0x3d800000, v73
	v_min_f32_e32 v73, 0, v139
	v_lshlrev_b32_e32 v139, 16, v146
	v_add_f32_e32 v75, 1.0, v75
	v_log_f32_e32 v75, v75
	s_nop 0
	v_fmac_f32_e32 v73, 0xbf317218, v75
	v_mul_f32_e64 v75, |v142|, s93
	v_exp_f32_e32 v75, v75
	v_fmac_f32_e32 v91, 0x3d800000, v73
	v_min_f32_e32 v73, 0, v142
	v_add_f32_e32 v75, 1.0, v75
	v_log_f32_e32 v75, v75
	s_nop 0
	v_fmac_f32_e32 v73, 0xbf317218, v75
	v_mul_f32_e64 v75, |v143|, s93
	v_exp_f32_e32 v75, v75
	v_fmac_f32_e32 v163, 0x3d800000, v73
	v_min_f32_e32 v73, 0, v143
	v_sub_f32_e32 v79, v128, v163
	v_add_f32_e32 v75, 1.0, v75
	v_log_f32_e32 v75, v75
	v_mul_f32_e32 v79, 0x3fb8aa3b, v79
	v_exp_f32_e32 v79, v79
	v_fmac_f32_e32 v73, 0xbf317218, v75
	v_fmac_f32_e32 v170, 0x3d800000, v73
	v_sub_f32_e32 v73, v130, v85
	v_mul_f32_e32 v73, 0x3fb8aa3b, v73
	v_sub_f32_e32 v75, v131, v91
	v_exp_f32_e32 v73, v73
	v_mul_f32_e32 v75, 0x3fb8aa3b, v75
	v_exp_f32_e32 v75, v75
	v_pk_mul_f32 v[72:73], v[72:73], v[138:139]
	v_and_b32_e32 v139, 0xffff0000, v146
	v_and_b32_e32 v138, 0xffff0000, v134
	v_pk_mul_f32 v[74:75], v[74:75], v[138:139]
	v_lshlrev_b32_e32 v139, 16, v147
	v_lshlrev_b32_e32 v138, 16, v135
	v_pk_mul_f32 v[78:79], v[78:79], v[138:139]
	v_sub_f32_e32 v134, v129, v170
	v_and_b32_e32 v139, 0xffff0000, v147
	global_load_dwordx4 v[144:147], v140, s[6:7] offset:3072
	v_mul_f32_e32 v134, 0x3fb8aa3b, v134
	v_exp_f32_e32 v137, v134
	v_and_b32_e32 v138, 0xffff0000, v135
	v_pk_mul_f32 v[134:135], v[136:137], v[138:139]
	v_add_co_u32_e32 v136, vcc, s0, v76
	s_add_u32 s0, s6, 0x85c00
	s_nop 0
	v_addc_co_u32_e32 v137, vcc, 0, v77, vcc
	s_addc_u32 s1, s7, 0
	global_load_dwordx2 v[142:143], v[136:137], off offset:2560
	s_waitcnt vmcnt(1)
	v_lshlrev_b32_e32 v140, 16, v144
	global_load_dwordx4 v[136:139], v3, s[0:1] offset:16
	v_pk_fma_f32 v[148:149], v[70:71], v[140:141], v[66:67] op_sel_hi:[1,0,1]
	v_pk_fma_f32 v[140:141], v[68:69], v[140:141], v[64:65] op_sel_hi:[1,0,1]
	v_and_b32_e32 v144, 0xffff0000, v144
	v_pk_fma_f32 v[148:149], v[62:63], v[144:145], v[148:149] op_sel_hi:[1,0,1]
	v_pk_fma_f32 v[140:141], v[60:61], v[144:145], v[140:141] op_sel_hi:[1,0,1]
	v_lshlrev_b32_e32 v144, 16, v145
	v_pk_fma_f32 v[148:149], v[58:59], v[144:145], v[148:149] op_sel_hi:[1,0,1]
	v_pk_fma_f32 v[140:141], v[56:57], v[144:145], v[140:141] op_sel_hi:[1,0,1]
	v_and_b32_e32 v144, 0xffff0000, v145
	v_pk_fma_f32 v[148:149], v[54:55], v[144:145], v[148:149] op_sel_hi:[1,0,1]
	v_pk_fma_f32 v[140:141], v[52:53], v[144:145], v[140:141] op_sel_hi:[1,0,1]
	v_lshlrev_b32_e32 v144, 16, v146
	v_pk_fma_f32 v[148:149], v[50:51], v[144:145], v[148:149] op_sel_hi:[1,0,1]
	v_pk_fma_f32 v[140:141], v[48:49], v[144:145], v[140:141] op_sel_hi:[1,0,1]
	v_and_b32_e32 v144, 0xffff0000, v146
	v_pk_fma_f32 v[148:149], v[46:47], v[144:145], v[148:149] op_sel_hi:[1,0,1]
	v_pk_fma_f32 v[140:141], v[44:45], v[144:145], v[140:141] op_sel_hi:[1,0,1]
	v_lshlrev_b32_e32 v144, 16, v147
	v_pk_fma_f32 v[148:149], v[42:43], v[144:145], v[148:149] op_sel_hi:[1,0,1]
	v_pk_fma_f32 v[140:141], v[40:41], v[144:145], v[140:141] op_sel_hi:[1,0,1]
	v_and_b32_e32 v144, 0xffff0000, v147
	v_pk_fma_f32 v[146:147], v[38:39], v[144:145], v[148:149] op_sel_hi:[1,0,1]
	v_pk_fma_f32 v[140:141], v[36:37], v[144:145], v[140:141] op_sel_hi:[1,0,1]
	s_add_u32 s0, s6, 0x88600
	s_addc_u32 s1, s7, 0
	s_waitcnt vmcnt(0)
	v_lshlrev_b32_e32 v144, 16, v136
	v_pk_fma_f32 v[146:147], v[34:35], v[144:145], v[146:147] op_sel_hi:[1,0,1]
	v_pk_fma_f32 v[140:141], v[32:33], v[144:145], v[140:141] op_sel_hi:[1,0,1]
	v_and_b32_e32 v136, 0xffff0000, v136
	v_pk_fma_f32 v[144:145], v[30:31], v[136:137], v[146:147] op_sel_hi:[1,0,1]
	v_pk_fma_f32 v[140:141], v[28:29], v[136:137], v[140:141] op_sel_hi:[1,0,1]
	v_lshlrev_b32_e32 v136, 16, v137
	v_pk_fma_f32 v[144:145], v[26:27], v[136:137], v[144:145] op_sel_hi:[1,0,1]
	v_pk_fma_f32 v[140:141], v[24:25], v[136:137], v[140:141] op_sel_hi:[1,0,1]
	v_and_b32_e32 v136, 0xffff0000, v137
	v_pk_fma_f32 v[144:145], v[22:23], v[136:137], v[144:145] op_sel_hi:[1,0,1]
	v_pk_fma_f32 v[136:137], v[20:21], v[136:137], v[140:141] op_sel_hi:[1,0,1]
	v_lshlrev_b32_e32 v140, 16, v138
	v_pk_fma_f32 v[144:145], v[18:19], v[140:141], v[144:145] op_sel_hi:[1,0,1]
	v_pk_fma_f32 v[136:137], v[16:17], v[140:141], v[136:137] op_sel_hi:[1,0,1]
	v_and_b32_e32 v138, 0xffff0000, v138
	v_pk_fma_f32 v[140:141], v[14:15], v[138:139], v[144:145] op_sel_hi:[1,0,1]
	v_pk_fma_f32 v[136:137], v[12:13], v[138:139], v[136:137] op_sel_hi:[1,0,1]
	v_lshlrev_b32_e32 v138, 16, v139
	v_pk_fma_f32 v[140:141], v[10:11], v[138:139], v[140:141] op_sel_hi:[1,0,1]
	v_pk_fma_f32 v[136:137], v[8:9], v[138:139], v[136:137] op_sel_hi:[1,0,1]
	v_and_b32_e32 v138, 0xffff0000, v139
	v_pk_fma_f32 v[136:137], v[4:5], v[138:139], v[136:137] op_sel_hi:[1,0,1]
	v_pk_fma_f32 v[140:141], v[6:7], v[138:139], v[140:141] op_sel_hi:[1,0,1]
	v_min_f32_e32 v138, 0, v136
	v_mul_f32_e64 v136, |v136|, s93
	v_exp_f32_e32 v136, v136
	v_add_co_u32_e32 v146, vcc, s63, v76
	v_add_f32_e32 v136, 1.0, v136
	v_log_f32_e32 v136, v136
	v_addc_co_u32_e32 v147, vcc, 0, v77, vcc
	global_load_dwordx2 v[154:155], v[146:147], off offset:1024
	v_fmac_f32_e32 v138, 0xbf317218, v136
	v_min_f32_e32 v136, 0, v137
	v_mul_f32_e64 v137, |v137|, s93
	v_exp_f32_e32 v137, v137
	v_fmac_f32_e32 v85, 0x3d800000, v138
	global_load_dwordx4 v[146:149], v3, s[0:1] offset:16
	s_mov_b32 s0, 0x88000
	v_add_f32_e32 v137, 1.0, v137
	v_log_f32_e32 v137, v137
	s_nop 0
	v_fmac_f32_e32 v136, 0xbf317218, v137
	v_mul_f32_e64 v137, |v140|, s93
	v_exp_f32_e32 v137, v137
	v_fmac_f32_e32 v91, 0x3d800000, v136
	v_min_f32_e32 v136, 0, v140
	v_add_f32_e32 v137, 1.0, v137
	v_log_f32_e32 v137, v137
	s_nop 0
	v_fmac_f32_e32 v136, 0xbf317218, v137
	v_mul_f32_e64 v137, |v141|, s93
	v_exp_f32_e32 v137, v137
	v_fmac_f32_e32 v163, 0x3d800000, v136
	v_min_f32_e32 v136, 0, v141
	v_add_f32_e32 v137, 1.0, v137
	v_log_f32_e32 v137, v137
	s_nop 0
	v_fmac_f32_e32 v136, 0xbf317218, v137
	v_sub_f32_e32 v137, v131, v91
	v_mul_f32_e32 v137, 0x3fb8aa3b, v137
	v_exp_f32_e32 v138, v137
	v_sub_f32_e32 v137, v128, v163
	v_fmac_f32_e32 v170, 0x3d800000, v136
	v_mul_f32_e32 v137, 0x3fb8aa3b, v137
	v_exp_f32_e32 v140, v137
	v_sub_f32_e32 v137, v129, v170
	v_mul_f32_e32 v137, 0x3fb8aa3b, v137
	v_exp_f32_e32 v144, v137
	v_mov_b32_e32 v137, 0x88000
	global_load_dwordx4 v[150:153], v137, s[6:7] offset:1536
	v_sub_f32_e32 v136, v130, v85
	v_mul_f32_e32 v136, 0x3fb8aa3b, v136
	v_exp_f32_e32 v136, v136
	s_waitcnt vmcnt(0)
	v_lshlrev_b32_e32 v156, 16, v150
	v_pk_fma_f32 v[158:159], v[70:71], v[156:157], v[66:67] op_sel_hi:[1,0,1]
	v_pk_fma_f32 v[156:157], v[68:69], v[156:157], v[64:65] op_sel_hi:[1,0,1]
	v_and_b32_e32 v150, 0xffff0000, v150
	v_pk_fma_f32 v[158:159], v[62:63], v[150:151], v[158:159] op_sel_hi:[1,0,1]
	v_pk_fma_f32 v[156:157], v[60:61], v[150:151], v[156:157] op_sel_hi:[1,0,1]
	v_lshlrev_b32_e32 v150, 16, v151
	v_pk_fma_f32 v[158:159], v[58:59], v[150:151], v[158:159] op_sel_hi:[1,0,1]
	v_pk_fma_f32 v[156:157], v[56:57], v[150:151], v[156:157] op_sel_hi:[1,0,1]
	v_and_b32_e32 v150, 0xffff0000, v151
	v_pk_fma_f32 v[158:159], v[54:55], v[150:151], v[158:159] op_sel_hi:[1,0,1]
	v_pk_fma_f32 v[150:151], v[52:53], v[150:151], v[156:157] op_sel_hi:[1,0,1]
	v_lshlrev_b32_e32 v156, 16, v152
	v_pk_fma_f32 v[158:159], v[50:51], v[156:157], v[158:159] op_sel_hi:[1,0,1]
	v_pk_fma_f32 v[150:151], v[48:49], v[156:157], v[150:151] op_sel_hi:[1,0,1]
	v_and_b32_e32 v152, 0xffff0000, v152
	v_pk_fma_f32 v[156:157], v[46:47], v[152:153], v[158:159] op_sel_hi:[1,0,1]
	v_pk_fma_f32 v[150:151], v[44:45], v[152:153], v[150:151] op_sel_hi:[1,0,1]
	v_lshlrev_b32_e32 v152, 16, v153
	v_pk_fma_f32 v[156:157], v[42:43], v[152:153], v[156:157] op_sel_hi:[1,0,1]
	v_pk_fma_f32 v[150:151], v[40:41], v[152:153], v[150:151] op_sel_hi:[1,0,1]
	v_and_b32_e32 v152, 0xffff0000, v153
	v_pk_fma_f32 v[156:157], v[38:39], v[152:153], v[156:157] op_sel_hi:[1,0,1]
	v_pk_fma_f32 v[150:151], v[36:37], v[152:153], v[150:151] op_sel_hi:[1,0,1]
	v_lshlrev_b32_e32 v152, 16, v146
	v_pk_fma_f32 v[156:157], v[34:35], v[152:153], v[156:157] op_sel_hi:[1,0,1]
	v_pk_fma_f32 v[150:151], v[32:33], v[152:153], v[150:151] op_sel_hi:[1,0,1]
	v_and_b32_e32 v146, 0xffff0000, v146
	v_pk_fma_f32 v[152:153], v[30:31], v[146:147], v[156:157] op_sel_hi:[1,0,1]
	v_pk_fma_f32 v[150:151], v[28:29], v[146:147], v[150:151] op_sel_hi:[1,0,1]
	v_lshlrev_b32_e32 v146, 16, v147
	v_pk_fma_f32 v[152:153], v[26:27], v[146:147], v[152:153] op_sel_hi:[1,0,1]
	v_pk_fma_f32 v[150:151], v[24:25], v[146:147], v[150:151] op_sel_hi:[1,0,1]
	v_and_b32_e32 v146, 0xffff0000, v147
	v_pk_fma_f32 v[152:153], v[22:23], v[146:147], v[152:153] op_sel_hi:[1,0,1]
	v_pk_fma_f32 v[146:147], v[20:21], v[146:147], v[150:151] op_sel_hi:[1,0,1]
	v_lshlrev_b32_e32 v150, 16, v148
	v_pk_fma_f32 v[152:153], v[18:19], v[150:151], v[152:153] op_sel_hi:[1,0,1]
	v_pk_fma_f32 v[146:147], v[16:17], v[150:151], v[146:147] op_sel_hi:[1,0,1]
	v_and_b32_e32 v148, 0xffff0000, v148
	v_pk_fma_f32 v[150:151], v[14:15], v[148:149], v[152:153] op_sel_hi:[1,0,1]
	v_pk_fma_f32 v[146:147], v[12:13], v[148:149], v[146:147] op_sel_hi:[1,0,1]
	v_lshlrev_b32_e32 v148, 16, v149
	v_pk_fma_f32 v[150:151], v[10:11], v[148:149], v[150:151] op_sel_hi:[1,0,1]
	v_pk_fma_f32 v[146:147], v[8:9], v[148:149], v[146:147] op_sel_hi:[1,0,1]
	v_and_b32_e32 v148, 0xffff0000, v149
	v_pk_fma_f32 v[146:147], v[4:5], v[148:149], v[146:147] op_sel_hi:[1,0,1]
	v_pk_fma_f32 v[150:151], v[6:7], v[148:149], v[150:151] op_sel_hi:[1,0,1]
	v_mul_f32_e64 v139, |v146|, s93
	v_exp_f32_e32 v139, v139
	v_min_f32_e32 v137, 0, v146
	v_lshlrev_b32_e32 v146, 16, v142
	v_mov_b32_e32 v148, 0x8b000
	v_add_f32_e32 v139, 1.0, v139
	v_log_f32_e32 v139, v139
	s_nop 0
	v_fmac_f32_e32 v137, 0xbf317218, v139
	v_mul_f32_e64 v139, |v147|, s93
	v_exp_f32_e32 v139, v139
	v_fmac_f32_e32 v85, 0x3d800000, v137
	v_min_f32_e32 v137, 0, v147
	v_lshlrev_b32_e32 v147, 16, v154
	v_add_f32_e32 v139, 1.0, v139
	v_log_f32_e32 v139, v139
	s_nop 0
	v_fmac_f32_e32 v137, 0xbf317218, v139
	v_mul_f32_e64 v139, |v150|, s93
	v_exp_f32_e32 v139, v139
	v_fmac_f32_e32 v91, 0x3d800000, v137
	v_min_f32_e32 v137, 0, v150
	v_add_f32_e32 v139, 1.0, v139
	v_log_f32_e32 v139, v139
	s_nop 0
	v_fmac_f32_e32 v137, 0xbf317218, v139
	v_mul_f32_e64 v139, |v151|, s93
	v_exp_f32_e32 v139, v139
	v_fmac_f32_e32 v163, 0x3d800000, v137
	v_min_f32_e32 v137, 0, v151
	v_sub_f32_e32 v141, v128, v163
	v_add_f32_e32 v139, 1.0, v139
	v_log_f32_e32 v139, v139
	v_mul_f32_e32 v141, 0x3fb8aa3b, v141
	v_exp_f32_e32 v141, v141
	v_fmac_f32_e32 v137, 0xbf317218, v139
	v_fmac_f32_e32 v170, 0x3d800000, v137
	v_sub_f32_e32 v137, v130, v85
	v_mul_f32_e32 v137, 0x3fb8aa3b, v137
	v_sub_f32_e32 v139, v131, v91
	v_exp_f32_e32 v137, v137
	v_mul_f32_e32 v139, 0x3fb8aa3b, v139
	v_exp_f32_e32 v139, v139
	v_pk_mul_f32 v[136:137], v[136:137], v[146:147]
	v_and_b32_e32 v147, 0xffff0000, v154
	v_and_b32_e32 v146, 0xffff0000, v142
	v_pk_mul_f32 v[138:139], v[138:139], v[146:147]
	v_lshlrev_b32_e32 v147, 16, v155
	v_lshlrev_b32_e32 v146, 16, v143
	v_pk_mul_f32 v[140:141], v[140:141], v[146:147]
	v_sub_f32_e32 v142, v129, v170
	v_and_b32_e32 v147, 0xffff0000, v155
	global_load_dwordx4 v[152:155], v148, s[6:7]
	v_mul_f32_e32 v142, 0x3fb8aa3b, v142
	v_exp_f32_e32 v145, v142
	v_and_b32_e32 v146, 0xffff0000, v143
	v_pk_mul_f32 v[142:143], v[144:145], v[146:147]
	v_add_co_u32_e32 v144, vcc, s0, v76
	s_add_u32 s0, s6, 0x8b000
	s_nop 0
	v_addc_co_u32_e32 v145, vcc, 0, v77, vcc
	s_addc_u32 s1, s7, 0
	global_load_dwordx2 v[150:151], v[144:145], off offset:3584
	s_waitcnt vmcnt(1)
	v_lshlrev_b32_e32 v148, 16, v152
	global_load_dwordx4 v[144:147], v3, s[0:1] offset:16
	v_pk_fma_f32 v[156:157], v[70:71], v[148:149], v[66:67] op_sel_hi:[1,0,1]
	v_pk_fma_f32 v[148:149], v[68:69], v[148:149], v[64:65] op_sel_hi:[1,0,1]
	v_and_b32_e32 v152, 0xffff0000, v152
	v_pk_fma_f32 v[156:157], v[62:63], v[152:153], v[156:157] op_sel_hi:[1,0,1]
	v_pk_fma_f32 v[148:149], v[60:61], v[152:153], v[148:149] op_sel_hi:[1,0,1]
	v_lshlrev_b32_e32 v152, 16, v153
	v_pk_fma_f32 v[156:157], v[58:59], v[152:153], v[156:157] op_sel_hi:[1,0,1]
	v_pk_fma_f32 v[148:149], v[56:57], v[152:153], v[148:149] op_sel_hi:[1,0,1]
	v_and_b32_e32 v152, 0xffff0000, v153
	v_pk_fma_f32 v[156:157], v[54:55], v[152:153], v[156:157] op_sel_hi:[1,0,1]
	v_pk_fma_f32 v[148:149], v[52:53], v[152:153], v[148:149] op_sel_hi:[1,0,1]
	v_lshlrev_b32_e32 v152, 16, v154
	v_pk_fma_f32 v[156:157], v[50:51], v[152:153], v[156:157] op_sel_hi:[1,0,1]
	v_pk_fma_f32 v[148:149], v[48:49], v[152:153], v[148:149] op_sel_hi:[1,0,1]
	v_and_b32_e32 v152, 0xffff0000, v154
	v_pk_fma_f32 v[156:157], v[46:47], v[152:153], v[156:157] op_sel_hi:[1,0,1]
	v_pk_fma_f32 v[148:149], v[44:45], v[152:153], v[148:149] op_sel_hi:[1,0,1]
	v_lshlrev_b32_e32 v152, 16, v155
	v_pk_fma_f32 v[156:157], v[42:43], v[152:153], v[156:157] op_sel_hi:[1,0,1]
	v_pk_fma_f32 v[148:149], v[40:41], v[152:153], v[148:149] op_sel_hi:[1,0,1]
	v_and_b32_e32 v152, 0xffff0000, v155
	v_pk_fma_f32 v[154:155], v[38:39], v[152:153], v[156:157] op_sel_hi:[1,0,1]
	v_pk_fma_f32 v[148:149], v[36:37], v[152:153], v[148:149] op_sel_hi:[1,0,1]
	s_add_u32 s0, s6, 0x8da00
	s_addc_u32 s1, s7, 0
	s_waitcnt vmcnt(0)
	v_lshlrev_b32_e32 v152, 16, v144
	v_pk_fma_f32 v[154:155], v[34:35], v[152:153], v[154:155] op_sel_hi:[1,0,1]
	v_pk_fma_f32 v[148:149], v[32:33], v[152:153], v[148:149] op_sel_hi:[1,0,1]
	v_and_b32_e32 v144, 0xffff0000, v144
	v_pk_fma_f32 v[152:153], v[30:31], v[144:145], v[154:155] op_sel_hi:[1,0,1]
	v_pk_fma_f32 v[148:149], v[28:29], v[144:145], v[148:149] op_sel_hi:[1,0,1]
	v_lshlrev_b32_e32 v144, 16, v145
	v_pk_fma_f32 v[152:153], v[26:27], v[144:145], v[152:153] op_sel_hi:[1,0,1]
	v_pk_fma_f32 v[148:149], v[24:25], v[144:145], v[148:149] op_sel_hi:[1,0,1]
	v_and_b32_e32 v144, 0xffff0000, v145
	v_pk_fma_f32 v[152:153], v[22:23], v[144:145], v[152:153] op_sel_hi:[1,0,1]
	v_pk_fma_f32 v[144:145], v[20:21], v[144:145], v[148:149] op_sel_hi:[1,0,1]
	v_lshlrev_b32_e32 v148, 16, v146
	v_pk_fma_f32 v[152:153], v[18:19], v[148:149], v[152:153] op_sel_hi:[1,0,1]
	v_pk_fma_f32 v[144:145], v[16:17], v[148:149], v[144:145] op_sel_hi:[1,0,1]
	v_and_b32_e32 v146, 0xffff0000, v146
	v_pk_fma_f32 v[148:149], v[14:15], v[146:147], v[152:153] op_sel_hi:[1,0,1]
	v_pk_fma_f32 v[144:145], v[12:13], v[146:147], v[144:145] op_sel_hi:[1,0,1]
	v_lshlrev_b32_e32 v146, 16, v147
	v_pk_fma_f32 v[148:149], v[10:11], v[146:147], v[148:149] op_sel_hi:[1,0,1]
	v_pk_fma_f32 v[144:145], v[8:9], v[146:147], v[144:145] op_sel_hi:[1,0,1]
	v_and_b32_e32 v146, 0xffff0000, v147
	v_pk_fma_f32 v[144:145], v[4:5], v[146:147], v[144:145] op_sel_hi:[1,0,1]
	v_pk_fma_f32 v[148:149], v[6:7], v[146:147], v[148:149] op_sel_hi:[1,0,1]
	v_min_f32_e32 v146, 0, v144
	v_mul_f32_e64 v144, |v144|, s93
	v_exp_f32_e32 v144, v144
	v_add_co_u32_e32 v154, vcc, s64, v76
	v_add_f32_e32 v144, 1.0, v144
	v_log_f32_e32 v144, v144
	v_addc_co_u32_e32 v155, vcc, 0, v77, vcc
	global_load_dwordx2 v[164:165], v[154:155], off offset:2048
	v_fmac_f32_e32 v146, 0xbf317218, v144
	v_min_f32_e32 v144, 0, v145
	v_mul_f32_e64 v145, |v145|, s93
	v_exp_f32_e32 v145, v145
	v_fmac_f32_e32 v85, 0x3d800000, v146
	global_load_dwordx4 v[154:157], v3, s[0:1] offset:16
	s_add_u32 s0, s6, 0x90400
	v_add_f32_e32 v145, 1.0, v145
	v_log_f32_e32 v145, v145
	s_addc_u32 s1, s7, 0
	v_fmac_f32_e32 v144, 0xbf317218, v145
	v_mul_f32_e64 v145, |v148|, s93
	v_exp_f32_e32 v145, v145
	v_fmac_f32_e32 v91, 0x3d800000, v144
	v_min_f32_e32 v144, 0, v148
	v_add_f32_e32 v145, 1.0, v145
	v_log_f32_e32 v145, v145
	s_nop 0
	v_fmac_f32_e32 v144, 0xbf317218, v145
	v_mul_f32_e64 v145, |v149|, s93
	v_exp_f32_e32 v145, v145
	v_fmac_f32_e32 v163, 0x3d800000, v144
	v_min_f32_e32 v144, 0, v149
	v_add_f32_e32 v145, 1.0, v145
	v_log_f32_e32 v145, v145
	s_nop 0
	v_fmac_f32_e32 v144, 0xbf317218, v145
	v_sub_f32_e32 v145, v131, v91
	v_mul_f32_e32 v145, 0x3fb8aa3b, v145
	v_exp_f32_e32 v146, v145
	v_sub_f32_e32 v145, v128, v163
	v_fmac_f32_e32 v170, 0x3d800000, v144
	v_mul_f32_e32 v145, 0x3fb8aa3b, v145
	v_exp_f32_e32 v148, v145
	v_sub_f32_e32 v145, v129, v170
	v_mul_f32_e32 v145, 0x3fb8aa3b, v145
	v_exp_f32_e32 v152, v145
	v_mov_b32_e32 v145, 0x8d000
	global_load_dwordx4 v[158:161], v145, s[6:7] offset:2560
	v_sub_f32_e32 v144, v130, v85
	v_mul_f32_e32 v144, 0x3fb8aa3b, v144
	v_exp_f32_e32 v144, v144
	s_waitcnt vmcnt(0)
	v_lshlrev_b32_e32 v162, 16, v158
	v_pk_fma_f32 v[166:167], v[70:71], v[162:163], v[66:67] op_sel_hi:[1,0,1]
	v_pk_fma_f32 v[168:169], v[68:69], v[162:163], v[64:65] op_sel_hi:[1,0,1]
	v_and_b32_e32 v158, 0xffff0000, v158
	v_pk_fma_f32 v[166:167], v[62:63], v[158:159], v[166:167] op_sel_hi:[1,0,1]
	v_pk_fma_f32 v[168:169], v[60:61], v[158:159], v[168:169] op_sel_hi:[1,0,1]
	v_lshlrev_b32_e32 v158, 16, v159
	v_pk_fma_f32 v[166:167], v[58:59], v[158:159], v[166:167] op_sel_hi:[1,0,1]
	v_pk_fma_f32 v[168:169], v[56:57], v[158:159], v[168:169] op_sel_hi:[1,0,1]
	v_and_b32_e32 v158, 0xffff0000, v159
	v_pk_fma_f32 v[166:167], v[54:55], v[158:159], v[166:167] op_sel_hi:[1,0,1]
	v_pk_fma_f32 v[158:159], v[52:53], v[158:159], v[168:169] op_sel_hi:[1,0,1]
	v_lshlrev_b32_e32 v162, 16, v160
	v_pk_fma_f32 v[166:167], v[50:51], v[162:163], v[166:167] op_sel_hi:[1,0,1]
	v_pk_fma_f32 v[158:159], v[48:49], v[162:163], v[158:159] op_sel_hi:[1,0,1]
	v_and_b32_e32 v160, 0xffff0000, v160
	v_pk_fma_f32 v[166:167], v[46:47], v[160:161], v[166:167] op_sel_hi:[1,0,1]
	v_pk_fma_f32 v[158:159], v[44:45], v[160:161], v[158:159] op_sel_hi:[1,0,1]
	v_lshlrev_b32_e32 v160, 16, v161
	v_pk_fma_f32 v[166:167], v[42:43], v[160:161], v[166:167] op_sel_hi:[1,0,1]
	v_pk_fma_f32 v[158:159], v[40:41], v[160:161], v[158:159] op_sel_hi:[1,0,1]
	v_and_b32_e32 v160, 0xffff0000, v161
	v_pk_fma_f32 v[166:167], v[38:39], v[160:161], v[166:167] op_sel_hi:[1,0,1]
	v_pk_fma_f32 v[158:159], v[36:37], v[160:161], v[158:159] op_sel_hi:[1,0,1]
	v_lshlrev_b32_e32 v160, 16, v154
	v_pk_fma_f32 v[166:167], v[34:35], v[160:161], v[166:167] op_sel_hi:[1,0,1]
	v_pk_fma_f32 v[158:159], v[32:33], v[160:161], v[158:159] op_sel_hi:[1,0,1]
	v_and_b32_e32 v154, 0xffff0000, v154
	v_pk_fma_f32 v[160:161], v[30:31], v[154:155], v[166:167] op_sel_hi:[1,0,1]
	v_pk_fma_f32 v[158:159], v[28:29], v[154:155], v[158:159] op_sel_hi:[1,0,1]
	v_lshlrev_b32_e32 v154, 16, v155
	v_pk_fma_f32 v[160:161], v[26:27], v[154:155], v[160:161] op_sel_hi:[1,0,1]
	v_pk_fma_f32 v[158:159], v[24:25], v[154:155], v[158:159] op_sel_hi:[1,0,1]
	v_and_b32_e32 v154, 0xffff0000, v155
	v_pk_fma_f32 v[160:161], v[22:23], v[154:155], v[160:161] op_sel_hi:[1,0,1]
	v_pk_fma_f32 v[154:155], v[20:21], v[154:155], v[158:159] op_sel_hi:[1,0,1]
	v_lshlrev_b32_e32 v158, 16, v156
	v_pk_fma_f32 v[160:161], v[18:19], v[158:159], v[160:161] op_sel_hi:[1,0,1]
	v_pk_fma_f32 v[154:155], v[16:17], v[158:159], v[154:155] op_sel_hi:[1,0,1]
	v_and_b32_e32 v156, 0xffff0000, v156
	v_pk_fma_f32 v[158:159], v[14:15], v[156:157], v[160:161] op_sel_hi:[1,0,1]
	v_pk_fma_f32 v[154:155], v[12:13], v[156:157], v[154:155] op_sel_hi:[1,0,1]
	v_lshlrev_b32_e32 v156, 16, v157
	v_pk_fma_f32 v[158:159], v[10:11], v[156:157], v[158:159] op_sel_hi:[1,0,1]
	v_pk_fma_f32 v[154:155], v[8:9], v[156:157], v[154:155] op_sel_hi:[1,0,1]
	v_and_b32_e32 v156, 0xffff0000, v157
	v_pk_fma_f32 v[154:155], v[4:5], v[156:157], v[154:155] op_sel_hi:[1,0,1]
	v_pk_fma_f32 v[158:159], v[6:7], v[156:157], v[158:159] op_sel_hi:[1,0,1]
	v_mul_f32_e64 v147, |v154|, s93
	v_exp_f32_e32 v147, v147
	v_min_f32_e32 v145, 0, v154
	v_lshlrev_b32_e32 v154, 16, v150
	v_add_f32_e32 v147, 1.0, v147
	v_log_f32_e32 v147, v147
	s_nop 0
	v_fmac_f32_e32 v145, 0xbf317218, v147
	v_mul_f32_e64 v147, |v155|, s93
	v_exp_f32_e32 v147, v147
	v_fmac_f32_e32 v85, 0x3d800000, v145
	v_min_f32_e32 v145, 0, v155
	v_lshlrev_b32_e32 v155, 16, v164
	v_add_f32_e32 v147, 1.0, v147
	v_log_f32_e32 v147, v147
	s_nop 0
	v_fmac_f32_e32 v145, 0xbf317218, v147
	v_mul_f32_e64 v147, |v158|, s93
	v_exp_f32_e32 v147, v147
	v_fmac_f32_e32 v91, 0x3d800000, v145
	v_min_f32_e32 v145, 0, v158
	v_mov_b32_e32 v158, 0x90000
	v_add_f32_e32 v147, 1.0, v147
	v_log_f32_e32 v147, v147
	s_nop 0
	v_fmac_f32_e32 v145, 0xbf317218, v147
	v_mul_f32_e64 v147, |v159|, s93
	v_exp_f32_e32 v147, v147
	v_fmac_f32_e32 v163, 0x3d800000, v145
	v_min_f32_e32 v145, 0, v159
	global_load_dwordx4 v[158:161], v158, s[6:7] offset:1024
	v_add_f32_e32 v147, 1.0, v147
	v_log_f32_e32 v147, v147
	v_sub_f32_e32 v149, v128, v163
	v_mul_f32_e32 v149, 0x3fb8aa3b, v149
	v_exp_f32_e32 v149, v149
	v_fmac_f32_e32 v145, 0xbf317218, v147
	v_fmac_f32_e32 v170, 0x3d800000, v145
	v_sub_f32_e32 v145, v130, v85
	v_mul_f32_e32 v145, 0x3fb8aa3b, v145
	v_exp_f32_e32 v145, v145
	v_sub_f32_e32 v147, v131, v91
	v_mul_f32_e32 v147, 0x3fb8aa3b, v147
	v_exp_f32_e32 v147, v147
	v_pk_mul_f32 v[144:145], v[144:145], v[154:155]
	v_and_b32_e32 v154, 0xffff0000, v150
	v_sub_f32_e32 v150, v129, v170
	v_mul_f32_e32 v150, 0x3fb8aa3b, v150
	v_exp_f32_e32 v153, v150
	v_and_b32_e32 v155, 0xffff0000, v164
	v_pk_mul_f32 v[146:147], v[146:147], v[154:155]
	v_lshlrev_b32_e32 v155, 16, v165
	v_lshlrev_b32_e32 v154, 16, v151
	v_pk_mul_f32 v[148:149], v[148:149], v[154:155]
	v_and_b32_e32 v155, 0xffff0000, v165
	v_and_b32_e32 v154, 0xffff0000, v151
	v_pk_mul_f32 v[150:151], v[152:153], v[154:155]
	global_load_dwordx4 v[154:157], v3, s[0:1] offset:16
	v_add_co_u32_e32 v152, vcc, s65, v76
	s_mov_b32 s0, 0x90000
	s_nop 0
	v_addc_co_u32_e32 v153, vcc, 0, v77, vcc
	global_load_dwordx2 v[152:153], v[152:153], off offset:512
	s_waitcnt vmcnt(2)
	v_lshlrev_b32_e32 v162, 16, v158
	v_pk_fma_f32 v[164:165], v[70:71], v[162:163], v[66:67] op_sel_hi:[1,0,1]
	v_pk_fma_f32 v[166:167], v[68:69], v[162:163], v[64:65] op_sel_hi:[1,0,1]
	v_and_b32_e32 v158, 0xffff0000, v158
	v_pk_fma_f32 v[164:165], v[62:63], v[158:159], v[164:165] op_sel_hi:[1,0,1]
	v_pk_fma_f32 v[166:167], v[60:61], v[158:159], v[166:167] op_sel_hi:[1,0,1]
	v_lshlrev_b32_e32 v158, 16, v159
	v_pk_fma_f32 v[164:165], v[58:59], v[158:159], v[164:165] op_sel_hi:[1,0,1]
	v_pk_fma_f32 v[166:167], v[56:57], v[158:159], v[166:167] op_sel_hi:[1,0,1]
	v_and_b32_e32 v158, 0xffff0000, v159
	v_pk_fma_f32 v[164:165], v[54:55], v[158:159], v[164:165] op_sel_hi:[1,0,1]
	v_pk_fma_f32 v[158:159], v[52:53], v[158:159], v[166:167] op_sel_hi:[1,0,1]
	v_lshlrev_b32_e32 v162, 16, v160
	v_pk_fma_f32 v[164:165], v[50:51], v[162:163], v[164:165] op_sel_hi:[1,0,1]
	v_pk_fma_f32 v[158:159], v[48:49], v[162:163], v[158:159] op_sel_hi:[1,0,1]
	v_and_b32_e32 v160, 0xffff0000, v160
	v_pk_fma_f32 v[164:165], v[46:47], v[160:161], v[164:165] op_sel_hi:[1,0,1]
	v_pk_fma_f32 v[158:159], v[44:45], v[160:161], v[158:159] op_sel_hi:[1,0,1]
	v_lshlrev_b32_e32 v160, 16, v161
	v_pk_fma_f32 v[164:165], v[42:43], v[160:161], v[164:165] op_sel_hi:[1,0,1]
	v_pk_fma_f32 v[158:159], v[40:41], v[160:161], v[158:159] op_sel_hi:[1,0,1]
	v_and_b32_e32 v160, 0xffff0000, v161
	v_pk_fma_f32 v[164:165], v[38:39], v[160:161], v[164:165] op_sel_hi:[1,0,1]
	v_pk_fma_f32 v[158:159], v[36:37], v[160:161], v[158:159] op_sel_hi:[1,0,1]
	s_waitcnt vmcnt(1)
	v_lshlrev_b32_e32 v160, 16, v154
	v_pk_fma_f32 v[164:165], v[34:35], v[160:161], v[164:165] op_sel_hi:[1,0,1]
	v_pk_fma_f32 v[158:159], v[32:33], v[160:161], v[158:159] op_sel_hi:[1,0,1]
	v_and_b32_e32 v154, 0xffff0000, v154
	v_pk_fma_f32 v[160:161], v[30:31], v[154:155], v[164:165] op_sel_hi:[1,0,1]
	v_pk_fma_f32 v[158:159], v[28:29], v[154:155], v[158:159] op_sel_hi:[1,0,1]
	v_lshlrev_b32_e32 v154, 16, v155
	v_pk_fma_f32 v[160:161], v[26:27], v[154:155], v[160:161] op_sel_hi:[1,0,1]
	v_pk_fma_f32 v[158:159], v[24:25], v[154:155], v[158:159] op_sel_hi:[1,0,1]
	v_and_b32_e32 v154, 0xffff0000, v155
	v_pk_fma_f32 v[160:161], v[22:23], v[154:155], v[160:161] op_sel_hi:[1,0,1]
	v_pk_fma_f32 v[154:155], v[20:21], v[154:155], v[158:159] op_sel_hi:[1,0,1]
	v_lshlrev_b32_e32 v158, 16, v156
	v_pk_fma_f32 v[160:161], v[18:19], v[158:159], v[160:161] op_sel_hi:[1,0,1]
	v_pk_fma_f32 v[154:155], v[16:17], v[158:159], v[154:155] op_sel_hi:[1,0,1]
	v_and_b32_e32 v156, 0xffff0000, v156
	v_pk_fma_f32 v[158:159], v[14:15], v[156:157], v[160:161] op_sel_hi:[1,0,1]
	v_pk_fma_f32 v[154:155], v[12:13], v[156:157], v[154:155] op_sel_hi:[1,0,1]
	v_lshlrev_b32_e32 v156, 16, v157
	v_pk_fma_f32 v[158:159], v[10:11], v[156:157], v[158:159] op_sel_hi:[1,0,1]
	v_pk_fma_f32 v[154:155], v[8:9], v[156:157], v[154:155] op_sel_hi:[1,0,1]
	v_and_b32_e32 v156, 0xffff0000, v157
	v_pk_fma_f32 v[154:155], v[4:5], v[156:157], v[154:155] op_sel_hi:[1,0,1]
	v_pk_fma_f32 v[158:159], v[6:7], v[156:157], v[158:159] op_sel_hi:[1,0,1]
	v_min_f32_e32 v156, 0, v154
	v_mul_f32_e64 v154, |v154|, s93
	v_exp_f32_e32 v154, v154
	v_add_co_u32_e32 v164, vcc, s0, v76
	s_add_u32 s0, s6, 0x92e00
	v_add_f32_e32 v154, 1.0, v154
	v_log_f32_e32 v154, v154
	v_addc_co_u32_e32 v165, vcc, 0, v77, vcc
	s_addc_u32 s1, s7, 0
	v_fmac_f32_e32 v156, 0xbf317218, v154
	v_min_f32_e32 v154, 0, v155
	v_mul_f32_e64 v155, |v155|, s93
	v_exp_f32_e32 v155, v155
	global_load_dwordx2 v[168:169], v[164:165], off offset:3072
	v_fmac_f32_e32 v85, 0x3d800000, v156
	global_load_dwordx4 v[164:167], v3, s[0:1] offset:16
	v_add_f32_e32 v155, 1.0, v155
	v_log_f32_e32 v155, v155
	s_add_u32 s0, s6, 0x95800
	s_addc_u32 s1, s7, 0
	v_fmac_f32_e32 v154, 0xbf317218, v155
	v_mul_f32_e64 v155, |v158|, s93
	v_exp_f32_e32 v155, v155
	v_fmac_f32_e32 v91, 0x3d800000, v154
	v_min_f32_e32 v154, 0, v158
	v_add_f32_e32 v155, 1.0, v155
	v_log_f32_e32 v155, v155
	s_nop 0
	v_fmac_f32_e32 v154, 0xbf317218, v155
	v_mul_f32_e64 v155, |v159|, s93
	v_exp_f32_e32 v155, v155
	v_fmac_f32_e32 v163, 0x3d800000, v154
	v_min_f32_e32 v154, 0, v159
	v_add_f32_e32 v155, 1.0, v155
	v_log_f32_e32 v155, v155
	s_nop 0
	v_fmac_f32_e32 v154, 0xbf317218, v155
	v_mov_b32_e32 v155, 0x92000
	global_load_dwordx4 v[172:175], v155, s[6:7] offset:3584
	v_fmac_f32_e32 v170, 0x3d800000, v154
	v_sub_f32_e32 v154, v130, v85
	v_mul_f32_e32 v154, 0x3fb8aa3b, v154
	v_exp_f32_e32 v160, v154
	v_sub_f32_e32 v154, v131, v91
	v_mul_f32_e32 v154, 0x3fb8aa3b, v154
	v_exp_f32_e32 v158, v154
	v_sub_f32_e32 v154, v128, v163
	v_mul_f32_e32 v154, 0x3fb8aa3b, v154
	v_exp_f32_e32 v156, v154
	v_sub_f32_e32 v154, v129, v170
	v_mul_f32_e32 v154, 0x3fb8aa3b, v154
	v_exp_f32_e32 v154, v154
	s_waitcnt vmcnt(0)
	v_lshlrev_b32_e32 v162, 16, v172
	v_pk_fma_f32 v[176:177], v[70:71], v[162:163], v[66:67] op_sel_hi:[1,0,1]
	v_pk_fma_f32 v[178:179], v[68:69], v[162:163], v[64:65] op_sel_hi:[1,0,1]
	v_and_b32_e32 v162, 0xffff0000, v172
	v_pk_fma_f32 v[176:177], v[62:63], v[162:163], v[176:177] op_sel_hi:[1,0,1]
	v_pk_fma_f32 v[178:179], v[60:61], v[162:163], v[178:179] op_sel_hi:[1,0,1]
	v_lshlrev_b32_e32 v162, 16, v173
	v_pk_fma_f32 v[176:177], v[58:59], v[162:163], v[176:177] op_sel_hi:[1,0,1]
	v_pk_fma_f32 v[178:179], v[56:57], v[162:163], v[178:179] op_sel_hi:[1,0,1]
	v_and_b32_e32 v162, 0xffff0000, v173
	v_pk_fma_f32 v[172:173], v[54:55], v[162:163], v[176:177] op_sel_hi:[1,0,1]
	v_pk_fma_f32 v[176:177], v[52:53], v[162:163], v[178:179] op_sel_hi:[1,0,1]
	v_lshlrev_b32_e32 v162, 16, v174
	v_pk_fma_f32 v[172:173], v[50:51], v[162:163], v[172:173] op_sel_hi:[1,0,1]
	v_pk_fma_f32 v[176:177], v[48:49], v[162:163], v[176:177] op_sel_hi:[1,0,1]
	v_and_b32_e32 v162, 0xffff0000, v174
	v_pk_fma_f32 v[172:173], v[46:47], v[162:163], v[172:173] op_sel_hi:[1,0,1]
	v_pk_fma_f32 v[176:177], v[44:45], v[162:163], v[176:177] op_sel_hi:[1,0,1]
	v_lshlrev_b32_e32 v162, 16, v175
	v_pk_fma_f32 v[172:173], v[42:43], v[162:163], v[172:173] op_sel_hi:[1,0,1]
	v_pk_fma_f32 v[176:177], v[40:41], v[162:163], v[176:177] op_sel_hi:[1,0,1]
	v_and_b32_e32 v162, 0xffff0000, v175
	v_pk_fma_f32 v[172:173], v[38:39], v[162:163], v[172:173] op_sel_hi:[1,0,1]
	v_pk_fma_f32 v[174:175], v[36:37], v[162:163], v[176:177] op_sel_hi:[1,0,1]
	v_lshlrev_b32_e32 v162, 16, v164
	v_pk_fma_f32 v[172:173], v[34:35], v[162:163], v[172:173] op_sel_hi:[1,0,1]
	v_pk_fma_f32 v[174:175], v[32:33], v[162:163], v[174:175] op_sel_hi:[1,0,1]
	v_and_b32_e32 v162, 0xffff0000, v164
	v_pk_fma_f32 v[172:173], v[30:31], v[162:163], v[172:173] op_sel_hi:[1,0,1]
	v_pk_fma_f32 v[174:175], v[28:29], v[162:163], v[174:175] op_sel_hi:[1,0,1]
	v_lshlrev_b32_e32 v162, 16, v165
	v_pk_fma_f32 v[172:173], v[26:27], v[162:163], v[172:173] op_sel_hi:[1,0,1]
	v_pk_fma_f32 v[174:175], v[24:25], v[162:163], v[174:175] op_sel_hi:[1,0,1]
	v_and_b32_e32 v162, 0xffff0000, v165
	v_pk_fma_f32 v[164:165], v[22:23], v[162:163], v[172:173] op_sel_hi:[1,0,1]
	v_pk_fma_f32 v[172:173], v[20:21], v[162:163], v[174:175] op_sel_hi:[1,0,1]
	v_lshlrev_b32_e32 v162, 16, v166
	v_pk_fma_f32 v[164:165], v[18:19], v[162:163], v[164:165] op_sel_hi:[1,0,1]
	v_pk_fma_f32 v[172:173], v[16:17], v[162:163], v[172:173] op_sel_hi:[1,0,1]
	v_and_b32_e32 v162, 0xffff0000, v166
	v_pk_fma_f32 v[164:165], v[14:15], v[162:163], v[164:165] op_sel_hi:[1,0,1]
	v_pk_fma_f32 v[172:173], v[12:13], v[162:163], v[172:173] op_sel_hi:[1,0,1]
	v_lshlrev_b32_e32 v162, 16, v167
	v_pk_fma_f32 v[164:165], v[10:11], v[162:163], v[164:165] op_sel_hi:[1,0,1]
	v_pk_fma_f32 v[172:173], v[8:9], v[162:163], v[172:173] op_sel_hi:[1,0,1]
	v_and_b32_e32 v162, 0xffff0000, v167
	v_pk_fma_f32 v[166:167], v[4:5], v[162:163], v[172:173] op_sel_hi:[1,0,1]
	v_pk_fma_f32 v[164:165], v[6:7], v[162:163], v[164:165] op_sel_hi:[1,0,1]
	v_mul_f32_e64 v157, |v166|, s93
	v_exp_f32_e32 v157, v157
	v_min_f32_e32 v155, 0, v166
	v_add_f32_e32 v157, 1.0, v157
	v_log_f32_e32 v157, v157
	s_nop 0
	v_fmac_f32_e32 v155, 0xbf317218, v157
	v_mul_f32_e64 v157, |v167|, s93
	v_exp_f32_e32 v157, v157
	v_fmac_f32_e32 v85, 0x3d800000, v155
	v_min_f32_e32 v155, 0, v167
	v_add_f32_e32 v157, 1.0, v157
	v_log_f32_e32 v157, v157
	s_nop 0
	v_fmac_f32_e32 v155, 0xbf317218, v157
	v_mul_f32_e64 v157, |v164|, s93
	v_exp_f32_e32 v157, v157
	v_fmac_f32_e32 v91, 0x3d800000, v155
	v_min_f32_e32 v155, 0, v164
	v_lshlrev_b32_e32 v164, 16, v152
	v_add_f32_e32 v157, 1.0, v157
	v_log_f32_e32 v157, v157
	s_nop 0
	v_fmac_f32_e32 v155, 0xbf317218, v157
	v_mul_f32_e64 v157, |v165|, s93
	v_exp_f32_e32 v157, v157
	v_fmac_f32_e32 v163, 0x3d800000, v155
	v_min_f32_e32 v155, 0, v165
	v_lshlrev_b32_e32 v165, 16, v168
	v_add_f32_e32 v157, 1.0, v157
	v_log_f32_e32 v157, v157
	s_nop 0
	v_fmac_f32_e32 v155, 0xbf317218, v157
	v_fmac_f32_e32 v170, 0x3d800000, v155
	v_sub_f32_e32 v155, v130, v85
	v_mul_f32_e32 v155, 0x3fb8aa3b, v155
	v_exp_f32_e32 v161, v155
	v_sub_f32_e32 v155, v131, v91
	v_mul_f32_e32 v155, 0x3fb8aa3b, v155
	v_exp_f32_e32 v159, v155
	v_pk_mul_f32 v[160:161], v[160:161], v[164:165]
	v_and_b32_e32 v164, 0xffff0000, v152
	v_sub_f32_e32 v152, v128, v163
	v_mul_f32_e32 v152, 0x3fb8aa3b, v152
	v_exp_f32_e32 v157, v152
	v_sub_f32_e32 v152, v129, v170
	v_mul_f32_e32 v152, 0x3fb8aa3b, v152
	v_exp_f32_e32 v155, v152
	v_and_b32_e32 v165, 0xffff0000, v168
	v_pk_mul_f32 v[158:159], v[158:159], v[164:165]
	v_lshlrev_b32_e32 v165, 16, v169
	v_lshlrev_b32_e32 v164, 16, v153
	v_pk_mul_f32 v[156:157], v[156:157], v[164:165]
	v_and_b32_e32 v165, 0xffff0000, v169
	v_and_b32_e32 v164, 0xffff0000, v153
	v_cvt_pk_bf16_f32 v152, v72, v73
	v_cvt_pk_bf16_f32 v72, v74, v75
	v_cvt_pk_bf16_f32 v73, v138, v139
	v_cvt_pk_bf16_f32 v74, v146, v147
	v_cvt_pk_bf16_f32 v75, v158, v159
	v_pk_mul_f32 v[164:165], v[154:155], v[164:165]
	global_store_dwordx4 v[132:133], v[72:75], off offset:3088
	v_cvt_pk_bf16_f32 v153, v136, v137
	v_cvt_pk_bf16_f32 v154, v144, v145
	v_cvt_pk_bf16_f32 v72, v78, v79
	v_cvt_pk_bf16_f32 v73, v140, v141
	v_cvt_pk_bf16_f32 v74, v148, v149
	v_cvt_pk_bf16_f32 v75, v156, v157
	v_cvt_pk_bf16_f32 v155, v160, v161
	global_store_dwordx4 v[132:133], v[72:75], off offset:3104
	global_store_dwordx4 v[132:133], v[152:155], off offset:3072
	s_nop 0
	v_cvt_pk_bf16_f32 v72, v134, v135
	v_cvt_pk_bf16_f32 v73, v142, v143
	v_cvt_pk_bf16_f32 v74, v150, v151
	v_cvt_pk_bf16_f32 v75, v164, v165
	global_store_dwordx4 v[132:133], v[72:75], off offset:3120
	v_mov_b32_e32 v134, 0x95000
	global_load_dwordx4 v[134:137], v134, s[6:7] offset:2048
	v_add_co_u32_e32 v72, vcc, s69, v76
	s_waitcnt vmcnt(0)
	v_lshlrev_b32_e32 v138, 16, v134
	v_addc_co_u32_e32 v73, vcc, 0, v77, vcc
	global_load_dwordx2 v[78:79], v[72:73], off offset:1536
	v_pk_fma_f32 v[140:141], v[70:71], v[138:139], v[66:67] op_sel_hi:[1,0,1]
	global_load_dwordx4 v[72:75], v3, s[0:1] offset:16
	v_pk_fma_f32 v[138:139], v[68:69], v[138:139], v[64:65] op_sel_hi:[1,0,1]
	v_and_b32_e32 v134, 0xffff0000, v134
	v_pk_fma_f32 v[140:141], v[62:63], v[134:135], v[140:141] op_sel_hi:[1,0,1]
	v_pk_fma_f32 v[138:139], v[60:61], v[134:135], v[138:139] op_sel_hi:[1,0,1]
	v_lshlrev_b32_e32 v134, 16, v135
	v_pk_fma_f32 v[140:141], v[58:59], v[134:135], v[140:141] op_sel_hi:[1,0,1]
	v_pk_fma_f32 v[138:139], v[56:57], v[134:135], v[138:139] op_sel_hi:[1,0,1]
	v_and_b32_e32 v134, 0xffff0000, v135
	v_pk_fma_f32 v[140:141], v[54:55], v[134:135], v[140:141] op_sel_hi:[1,0,1]
	v_pk_fma_f32 v[134:135], v[52:53], v[134:135], v[138:139] op_sel_hi:[1,0,1]
	v_lshlrev_b32_e32 v138, 16, v136
	v_pk_fma_f32 v[140:141], v[50:51], v[138:139], v[140:141] op_sel_hi:[1,0,1]
	v_pk_fma_f32 v[134:135], v[48:49], v[138:139], v[134:135] op_sel_hi:[1,0,1]
	v_and_b32_e32 v136, 0xffff0000, v136
	v_pk_fma_f32 v[138:139], v[46:47], v[136:137], v[140:141] op_sel_hi:[1,0,1]
	v_pk_fma_f32 v[134:135], v[44:45], v[136:137], v[134:135] op_sel_hi:[1,0,1]
	v_lshlrev_b32_e32 v136, 16, v137
	v_pk_fma_f32 v[138:139], v[42:43], v[136:137], v[138:139] op_sel_hi:[1,0,1]
	v_pk_fma_f32 v[134:135], v[40:41], v[136:137], v[134:135] op_sel_hi:[1,0,1]
	v_and_b32_e32 v136, 0xffff0000, v137
	v_pk_fma_f32 v[138:139], v[38:39], v[136:137], v[138:139] op_sel_hi:[1,0,1]
	v_pk_fma_f32 v[134:135], v[36:37], v[136:137], v[134:135] op_sel_hi:[1,0,1]
	s_add_u32 s0, s6, 0x98200
	s_addc_u32 s1, s7, 0
	s_waitcnt vmcnt(0)
	v_lshlrev_b32_e32 v136, 16, v72
	v_pk_fma_f32 v[138:139], v[34:35], v[136:137], v[138:139] op_sel_hi:[1,0,1]
	v_pk_fma_f32 v[134:135], v[32:33], v[136:137], v[134:135] op_sel_hi:[1,0,1]
	v_and_b32_e32 v72, 0xffff0000, v72
	v_pk_fma_f32 v[136:137], v[30:31], v[72:73], v[138:139] op_sel_hi:[1,0,1]
	v_pk_fma_f32 v[134:135], v[28:29], v[72:73], v[134:135] op_sel_hi:[1,0,1]
	v_lshlrev_b32_e32 v72, 16, v73
	v_pk_fma_f32 v[136:137], v[26:27], v[72:73], v[136:137] op_sel_hi:[1,0,1]
	v_pk_fma_f32 v[134:135], v[24:25], v[72:73], v[134:135] op_sel_hi:[1,0,1]
	v_and_b32_e32 v72, 0xffff0000, v73
	v_pk_fma_f32 v[136:137], v[22:23], v[72:73], v[136:137] op_sel_hi:[1,0,1]
	v_pk_fma_f32 v[72:73], v[20:21], v[72:73], v[134:135] op_sel_hi:[1,0,1]
	v_lshlrev_b32_e32 v134, 16, v74
	v_pk_fma_f32 v[136:137], v[18:19], v[134:135], v[136:137] op_sel_hi:[1,0,1]
	v_pk_fma_f32 v[72:73], v[16:17], v[134:135], v[72:73] op_sel_hi:[1,0,1]
	v_and_b32_e32 v74, 0xffff0000, v74
	v_pk_fma_f32 v[134:135], v[14:15], v[74:75], v[136:137] op_sel_hi:[1,0,1]
	v_pk_fma_f32 v[72:73], v[12:13], v[74:75], v[72:73] op_sel_hi:[1,0,1]
	v_lshlrev_b32_e32 v74, 16, v75
	v_pk_fma_f32 v[134:135], v[10:11], v[74:75], v[134:135] op_sel_hi:[1,0,1]
	v_pk_fma_f32 v[72:73], v[8:9], v[74:75], v[72:73] op_sel_hi:[1,0,1]
	v_and_b32_e32 v74, 0xffff0000, v75
	v_pk_fma_f32 v[72:73], v[4:5], v[74:75], v[72:73] op_sel_hi:[1,0,1]
	v_pk_fma_f32 v[134:135], v[6:7], v[74:75], v[134:135] op_sel_hi:[1,0,1]
	v_min_f32_e32 v74, 0, v72
	v_mul_f32_e64 v72, |v72|, s93
	v_exp_f32_e32 v72, v72
	v_add_co_u32_e32 v138, vcc, s70, v76
	v_add_f32_e32 v72, 1.0, v72
	v_log_f32_e32 v72, v72
	v_addc_co_u32_e32 v139, vcc, 0, v77, vcc
	global_load_dwordx2 v[146:147], v[138:139], off
	v_fmac_f32_e32 v74, 0xbf317218, v72
	v_min_f32_e32 v72, 0, v73
	v_mul_f32_e64 v73, |v73|, s93
	v_exp_f32_e32 v73, v73
	global_load_dwordx4 v[138:141], v3, s[0:1] offset:16
	v_fmac_f32_e32 v85, 0x3d800000, v74
	s_mov_b32 s0, 0x98000
	v_add_f32_e32 v73, 1.0, v73
	v_log_f32_e32 v73, v73
	s_nop 0
	v_fmac_f32_e32 v72, 0xbf317218, v73
	v_mul_f32_e64 v73, |v134|, s93
	v_exp_f32_e32 v73, v73
	v_fmac_f32_e32 v91, 0x3d800000, v72
	v_min_f32_e32 v72, 0, v134
	v_add_f32_e32 v73, 1.0, v73
	v_log_f32_e32 v73, v73
	s_nop 0
	v_fmac_f32_e32 v72, 0xbf317218, v73
	v_mul_f32_e64 v73, |v135|, s93
	v_exp_f32_e32 v73, v73
	v_fmac_f32_e32 v163, 0x3d800000, v72
	v_min_f32_e32 v72, 0, v135
	v_add_f32_e32 v73, 1.0, v73
	v_log_f32_e32 v73, v73
	s_nop 0
	v_fmac_f32_e32 v72, 0xbf317218, v73
	v_mov_b32_e32 v73, 0x98000
	global_load_dwordx4 v[142:145], v73, s[6:7] offset:512
	v_fmac_f32_e32 v170, 0x3d800000, v72
	v_sub_f32_e32 v72, v130, v85
	v_mul_f32_e32 v72, 0x3fb8aa3b, v72
	v_exp_f32_e32 v134, v72
	v_sub_f32_e32 v72, v131, v91
	v_mul_f32_e32 v72, 0x3fb8aa3b, v72
	v_exp_f32_e32 v136, v72
	v_sub_f32_e32 v72, v128, v163
	v_mul_f32_e32 v72, 0x3fb8aa3b, v72
	v_exp_f32_e32 v74, v72
	v_sub_f32_e32 v72, v129, v170
	v_mul_f32_e32 v72, 0x3fb8aa3b, v72
	v_exp_f32_e32 v72, v72
	s_waitcnt vmcnt(0)
	v_lshlrev_b32_e32 v148, 16, v142
	v_pk_fma_f32 v[150:151], v[70:71], v[148:149], v[66:67] op_sel_hi:[1,0,1]
	v_pk_fma_f32 v[148:149], v[68:69], v[148:149], v[64:65] op_sel_hi:[1,0,1]
	v_and_b32_e32 v142, 0xffff0000, v142
	v_pk_fma_f32 v[150:151], v[62:63], v[142:143], v[150:151] op_sel_hi:[1,0,1]
	v_pk_fma_f32 v[148:149], v[60:61], v[142:143], v[148:149] op_sel_hi:[1,0,1]
	v_lshlrev_b32_e32 v142, 16, v143
	v_pk_fma_f32 v[150:151], v[58:59], v[142:143], v[150:151] op_sel_hi:[1,0,1]
	v_pk_fma_f32 v[148:149], v[56:57], v[142:143], v[148:149] op_sel_hi:[1,0,1]
	v_and_b32_e32 v142, 0xffff0000, v143
	v_pk_fma_f32 v[150:151], v[54:55], v[142:143], v[150:151] op_sel_hi:[1,0,1]
	v_pk_fma_f32 v[142:143], v[52:53], v[142:143], v[148:149] op_sel_hi:[1,0,1]
	v_lshlrev_b32_e32 v148, 16, v144
	v_pk_fma_f32 v[150:151], v[50:51], v[148:149], v[150:151] op_sel_hi:[1,0,1]
	v_pk_fma_f32 v[142:143], v[48:49], v[148:149], v[142:143] op_sel_hi:[1,0,1]
	v_and_b32_e32 v144, 0xffff0000, v144
	v_pk_fma_f32 v[148:149], v[46:47], v[144:145], v[150:151] op_sel_hi:[1,0,1]
	v_pk_fma_f32 v[142:143], v[44:45], v[144:145], v[142:143] op_sel_hi:[1,0,1]
	v_lshlrev_b32_e32 v144, 16, v145
	v_pk_fma_f32 v[148:149], v[42:43], v[144:145], v[148:149] op_sel_hi:[1,0,1]
	v_pk_fma_f32 v[142:143], v[40:41], v[144:145], v[142:143] op_sel_hi:[1,0,1]
	v_and_b32_e32 v144, 0xffff0000, v145
	v_pk_fma_f32 v[148:149], v[38:39], v[144:145], v[148:149] op_sel_hi:[1,0,1]
	v_pk_fma_f32 v[142:143], v[36:37], v[144:145], v[142:143] op_sel_hi:[1,0,1]
	v_lshlrev_b32_e32 v144, 16, v138
	v_pk_fma_f32 v[148:149], v[34:35], v[144:145], v[148:149] op_sel_hi:[1,0,1]
	v_pk_fma_f32 v[142:143], v[32:33], v[144:145], v[142:143] op_sel_hi:[1,0,1]
	v_and_b32_e32 v138, 0xffff0000, v138
	v_pk_fma_f32 v[144:145], v[30:31], v[138:139], v[148:149] op_sel_hi:[1,0,1]
	v_pk_fma_f32 v[142:143], v[28:29], v[138:139], v[142:143] op_sel_hi:[1,0,1]
	v_lshlrev_b32_e32 v138, 16, v139
	v_pk_fma_f32 v[144:145], v[26:27], v[138:139], v[144:145] op_sel_hi:[1,0,1]
	v_pk_fma_f32 v[142:143], v[24:25], v[138:139], v[142:143] op_sel_hi:[1,0,1]
	v_and_b32_e32 v138, 0xffff0000, v139
	v_pk_fma_f32 v[144:145], v[22:23], v[138:139], v[144:145] op_sel_hi:[1,0,1]
	v_pk_fma_f32 v[138:139], v[20:21], v[138:139], v[142:143] op_sel_hi:[1,0,1]
	v_lshlrev_b32_e32 v142, 16, v140
	v_pk_fma_f32 v[144:145], v[18:19], v[142:143], v[144:145] op_sel_hi:[1,0,1]
	v_pk_fma_f32 v[138:139], v[16:17], v[142:143], v[138:139] op_sel_hi:[1,0,1]
	v_and_b32_e32 v140, 0xffff0000, v140
	v_pk_fma_f32 v[142:143], v[14:15], v[140:141], v[144:145] op_sel_hi:[1,0,1]
	v_pk_fma_f32 v[138:139], v[12:13], v[140:141], v[138:139] op_sel_hi:[1,0,1]
	v_lshlrev_b32_e32 v140, 16, v141
	v_pk_fma_f32 v[142:143], v[10:11], v[140:141], v[142:143] op_sel_hi:[1,0,1]
	v_pk_fma_f32 v[138:139], v[8:9], v[140:141], v[138:139] op_sel_hi:[1,0,1]
	v_and_b32_e32 v140, 0xffff0000, v141
	v_pk_fma_f32 v[138:139], v[4:5], v[140:141], v[138:139] op_sel_hi:[1,0,1]
	v_pk_fma_f32 v[142:143], v[6:7], v[140:141], v[142:143] op_sel_hi:[1,0,1]
	v_mul_f32_e64 v75, |v138|, s93
	v_exp_f32_e32 v75, v75
	v_min_f32_e32 v73, 0, v138
	v_lshlrev_b32_e32 v138, 16, v78
	v_add_f32_e32 v75, 1.0, v75
	v_log_f32_e32 v75, v75
	s_nop 0
	v_fmac_f32_e32 v73, 0xbf317218, v75
	v_mul_f32_e64 v75, |v139|, s93
	v_exp_f32_e32 v75, v75
	v_fmac_f32_e32 v85, 0x3d800000, v73
	v_min_f32_e32 v73, 0, v139
	v_lshlrev_b32_e32 v139, 16, v146
	v_add_f32_e32 v75, 1.0, v75
	v_log_f32_e32 v75, v75
	s_nop 0
	v_fmac_f32_e32 v73, 0xbf317218, v75
	v_mul_f32_e64 v75, |v142|, s93
	v_exp_f32_e32 v75, v75
	v_fmac_f32_e32 v91, 0x3d800000, v73
	v_min_f32_e32 v73, 0, v142
	v_mov_b32_e32 v142, 0x9a000
	v_add_f32_e32 v75, 1.0, v75
	v_log_f32_e32 v75, v75
	s_nop 0
	v_fmac_f32_e32 v73, 0xbf317218, v75
	v_mul_f32_e64 v75, |v143|, s93
	v_exp_f32_e32 v75, v75
	v_fmac_f32_e32 v163, 0x3d800000, v73
	v_min_f32_e32 v73, 0, v143
	global_load_dwordx4 v[142:145], v142, s[6:7] offset:3072
	v_add_f32_e32 v75, 1.0, v75
	v_log_f32_e32 v75, v75
	s_nop 0
	v_fmac_f32_e32 v73, 0xbf317218, v75
	v_fmac_f32_e32 v170, 0x3d800000, v73
	v_sub_f32_e32 v73, v130, v85
	v_mul_f32_e32 v73, 0x3fb8aa3b, v73
	v_exp_f32_e32 v135, v73
	v_sub_f32_e32 v73, v131, v91
	v_mul_f32_e32 v73, 0x3fb8aa3b, v73
	v_exp_f32_e32 v137, v73
	v_sub_f32_e32 v73, v128, v163
	v_mul_f32_e32 v73, 0x3fb8aa3b, v73
	v_exp_f32_e32 v75, v73
	v_sub_f32_e32 v73, v129, v170
	v_mul_f32_e32 v73, 0x3fb8aa3b, v73
	v_exp_f32_e32 v73, v73
	v_pk_mul_f32 v[134:135], v[134:135], v[138:139]
	v_and_b32_e32 v139, 0xffff0000, v146
	v_and_b32_e32 v138, 0xffff0000, v78
	v_pk_mul_f32 v[136:137], v[136:137], v[138:139]
	v_lshlrev_b32_e32 v139, 16, v147
	v_lshlrev_b32_e32 v138, 16, v79
	v_pk_mul_f32 v[138:139], v[74:75], v[138:139]
	v_and_b32_e32 v75, 0xffff0000, v147
	v_and_b32_e32 v74, 0xffff0000, v79
	v_pk_mul_f32 v[140:141], v[72:73], v[74:75]
	v_add_co_u32_e32 v72, vcc, s0, v76
	s_add_u32 s0, s6, 0x9ac00
	s_nop 0
	v_addc_co_u32_e32 v73, vcc, 0, v77, vcc
	s_addc_u32 s1, s7, 0
	global_load_dwordx2 v[78:79], v[72:73], off offset:2560
	s_waitcnt vmcnt(1)
	v_lshlrev_b32_e32 v146, 16, v142
	global_load_dwordx4 v[72:75], v3, s[0:1] offset:16
	v_pk_fma_f32 v[148:149], v[70:71], v[146:147], v[66:67] op_sel_hi:[1,0,1]
	v_pk_fma_f32 v[146:147], v[68:69], v[146:147], v[64:65] op_sel_hi:[1,0,1]
	v_and_b32_e32 v142, 0xffff0000, v142
	v_pk_fma_f32 v[148:149], v[62:63], v[142:143], v[148:149] op_sel_hi:[1,0,1]
	v_pk_fma_f32 v[146:147], v[60:61], v[142:143], v[146:147] op_sel_hi:[1,0,1]
	v_lshlrev_b32_e32 v142, 16, v143
	v_pk_fma_f32 v[148:149], v[58:59], v[142:143], v[148:149] op_sel_hi:[1,0,1]
	v_pk_fma_f32 v[146:147], v[56:57], v[142:143], v[146:147] op_sel_hi:[1,0,1]
	v_and_b32_e32 v142, 0xffff0000, v143
	v_pk_fma_f32 v[148:149], v[54:55], v[142:143], v[148:149] op_sel_hi:[1,0,1]
	v_pk_fma_f32 v[142:143], v[52:53], v[142:143], v[146:147] op_sel_hi:[1,0,1]
	v_lshlrev_b32_e32 v146, 16, v144
	v_pk_fma_f32 v[148:149], v[50:51], v[146:147], v[148:149] op_sel_hi:[1,0,1]
	v_pk_fma_f32 v[142:143], v[48:49], v[146:147], v[142:143] op_sel_hi:[1,0,1]
	v_and_b32_e32 v144, 0xffff0000, v144
	v_pk_fma_f32 v[146:147], v[46:47], v[144:145], v[148:149] op_sel_hi:[1,0,1]
	v_pk_fma_f32 v[142:143], v[44:45], v[144:145], v[142:143] op_sel_hi:[1,0,1]
	v_lshlrev_b32_e32 v144, 16, v145
	v_pk_fma_f32 v[146:147], v[42:43], v[144:145], v[146:147] op_sel_hi:[1,0,1]
	v_pk_fma_f32 v[142:143], v[40:41], v[144:145], v[142:143] op_sel_hi:[1,0,1]
	v_and_b32_e32 v144, 0xffff0000, v145
	v_pk_fma_f32 v[146:147], v[38:39], v[144:145], v[146:147] op_sel_hi:[1,0,1]
	v_pk_fma_f32 v[142:143], v[36:37], v[144:145], v[142:143] op_sel_hi:[1,0,1]
	s_add_u32 s0, s6, 0x9d600
	s_addc_u32 s1, s7, 0
	s_waitcnt vmcnt(0)
	v_lshlrev_b32_e32 v144, 16, v72
	v_pk_fma_f32 v[146:147], v[34:35], v[144:145], v[146:147] op_sel_hi:[1,0,1]
	v_pk_fma_f32 v[142:143], v[32:33], v[144:145], v[142:143] op_sel_hi:[1,0,1]
	v_and_b32_e32 v72, 0xffff0000, v72
	v_pk_fma_f32 v[144:145], v[30:31], v[72:73], v[146:147] op_sel_hi:[1,0,1]
	v_pk_fma_f32 v[142:143], v[28:29], v[72:73], v[142:143] op_sel_hi:[1,0,1]
	v_lshlrev_b32_e32 v72, 16, v73
	v_pk_fma_f32 v[144:145], v[26:27], v[72:73], v[144:145] op_sel_hi:[1,0,1]
	v_pk_fma_f32 v[142:143], v[24:25], v[72:73], v[142:143] op_sel_hi:[1,0,1]
	v_and_b32_e32 v72, 0xffff0000, v73
	v_pk_fma_f32 v[144:145], v[22:23], v[72:73], v[144:145] op_sel_hi:[1,0,1]
	v_pk_fma_f32 v[72:73], v[20:21], v[72:73], v[142:143] op_sel_hi:[1,0,1]
	v_lshlrev_b32_e32 v142, 16, v74
	v_pk_fma_f32 v[144:145], v[18:19], v[142:143], v[144:145] op_sel_hi:[1,0,1]
	v_pk_fma_f32 v[72:73], v[16:17], v[142:143], v[72:73] op_sel_hi:[1,0,1]
	v_and_b32_e32 v74, 0xffff0000, v74
	v_pk_fma_f32 v[142:143], v[14:15], v[74:75], v[144:145] op_sel_hi:[1,0,1]
	v_pk_fma_f32 v[72:73], v[12:13], v[74:75], v[72:73] op_sel_hi:[1,0,1]
	v_lshlrev_b32_e32 v74, 16, v75
	v_pk_fma_f32 v[142:143], v[10:11], v[74:75], v[142:143] op_sel_hi:[1,0,1]
	v_pk_fma_f32 v[72:73], v[8:9], v[74:75], v[72:73] op_sel_hi:[1,0,1]
	v_and_b32_e32 v74, 0xffff0000, v75
	v_pk_fma_f32 v[72:73], v[4:5], v[74:75], v[72:73] op_sel_hi:[1,0,1]
	v_pk_fma_f32 v[142:143], v[6:7], v[74:75], v[142:143] op_sel_hi:[1,0,1]
	v_min_f32_e32 v74, 0, v72
	v_mul_f32_e64 v72, |v72|, s93
	v_exp_f32_e32 v72, v72
	s_nop 0
	v_add_f32_e32 v72, 1.0, v72
	v_log_f32_e32 v72, v72
	s_nop 0
	v_fmac_f32_e32 v74, 0xbf317218, v72
	v_min_f32_e32 v72, 0, v73
	v_mul_f32_e64 v73, |v73|, s93
	v_exp_f32_e32 v73, v73
	v_fmac_f32_e32 v85, 0x3d800000, v74
	v_add_f32_e32 v73, 1.0, v73
	v_log_f32_e32 v73, v73
	s_nop 0
	v_fmac_f32_e32 v72, 0xbf317218, v73
	v_mul_f32_e64 v73, |v142|, s93
	v_exp_f32_e32 v73, v73
	v_fmac_f32_e32 v91, 0x3d800000, v72
	v_min_f32_e32 v72, 0, v142
	v_add_f32_e32 v73, 1.0, v73
	v_log_f32_e32 v73, v73
	s_nop 0
	v_fmac_f32_e32 v72, 0xbf317218, v73
	v_mul_f32_e64 v73, |v143|, s93
	v_exp_f32_e32 v73, v73
	v_fmac_f32_e32 v163, 0x3d800000, v72
	v_min_f32_e32 v72, 0, v143
	v_mov_b32_e32 v143, 0x9d000
	v_add_f32_e32 v73, 1.0, v73
	v_log_f32_e32 v73, v73
	global_load_dwordx4 v[152:155], v143, s[6:7] offset:1536
	v_fmac_f32_e32 v72, 0xbf317218, v73
	v_fmac_f32_e32 v170, 0x3d800000, v72
	v_sub_f32_e32 v72, v130, v85
	v_mul_f32_e32 v72, 0x3fb8aa3b, v72
	v_exp_f32_e32 v142, v72
	v_sub_f32_e32 v72, v131, v91
	v_mul_f32_e32 v72, 0x3fb8aa3b, v72
	v_exp_f32_e32 v144, v72
	v_sub_f32_e32 v72, v128, v163
	v_mul_f32_e32 v72, 0x3fb8aa3b, v72
	v_exp_f32_e32 v146, v72
	v_sub_f32_e32 v72, v129, v170
	v_mul_f32_e32 v72, 0x3fb8aa3b, v72
	v_exp_f32_e32 v148, v72
	v_add_co_u32_e32 v72, vcc, s71, v76
	s_waitcnt vmcnt(0)
	v_lshlrev_b32_e32 v156, 16, v152
	v_addc_co_u32_e32 v73, vcc, 0, v77, vcc
	global_load_dwordx2 v[150:151], v[72:73], off offset:1024
	v_pk_fma_f32 v[158:159], v[70:71], v[156:157], v[66:67] op_sel_hi:[1,0,1]
	global_load_dwordx4 v[72:75], v3, s[0:1] offset:16
	v_pk_fma_f32 v[156:157], v[68:69], v[156:157], v[64:65] op_sel_hi:[1,0,1]
	v_and_b32_e32 v152, 0xffff0000, v152
	v_pk_fma_f32 v[158:159], v[62:63], v[152:153], v[158:159] op_sel_hi:[1,0,1]
	v_pk_fma_f32 v[156:157], v[60:61], v[152:153], v[156:157] op_sel_hi:[1,0,1]
	v_lshlrev_b32_e32 v152, 16, v153
	v_pk_fma_f32 v[158:159], v[58:59], v[152:153], v[158:159] op_sel_hi:[1,0,1]
	v_pk_fma_f32 v[156:157], v[56:57], v[152:153], v[156:157] op_sel_hi:[1,0,1]
	v_and_b32_e32 v152, 0xffff0000, v153
	v_pk_fma_f32 v[158:159], v[54:55], v[152:153], v[158:159] op_sel_hi:[1,0,1]
	v_pk_fma_f32 v[152:153], v[52:53], v[152:153], v[156:157] op_sel_hi:[1,0,1]
	v_lshlrev_b32_e32 v156, 16, v154
	v_pk_fma_f32 v[158:159], v[50:51], v[156:157], v[158:159] op_sel_hi:[1,0,1]
	v_pk_fma_f32 v[152:153], v[48:49], v[156:157], v[152:153] op_sel_hi:[1,0,1]
	v_and_b32_e32 v154, 0xffff0000, v154
	v_pk_fma_f32 v[156:157], v[46:47], v[154:155], v[158:159] op_sel_hi:[1,0,1]
	v_pk_fma_f32 v[152:153], v[44:45], v[154:155], v[152:153] op_sel_hi:[1,0,1]
	v_lshlrev_b32_e32 v154, 16, v155
	v_pk_fma_f32 v[156:157], v[42:43], v[154:155], v[156:157] op_sel_hi:[1,0,1]
	v_pk_fma_f32 v[152:153], v[40:41], v[154:155], v[152:153] op_sel_hi:[1,0,1]
	v_and_b32_e32 v154, 0xffff0000, v155
	v_pk_fma_f32 v[156:157], v[38:39], v[154:155], v[156:157] op_sel_hi:[1,0,1]
	v_pk_fma_f32 v[152:153], v[36:37], v[154:155], v[152:153] op_sel_hi:[1,0,1]
	s_mov_b32 s0, 0x9d000
	s_waitcnt vmcnt(0)
	v_lshlrev_b32_e32 v154, 16, v72
	v_pk_fma_f32 v[156:157], v[34:35], v[154:155], v[156:157] op_sel_hi:[1,0,1]
	v_pk_fma_f32 v[152:153], v[32:33], v[154:155], v[152:153] op_sel_hi:[1,0,1]
	v_and_b32_e32 v72, 0xffff0000, v72
	v_pk_fma_f32 v[154:155], v[30:31], v[72:73], v[156:157] op_sel_hi:[1,0,1]
	v_pk_fma_f32 v[152:153], v[28:29], v[72:73], v[152:153] op_sel_hi:[1,0,1]
	v_lshlrev_b32_e32 v72, 16, v73
	v_pk_fma_f32 v[154:155], v[26:27], v[72:73], v[154:155] op_sel_hi:[1,0,1]
	v_pk_fma_f32 v[152:153], v[24:25], v[72:73], v[152:153] op_sel_hi:[1,0,1]
	v_and_b32_e32 v72, 0xffff0000, v73
	v_pk_fma_f32 v[154:155], v[22:23], v[72:73], v[154:155] op_sel_hi:[1,0,1]
	v_pk_fma_f32 v[72:73], v[20:21], v[72:73], v[152:153] op_sel_hi:[1,0,1]
	v_lshlrev_b32_e32 v152, 16, v74
	v_pk_fma_f32 v[154:155], v[18:19], v[152:153], v[154:155] op_sel_hi:[1,0,1]
	v_pk_fma_f32 v[72:73], v[16:17], v[152:153], v[72:73] op_sel_hi:[1,0,1]
	v_and_b32_e32 v74, 0xffff0000, v74
	v_pk_fma_f32 v[152:153], v[14:15], v[74:75], v[154:155] op_sel_hi:[1,0,1]
	v_pk_fma_f32 v[72:73], v[12:13], v[74:75], v[72:73] op_sel_hi:[1,0,1]
	v_lshlrev_b32_e32 v74, 16, v75
	v_pk_fma_f32 v[152:153], v[10:11], v[74:75], v[152:153] op_sel_hi:[1,0,1]
	v_pk_fma_f32 v[72:73], v[8:9], v[74:75], v[72:73] op_sel_hi:[1,0,1]
	v_and_b32_e32 v74, 0xffff0000, v75
	v_pk_fma_f32 v[72:73], v[4:5], v[74:75], v[72:73] op_sel_hi:[1,0,1]
	v_pk_fma_f32 v[152:153], v[6:7], v[74:75], v[152:153] op_sel_hi:[1,0,1]
	v_min_f32_e32 v74, 0, v72
	v_mul_f32_e64 v72, |v72|, s93
	v_exp_f32_e32 v72, v72
	s_nop 0
	v_add_f32_e32 v72, 1.0, v72
	v_log_f32_e32 v72, v72
	s_nop 0
	v_fmac_f32_e32 v74, 0xbf317218, v72
	v_min_f32_e32 v72, 0, v73
	v_mul_f32_e64 v73, |v73|, s93
	v_exp_f32_e32 v73, v73
	v_fmac_f32_e32 v85, 0x3d800000, v74
	v_add_f32_e32 v73, 1.0, v73
	v_log_f32_e32 v73, v73
	s_nop 0
	v_fmac_f32_e32 v72, 0xbf317218, v73
	v_mul_f32_e64 v73, |v152|, s93
	v_exp_f32_e32 v73, v73
	v_fmac_f32_e32 v91, 0x3d800000, v72
	v_min_f32_e32 v72, 0, v152
	v_add_f32_e32 v73, 1.0, v73
	v_log_f32_e32 v73, v73
	s_nop 0
	v_fmac_f32_e32 v72, 0xbf317218, v73
	v_mul_f32_e64 v73, |v153|, s93
	v_exp_f32_e32 v73, v73
	v_fmac_f32_e32 v163, 0x3d800000, v72
	v_min_f32_e32 v72, 0, v153
	v_add_f32_e32 v73, 1.0, v73
	v_log_f32_e32 v73, v73
	s_nop 0
	v_fmac_f32_e32 v72, 0xbf317218, v73
	v_fmac_f32_e32 v170, 0x3d800000, v72
	v_sub_f32_e32 v72, v130, v85
	v_mul_f32_e32 v72, 0x3fb8aa3b, v72
	v_exp_f32_e32 v143, v72
	v_lshlrev_b32_e32 v73, 16, v150
	v_lshlrev_b32_e32 v72, 16, v78
	v_pk_mul_f32 v[142:143], v[142:143], v[72:73]
	v_sub_f32_e32 v72, v131, v91
	v_mul_f32_e32 v72, 0x3fb8aa3b, v72
	v_exp_f32_e32 v145, v72
	v_and_b32_e32 v73, 0xffff0000, v150
	v_and_b32_e32 v72, 0xffff0000, v78
	v_mov_b32_e32 v150, 0xa0000
	v_pk_mul_f32 v[144:145], v[144:145], v[72:73]
	v_sub_f32_e32 v72, v128, v163
	v_mul_f32_e32 v72, 0x3fb8aa3b, v72
	v_exp_f32_e32 v147, v72
	v_lshlrev_b32_e32 v73, 16, v151
	v_lshlrev_b32_e32 v72, 16, v79
	v_pk_mul_f32 v[146:147], v[146:147], v[72:73]
	v_sub_f32_e32 v72, v129, v170
	v_and_b32_e32 v73, 0xffff0000, v151
	global_load_dwordx4 v[150:153], v150, s[6:7]
	v_mul_f32_e32 v72, 0x3fb8aa3b, v72
	v_exp_f32_e32 v149, v72
	v_and_b32_e32 v72, 0xffff0000, v79
	v_pk_mul_f32 v[148:149], v[148:149], v[72:73]
	v_add_co_u32_e32 v72, vcc, s0, v76
	s_add_u32 s0, s6, 0xa0000
	s_nop 0
	v_addc_co_u32_e32 v73, vcc, 0, v77, vcc
	s_addc_u32 s1, s7, 0
	global_load_dwordx2 v[78:79], v[72:73], off offset:3584
	s_waitcnt vmcnt(1)
	v_lshlrev_b32_e32 v154, 16, v150
	global_load_dwordx4 v[72:75], v3, s[0:1] offset:16
	v_pk_fma_f32 v[156:157], v[70:71], v[154:155], v[66:67] op_sel_hi:[1,0,1]
	v_pk_fma_f32 v[154:155], v[68:69], v[154:155], v[64:65] op_sel_hi:[1,0,1]
	v_and_b32_e32 v150, 0xffff0000, v150
	v_pk_fma_f32 v[156:157], v[62:63], v[150:151], v[156:157] op_sel_hi:[1,0,1]
	v_pk_fma_f32 v[154:155], v[60:61], v[150:151], v[154:155] op_sel_hi:[1,0,1]
	v_lshlrev_b32_e32 v150, 16, v151
	v_pk_fma_f32 v[156:157], v[58:59], v[150:151], v[156:157] op_sel_hi:[1,0,1]
	v_pk_fma_f32 v[154:155], v[56:57], v[150:151], v[154:155] op_sel_hi:[1,0,1]
	v_and_b32_e32 v150, 0xffff0000, v151
	v_pk_fma_f32 v[156:157], v[54:55], v[150:151], v[156:157] op_sel_hi:[1,0,1]
	v_pk_fma_f32 v[150:151], v[52:53], v[150:151], v[154:155] op_sel_hi:[1,0,1]
	v_lshlrev_b32_e32 v154, 16, v152
	v_pk_fma_f32 v[156:157], v[50:51], v[154:155], v[156:157] op_sel_hi:[1,0,1]
	v_pk_fma_f32 v[150:151], v[48:49], v[154:155], v[150:151] op_sel_hi:[1,0,1]
	v_and_b32_e32 v152, 0xffff0000, v152
	v_pk_fma_f32 v[154:155], v[46:47], v[152:153], v[156:157] op_sel_hi:[1,0,1]
	v_pk_fma_f32 v[150:151], v[44:45], v[152:153], v[150:151] op_sel_hi:[1,0,1]
	v_lshlrev_b32_e32 v152, 16, v153
	v_pk_fma_f32 v[154:155], v[42:43], v[152:153], v[154:155] op_sel_hi:[1,0,1]
	v_pk_fma_f32 v[150:151], v[40:41], v[152:153], v[150:151] op_sel_hi:[1,0,1]
	v_and_b32_e32 v152, 0xffff0000, v153
	v_pk_fma_f32 v[154:155], v[38:39], v[152:153], v[154:155] op_sel_hi:[1,0,1]
	v_pk_fma_f32 v[150:151], v[36:37], v[152:153], v[150:151] op_sel_hi:[1,0,1]
	s_add_u32 s0, s6, 0xa2a00
	s_addc_u32 s1, s7, 0
	s_waitcnt vmcnt(0)
	v_lshlrev_b32_e32 v152, 16, v72
	v_pk_fma_f32 v[154:155], v[34:35], v[152:153], v[154:155] op_sel_hi:[1,0,1]
	v_pk_fma_f32 v[150:151], v[32:33], v[152:153], v[150:151] op_sel_hi:[1,0,1]
	v_and_b32_e32 v72, 0xffff0000, v72
	v_pk_fma_f32 v[152:153], v[30:31], v[72:73], v[154:155] op_sel_hi:[1,0,1]
	v_pk_fma_f32 v[150:151], v[28:29], v[72:73], v[150:151] op_sel_hi:[1,0,1]
	v_lshlrev_b32_e32 v72, 16, v73
	v_pk_fma_f32 v[152:153], v[26:27], v[72:73], v[152:153] op_sel_hi:[1,0,1]
	v_pk_fma_f32 v[150:151], v[24:25], v[72:73], v[150:151] op_sel_hi:[1,0,1]
	v_and_b32_e32 v72, 0xffff0000, v73
	v_pk_fma_f32 v[152:153], v[22:23], v[72:73], v[152:153] op_sel_hi:[1,0,1]
	v_pk_fma_f32 v[72:73], v[20:21], v[72:73], v[150:151] op_sel_hi:[1,0,1]
	v_lshlrev_b32_e32 v150, 16, v74
	v_pk_fma_f32 v[152:153], v[18:19], v[150:151], v[152:153] op_sel_hi:[1,0,1]
	v_pk_fma_f32 v[72:73], v[16:17], v[150:151], v[72:73] op_sel_hi:[1,0,1]
	v_and_b32_e32 v74, 0xffff0000, v74
	v_pk_fma_f32 v[150:151], v[14:15], v[74:75], v[152:153] op_sel_hi:[1,0,1]
	v_pk_fma_f32 v[72:73], v[12:13], v[74:75], v[72:73] op_sel_hi:[1,0,1]
	v_lshlrev_b32_e32 v74, 16, v75
	v_pk_fma_f32 v[150:151], v[10:11], v[74:75], v[150:151] op_sel_hi:[1,0,1]
	v_pk_fma_f32 v[72:73], v[8:9], v[74:75], v[72:73] op_sel_hi:[1,0,1]
	v_and_b32_e32 v74, 0xffff0000, v75
	v_pk_fma_f32 v[72:73], v[4:5], v[74:75], v[72:73] op_sel_hi:[1,0,1]
	v_pk_fma_f32 v[150:151], v[6:7], v[74:75], v[150:151] op_sel_hi:[1,0,1]
	v_min_f32_e32 v74, 0, v72
	v_mul_f32_e64 v72, |v72|, s93
	v_exp_f32_e32 v72, v72
	s_nop 0
	v_add_f32_e32 v72, 1.0, v72
	v_log_f32_e32 v72, v72
	s_nop 0
	v_fmac_f32_e32 v74, 0xbf317218, v72
	v_min_f32_e32 v72, 0, v73
	v_mul_f32_e64 v73, |v73|, s93
	v_exp_f32_e32 v73, v73
	v_fmac_f32_e32 v85, 0x3d800000, v74
	v_add_f32_e32 v73, 1.0, v73
	v_log_f32_e32 v73, v73
	s_nop 0
	v_fmac_f32_e32 v72, 0xbf317218, v73
	v_mul_f32_e64 v73, |v150|, s93
	v_exp_f32_e32 v73, v73
	v_fmac_f32_e32 v91, 0x3d800000, v72
	v_min_f32_e32 v72, 0, v150
	v_add_f32_e32 v73, 1.0, v73
	v_log_f32_e32 v73, v73
	s_nop 0
	v_fmac_f32_e32 v72, 0xbf317218, v73
	v_mul_f32_e64 v73, |v151|, s93
	v_exp_f32_e32 v73, v73
	v_fmac_f32_e32 v163, 0x3d800000, v72
	v_min_f32_e32 v72, 0, v151
	v_mov_b32_e32 v151, 0xa2000
	v_add_f32_e32 v73, 1.0, v73
	v_log_f32_e32 v73, v73
	global_load_dwordx4 v[164:167], v151, s[6:7] offset:2560
	v_fmac_f32_e32 v72, 0xbf317218, v73
	v_fmac_f32_e32 v170, 0x3d800000, v72
	v_sub_f32_e32 v72, v130, v85
	v_mul_f32_e32 v72, 0x3fb8aa3b, v72
	v_exp_f32_e32 v150, v72
	v_sub_f32_e32 v72, v131, v91
	v_mul_f32_e32 v72, 0x3fb8aa3b, v72
	v_exp_f32_e32 v152, v72
	v_sub_f32_e32 v72, v128, v163
	v_mul_f32_e32 v72, 0x3fb8aa3b, v72
	v_exp_f32_e32 v154, v72
	v_sub_f32_e32 v72, v129, v170
	v_mul_f32_e32 v72, 0x3fb8aa3b, v72
	v_exp_f32_e32 v156, v72
	v_add_co_u32_e32 v72, vcc, s10, v76
	s_waitcnt vmcnt(0)
	v_lshlrev_b32_e32 v160, 16, v164
	v_addc_co_u32_e32 v73, vcc, 0, v77, vcc
	global_load_dwordx2 v[158:159], v[72:73], off offset:2048
	v_pk_fma_f32 v[168:169], v[70:71], v[160:161], v[66:67] op_sel_hi:[1,0,1]
	global_load_dwordx4 v[72:75], v3, s[0:1] offset:16
	v_pk_fma_f32 v[160:161], v[68:69], v[160:161], v[64:65] op_sel_hi:[1,0,1]
	v_and_b32_e32 v162, 0xffff0000, v164
	v_pk_fma_f32 v[168:169], v[62:63], v[162:163], v[168:169] op_sel_hi:[1,0,1]
	v_pk_fma_f32 v[160:161], v[60:61], v[162:163], v[160:161] op_sel_hi:[1,0,1]
	v_lshlrev_b32_e32 v162, 16, v165
	v_pk_fma_f32 v[168:169], v[58:59], v[162:163], v[168:169] op_sel_hi:[1,0,1]
	v_pk_fma_f32 v[160:161], v[56:57], v[162:163], v[160:161] op_sel_hi:[1,0,1]
	v_and_b32_e32 v162, 0xffff0000, v165
	v_pk_fma_f32 v[164:165], v[54:55], v[162:163], v[168:169] op_sel_hi:[1,0,1]
	v_pk_fma_f32 v[160:161], v[52:53], v[162:163], v[160:161] op_sel_hi:[1,0,1]
	v_lshlrev_b32_e32 v162, 16, v166
	v_pk_fma_f32 v[164:165], v[50:51], v[162:163], v[164:165] op_sel_hi:[1,0,1]
	v_pk_fma_f32 v[160:161], v[48:49], v[162:163], v[160:161] op_sel_hi:[1,0,1]
	v_and_b32_e32 v162, 0xffff0000, v166
	v_pk_fma_f32 v[164:165], v[46:47], v[162:163], v[164:165] op_sel_hi:[1,0,1]
	v_pk_fma_f32 v[160:161], v[44:45], v[162:163], v[160:161] op_sel_hi:[1,0,1]
	v_lshlrev_b32_e32 v162, 16, v167
	v_pk_fma_f32 v[164:165], v[42:43], v[162:163], v[164:165] op_sel_hi:[1,0,1]
	v_pk_fma_f32 v[160:161], v[40:41], v[162:163], v[160:161] op_sel_hi:[1,0,1]
	v_and_b32_e32 v162, 0xffff0000, v167
	v_pk_fma_f32 v[164:165], v[38:39], v[162:163], v[164:165] op_sel_hi:[1,0,1]
	v_pk_fma_f32 v[160:161], v[36:37], v[162:163], v[160:161] op_sel_hi:[1,0,1]
	s_add_u32 s0, s6, 0xa5400
	s_addc_u32 s1, s7, 0
	s_waitcnt vmcnt(0)
	v_lshlrev_b32_e32 v162, 16, v72
	v_pk_fma_f32 v[164:165], v[34:35], v[162:163], v[164:165] op_sel_hi:[1,0,1]
	v_pk_fma_f32 v[160:161], v[32:33], v[162:163], v[160:161] op_sel_hi:[1,0,1]
	v_and_b32_e32 v72, 0xffff0000, v72
	v_pk_fma_f32 v[164:165], v[30:31], v[72:73], v[164:165] op_sel_hi:[1,0,1]
	v_pk_fma_f32 v[160:161], v[28:29], v[72:73], v[160:161] op_sel_hi:[1,0,1]
	v_lshlrev_b32_e32 v72, 16, v73
	v_pk_fma_f32 v[164:165], v[26:27], v[72:73], v[164:165] op_sel_hi:[1,0,1]
	v_pk_fma_f32 v[160:161], v[24:25], v[72:73], v[160:161] op_sel_hi:[1,0,1]
	v_and_b32_e32 v72, 0xffff0000, v73
	v_pk_fma_f32 v[164:165], v[22:23], v[72:73], v[164:165] op_sel_hi:[1,0,1]
	v_pk_fma_f32 v[72:73], v[20:21], v[72:73], v[160:161] op_sel_hi:[1,0,1]
	v_lshlrev_b32_e32 v160, 16, v74
	v_pk_fma_f32 v[164:165], v[18:19], v[160:161], v[164:165] op_sel_hi:[1,0,1]
	v_pk_fma_f32 v[72:73], v[16:17], v[160:161], v[72:73] op_sel_hi:[1,0,1]
	v_and_b32_e32 v74, 0xffff0000, v74
	v_pk_fma_f32 v[160:161], v[14:15], v[74:75], v[164:165] op_sel_hi:[1,0,1]
	v_pk_fma_f32 v[72:73], v[12:13], v[74:75], v[72:73] op_sel_hi:[1,0,1]
	v_lshlrev_b32_e32 v74, 16, v75
	v_pk_fma_f32 v[160:161], v[10:11], v[74:75], v[160:161] op_sel_hi:[1,0,1]
	v_pk_fma_f32 v[72:73], v[8:9], v[74:75], v[72:73] op_sel_hi:[1,0,1]
	v_and_b32_e32 v74, 0xffff0000, v75
	v_pk_fma_f32 v[72:73], v[4:5], v[74:75], v[72:73] op_sel_hi:[1,0,1]
	v_pk_fma_f32 v[160:161], v[6:7], v[74:75], v[160:161] op_sel_hi:[1,0,1]
	v_min_f32_e32 v74, 0, v72
	v_mul_f32_e64 v72, |v72|, s93
	v_exp_f32_e32 v72, v72
	s_nop 0
	v_add_f32_e32 v72, 1.0, v72
	v_log_f32_e32 v72, v72
	s_nop 0
	v_fmac_f32_e32 v74, 0xbf317218, v72
	v_min_f32_e32 v72, 0, v73
	v_mul_f32_e64 v73, |v73|, s93
	v_exp_f32_e32 v73, v73
	v_fmac_f32_e32 v85, 0x3d800000, v74
	v_add_f32_e32 v73, 1.0, v73
	v_log_f32_e32 v73, v73
	s_nop 0
	v_fmac_f32_e32 v72, 0xbf317218, v73
	v_mul_f32_e64 v73, |v160|, s93
	v_exp_f32_e32 v73, v73
	v_fmac_f32_e32 v91, 0x3d800000, v72
	v_min_f32_e32 v72, 0, v160
	v_add_f32_e32 v73, 1.0, v73
	v_log_f32_e32 v73, v73
	s_nop 0
	v_fmac_f32_e32 v72, 0xbf317218, v73
	v_mul_f32_e64 v73, |v161|, s93
	v_exp_f32_e32 v73, v73
	v_fmac_f32_e32 v163, 0x3d800000, v72
	v_min_f32_e32 v72, 0, v161
	v_add_f32_e32 v73, 1.0, v73
	v_log_f32_e32 v73, v73
	s_nop 0
	v_fmac_f32_e32 v72, 0xbf317218, v73
	v_fmac_f32_e32 v170, 0x3d800000, v72
	v_sub_f32_e32 v72, v130, v85
	v_mul_f32_e32 v72, 0x3fb8aa3b, v72
	v_exp_f32_e32 v151, v72
	v_lshlrev_b32_e32 v73, 16, v158
	v_lshlrev_b32_e32 v72, 16, v78
	v_pk_mul_f32 v[150:151], v[150:151], v[72:73]
	v_sub_f32_e32 v72, v131, v91
	v_mul_f32_e32 v72, 0x3fb8aa3b, v72
	v_exp_f32_e32 v153, v72
	v_and_b32_e32 v73, 0xffff0000, v158
	v_and_b32_e32 v72, 0xffff0000, v78
	v_mov_b32_e32 v78, 0xa5000
	v_pk_mul_f32 v[152:153], v[152:153], v[72:73]
	v_sub_f32_e32 v72, v128, v163
	v_mul_f32_e32 v72, 0x3fb8aa3b, v72
	v_exp_f32_e32 v155, v72
	v_lshlrev_b32_e32 v73, 16, v159
	v_lshlrev_b32_e32 v72, 16, v79
	global_load_dwordx4 v[164:167], v78, s[6:7] offset:1024
	v_pk_mul_f32 v[154:155], v[154:155], v[72:73]
	v_sub_f32_e32 v72, v129, v170
	v_mul_f32_e32 v72, 0x3fb8aa3b, v72
	v_exp_f32_e32 v157, v72
	v_and_b32_e32 v73, 0xffff0000, v159
	v_and_b32_e32 v72, 0xffff0000, v79
	v_pk_mul_f32 v[156:157], v[156:157], v[72:73]
	v_add_co_u32_e32 v72, vcc, s73, v76
	s_waitcnt vmcnt(0)
	v_lshlrev_b32_e32 v78, 16, v164
	v_addc_co_u32_e32 v73, vcc, 0, v77, vcc
	global_load_dwordx2 v[158:159], v[72:73], off offset:512
	v_pk_fma_f32 v[160:161], v[70:71], v[78:79], v[66:67] op_sel_hi:[1,0,1]
	global_load_dwordx4 v[72:75], v3, s[0:1] offset:16
	v_pk_fma_f32 v[78:79], v[68:69], v[78:79], v[64:65] op_sel_hi:[1,0,1]
	v_and_b32_e32 v162, 0xffff0000, v164
	v_pk_fma_f32 v[160:161], v[62:63], v[162:163], v[160:161] op_sel_hi:[1,0,1]
	v_pk_fma_f32 v[78:79], v[60:61], v[162:163], v[78:79] op_sel_hi:[1,0,1]
	v_lshlrev_b32_e32 v162, 16, v165
	v_pk_fma_f32 v[160:161], v[58:59], v[162:163], v[160:161] op_sel_hi:[1,0,1]
	v_pk_fma_f32 v[78:79], v[56:57], v[162:163], v[78:79] op_sel_hi:[1,0,1]
	v_and_b32_e32 v162, 0xffff0000, v165
	v_pk_fma_f32 v[160:161], v[54:55], v[162:163], v[160:161] op_sel_hi:[1,0,1]
	v_pk_fma_f32 v[78:79], v[52:53], v[162:163], v[78:79] op_sel_hi:[1,0,1]
	v_lshlrev_b32_e32 v162, 16, v166
	v_pk_fma_f32 v[160:161], v[50:51], v[162:163], v[160:161] op_sel_hi:[1,0,1]
	v_pk_fma_f32 v[78:79], v[48:49], v[162:163], v[78:79] op_sel_hi:[1,0,1]
	v_and_b32_e32 v162, 0xffff0000, v166
	v_pk_fma_f32 v[160:161], v[46:47], v[162:163], v[160:161] op_sel_hi:[1,0,1]
	v_pk_fma_f32 v[78:79], v[44:45], v[162:163], v[78:79] op_sel_hi:[1,0,1]
	v_lshlrev_b32_e32 v162, 16, v167
	v_pk_fma_f32 v[160:161], v[42:43], v[162:163], v[160:161] op_sel_hi:[1,0,1]
	v_pk_fma_f32 v[78:79], v[40:41], v[162:163], v[78:79] op_sel_hi:[1,0,1]
	v_and_b32_e32 v162, 0xffff0000, v167
	v_pk_fma_f32 v[160:161], v[38:39], v[162:163], v[160:161] op_sel_hi:[1,0,1]
	v_pk_fma_f32 v[78:79], v[36:37], v[162:163], v[78:79] op_sel_hi:[1,0,1]
	s_mov_b32 s0, 0xa5000
	s_waitcnt vmcnt(0)
	v_lshlrev_b32_e32 v162, 16, v72
	v_pk_fma_f32 v[160:161], v[34:35], v[162:163], v[160:161] op_sel_hi:[1,0,1]
	v_pk_fma_f32 v[78:79], v[32:33], v[162:163], v[78:79] op_sel_hi:[1,0,1]
	v_and_b32_e32 v72, 0xffff0000, v72
	v_pk_fma_f32 v[160:161], v[30:31], v[72:73], v[160:161] op_sel_hi:[1,0,1]
	v_pk_fma_f32 v[78:79], v[28:29], v[72:73], v[78:79] op_sel_hi:[1,0,1]
	v_lshlrev_b32_e32 v72, 16, v73
	v_pk_fma_f32 v[160:161], v[26:27], v[72:73], v[160:161] op_sel_hi:[1,0,1]
	v_pk_fma_f32 v[78:79], v[24:25], v[72:73], v[78:79] op_sel_hi:[1,0,1]
	v_and_b32_e32 v72, 0xffff0000, v73
	v_pk_fma_f32 v[160:161], v[22:23], v[72:73], v[160:161] op_sel_hi:[1,0,1]
	v_pk_fma_f32 v[72:73], v[20:21], v[72:73], v[78:79] op_sel_hi:[1,0,1]
	v_lshlrev_b32_e32 v78, 16, v74
	v_pk_fma_f32 v[160:161], v[18:19], v[78:79], v[160:161] op_sel_hi:[1,0,1]
	v_pk_fma_f32 v[72:73], v[16:17], v[78:79], v[72:73] op_sel_hi:[1,0,1]
	v_and_b32_e32 v74, 0xffff0000, v74
	v_pk_fma_f32 v[78:79], v[14:15], v[74:75], v[160:161] op_sel_hi:[1,0,1]
	v_pk_fma_f32 v[72:73], v[12:13], v[74:75], v[72:73] op_sel_hi:[1,0,1]
	v_lshlrev_b32_e32 v74, 16, v75
	v_pk_fma_f32 v[78:79], v[10:11], v[74:75], v[78:79] op_sel_hi:[1,0,1]
	v_pk_fma_f32 v[72:73], v[8:9], v[74:75], v[72:73] op_sel_hi:[1,0,1]
	v_and_b32_e32 v74, 0xffff0000, v75
	v_pk_fma_f32 v[72:73], v[4:5], v[74:75], v[72:73] op_sel_hi:[1,0,1]
	v_pk_fma_f32 v[78:79], v[6:7], v[74:75], v[78:79] op_sel_hi:[1,0,1]
	v_min_f32_e32 v74, 0, v72
	v_mul_f32_e64 v72, |v72|, s93
	v_exp_f32_e32 v72, v72
	s_nop 0
	v_add_f32_e32 v72, 1.0, v72
	v_log_f32_e32 v72, v72
	s_nop 0
	v_fmac_f32_e32 v74, 0xbf317218, v72
	v_min_f32_e32 v72, 0, v73
	v_mul_f32_e64 v73, |v73|, s93
	v_exp_f32_e32 v73, v73
	v_fmac_f32_e32 v85, 0x3d800000, v74
	v_add_f32_e32 v73, 1.0, v73
	v_log_f32_e32 v73, v73
	s_nop 0
	v_fmac_f32_e32 v72, 0xbf317218, v73
	v_mul_f32_e64 v73, |v78|, s93
	v_exp_f32_e32 v73, v73
	v_fmac_f32_e32 v91, 0x3d800000, v72
	v_min_f32_e32 v72, 0, v78
	v_add_f32_e32 v73, 1.0, v73
	v_log_f32_e32 v73, v73
	s_nop 0
	v_fmac_f32_e32 v72, 0xbf317218, v73
	v_mul_f32_e64 v73, |v79|, s93
	v_exp_f32_e32 v73, v73
	v_fmac_f32_e32 v163, 0x3d800000, v72
	v_min_f32_e32 v72, 0, v79
	v_add_f32_e32 v73, 1.0, v73
	v_log_f32_e32 v73, v73
	s_nop 0
	v_fmac_f32_e32 v72, 0xbf317218, v73
	v_fmac_f32_e32 v170, 0x3d800000, v72
	v_sub_f32_e32 v72, v130, v85
	v_mul_f32_e32 v72, 0x3fb8aa3b, v72
	v_exp_f32_e32 v166, v72
	v_sub_f32_e32 v72, v131, v91
	v_mul_f32_e32 v72, 0x3fb8aa3b, v72
	v_exp_f32_e32 v164, v72
	v_sub_f32_e32 v72, v128, v163
	v_mul_f32_e32 v72, 0x3fb8aa3b, v72
	v_exp_f32_e32 v162, v72
	v_sub_f32_e32 v72, v129, v170
	v_mul_f32_e32 v72, 0x3fb8aa3b, v72
	v_exp_f32_e32 v160, v72
	v_add_co_u32_e32 v72, vcc, s0, v76
	v_mov_b32_e32 v76, 0xa7000
	s_nop 0
	v_addc_co_u32_e32 v73, vcc, 0, v77, vcc
	global_load_dwordx4 v[76:79], v76, s[6:7] offset:3584
	s_add_u32 s0, s6, 0xa7e00
	s_addc_u32 s1, s7, 0
	global_load_dwordx2 v[168:169], v[72:73], off offset:3072
	s_waitcnt vmcnt(1)
	v_lshlrev_b32_e32 v172, 16, v76
	global_load_dwordx4 v[72:75], v3, s[0:1] offset:16
	v_pk_fma_f32 v[64:65], v[68:69], v[172:173], v[64:65] op_sel_hi:[1,0,1]
	v_and_b32_e32 v68, 0xffff0000, v76
	v_pk_fma_f32 v[60:61], v[60:61], v[68:69], v[64:65] op_sel_hi:[1,0,1]
	v_lshlrev_b32_e32 v64, 16, v77
	v_pk_fma_f32 v[56:57], v[56:57], v[64:65], v[60:61] op_sel_hi:[1,0,1]
	v_and_b32_e32 v60, 0xffff0000, v77
	v_pk_fma_f32 v[52:53], v[52:53], v[60:61], v[56:57] op_sel_hi:[1,0,1]
	v_lshlrev_b32_e32 v56, 16, v78
	v_pk_fma_f32 v[48:49], v[48:49], v[56:57], v[52:53] op_sel_hi:[1,0,1]
	v_and_b32_e32 v52, 0xffff0000, v78
	v_pk_fma_f32 v[44:45], v[44:45], v[52:53], v[48:49] op_sel_hi:[1,0,1]
	v_lshlrev_b32_e32 v48, 16, v79
	v_pk_fma_f32 v[40:41], v[40:41], v[48:49], v[44:45] op_sel_hi:[1,0,1]
	v_and_b32_e32 v44, 0xffff0000, v79
	v_pk_fma_f32 v[36:37], v[36:37], v[44:45], v[40:41] op_sel_hi:[1,0,1]
	v_pk_fma_f32 v[66:67], v[70:71], v[172:173], v[66:67] op_sel_hi:[1,0,1]
	s_add_u32 s0, s6, s16
	v_pk_fma_f32 v[62:63], v[62:63], v[68:69], v[66:67] op_sel_hi:[1,0,1]
	s_addc_u32 s1, s7, 0
	v_pk_fma_f32 v[58:59], v[58:59], v[64:65], v[62:63] op_sel_hi:[1,0,1]
	s_waitcnt vmcnt(0)
	v_lshlrev_b32_e32 v40, 16, v72
	v_pk_fma_f32 v[32:33], v[32:33], v[40:41], v[36:37] op_sel_hi:[1,0,1]
	v_and_b32_e32 v36, 0xffff0000, v72
	v_pk_fma_f32 v[28:29], v[28:29], v[36:37], v[32:33] op_sel_hi:[1,0,1]
	v_lshlrev_b32_e32 v32, 16, v73
	v_pk_fma_f32 v[24:25], v[24:25], v[32:33], v[28:29] op_sel_hi:[1,0,1]
	v_and_b32_e32 v28, 0xffff0000, v73
	v_pk_fma_f32 v[20:21], v[20:21], v[28:29], v[24:25] op_sel_hi:[1,0,1]
	v_lshlrev_b32_e32 v24, 16, v74
	v_pk_fma_f32 v[16:17], v[16:17], v[24:25], v[20:21] op_sel_hi:[1,0,1]
	v_and_b32_e32 v20, 0xffff0000, v74
	v_pk_fma_f32 v[12:13], v[12:13], v[20:21], v[16:17] op_sel_hi:[1,0,1]
	v_lshlrev_b32_e32 v16, 16, v75
	v_pk_fma_f32 v[8:9], v[8:9], v[16:17], v[12:13] op_sel_hi:[1,0,1]
	v_and_b32_e32 v12, 0xffff0000, v75
	v_pk_fma_f32 v[4:5], v[4:5], v[12:13], v[8:9] op_sel_hi:[1,0,1]
	v_pk_fma_f32 v[54:55], v[54:55], v[60:61], v[58:59] op_sel_hi:[1,0,1]
	v_min_f32_e32 v8, 0, v4
	v_mul_f32_e64 v4, |v4|, s93
	v_exp_f32_e32 v4, v4
	v_pk_fma_f32 v[50:51], v[50:51], v[56:57], v[54:55] op_sel_hi:[1,0,1]
	v_add_f32_e32 v4, 1.0, v4
	v_log_f32_e32 v4, v4
	v_pk_fma_f32 v[46:47], v[46:47], v[52:53], v[50:51] op_sel_hi:[1,0,1]
	v_fmac_f32_e32 v8, 0xbf317218, v4
	v_pk_fma_f32 v[42:43], v[42:43], v[48:49], v[46:47] op_sel_hi:[1,0,1]
	v_min_f32_e32 v4, 0, v5
	v_mul_f32_e64 v5, |v5|, s93
	v_pk_fma_f32 v[38:39], v[38:39], v[44:45], v[42:43] op_sel_hi:[1,0,1]
	v_exp_f32_e32 v5, v5
	v_pk_fma_f32 v[34:35], v[34:35], v[40:41], v[38:39] op_sel_hi:[1,0,1]
	v_fmac_f32_e32 v85, 0x3d800000, v8
	v_pk_fma_f32 v[30:31], v[30:31], v[36:37], v[34:35] op_sel_hi:[1,0,1]
	v_add_f32_e32 v5, 1.0, v5
	v_pk_fma_f32 v[26:27], v[26:27], v[32:33], v[30:31] op_sel_hi:[1,0,1]
	v_log_f32_e32 v5, v5
	v_pk_fma_f32 v[22:23], v[22:23], v[28:29], v[26:27] op_sel_hi:[1,0,1]
	v_lshl_add_u64 v[34:35], v[88:89], 1, s[0:1]
	v_pk_fma_f32 v[18:19], v[18:19], v[24:25], v[22:23] op_sel_hi:[1,0,1]
	v_fmac_f32_e32 v4, 0xbf317218, v5
	v_pk_fma_f32 v[14:15], v[14:15], v[20:21], v[18:19] op_sel_hi:[1,0,1]
	v_fmac_f32_e32 v91, 0x3d800000, v4
	v_pk_fma_f32 v[10:11], v[10:11], v[16:17], v[14:15] op_sel_hi:[1,0,1]
	s_nop 0
	v_pk_fma_f32 v[6:7], v[6:7], v[12:13], v[10:11] op_sel_hi:[1,0,1]
	s_nop 0
	v_mul_f32_e64 v5, |v6|, s93
	v_exp_f32_e32 v5, v5
	v_min_f32_e32 v4, 0, v6
	v_cvt_pk_bf16_f32 v6, v150, v151
	v_add_f32_e32 v5, 1.0, v5
	v_log_f32_e32 v5, v5
	s_nop 0
	v_fmac_f32_e32 v4, 0xbf317218, v5
	v_mul_f32_e64 v5, |v7|, s93
	v_exp_f32_e32 v5, v5
	v_fmac_f32_e32 v163, 0x3d800000, v4
	v_min_f32_e32 v4, 0, v7
	v_add_f32_e32 v5, 1.0, v5
	v_log_f32_e32 v5, v5
	s_nop 0
	v_fmac_f32_e32 v4, 0xbf317218, v5
	v_fmac_f32_e32 v170, 0x3d800000, v4
	v_sub_f32_e32 v4, v130, v85
	v_mul_f32_e32 v4, 0x3fb8aa3b, v4
	v_exp_f32_e32 v167, v4
	v_lshlrev_b32_e32 v5, 16, v168
	v_lshlrev_b32_e32 v4, 16, v158
	v_pk_mul_f32 v[8:9], v[166:167], v[4:5]
	v_sub_f32_e32 v4, v131, v91
	v_mul_f32_e32 v4, 0x3fb8aa3b, v4
	v_exp_f32_e32 v165, v4
	v_and_b32_e32 v5, 0xffff0000, v168
	v_and_b32_e32 v4, 0xffff0000, v158
	v_cvt_pk_bf16_f32 v7, v8, v9
	v_pk_mul_f32 v[10:11], v[164:165], v[4:5]
	v_sub_f32_e32 v4, v128, v163
	v_mul_f32_e32 v4, 0x3fb8aa3b, v4
	v_exp_f32_e32 v163, v4
	v_lshlrev_b32_e32 v5, 16, v169
	v_lshlrev_b32_e32 v4, 16, v159
	v_add_co_u32_e32 v8, vcc, s33, v34
	v_pk_mul_f32 v[12:13], v[162:163], v[4:5]
	v_sub_f32_e32 v4, v129, v170
	v_mul_f32_e32 v4, 0x3fb8aa3b, v4
	v_exp_f32_e32 v161, v4
	v_and_b32_e32 v5, 0xffff0000, v169
	v_and_b32_e32 v4, 0xffff0000, v159
	v_addc_co_u32_e32 v9, vcc, 0, v35, vcc
	v_pk_mul_f32 v[14:15], v[160:161], v[4:5]
	v_cvt_pk_bf16_f32 v4, v134, v135
	v_cvt_pk_bf16_f32 v5, v142, v143
	global_store_dwordx4 v[132:133], v[4:7], off offset:3584
	s_nop 1
	v_cvt_pk_bf16_f32 v4, v136, v137
	v_cvt_pk_bf16_f32 v5, v144, v145
	v_cvt_pk_bf16_f32 v6, v152, v153
	v_cvt_pk_bf16_f32 v7, v10, v11
	global_store_dwordx4 v[132:133], v[4:7], off offset:3600
	s_nop 1
	v_cvt_pk_bf16_f32 v4, v138, v139
	v_cvt_pk_bf16_f32 v5, v146, v147
	v_cvt_pk_bf16_f32 v6, v154, v155
	v_cvt_pk_bf16_f32 v7, v12, v13
	global_store_dwordx4 v[132:133], v[4:7], off offset:3616
	s_nop 1
	v_cvt_pk_bf16_f32 v4, v140, v141
	v_cvt_pk_bf16_f32 v5, v148, v149
	v_cvt_pk_bf16_f32 v6, v156, v157
	v_cvt_pk_bf16_f32 v7, v14, v15
	global_store_dwordx4 v[132:133], v[4:7], off offset:3632
	global_load_dwordx4 v[8:11], v[8:9], off offset:1536
	s_nop 0
	v_mad_u64_u32 v[4:5], s[0:1], s17, 12, v[90:91]
	s_movk_i32 s0, 0x6000
	s_nop 0
	v_add_co_u32_e32 v12, vcc, s0, v34
	s_mov_b32 s0, 0xb000
	s_nop 0
	v_addc_co_u32_e32 v13, vcc, 0, v35, vcc
	v_add_co_u32_e32 v16, vcc, s5, v34
	v_ashrrev_i32_e32 v5, 31, v4
	s_nop 0
	v_addc_co_u32_e32 v17, vcc, 0, v35, vcc
	v_add_co_u32_e32 v20, vcc, s0, v34
	s_mov_b32 s0, 0x13000
	s_nop 0
	v_addc_co_u32_e32 v21, vcc, 0, v35, vcc
	v_add_co_u32_e32 v24, vcc, s11, v34
	v_lshlrev_b64 v[4:5], 12, v[4:5]
	s_nop 0
	v_addc_co_u32_e32 v25, vcc, 0, v35, vcc
	v_add_co_u32_e32 v28, vcc, s2, v34
	v_lshl_add_u64 v[32:33], v[92:93], 0, v[4:5]
	s_nop 0
	v_addc_co_u32_e32 v29, vcc, 0, v35, vcc
	v_add_co_u32_e32 v36, vcc, s0, v34
	global_load_dwordx4 v[4:7], v[34:35], off offset:3072
	s_nop 0
	v_addc_co_u32_e32 v37, vcc, 0, v35, vcc
	global_load_dwordx4 v[12:15], v[12:13], off
	s_mov_b32 s0, 0x1b000
	global_load_dwordx4 v[20:23], v[20:21], off offset:1024
	s_waitcnt vmcnt(2)
	v_and_b32_e32 v40, 0xffff, v4
	global_load_dwordx4 v[28:31], v[28:29], off offset:2048
	v_lshl_or_b32 v40, v8, 16, v40
	global_load_dwordx4 v[16:19], v[16:17], off offset:2560
	s_waitcnt vmcnt(3)
	v_and_b32_e32 v41, 0xffff, v12
	global_load_dwordx4 v[24:27], v[24:25], off offset:3584
	s_waitcnt vmcnt(3)
	v_and_b32_e32 v42, 0xffff, v20
	global_load_dwordx4 v[36:39], v[36:37], off offset:512
	v_lshrrev_b32_e32 v4, 16, v4
	s_waitcnt vmcnt(3)
	v_and_b32_e32 v43, 0xffff, v28
	s_waitcnt vmcnt(2)
	v_lshl_or_b32 v41, v16, 16, v41
	s_waitcnt vmcnt(1)
	v_lshl_or_b32 v42, v24, 16, v42
	s_waitcnt vmcnt(0)
	v_lshl_or_b32 v43, v36, 16, v43
	global_store_dwordx4 v[32:33], v[40:43], off
	s_nop 1
	v_and_or_b32 v40, v8, s95, v4
	v_lshrrev_b32_e32 v4, 16, v12
	v_and_or_b32 v41, v16, s95, v4
	v_lshrrev_b32_e32 v4, 16, v20
	v_and_or_b32 v42, v24, s95, v4
	v_lshrrev_b32_e32 v4, 16, v28
	v_and_or_b32 v43, v36, s95, v4
	v_and_b32_e32 v4, 0xffff, v5
	global_store_dwordx4 v[32:33], v[40:43], off offset:16
	s_nop 1
	v_lshl_or_b32 v40, v9, 16, v4
	v_and_b32_e32 v4, 0xffff, v13
	v_lshl_or_b32 v41, v17, 16, v4
	v_and_b32_e32 v4, 0xffff, v21
	v_lshl_or_b32 v42, v25, 16, v4
	v_and_b32_e32 v4, 0xffff, v29
	v_lshl_or_b32 v43, v37, 16, v4
	v_lshrrev_b32_e32 v4, 16, v5
	global_store_dwordx4 v[32:33], v[40:43], off offset:32
	v_lshrrev_b32_e32 v5, 16, v15
	v_and_or_b32 v5, v19, s95, v5
	v_and_or_b32 v40, v9, s95, v4
	v_lshrrev_b32_e32 v4, 16, v13
	v_and_or_b32 v41, v17, s95, v4
	v_lshrrev_b32_e32 v4, 16, v21
	v_and_or_b32 v42, v25, s95, v4
	v_lshrrev_b32_e32 v4, 16, v29
	v_and_or_b32 v43, v37, s95, v4
	v_and_b32_e32 v4, 0xffff, v6
	global_store_dwordx4 v[32:33], v[40:43], off offset:48
	s_nop 1
	v_lshl_or_b32 v40, v10, 16, v4
	v_and_b32_e32 v4, 0xffff, v14
	v_lshl_or_b32 v41, v18, 16, v4
	v_and_b32_e32 v4, 0xffff, v22
	v_lshl_or_b32 v42, v26, 16, v4
	v_and_b32_e32 v4, 0xffff, v30
	v_lshl_or_b32 v43, v38, 16, v4
	v_lshrrev_b32_e32 v4, 16, v6
	global_store_dwordx4 v[32:33], v[40:43], off offset:64
	v_lshrrev_b32_e32 v6, 16, v23
	v_and_or_b32 v6, v27, s95, v6
	v_and_or_b32 v40, v10, s95, v4
	v_lshrrev_b32_e32 v4, 16, v14
	v_and_or_b32 v41, v18, s95, v4
	v_lshrrev_b32_e32 v4, 16, v22
	v_and_or_b32 v42, v26, s95, v4
	v_lshrrev_b32_e32 v4, 16, v30
	v_and_or_b32 v43, v38, s95, v4
	v_and_b32_e32 v4, 0xffff, v7
	global_store_dwordx4 v[32:33], v[40:43], off offset:80
	s_nop 1
	v_lshl_or_b32 v40, v11, 16, v4
	v_and_b32_e32 v4, 0xffff, v15
	v_lshl_or_b32 v41, v19, 16, v4
	v_and_b32_e32 v4, 0xffff, v23
	v_lshl_or_b32 v42, v27, 16, v4
	v_and_b32_e32 v4, 0xffff, v31
	v_lshl_or_b32 v43, v39, 16, v4
	v_lshrrev_b32_e32 v4, 16, v7
	v_lshrrev_b32_e32 v7, 16, v31
	v_and_or_b32 v4, v11, s95, v4
	v_and_or_b32 v7, v39, s95, v7
	global_store_dwordx4 v[32:33], v[4:7], off offset:112
	global_store_dwordx4 v[32:33], v[40:43], off offset:96
	s_nop 0
	v_add_co_u32_e32 v4, vcc, s18, v34
	s_nop 1
	v_addc_co_u32_e32 v5, vcc, 0, v35, vcc
	v_add_co_u32_e32 v8, vcc, s4, v34
	global_load_dwordx4 v[4:7], v[4:5], off offset:3072
	s_nop 0
	v_addc_co_u32_e32 v9, vcc, 0, v35, vcc
	v_add_co_u32_e32 v12, vcc, s0, v34
	s_mov_b32 s0, 0x20000
	s_nop 0
	v_addc_co_u32_e32 v13, vcc, 0, v35, vcc
	v_add_co_u32_e32 v16, vcc, s19, v34
	global_load_dwordx4 v[12:15], v[12:13], off
	s_nop 0
	v_addc_co_u32_e32 v17, vcc, 0, v35, vcc
	v_add_co_u32_e32 v20, vcc, s0, v34
	s_mov_b32 s0, 0x28000
	s_nop 0
	v_addc_co_u32_e32 v21, vcc, 0, v35, vcc
	v_add_co_u32_e32 v24, vcc, s20, v34
	global_load_dwordx4 v[20:23], v[20:21], off offset:1024
	s_nop 0
	v_addc_co_u32_e32 v25, vcc, 0, v35, vcc
	v_add_co_u32_e32 v28, vcc, s21, v34
	global_load_dwordx4 v[8:11], v[8:9], off offset:1536
	s_nop 0
	v_addc_co_u32_e32 v29, vcc, 0, v35, vcc
	v_add_co_u32_e32 v36, vcc, s0, v34
	global_load_dwordx4 v[28:31], v[28:29], off offset:2048
	s_nop 0
	v_addc_co_u32_e32 v37, vcc, 0, v35, vcc
	global_load_dwordx4 v[16:19], v[16:17], off offset:2560
	s_mov_b32 s0, 0x30000
	global_load_dwordx4 v[24:27], v[24:25], off offset:3584
	s_waitcnt vmcnt(6)
	v_and_b32_e32 v40, 0xffff, v4
	global_load_dwordx4 v[36:39], v[36:37], off offset:512
	v_lshrrev_b32_e32 v4, 16, v4
	s_waitcnt vmcnt(6)
	v_and_b32_e32 v41, 0xffff, v12
	s_waitcnt vmcnt(5)
	v_and_b32_e32 v42, 0xffff, v20
	s_waitcnt vmcnt(4)
	v_lshl_or_b32 v40, v8, 16, v40
	s_waitcnt vmcnt(3)
	v_and_b32_e32 v43, 0xffff, v28
	s_waitcnt vmcnt(2)
	v_lshl_or_b32 v41, v16, 16, v41
	s_waitcnt vmcnt(1)
	v_lshl_or_b32 v42, v24, 16, v42
	s_waitcnt vmcnt(0)
	v_lshl_or_b32 v43, v36, 16, v43
	global_store_dwordx4 v[32:33], v[40:43], off offset:512
	s_nop 1
	v_and_or_b32 v40, v8, s95, v4
	v_lshrrev_b32_e32 v4, 16, v12
	v_and_or_b32 v41, v16, s95, v4
	v_lshrrev_b32_e32 v4, 16, v20
	v_and_or_b32 v42, v24, s95, v4
	v_lshrrev_b32_e32 v4, 16, v28
	v_and_or_b32 v43, v36, s95, v4
	v_and_b32_e32 v4, 0xffff, v5
	global_store_dwordx4 v[32:33], v[40:43], off offset:528
	s_nop 1
	v_lshl_or_b32 v40, v9, 16, v4
	v_and_b32_e32 v4, 0xffff, v13
	v_lshl_or_b32 v41, v17, 16, v4
	v_and_b32_e32 v4, 0xffff, v21
	v_lshl_or_b32 v42, v25, 16, v4
	v_and_b32_e32 v4, 0xffff, v29
	v_lshl_or_b32 v43, v37, 16, v4
	v_lshrrev_b32_e32 v4, 16, v5
	global_store_dwordx4 v[32:33], v[40:43], off offset:544
	v_lshrrev_b32_e32 v5, 16, v15
	v_and_or_b32 v5, v19, s95, v5
	v_and_or_b32 v40, v9, s95, v4
	v_lshrrev_b32_e32 v4, 16, v13
	v_and_or_b32 v41, v17, s95, v4
	v_lshrrev_b32_e32 v4, 16, v21
	v_and_or_b32 v42, v25, s95, v4
	v_lshrrev_b32_e32 v4, 16, v29
	v_and_or_b32 v43, v37, s95, v4
	v_and_b32_e32 v4, 0xffff, v6
	global_store_dwordx4 v[32:33], v[40:43], off offset:560
	s_nop 1
	v_lshl_or_b32 v40, v10, 16, v4
	v_and_b32_e32 v4, 0xffff, v14
	v_lshl_or_b32 v41, v18, 16, v4
	v_and_b32_e32 v4, 0xffff, v22
	v_lshl_or_b32 v42, v26, 16, v4
	v_and_b32_e32 v4, 0xffff, v30
	v_lshl_or_b32 v43, v38, 16, v4
	v_lshrrev_b32_e32 v4, 16, v6
	global_store_dwordx4 v[32:33], v[40:43], off offset:576
	v_lshrrev_b32_e32 v6, 16, v23
	v_and_or_b32 v6, v27, s95, v6
	v_and_or_b32 v40, v10, s95, v4
	v_lshrrev_b32_e32 v4, 16, v14
	v_and_or_b32 v41, v18, s95, v4
	v_lshrrev_b32_e32 v4, 16, v22
	v_and_or_b32 v42, v26, s95, v4
	v_lshrrev_b32_e32 v4, 16, v30
	v_and_or_b32 v43, v38, s95, v4
	v_and_b32_e32 v4, 0xffff, v7
	global_store_dwordx4 v[32:33], v[40:43], off offset:592
	s_nop 1
	v_lshl_or_b32 v40, v11, 16, v4
	v_and_b32_e32 v4, 0xffff, v15
	v_lshl_or_b32 v41, v19, 16, v4
	v_and_b32_e32 v4, 0xffff, v23
	v_lshl_or_b32 v42, v27, 16, v4
	v_and_b32_e32 v4, 0xffff, v31
	v_lshl_or_b32 v43, v39, 16, v4
	v_lshrrev_b32_e32 v4, 16, v7
	v_lshrrev_b32_e32 v7, 16, v31
	v_and_or_b32 v4, v11, s95, v4
	v_and_or_b32 v7, v39, s95, v7
	global_store_dwordx4 v[32:33], v[4:7], off offset:624
	global_store_dwordx4 v[32:33], v[40:43], off offset:608
	s_nop 0
	v_add_co_u32_e32 v4, vcc, s22, v34
	s_nop 1
	v_addc_co_u32_e32 v5, vcc, 0, v35, vcc
	v_add_co_u32_e32 v8, vcc, s23, v34
	global_load_dwordx4 v[4:7], v[4:5], off offset:3072
	s_nop 0
	v_addc_co_u32_e32 v9, vcc, 0, v35, vcc
	v_add_co_u32_e32 v12, vcc, s0, v34
	s_mov_b32 s0, 0x35000
	s_nop 0
	v_addc_co_u32_e32 v13, vcc, 0, v35, vcc
	v_add_co_u32_e32 v16, vcc, s24, v34
	global_load_dwordx4 v[12:15], v[12:13], off
	s_nop 0
	v_addc_co_u32_e32 v17, vcc, 0, v35, vcc
	v_add_co_u32_e32 v20, vcc, s0, v34
	s_mov_b32 s0, 0x3d000
	s_nop 0
	v_addc_co_u32_e32 v21, vcc, 0, v35, vcc
	v_add_co_u32_e32 v24, vcc, s25, v34
	global_load_dwordx4 v[20:23], v[20:21], off offset:1024
	s_nop 0
	v_addc_co_u32_e32 v25, vcc, 0, v35, vcc
	v_add_co_u32_e32 v28, vcc, s26, v34
	global_load_dwordx4 v[8:11], v[8:9], off offset:1536
	s_nop 0
	v_addc_co_u32_e32 v29, vcc, 0, v35, vcc
	v_add_co_u32_e32 v36, vcc, s0, v34
	global_load_dwordx4 v[28:31], v[28:29], off offset:2048
	s_nop 0
	v_addc_co_u32_e32 v37, vcc, 0, v35, vcc
	global_load_dwordx4 v[16:19], v[16:17], off offset:2560
	s_mov_b32 s0, 0x45000
	global_load_dwordx4 v[24:27], v[24:25], off offset:3584
	s_waitcnt vmcnt(6)
	v_and_b32_e32 v40, 0xffff, v4
	global_load_dwordx4 v[36:39], v[36:37], off offset:512
	v_lshrrev_b32_e32 v4, 16, v4
	s_waitcnt vmcnt(6)
	v_and_b32_e32 v41, 0xffff, v12
	s_waitcnt vmcnt(5)
	v_and_b32_e32 v42, 0xffff, v20
	s_waitcnt vmcnt(4)
	v_lshl_or_b32 v40, v8, 16, v40
	s_waitcnt vmcnt(3)
	v_and_b32_e32 v43, 0xffff, v28
	s_waitcnt vmcnt(2)
	v_lshl_or_b32 v41, v16, 16, v41
	s_waitcnt vmcnt(1)
	v_lshl_or_b32 v42, v24, 16, v42
	s_waitcnt vmcnt(0)
	v_lshl_or_b32 v43, v36, 16, v43
	global_store_dwordx4 v[32:33], v[40:43], off offset:1024
	s_nop 1
	v_and_or_b32 v40, v8, s95, v4
	v_lshrrev_b32_e32 v4, 16, v12
	v_and_or_b32 v41, v16, s95, v4
	v_lshrrev_b32_e32 v4, 16, v20
	v_and_or_b32 v42, v24, s95, v4
	v_lshrrev_b32_e32 v4, 16, v28
	v_and_or_b32 v43, v36, s95, v4
	v_and_b32_e32 v4, 0xffff, v5
	global_store_dwordx4 v[32:33], v[40:43], off offset:1040
	s_nop 1
	v_lshl_or_b32 v40, v9, 16, v4
	v_and_b32_e32 v4, 0xffff, v13
	v_lshl_or_b32 v41, v17, 16, v4
	v_and_b32_e32 v4, 0xffff, v21
	v_lshl_or_b32 v42, v25, 16, v4
	v_and_b32_e32 v4, 0xffff, v29
	v_lshl_or_b32 v43, v37, 16, v4
	v_lshrrev_b32_e32 v4, 16, v5
	global_store_dwordx4 v[32:33], v[40:43], off offset:1056
	v_lshrrev_b32_e32 v5, 16, v15
	v_and_or_b32 v5, v19, s95, v5
	v_and_or_b32 v40, v9, s95, v4
	v_lshrrev_b32_e32 v4, 16, v13
	v_and_or_b32 v41, v17, s95, v4
	v_lshrrev_b32_e32 v4, 16, v21
	v_and_or_b32 v42, v25, s95, v4
	v_lshrrev_b32_e32 v4, 16, v29
	v_and_or_b32 v43, v37, s95, v4
	v_and_b32_e32 v4, 0xffff, v6
	global_store_dwordx4 v[32:33], v[40:43], off offset:1072
	s_nop 1
	v_lshl_or_b32 v40, v10, 16, v4
	v_and_b32_e32 v4, 0xffff, v14
	v_lshl_or_b32 v41, v18, 16, v4
	v_and_b32_e32 v4, 0xffff, v22
	v_lshl_or_b32 v42, v26, 16, v4
	v_and_b32_e32 v4, 0xffff, v30
	v_lshl_or_b32 v43, v38, 16, v4
	v_lshrrev_b32_e32 v4, 16, v6
	global_store_dwordx4 v[32:33], v[40:43], off offset:1088
	v_lshrrev_b32_e32 v6, 16, v23
	v_and_or_b32 v6, v27, s95, v6
	v_and_or_b32 v40, v10, s95, v4
	v_lshrrev_b32_e32 v4, 16, v14
	v_and_or_b32 v41, v18, s95, v4
	v_lshrrev_b32_e32 v4, 16, v22
	v_and_or_b32 v42, v26, s95, v4
	v_lshrrev_b32_e32 v4, 16, v30
	v_and_or_b32 v43, v38, s95, v4
	v_and_b32_e32 v4, 0xffff, v7
	global_store_dwordx4 v[32:33], v[40:43], off offset:1104
	s_nop 1
	v_lshl_or_b32 v40, v11, 16, v4
	v_and_b32_e32 v4, 0xffff, v15
	v_lshl_or_b32 v41, v19, 16, v4
	v_and_b32_e32 v4, 0xffff, v23
	v_lshl_or_b32 v42, v27, 16, v4
	v_and_b32_e32 v4, 0xffff, v31
	v_lshl_or_b32 v43, v39, 16, v4
	v_lshrrev_b32_e32 v4, 16, v7
	v_lshrrev_b32_e32 v7, 16, v31
	v_and_or_b32 v4, v11, s95, v4
	v_and_or_b32 v7, v39, s95, v7
	global_store_dwordx4 v[32:33], v[4:7], off offset:1136
	global_store_dwordx4 v[32:33], v[40:43], off offset:1120
	s_nop 0
	v_add_co_u32_e32 v4, vcc, s27, v34
	s_nop 1
	v_addc_co_u32_e32 v5, vcc, 0, v35, vcc
	v_add_co_u32_e32 v8, vcc, s28, v34
	global_load_dwordx4 v[4:7], v[4:5], off offset:3072
	s_nop 0
	v_addc_co_u32_e32 v9, vcc, 0, v35, vcc
	v_add_co_u32_e32 v12, vcc, s0, v34
	s_mov_b32 s0, 0x4a000
	s_nop 0
	v_addc_co_u32_e32 v13, vcc, 0, v35, vcc
	v_add_co_u32_e32 v16, vcc, s29, v34
	global_load_dwordx4 v[12:15], v[12:13], off
	s_nop 0
	v_addc_co_u32_e32 v17, vcc, 0, v35, vcc
	v_add_co_u32_e32 v20, vcc, s0, v34
	s_mov_b32 s0, 0x52000
	s_nop 0
	v_addc_co_u32_e32 v21, vcc, 0, v35, vcc
	v_add_co_u32_e32 v24, vcc, s30, v34
	global_load_dwordx4 v[20:23], v[20:21], off offset:1024
	s_nop 0
	v_addc_co_u32_e32 v25, vcc, 0, v35, vcc
	v_add_co_u32_e32 v28, vcc, s31, v34
	global_load_dwordx4 v[8:11], v[8:9], off offset:1536
	s_nop 0
	v_addc_co_u32_e32 v29, vcc, 0, v35, vcc
	v_add_co_u32_e32 v36, vcc, s0, v34
	global_load_dwordx4 v[28:31], v[28:29], off offset:2048
	s_nop 0
	v_addc_co_u32_e32 v37, vcc, 0, v35, vcc
	global_load_dwordx4 v[16:19], v[16:17], off offset:2560
	s_mov_b32 s0, 0x5a000
	global_load_dwordx4 v[24:27], v[24:25], off offset:3584
	s_waitcnt vmcnt(6)
	v_and_b32_e32 v40, 0xffff, v4
	global_load_dwordx4 v[36:39], v[36:37], off offset:512
	v_lshrrev_b32_e32 v4, 16, v4
	s_waitcnt vmcnt(6)
	v_and_b32_e32 v41, 0xffff, v12
	s_waitcnt vmcnt(5)
	v_and_b32_e32 v42, 0xffff, v20
	s_waitcnt vmcnt(4)
	v_lshl_or_b32 v40, v8, 16, v40
	s_waitcnt vmcnt(3)
	v_and_b32_e32 v43, 0xffff, v28
	s_waitcnt vmcnt(2)
	v_lshl_or_b32 v41, v16, 16, v41
	s_waitcnt vmcnt(1)
	v_lshl_or_b32 v42, v24, 16, v42
	s_waitcnt vmcnt(0)
	v_lshl_or_b32 v43, v36, 16, v43
	global_store_dwordx4 v[32:33], v[40:43], off offset:1536
	s_nop 1
	v_and_or_b32 v40, v8, s95, v4
	v_lshrrev_b32_e32 v4, 16, v12
	v_and_or_b32 v41, v16, s95, v4
	v_lshrrev_b32_e32 v4, 16, v20
	v_and_or_b32 v42, v24, s95, v4
	v_lshrrev_b32_e32 v4, 16, v28
	v_and_or_b32 v43, v36, s95, v4
	v_and_b32_e32 v4, 0xffff, v5
	global_store_dwordx4 v[32:33], v[40:43], off offset:1552
	s_nop 1
	v_lshl_or_b32 v40, v9, 16, v4
	v_and_b32_e32 v4, 0xffff, v13
	v_lshl_or_b32 v41, v17, 16, v4
	v_and_b32_e32 v4, 0xffff, v21
	v_lshl_or_b32 v42, v25, 16, v4
	v_and_b32_e32 v4, 0xffff, v29
	v_lshl_or_b32 v43, v37, 16, v4
	v_lshrrev_b32_e32 v4, 16, v5
	global_store_dwordx4 v[32:33], v[40:43], off offset:1568
	v_lshrrev_b32_e32 v5, 16, v15
	v_and_or_b32 v5, v19, s95, v5
	v_and_or_b32 v40, v9, s95, v4
	v_lshrrev_b32_e32 v4, 16, v13
	v_and_or_b32 v41, v17, s95, v4
	v_lshrrev_b32_e32 v4, 16, v21
	v_and_or_b32 v42, v25, s95, v4
	v_lshrrev_b32_e32 v4, 16, v29
	v_and_or_b32 v43, v37, s95, v4
	v_and_b32_e32 v4, 0xffff, v6
	global_store_dwordx4 v[32:33], v[40:43], off offset:1584
	s_nop 1
	v_lshl_or_b32 v40, v10, 16, v4
	v_and_b32_e32 v4, 0xffff, v14
	v_lshl_or_b32 v41, v18, 16, v4
	v_and_b32_e32 v4, 0xffff, v22
	v_lshl_or_b32 v42, v26, 16, v4
	v_and_b32_e32 v4, 0xffff, v30
	v_lshl_or_b32 v43, v38, 16, v4
	v_lshrrev_b32_e32 v4, 16, v6
	global_store_dwordx4 v[32:33], v[40:43], off offset:1600
	v_lshrrev_b32_e32 v6, 16, v23
	v_and_or_b32 v6, v27, s95, v6
	v_and_or_b32 v40, v10, s95, v4
	v_lshrrev_b32_e32 v4, 16, v14
	v_and_or_b32 v41, v18, s95, v4
	v_lshrrev_b32_e32 v4, 16, v22
	v_and_or_b32 v42, v26, s95, v4
	v_lshrrev_b32_e32 v4, 16, v30
	v_and_or_b32 v43, v38, s95, v4
	v_and_b32_e32 v4, 0xffff, v7
	global_store_dwordx4 v[32:33], v[40:43], off offset:1616
	s_nop 1
	v_lshl_or_b32 v40, v11, 16, v4
	v_and_b32_e32 v4, 0xffff, v15
	v_lshl_or_b32 v41, v19, 16, v4
	v_and_b32_e32 v4, 0xffff, v23
	v_lshl_or_b32 v42, v27, 16, v4
	v_and_b32_e32 v4, 0xffff, v31
	v_lshl_or_b32 v43, v39, 16, v4
	v_lshrrev_b32_e32 v4, 16, v7
	v_lshrrev_b32_e32 v7, 16, v31
	v_and_or_b32 v4, v11, s95, v4
	v_and_or_b32 v7, v39, s95, v7
	global_store_dwordx4 v[32:33], v[4:7], off offset:1648
	global_store_dwordx4 v[32:33], v[40:43], off offset:1632
	s_nop 0
	v_add_co_u32_e32 v4, vcc, s34, v34
	s_nop 1
	v_addc_co_u32_e32 v5, vcc, 0, v35, vcc
	v_add_co_u32_e32 v8, vcc, s35, v34
	global_load_dwordx4 v[4:7], v[4:5], off offset:3072
	s_nop 0
	v_addc_co_u32_e32 v9, vcc, 0, v35, vcc
	v_add_co_u32_e32 v12, vcc, s0, v34
	s_mov_b32 s0, 0x5f000
	s_nop 0
	v_addc_co_u32_e32 v13, vcc, 0, v35, vcc
	v_add_co_u32_e32 v16, vcc, s46, v34
	global_load_dwordx4 v[12:15], v[12:13], off
	s_nop 0
	v_addc_co_u32_e32 v17, vcc, 0, v35, vcc
	v_add_co_u32_e32 v20, vcc, s0, v34
	s_mov_b32 s0, 0x67000
	s_nop 0
	v_addc_co_u32_e32 v21, vcc, 0, v35, vcc
	v_add_co_u32_e32 v24, vcc, s47, v34
	global_load_dwordx4 v[20:23], v[20:21], off offset:1024
	s_nop 0
	v_addc_co_u32_e32 v25, vcc, 0, v35, vcc
	v_add_co_u32_e32 v28, vcc, s48, v34
	global_load_dwordx4 v[8:11], v[8:9], off offset:1536
	s_nop 0
	v_addc_co_u32_e32 v29, vcc, 0, v35, vcc
	v_add_co_u32_e32 v36, vcc, s0, v34
	global_load_dwordx4 v[28:31], v[28:29], off offset:2048
	s_nop 0
	v_addc_co_u32_e32 v37, vcc, 0, v35, vcc
	global_load_dwordx4 v[16:19], v[16:17], off offset:2560
	s_mov_b32 s0, 0x6f000
	global_load_dwordx4 v[24:27], v[24:25], off offset:3584
	s_waitcnt vmcnt(6)
	v_and_b32_e32 v40, 0xffff, v4
	global_load_dwordx4 v[36:39], v[36:37], off offset:512
	v_lshrrev_b32_e32 v4, 16, v4
	s_waitcnt vmcnt(6)
	v_and_b32_e32 v41, 0xffff, v12
	s_waitcnt vmcnt(5)
	v_and_b32_e32 v42, 0xffff, v20
	s_waitcnt vmcnt(4)
	v_lshl_or_b32 v40, v8, 16, v40
	s_waitcnt vmcnt(3)
	v_and_b32_e32 v43, 0xffff, v28
	s_waitcnt vmcnt(2)
	v_lshl_or_b32 v41, v16, 16, v41
	s_waitcnt vmcnt(1)
	v_lshl_or_b32 v42, v24, 16, v42
	s_waitcnt vmcnt(0)
	v_lshl_or_b32 v43, v36, 16, v43
	global_store_dwordx4 v[32:33], v[40:43], off offset:2048
	s_nop 1
	v_and_or_b32 v40, v8, s95, v4
	v_lshrrev_b32_e32 v4, 16, v12
	v_and_or_b32 v41, v16, s95, v4
	v_lshrrev_b32_e32 v4, 16, v20
	v_and_or_b32 v42, v24, s95, v4
	v_lshrrev_b32_e32 v4, 16, v28
	v_and_or_b32 v43, v36, s95, v4
	v_and_b32_e32 v4, 0xffff, v5
	global_store_dwordx4 v[32:33], v[40:43], off offset:2064
	s_nop 1
	v_lshl_or_b32 v40, v9, 16, v4
	v_and_b32_e32 v4, 0xffff, v13
	v_lshl_or_b32 v41, v17, 16, v4
	v_and_b32_e32 v4, 0xffff, v21
	v_lshl_or_b32 v42, v25, 16, v4
	v_and_b32_e32 v4, 0xffff, v29
	v_lshl_or_b32 v43, v37, 16, v4
	v_lshrrev_b32_e32 v4, 16, v5
	global_store_dwordx4 v[32:33], v[40:43], off offset:2080
	v_lshrrev_b32_e32 v5, 16, v15
	v_and_or_b32 v5, v19, s95, v5
	v_and_or_b32 v40, v9, s95, v4
	v_lshrrev_b32_e32 v4, 16, v13
	v_and_or_b32 v41, v17, s95, v4
	v_lshrrev_b32_e32 v4, 16, v21
	v_and_or_b32 v42, v25, s95, v4
	v_lshrrev_b32_e32 v4, 16, v29
	v_and_or_b32 v43, v37, s95, v4
	v_and_b32_e32 v4, 0xffff, v6
	global_store_dwordx4 v[32:33], v[40:43], off offset:2096
	s_nop 1
	v_lshl_or_b32 v40, v10, 16, v4
	v_and_b32_e32 v4, 0xffff, v14
	v_lshl_or_b32 v41, v18, 16, v4
	v_and_b32_e32 v4, 0xffff, v22
	v_lshl_or_b32 v42, v26, 16, v4
	v_and_b32_e32 v4, 0xffff, v30
	v_lshl_or_b32 v43, v38, 16, v4
	v_lshrrev_b32_e32 v4, 16, v6
	global_store_dwordx4 v[32:33], v[40:43], off offset:2112
	v_lshrrev_b32_e32 v6, 16, v23
	v_and_or_b32 v6, v27, s95, v6
	v_and_or_b32 v40, v10, s95, v4
	v_lshrrev_b32_e32 v4, 16, v14
	v_and_or_b32 v41, v18, s95, v4
	v_lshrrev_b32_e32 v4, 16, v22
	v_and_or_b32 v42, v26, s95, v4
	v_lshrrev_b32_e32 v4, 16, v30
	v_and_or_b32 v43, v38, s95, v4
	v_and_b32_e32 v4, 0xffff, v7
	global_store_dwordx4 v[32:33], v[40:43], off offset:2128
	s_nop 1
	v_lshl_or_b32 v40, v11, 16, v4
	v_and_b32_e32 v4, 0xffff, v15
	v_lshl_or_b32 v41, v19, 16, v4
	v_and_b32_e32 v4, 0xffff, v23
	v_lshl_or_b32 v42, v27, 16, v4
	v_and_b32_e32 v4, 0xffff, v31
	v_lshl_or_b32 v43, v39, 16, v4
	v_lshrrev_b32_e32 v4, 16, v7
	v_lshrrev_b32_e32 v7, 16, v31
	v_and_or_b32 v4, v11, s95, v4
	v_and_or_b32 v7, v39, s95, v7
	global_store_dwordx4 v[32:33], v[4:7], off offset:2160
	global_store_dwordx4 v[32:33], v[40:43], off offset:2144
	s_nop 0
	v_add_co_u32_e32 v4, vcc, s49, v34
	s_nop 1
	v_addc_co_u32_e32 v5, vcc, 0, v35, vcc
	v_add_co_u32_e32 v8, vcc, s50, v34
	global_load_dwordx4 v[4:7], v[4:5], off offset:3072
	s_nop 0
	v_addc_co_u32_e32 v9, vcc, 0, v35, vcc
	v_add_co_u32_e32 v12, vcc, s0, v34
	s_mov_b32 s0, 0x74000
	s_nop 0
	v_addc_co_u32_e32 v13, vcc, 0, v35, vcc
	v_add_co_u32_e32 v16, vcc, s55, v34
	global_load_dwordx4 v[12:15], v[12:13], off
	s_nop 0
	v_addc_co_u32_e32 v17, vcc, 0, v35, vcc
	v_add_co_u32_e32 v20, vcc, s0, v34
	s_mov_b32 s0, 0x7c000
	s_nop 0
	v_addc_co_u32_e32 v21, vcc, 0, v35, vcc
	v_add_co_u32_e32 v24, vcc, s56, v34
	global_load_dwordx4 v[20:23], v[20:21], off offset:1024
	s_nop 0
	v_addc_co_u32_e32 v25, vcc, 0, v35, vcc
	v_add_co_u32_e32 v28, vcc, s57, v34
	global_load_dwordx4 v[8:11], v[8:9], off offset:1536
	s_nop 0
	v_addc_co_u32_e32 v29, vcc, 0, v35, vcc
	v_add_co_u32_e32 v36, vcc, s0, v34
	global_load_dwordx4 v[28:31], v[28:29], off offset:2048
	s_nop 0
	v_addc_co_u32_e32 v37, vcc, 0, v35, vcc
	global_load_dwordx4 v[16:19], v[16:17], off offset:2560
	s_mov_b32 s0, 0x84000
	global_load_dwordx4 v[24:27], v[24:25], off offset:3584
	v_readlane_b32 s56, v253, 10
	global_load_dwordx4 v[36:39], v[36:37], off offset:512
	v_readlane_b32 s57, v253, 11
	s_waitcnt vmcnt(7)
	v_and_b32_e32 v40, 0xffff, v4
	v_lshrrev_b32_e32 v4, 16, v4
	s_waitcnt vmcnt(6)
	v_and_b32_e32 v41, 0xffff, v12
	s_waitcnt vmcnt(5)
	v_and_b32_e32 v42, 0xffff, v20
	s_waitcnt vmcnt(4)
	v_lshl_or_b32 v40, v8, 16, v40
	s_waitcnt vmcnt(3)
	v_and_b32_e32 v43, 0xffff, v28
	s_waitcnt vmcnt(2)
	v_lshl_or_b32 v41, v16, 16, v41
	s_waitcnt vmcnt(1)
	v_lshl_or_b32 v42, v24, 16, v42
	s_waitcnt vmcnt(0)
	v_lshl_or_b32 v43, v36, 16, v43
	global_store_dwordx4 v[32:33], v[40:43], off offset:2560
	s_nop 1
	v_and_or_b32 v40, v8, s95, v4
	v_lshrrev_b32_e32 v4, 16, v12
	v_and_or_b32 v41, v16, s95, v4
	v_lshrrev_b32_e32 v4, 16, v20
	v_and_or_b32 v42, v24, s95, v4
	v_lshrrev_b32_e32 v4, 16, v28
	v_and_or_b32 v43, v36, s95, v4
	v_and_b32_e32 v4, 0xffff, v5
	global_store_dwordx4 v[32:33], v[40:43], off offset:2576
	s_nop 1
	v_lshl_or_b32 v40, v9, 16, v4
	v_and_b32_e32 v4, 0xffff, v13
	v_lshl_or_b32 v41, v17, 16, v4
	v_and_b32_e32 v4, 0xffff, v21
	v_lshl_or_b32 v42, v25, 16, v4
	v_and_b32_e32 v4, 0xffff, v29
	v_lshl_or_b32 v43, v37, 16, v4
	v_lshrrev_b32_e32 v4, 16, v5
	global_store_dwordx4 v[32:33], v[40:43], off offset:2592
	v_lshrrev_b32_e32 v5, 16, v15
	v_and_or_b32 v5, v19, s95, v5
	v_and_or_b32 v40, v9, s95, v4
	v_lshrrev_b32_e32 v4, 16, v13
	v_and_or_b32 v41, v17, s95, v4
	v_lshrrev_b32_e32 v4, 16, v21
	v_and_or_b32 v42, v25, s95, v4
	v_lshrrev_b32_e32 v4, 16, v29
	v_and_or_b32 v43, v37, s95, v4
	v_and_b32_e32 v4, 0xffff, v6
	global_store_dwordx4 v[32:33], v[40:43], off offset:2608
	s_nop 1
	v_lshl_or_b32 v40, v10, 16, v4
	v_and_b32_e32 v4, 0xffff, v14
	v_lshl_or_b32 v41, v18, 16, v4
	v_and_b32_e32 v4, 0xffff, v22
	v_lshl_or_b32 v42, v26, 16, v4
	v_and_b32_e32 v4, 0xffff, v30
	v_lshl_or_b32 v43, v38, 16, v4
	v_lshrrev_b32_e32 v4, 16, v6
	global_store_dwordx4 v[32:33], v[40:43], off offset:2624
	v_lshrrev_b32_e32 v6, 16, v23
	v_and_or_b32 v6, v27, s95, v6
	v_and_or_b32 v40, v10, s95, v4
	v_lshrrev_b32_e32 v4, 16, v14
	v_and_or_b32 v41, v18, s95, v4
	v_lshrrev_b32_e32 v4, 16, v22
	v_and_or_b32 v42, v26, s95, v4
	v_lshrrev_b32_e32 v4, 16, v30
	v_and_or_b32 v43, v38, s95, v4
	v_and_b32_e32 v4, 0xffff, v7
	global_store_dwordx4 v[32:33], v[40:43], off offset:2640
	s_nop 1
	v_lshl_or_b32 v40, v11, 16, v4
	v_and_b32_e32 v4, 0xffff, v15
	v_lshl_or_b32 v41, v19, 16, v4
	v_and_b32_e32 v4, 0xffff, v23
	v_lshl_or_b32 v42, v27, 16, v4
	v_and_b32_e32 v4, 0xffff, v31
	v_lshl_or_b32 v43, v39, 16, v4
	v_lshrrev_b32_e32 v4, 16, v7
	v_lshrrev_b32_e32 v7, 16, v31
	v_and_or_b32 v4, v11, s95, v4
	v_and_or_b32 v7, v39, s95, v7
	global_store_dwordx4 v[32:33], v[4:7], off offset:2672
	global_store_dwordx4 v[32:33], v[40:43], off offset:2656
	s_nop 0
	v_add_co_u32_e32 v4, vcc, s60, v34
	s_nop 1
	v_addc_co_u32_e32 v5, vcc, 0, v35, vcc
	v_add_co_u32_e32 v8, vcc, s62, v34
	global_load_dwordx4 v[4:7], v[4:5], off offset:3072
	s_nop 0
	v_addc_co_u32_e32 v9, vcc, 0, v35, vcc
	v_add_co_u32_e32 v12, vcc, s0, v34
	s_mov_b32 s0, 0x89000
	s_nop 0
	v_addc_co_u32_e32 v13, vcc, 0, v35, vcc
	v_add_co_u32_e32 v16, vcc, s63, v34
	global_load_dwordx4 v[12:15], v[12:13], off
	s_nop 0
	v_addc_co_u32_e32 v17, vcc, 0, v35, vcc
	v_add_co_u32_e32 v20, vcc, s0, v34
	s_mov_b32 s0, 0x91000
	s_nop 0
	v_addc_co_u32_e32 v21, vcc, 0, v35, vcc
	v_add_co_u32_e32 v24, vcc, s64, v34
	global_load_dwordx4 v[20:23], v[20:21], off offset:1024
	s_nop 0
	v_addc_co_u32_e32 v25, vcc, 0, v35, vcc
	v_add_co_u32_e32 v28, vcc, s65, v34
	global_load_dwordx4 v[8:11], v[8:9], off offset:1536
	s_nop 0
	v_addc_co_u32_e32 v29, vcc, 0, v35, vcc
	v_add_co_u32_e32 v36, vcc, s0, v34
	global_load_dwordx4 v[28:31], v[28:29], off offset:2048
	s_nop 0
	v_addc_co_u32_e32 v37, vcc, 0, v35, vcc
	global_load_dwordx4 v[16:19], v[16:17], off offset:2560
	s_mov_b32 s0, 0x99000
	global_load_dwordx4 v[24:27], v[24:25], off offset:3584
	s_waitcnt vmcnt(6)
	v_and_b32_e32 v40, 0xffff, v4
	global_load_dwordx4 v[36:39], v[36:37], off offset:512
	v_lshrrev_b32_e32 v4, 16, v4
	s_waitcnt vmcnt(6)
	v_and_b32_e32 v41, 0xffff, v12
	s_waitcnt vmcnt(5)
	v_and_b32_e32 v42, 0xffff, v20
	s_waitcnt vmcnt(4)
	v_lshl_or_b32 v40, v8, 16, v40
	s_waitcnt vmcnt(3)
	v_and_b32_e32 v43, 0xffff, v28
	s_waitcnt vmcnt(2)
	v_lshl_or_b32 v41, v16, 16, v41
	s_waitcnt vmcnt(1)
	v_lshl_or_b32 v42, v24, 16, v42
	s_waitcnt vmcnt(0)
	v_lshl_or_b32 v43, v36, 16, v43
	global_store_dwordx4 v[32:33], v[40:43], off offset:3072
	s_nop 1
	v_and_or_b32 v40, v8, s95, v4
	v_lshrrev_b32_e32 v4, 16, v12
	v_and_or_b32 v41, v16, s95, v4
	v_lshrrev_b32_e32 v4, 16, v20
	v_and_or_b32 v42, v24, s95, v4
	v_lshrrev_b32_e32 v4, 16, v28
	v_and_or_b32 v43, v36, s95, v4
	v_and_b32_e32 v4, 0xffff, v5
	global_store_dwordx4 v[32:33], v[40:43], off offset:3088
	s_nop 1
	v_lshl_or_b32 v40, v9, 16, v4
	v_and_b32_e32 v4, 0xffff, v13
	v_lshl_or_b32 v41, v17, 16, v4
	v_and_b32_e32 v4, 0xffff, v21
	v_lshl_or_b32 v42, v25, 16, v4
	v_and_b32_e32 v4, 0xffff, v29
	v_lshl_or_b32 v43, v37, 16, v4
	v_lshrrev_b32_e32 v4, 16, v5
	global_store_dwordx4 v[32:33], v[40:43], off offset:3104
	v_lshrrev_b32_e32 v5, 16, v15
	v_and_or_b32 v5, v19, s95, v5
	v_and_or_b32 v40, v9, s95, v4
	v_lshrrev_b32_e32 v4, 16, v13
	v_and_or_b32 v41, v17, s95, v4
	v_lshrrev_b32_e32 v4, 16, v21
	v_and_or_b32 v42, v25, s95, v4
	v_lshrrev_b32_e32 v4, 16, v29
	v_and_or_b32 v43, v37, s95, v4
	v_and_b32_e32 v4, 0xffff, v6
	global_store_dwordx4 v[32:33], v[40:43], off offset:3120
	s_nop 1
	v_lshl_or_b32 v40, v10, 16, v4
	v_and_b32_e32 v4, 0xffff, v14
	v_lshl_or_b32 v41, v18, 16, v4
	v_and_b32_e32 v4, 0xffff, v22
	v_lshl_or_b32 v42, v26, 16, v4
	v_and_b32_e32 v4, 0xffff, v30
	v_lshl_or_b32 v43, v38, 16, v4
	v_lshrrev_b32_e32 v4, 16, v6
	global_store_dwordx4 v[32:33], v[40:43], off offset:3136
	v_lshrrev_b32_e32 v6, 16, v23
	v_and_or_b32 v6, v27, s95, v6
	v_and_or_b32 v40, v10, s95, v4
	v_lshrrev_b32_e32 v4, 16, v14
	v_and_or_b32 v41, v18, s95, v4
	v_lshrrev_b32_e32 v4, 16, v22
	v_and_or_b32 v42, v26, s95, v4
	v_lshrrev_b32_e32 v4, 16, v30
	v_and_or_b32 v43, v38, s95, v4
	v_and_b32_e32 v4, 0xffff, v7
	global_store_dwordx4 v[32:33], v[40:43], off offset:3152
	s_nop 1
	v_lshl_or_b32 v40, v11, 16, v4
	v_and_b32_e32 v4, 0xffff, v15
	v_lshl_or_b32 v41, v19, 16, v4
	v_and_b32_e32 v4, 0xffff, v23
	v_lshl_or_b32 v42, v27, 16, v4
	v_and_b32_e32 v4, 0xffff, v31
	v_lshl_or_b32 v43, v39, 16, v4
	v_lshrrev_b32_e32 v4, 16, v7
	v_lshrrev_b32_e32 v7, 16, v31
	v_and_or_b32 v4, v11, s95, v4
	v_and_or_b32 v7, v39, s95, v7
	global_store_dwordx4 v[32:33], v[4:7], off offset:3184
	global_store_dwordx4 v[32:33], v[40:43], off offset:3168
	s_nop 0
	v_add_co_u32_e32 v4, vcc, s69, v34
	s_nop 1
	v_addc_co_u32_e32 v5, vcc, 0, v35, vcc
	v_add_co_u32_e32 v8, vcc, s70, v34
	global_load_dwordx4 v[4:7], v[4:5], off offset:3072
	s_nop 0
	v_addc_co_u32_e32 v9, vcc, 0, v35, vcc
	v_add_co_u32_e32 v12, vcc, s0, v34
	s_mov_b32 s0, 0x9e000
	s_nop 0
	v_addc_co_u32_e32 v13, vcc, 0, v35, vcc
	v_add_co_u32_e32 v16, vcc, s71, v34
	global_load_dwordx4 v[12:15], v[12:13], off
	s_nop 0
	v_addc_co_u32_e32 v17, vcc, 0, v35, vcc
	v_add_co_u32_e32 v20, vcc, s0, v34
	s_mov_b32 s0, 0xa6000
	s_nop 0
	v_addc_co_u32_e32 v21, vcc, 0, v35, vcc
	v_add_co_u32_e32 v24, vcc, s10, v34
	global_load_dwordx4 v[20:23], v[20:21], off offset:1024
	s_nop 0
	v_addc_co_u32_e32 v25, vcc, 0, v35, vcc
	v_add_co_u32_e32 v28, vcc, s73, v34
	global_load_dwordx4 v[8:11], v[8:9], off offset:1536
	s_nop 0
	v_addc_co_u32_e32 v29, vcc, 0, v35, vcc
	v_add_co_u32_e32 v34, vcc, s0, v34
	global_load_dwordx4 v[28:31], v[28:29], off offset:2048
	s_nop 0
	v_addc_co_u32_e32 v35, vcc, 0, v35, vcc
	global_load_dwordx4 v[16:19], v[16:17], off offset:2560
	s_waitcnt vmcnt(5)
	v_and_b32_e32 v38, 0xffff, v4
	global_load_dwordx4 v[24:27], v[24:25], off offset:3584
	v_lshrrev_b32_e32 v4, 16, v4
	global_load_dwordx4 v[34:37], v[34:35], off offset:512
	s_waitcnt vmcnt(6)
	v_and_b32_e32 v39, 0xffff, v12
	s_waitcnt vmcnt(5)
	v_and_b32_e32 v40, 0xffff, v20
	s_waitcnt vmcnt(4)
	v_lshl_or_b32 v38, v8, 16, v38
	s_waitcnt vmcnt(3)
	v_and_b32_e32 v41, 0xffff, v28
	s_waitcnt vmcnt(2)
	v_lshl_or_b32 v39, v16, 16, v39
	s_waitcnt vmcnt(1)
	v_lshl_or_b32 v40, v24, 16, v40
	s_waitcnt vmcnt(0)
	v_lshl_or_b32 v41, v34, 16, v41
	global_store_dwordx4 v[32:33], v[38:41], off offset:3584
	s_nop 1
	v_and_or_b32 v38, v8, s95, v4
	v_lshrrev_b32_e32 v4, 16, v12
	v_and_or_b32 v39, v16, s95, v4
	v_lshrrev_b32_e32 v4, 16, v20
	v_and_or_b32 v40, v24, s95, v4
	v_lshrrev_b32_e32 v4, 16, v28
	v_and_or_b32 v41, v34, s95, v4
	v_and_b32_e32 v4, 0xffff, v5
	global_store_dwordx4 v[32:33], v[38:41], off offset:3600
	s_nop 1
	v_lshl_or_b32 v38, v9, 16, v4
	v_and_b32_e32 v4, 0xffff, v13
	v_lshl_or_b32 v39, v17, 16, v4
	v_and_b32_e32 v4, 0xffff, v21
	v_lshl_or_b32 v40, v25, 16, v4
	v_and_b32_e32 v4, 0xffff, v29
	v_lshl_or_b32 v41, v35, 16, v4
	v_lshrrev_b32_e32 v4, 16, v5
	global_store_dwordx4 v[32:33], v[38:41], off offset:3616
	v_lshrrev_b32_e32 v5, 16, v15
	v_and_or_b32 v5, v19, s95, v5
	v_and_or_b32 v38, v9, s95, v4
	v_lshrrev_b32_e32 v4, 16, v13
	v_and_or_b32 v39, v17, s95, v4
	v_lshrrev_b32_e32 v4, 16, v21
	v_and_or_b32 v40, v25, s95, v4
	v_lshrrev_b32_e32 v4, 16, v29
	v_and_or_b32 v41, v35, s95, v4
	v_and_b32_e32 v4, 0xffff, v6
	global_store_dwordx4 v[32:33], v[38:41], off offset:3632
	s_nop 1
	v_lshl_or_b32 v38, v10, 16, v4
	v_and_b32_e32 v4, 0xffff, v14
	v_lshl_or_b32 v39, v18, 16, v4
	v_and_b32_e32 v4, 0xffff, v22
	v_lshl_or_b32 v40, v26, 16, v4
	v_and_b32_e32 v4, 0xffff, v30
	v_lshl_or_b32 v41, v36, 16, v4
	v_lshrrev_b32_e32 v4, 16, v6
	global_store_dwordx4 v[32:33], v[38:41], off offset:3648
	v_lshrrev_b32_e32 v6, 16, v23
	v_and_or_b32 v6, v27, s95, v6
	v_and_or_b32 v38, v10, s95, v4
	v_lshrrev_b32_e32 v4, 16, v14
	v_and_or_b32 v39, v18, s95, v4
	v_lshrrev_b32_e32 v4, 16, v22
	v_and_or_b32 v40, v26, s95, v4
	v_lshrrev_b32_e32 v4, 16, v30
	v_and_or_b32 v41, v36, s95, v4
	v_and_b32_e32 v4, 0xffff, v7
	global_store_dwordx4 v[32:33], v[38:41], off offset:3664
	s_nop 1
	v_lshl_or_b32 v38, v11, 16, v4
	v_and_b32_e32 v4, 0xffff, v15
	v_lshl_or_b32 v39, v19, 16, v4
	v_and_b32_e32 v4, 0xffff, v23
	v_lshl_or_b32 v40, v27, 16, v4
	v_and_b32_e32 v4, 0xffff, v31
	v_lshl_or_b32 v41, v37, 16, v4
	v_lshrrev_b32_e32 v4, 16, v7
	v_lshrrev_b32_e32 v7, 16, v31
	v_and_or_b32 v4, v11, s95, v4
	v_and_or_b32 v7, v37, s95, v7
	global_store_dwordx4 v[32:33], v[38:41], off offset:3680
	global_store_dwordx4 v[32:33], v[4:7], off offset:3696
	s_branch .LBB0_566
